# prep: packed-f32 forward substitution on 4 waves with prefetched L ring replaces compiler solve
# speedup vs baseline: 1.0249x; 1.0249x over previous
; __device__ __forceinline__ void dn_prep_task(const P& p, int task, unsigned char* sm, int tid) {
;     const int h = task & 3, bc = task >> 2, ck = bc % 36, b = bc / 36;
;     const int m0 = ck < 4 ? MLAT + b * TCTX + ck * 64 : b * TLAT + (ck - 4) * 64;
;     const int wave = tid >> 6, lane = tid & 63, dir = tid >> 8, t2 = tid & 255;
;     bf16_t* kn_s = (bf16_t*)sm;
;     bf16_t* qn_s = kn_s + 64 * 136;
;     float* KK = (float*)(sm + 34816);
;     float* QK = KK + 64 * 65;
;     float* gc_s = (float*)(sm + 68096);
;     float* be_s = gc_s + 128;
;     float* Ls = be_s + 128;
;     bf16_t* v_s = (bf16_t*)(sm + 101888);
;     {
;         const int r = tid >> 3, c16 = (tid & 7) * 16;
;         const bf16_t* ks = (const bf16_t*)(p.ws + WS_KN) + (size_t)(m0 + r) * 512 + h * 128 + c16;
;         const bf16_t* qs = (const bf16_t*)(p.ws + WS_QN) + (size_t)(m0 + r) * 512 + h * 128 + c16;
;         *(u32x4*)(kn_s + r * 136 + c16) = *(const u32x4*)ks; *(u32x4*)(kn_s + r * 136 + c16 + 8) = *(const u32x4*)(ks + 8);
;         *(u32x4*)(qn_s + r * 136 + c16) = *(const u32x4*)qs; *(u32x4*)(qn_s + r * 136 + c16 + 8) = *(const u32x4*)(qs + 8);
;         const bf16_t* vs = (const bf16_t*)(p.ws + WS_VV) + (size_t)(m0 + r) * 512 + h * 128 + c16;
;         *(u32x4*)(v_s + r * 136 + c16) = *(const u32x4*)vs; *(u32x4*)(v_s + r * 136 + c16 + 8) = *(const u32x4*)(vs + 8);
;     }
;     if (t2 < 64) {
;         const int tok = dir ? 63 - t2 : t2;
;         const float* gb = (const float*)(p.ws + WS_GB) + (size_t)(m0 + tok) * 16;
;         float gv = gb[dir * 4 + h]; const float bv = gb[8 + dir * 4 + h];
; #pragma unroll
;         for (int o = 1; o < 64; o <<= 1) { const float v = __shfl_up(gv, o); if (lane >= o) gv += v; }
;         gc_s[dir * 64 + t2] = gv; be_s[dir * 64 + t2] = bv;
;     }
;     __syncthreads();
;     {
;         const int which = wave >> 2, it = wave & 3, fr = lane & 15, g = lane >> 4;
;         const bf16_t* As = which ? qn_s : kn_s; float* Out = which ? QK : KK;
;         bf16x8 a[4];
; #pragma unroll
;         for (int ks = 0; ks < 4; ++ks) a[ks] = *(const bf16x8*)(As + (it * 16 + fr) * 136 + ks * 32 + g * 8);
; #pragma unroll
;         for (int jt = 0; jt < 4; ++jt) {
;             f32x4 acc = {0.f, 0.f, 0.f, 0.f};
; #pragma unroll
.LBB0_569:
	s_or_b64 exec, exec, s[2:3]
	v_readlane_b32 s2, v253, 62
	v_mov_b32_e32 v0, v1
	v_readlane_b32 s3, v253, 63
	s_waitcnt lgkmcnt(0)
	s_barrier
	s_andn2_b64 vcc, exec, s[2:3]
	v_readfirstlane_b32 s2, v0
	s_cbranch_vccnz .LBB0_665
	v_readlane_b32 s6, v254, 54
	v_readlane_b32 s7, v254, 55
	s_load_dwordx2 s[44:45], s[6:7], s2 offset:0xa8
	s_movk_i32 s1, 0xff
	v_cmp_lt_u32_e64 s[6:7], s1, v144
	v_lshlrev_b32_e32 v88, 4, v144
	v_ashrrev_i32_e32 v9, 3, v144
	s_waitcnt lgkmcnt(0)
	s_add_u32 s46, s44, 0x11300000
	s_addc_u32 s47, s45, 0
	s_add_u32 s48, s44, 0x10100000
	s_addc_u32 s49, s45, 0
	s_add_u32 s28, s44, 0x12500000
	s_addc_u32 s29, s45, 0
	v_writelane_b32 v255, s6, 10
	v_and_b32_e32 v2, 0x70, v88
	s_movk_i32 s3, 0x110
	v_writelane_b32 v255, s7, 11
	s_add_u32 s6, s44, 0xff00000
	v_mul_lo_u32 v0, v9, s3
	v_lshlrev_b32_e32 v3, 1, v2
	v_readlane_b32 s42, v254, 43
	s_addc_u32 s7, s45, 0
	v_add3_u32 v89, 0, v0, v3
	v_add3_u32 v90, s42, v0, v3
	v_and_b32_e32 v0, 63, v144
	v_writelane_b32 v255, s6, 14
	v_and_b32_e32 v8, 0xff, v144
	s_movk_i32 s2, 0x100
	v_writelane_b32 v255, s7, 15
	v_cmp_eq_u32_e64 s[6:7], 0, v0
	v_cmp_gt_u32_e32 vcc, s2, v144
	v_sub_u32_e32 v3, 63, v8
	v_writelane_b32 v255, s6, 16
	v_cndmask_b32_e32 v91, v3, v8, vcc
	v_and_b32_e32 v3, 0xffffff00, v144
	v_writelane_b32 v255, s7, 17
	v_cmp_gt_u32_e64 s[6:7], 2, v0
	v_lshlrev_b32_e32 v6, 2, v8
	v_readlane_b32 s1, v254, 44
	v_writelane_b32 v255, s6, 18
	v_readlane_b32 s50, v254, 45
	v_readlane_b32 s2, v254, 46
	v_writelane_b32 v255, s7, 19
	v_cmp_gt_u32_e64 s[6:7], 4, v0
	s_waitcnt vmcnt(1)
	v_mov_b32_e32 v5, s2
	v_lshrrev_b32_e32 v7, 2, v144
	v_writelane_b32 v255, s6, 20
	v_cndmask_b32_e64 v5, v5, 0, vcc
	v_readlane_b32 s2, v254, 48
	v_writelane_b32 v255, s7, 21
	v_cmp_gt_u32_e64 s[6:7], 8, v0
	v_bfe_u32 v22, v144, 2, 6
	v_ashrrev_i32_e32 v4, 8, v144
	v_writelane_b32 v255, s6, 22
	v_bitop3_b32 v14, v88, 62, 48 bitop3:0x6c
	v_bitop3_b32 v15, v88, 61, 48 bitop3:0x6c
	v_writelane_b32 v255, s7, 23
	v_cmp_gt_u32_e64 s[6:7], 16, v0
	v_bitop3_b32 v13, v88, 63, 48 bitop3:0x6c
	v_bitop3_b32 v20, v88, 60, 48 bitop3:0x6c
	v_writelane_b32 v255, s6, 24
	v_bitop3_b32 v23, v88, 59, 48 bitop3:0x6c
	v_bitop3_b32 v31, v88, 58, 48 bitop3:0x6c
	v_writelane_b32 v255, s7, 25
	v_cmp_gt_u32_e64 s[6:7], 32, v0
	v_or_b32_e32 v0, v3, v6
	v_add_u32_e32 v92, s1, v0
	v_add_u32_e32 v93, s50, v0
	v_and_b32_e32 v0, 15, v144
	v_and_or_b32 v11, v7, 48, v0
	v_mad_u32_u24 v24, v11, s3, v5
	v_mov_b32_e32 v5, s2
	v_readlane_b32 s2, v254, 47
	v_and_b32_e32 v7, 60, v7
	v_mul_u32_u24_e32 v29, 0x104, v7
	v_mov_b32_e32 v11, s2
	v_cndmask_b32_e32 v5, v5, v11, vcc
	v_readlane_b32 s2, v254, 49
	v_xor_b32_e32 v7, 63, v22
	v_writelane_b32 v255, s6, 26
	v_lshl_add_u32 v27, v0, 2, v5
	v_mul_u32_u24_e32 v28, 0x110, v0
	v_lshl_add_u32 v94, v4, 14, s2
	v_and_b32_e32 v0, 48, v88
	v_cndmask_b32_e32 v7, v7, v22, vcc
	s_movk_i32 s2, 0x104
	v_writelane_b32 v255, s7, 27
	v_lshlrev_b32_e32 v11, 8, v22
	v_mad_u32_u24 v12, v7, s2, 0
	v_cmp_gt_u32_e64 s[2:3], v22, v0
	v_lshlrev_b32_e32 v17, 2, v0
	v_add3_u32 v96, v94, v11, v17
	v_writelane_b32 v255, s2, 8
	v_or_b32_e32 v11, 1, v0
	v_or_b32_e32 v21, 4, v0
	v_writelane_b32 v255, s3, 9
	v_cmp_gt_u32_e64 s[2:3], v22, v11
	v_cndmask_b32_e32 v11, v14, v11, vcc
	v_or_b32_e32 v14, 2, v0
	v_writelane_b32 v255, s2, 28
	v_or_b32_e32 v30, 5, v0
	v_or_b32_e32 v32, 6, v0
	v_writelane_b32 v255, s3, 29
	v_cmp_gt_u32_e64 s[2:3], v22, v14
	v_cndmask_b32_e32 v14, v15, v14, vcc
	v_or_b32_e32 v15, 3, v0
	v_writelane_b32 v255, s2, 30
	v_or_b32_e32 v34, 7, v0
	v_or_b32_e32 v36, 8, v0
	v_writelane_b32 v255, s3, 31
	v_cmp_gt_u32_e64 s[2:3], v22, v15
	v_or_b32_e32 v38, 9, v0
	v_or_b32_e32 v40, 10, v0
	v_writelane_b32 v255, s2, 32
	v_or_b32_e32 v42, 11, v0
	v_or_b32_e32 v44, 12, v0
	v_writelane_b32 v255, s3, 33
	v_cmp_gt_u32_e64 s[2:3], v22, v21
	v_or_b32_e32 v46, 13, v0
	v_or_b32_e32 v48, 14, v0
	v_writelane_b32 v255, s2, 34
	v_bitop3_b32 v33, v88, 57, 48 bitop3:0x6c
	v_bitop3_b32 v35, v88, 56, 48 bitop3:0x6c
	v_writelane_b32 v255, s3, 35
	v_cmp_gt_u32_e64 s[2:3], v22, v30
	v_bitop3_b32 v37, v88, 55, 48 bitop3:0x6c
	v_bitop3_b32 v39, v88, 54, 48 bitop3:0x6c
	v_writelane_b32 v255, s2, 36
	v_bitop3_b32 v41, v88, 53, 48 bitop3:0x6c
	v_bitop3_b32 v43, v88, 52, 48 bitop3:0x6c
	v_writelane_b32 v255, s3, 37
	v_cmp_gt_u32_e64 s[2:3], v22, v32
	v_bitop3_b32 v45, v88, 51, 48 bitop3:0x6c
	v_bitop3_b32 v47, v88, 50, 48 bitop3:0x6c
	v_writelane_b32 v255, s2, 38
	v_bitop3_b32 v49, v88, 49, 48 bitop3:0x6c
	v_or_b32_e32 v50, 15, v0
	v_writelane_b32 v255, s3, 39
	v_cmp_gt_u32_e64 s[2:3], v22, v34
	v_bitop3_b32 v51, v88, 48, v88 bitop3:0xc
	v_cndmask_b32_e32 v13, v13, v0, vcc
	v_writelane_b32 v255, s2, 40
	v_cndmask_b32_e32 v15, v20, v15, vcc
	v_cndmask_b32_e32 v21, v23, v21, vcc
	v_writelane_b32 v255, s3, 41
	v_cmp_gt_u32_e64 s[2:3], v22, v36
	v_cndmask_b32_e32 v30, v31, v30, vcc
	v_cndmask_b32_e32 v32, v33, v32, vcc
	v_writelane_b32 v255, s2, 42
	v_cndmask_b32_e32 v34, v35, v34, vcc
	v_cndmask_b32_e32 v36, v37, v36, vcc
	v_writelane_b32 v255, s3, 43
	v_cmp_gt_u32_e64 s[2:3], v22, v38
	v_cndmask_b32_e32 v38, v39, v38, vcc
	v_cmp_gt_u32_e64 s[86:87], v22, v50
	v_writelane_b32 v255, s2, 44
	v_cndmask_b32_e32 v50, v51, v50, vcc
	v_lshlrev_b32_e32 v16, 2, v13
	v_writelane_b32 v255, s3, 45
	v_cmp_gt_u32_e64 s[2:3], v22, v40
; __device__ __forceinline__ void dn_prep_task(const P& p, int task, unsigned char* sm, int tid) {
;     const int h = task & 3, bc = task >> 2, ck = bc % 36, b = bc / 36;
;     const int m0 = ck < 4 ? MLAT + b * TCTX + ck * 64 : b * TLAT + (ck - 4) * 64;
;     const int wave = tid >> 6, lane = tid & 63, dir = tid >> 8, t2 = tid & 255;
;     bf16_t* kn_s = (bf16_t*)sm;
;     bf16_t* qn_s = kn_s + 64 * 136;
;     float* KK = (float*)(sm + 34816);
;     float* QK = KK + 64 * 65;
;     float* gc_s = (float*)(sm + 68096);
;     float* be_s = gc_s + 128;
;     float* Ls = be_s + 128;
;     bf16_t* v_s = (bf16_t*)(sm + 101888);
;     {
;         const int r = tid >> 3, c16 = (tid & 7) * 16;
;         const bf16_t* ks = (const bf16_t*)(p.ws + WS_KN) + (size_t)(m0 + r) * 512 + h * 128 + c16;
;         const bf16_t* qs = (const bf16_t*)(p.ws + WS_QN) + (size_t)(m0 + r) * 512 + h * 128 + c16;
;         *(u32x4*)(kn_s + r * 136 + c16) = *(const u32x4*)ks; *(u32x4*)(kn_s + r * 136 + c16 + 8) = *(const u32x4*)(ks + 8);
;         *(u32x4*)(qn_s + r * 136 + c16) = *(const u32x4*)qs; *(u32x4*)(qn_s + r * 136 + c16 + 8) = *(const u32x4*)(qs + 8);
;         const bf16_t* vs = (const bf16_t*)(p.ws + WS_VV) + (size_t)(m0 + r) * 512 + h * 128 + c16;
;         *(u32x4*)(v_s + r * 136 + c16) = *(const u32x4*)vs; *(u32x4*)(v_s + r * 136 + c16 + 8) = *(const u32x4*)(vs + 8);
;     }
;     if (t2 < 64) {
;         const int tok = dir ? 63 - t2 : t2;
;         const float* gb = (const float*)(p.ws + WS_GB) + (size_t)(m0 + tok) * 16;
;         float gv = gb[dir * 4 + h]; const float bv = gb[8 + dir * 4 + h];
; #pragma unroll
;         for (int o = 1; o < 64; o <<= 1) { const float v = __shfl_up(gv, o); if (lane >= o) gv += v; }
;         gc_s[dir * 64 + t2] = gv; be_s[dir * 64 + t2] = bv;
;     }
;     __syncthreads();
;     {
;         const int which = wave >> 2, it = wave & 3, fr = lane & 15, g = lane >> 4;
;         const bf16_t* As = which ? qn_s : kn_s; float* Out = which ? QK : KK;
;         bf16x8 a[4];
; #pragma unroll
;         for (int ks = 0; ks < 4; ++ks) a[ks] = *(const bf16x8*)(As + (it * 16 + fr) * 136 + ks * 32 + g * 8);
; #pragma unroll
;         for (int jt = 0; jt < 4; ++jt) {
;             f32x4 acc = {0.f, 0.f, 0.f, 0.f};
; #pragma unroll
	v_cndmask_b32_e32 v40, v41, v40, vcc
	v_lshlrev_b32_e32 v18, 2, v11
	v_writelane_b32 v255, s2, 46
	v_lshlrev_b32_e32 v19, 2, v14
	v_lshlrev_b32_e32 v20, 2, v15
	v_writelane_b32 v255, s3, 47
	v_cmp_gt_u32_e64 s[2:3], v22, v42
	v_cndmask_b32_e32 v42, v43, v42, vcc
	v_lshlrev_b32_e32 v23, 2, v21
	v_writelane_b32 v255, s2, 48
	v_lshlrev_b32_e32 v31, 2, v30
	v_lshlrev_b32_e32 v33, 2, v32
	v_writelane_b32 v255, s3, 49
	v_cmp_gt_u32_e64 s[2:3], v22, v44
	v_cndmask_b32_e32 v44, v45, v44, vcc
	v_lshlrev_b32_e32 v35, 2, v34
	v_writelane_b32 v255, s2, 50
	v_lshlrev_b32_e32 v37, 2, v36
	v_lshlrev_b32_e32 v39, 2, v38
	v_writelane_b32 v255, s3, 51
	v_cmp_gt_u32_e64 s[2:3], v22, v46
	v_cndmask_b32_e32 v46, v47, v46, vcc
	v_lshlrev_b32_e32 v41, 2, v40
	v_writelane_b32 v255, s2, 52
	v_lshlrev_b32_e32 v43, 2, v42
	v_lshlrev_b32_e32 v45, 2, v44
	v_writelane_b32 v255, s3, 53
	v_cmp_gt_u32_e64 s[2:3], v22, v48
	v_cndmask_b32_e32 v48, v49, v48, vcc
	v_lshlrev_b32_e32 v47, 2, v46
	v_writelane_b32 v255, s2, 54
	v_lshlrev_b32_e32 v49, 2, v48
	v_lshlrev_b32_e32 v51, 2, v50
	v_writelane_b32 v255, s3, 55
	v_cmp_eq_u32_e64 s[2:3], 0, v8
	v_cmp_ge_u32_e64 s[8:9], v7, v32
	v_mul_u32_u24_e32 v32, 0x110, v0
	v_writelane_b32 v255, s2, 56
	v_lshlrev_b32_e32 v0, 1, v8
	v_readlane_b32 s76, v254, 28
	v_writelane_b32 v255, s3, 57
	s_movk_i32 s2, 0x80
	v_ashrrev_i32_e32 v5, 31, v4
	v_add_u32_e32 v95, v12, v16
	v_add_u32_e32 v97, v12, v18
	v_add_u32_e32 v98, v12, v19
	v_add_u32_e32 v99, v12, v20
	v_add_u32_e32 v100, v12, v23
	v_add_u32_e32 v101, v12, v31
	v_add_u32_e32 v102, v12, v33
	v_add_u32_e32 v103, v12, v35
	v_add_u32_e32 v104, v12, v37
	v_add_u32_e32 v105, v12, v39
	v_add_u32_e32 v106, v12, v41
	v_add_u32_e32 v107, v12, v43
	v_add_u32_e32 v108, v12, v45
	v_add_u32_e32 v109, v12, v47
	v_add_u32_e32 v110, v12, v49
	v_add_u32_e32 v111, v12, v51
	v_mul_u32_u24_e32 v12, 0x104, v22
	v_cmp_gt_u32_e64 s[30:31], s2, v8
	s_movk_i32 s2, 0x7f
	v_add_u32_e32 v113, 0, v0
	v_add_u32_e32 v115, s42, v0
	v_add_u32_e32 v116, v94, v0
	v_lshlrev_b32_e32 v0, 6, v144
	v_add_u32_e32 v119, s1, v3
	v_readlane_b32 s77, v254, 29
	v_readlane_b32 s72, v254, 38
	v_cmp_ge_u32_e64 s[88:89], v7, v13
	v_add3_u32 v112, 0, v12, v17
	v_cmp_ge_u32_e64 s[90:91], v7, v11
	v_cmp_ge_u32_e64 s[84:85], v7, v21
	v_ashrrev_i32_e32 v11, 2, v144
	v_cmp_lt_u32_e64 s[34:35], s2, v8
	v_add_u32_e32 v128, v119, v20
	v_lshl_add_u64 v[12:13], v[0:1], 1, s[76:77]
	v_and_b32_e32 v0, 3, v144
	v_readlane_b32 s2, v254, 32
	v_lshlrev_b64 v[20:21], 10, v[4:5]
	v_readlane_b32 s73, v254, 39
	v_lshlrev_b32_e32 v10, 2, v4
	v_cmp_ge_u32_e64 s[92:93], v7, v14
	v_cmp_ge_u32_e64 s[94:95], v7, v15
	v_cmp_ge_u32_e64 s[6:7], v7, v30
	v_cmp_ge_u32_e64 s[10:11], v7, v34
	v_cmp_ge_u32_e64 s[12:13], v7, v36
	v_cmp_ge_u32_e64 s[14:15], v7, v38
	v_cmp_ge_u32_e64 s[16:17], v7, v40
	v_cmp_ge_u32_e64 s[18:19], v7, v42
	v_cmp_ge_u32_e64 s[20:21], v7, v44
	v_cmp_ge_u32_e64 s[22:23], v7, v46
	v_cmp_ge_u32_e64 s[24:25], v7, v48
	v_cmp_ge_u32_e64 s[26:27], v7, v50
	v_lshlrev_b32_e32 v14, 6, v11
	v_lshl_add_u32 v124, v7, 2, v119
	v_add_u32_e32 v126, v119, v18
	v_add_u32_e32 v127, v119, v19
	v_lshlrev_b32_e32 v0, 5, v0
	v_readlane_b32 s3, v254, 33
	v_lshl_add_u64 v[18:19], s[72:73], 0, v[20:21]
	v_mov_b32_e32 v7, v1
	v_lshlrev_b64 v[4:5], 13, v[4:5]
	v_and_b32_e32 v25, 48, v144
	v_ashrrev_i32_e32 v15, 31, v14
	v_add_u32_e32 v123, v119, v17
	v_add_u32_e32 v125, v119, v16
	v_lshl_add_u64 v[16:17], s[2:3], 0, v[0:1]
	v_lshl_add_u64 v[18:19], v[18:19], 0, v[6:7]
	v_readlane_b32 s72, v254, 40
	v_lshl_add_u64 v[4:5], s[2:3], 0, v[4:5]
	v_lshlrev_b32_e32 v6, 7, v22
	v_add_u32_e32 v26, 0, v25
	v_lshl_add_u32 v30, v11, 1, 0
	s_add_u32 s42, s44, 0x7f00000
	v_add_u32_e32 v120, s50, v3
	v_and_b32_e32 v3, 0xfc, v144
	v_lshl_add_u64 v[14:15], v[14:15], 1, v[16:17]
	v_lshlrev_b32_e32 v16, 7, v8
	v_mov_b32_e32 v17, v1
	v_readlane_b32 s73, v254, 41
	v_lshl_add_u64 v[4:5], v[4:5], 0, v[6:7]
	v_cmp_gt_u32_e64 s[40:41], 64, v8
	v_add_u32_e32 v114, 0xffffff00, v113
	v_add_u32_e32 v117, 0xffffff00, v116
	s_addc_u32 s43, s45, 0
	v_lshlrev_b32_e32 v118, 4, v8
	v_add_u32_e32 v121, v119, v3
	v_add_u32_e32 v122, v120, v3
	v_add_u32_e32 v129, v119, v23
	v_add_u32_e32 v130, v119, v31
	v_add_u32_e32 v131, v119, v33
	v_add_u32_e32 v132, v119, v35
	v_add_u32_e32 v133, v119, v37
	v_add_u32_e32 v134, v119, v39
	v_add_u32_e32 v135, v119, v41
	v_add_u32_e32 v136, v119, v43
	v_add_u32_e32 v137, v119, v45
	v_add_u32_e32 v143, v119, v47
	v_add_u32_e32 v145, v119, v49
	v_add_u32_e32 v146, v119, v51
	v_lshl_add_u32 v147, v91, 2, v119
	v_ashrrev_i32_e32 v11, 31, v10
	v_lshl_add_u64 v[16:17], s[76:77], 0, v[16:17]
	v_lshl_add_u64 v[20:21], s[72:73], 0, v[20:21]
	v_lshl_add_u64 v[22:23], v[4:5], 0, v[0:1]
	v_lshlrev_b32_e32 v0, 1, v2
	v_add_u32_e32 v148, v24, v25
	v_add_u32_e32 v149, v26, v28
	v_add_u32_e32 v150, v27, v29
	v_add_u32_e32 v151, v30, v32
	v_lshlrev_b32_e32 v24, 4, v8
	v_readlane_b32 s2, v254, 56
	v_readlane_b32 s3, v254, 57
	s_branch .LBB0_573
.LBB0_573:
	s_ashr_i32 s3, s2, 2
	s_mul_hi_i32 s50, s3, 0x38e38e39
	s_lshr_b32 s52, s50, 31
	s_ashr_i32 s50, s50, 3
	s_add_i32 s50, s50, s52
	s_mul_i32 s52, s50, 36
	s_sub_i32 s52, s3, s52
	s_cmp_gt_i32 s52, 3
	s_mov_b64 s[80:81], -1
	s_cbranch_scc0 .LBB0_575
	s_lshl_b32 s3, s50, 11
	s_lshl_b32 s54, s52, 6
	s_add_i32 s3, s54, s3
	s_addk_i32 s3, 0xff00
	s_mov_b64 s[80:81], 0

; __device__ __forceinline__ unsigned pk2(float lo, float hi) { unsigned r; asm("v_cvt_pk_bf16_f32 %0, %1, %2" : "=v"(r) : "v"(lo), "v"(hi)); return r; }
; template <int DIR>
; __device__ __forceinline__ void dn_solve(const P& p, int task, int m0, int h, int t2, const bf16_t* kn_s, const bf16_t* v_s, const float* gc, const float* be, float* L) {
;     float x[64];
;     if (t2 < 128) {
; #pragma unroll
;         for (int cp = 0; cp < 64; ++cp) { const int tok = DIR ? 63 - cp : cp; x[cp] = bf2f(v_s[tok * 136 + t2]) * be[cp]; }
;     } else {
;         const int k = t2 - 128;
; #pragma unroll
;         for (int cp = 0; cp < 64; ++cp) { const int tok = DIR ? 63 - cp : cp; x[cp] = bf2f(kn_s[tok * 136 + k]) * be[cp] * __expf(gc[cp]); }
;     }
; __device__ __forceinline__ void dn_prep_task(const P& p, int task, unsigned char* sm, int tid) {
;     ...
;     {
;         const int k = tid >> 2, tk0 = (tid & 3) * 16; float kv[16];
; #pragma unroll
;         for (int i = 0; i < 16; ++i) kv[i] = bf2f(kn_s[(tk0 + i) * 136 + k]);
;         bf16_t* kd = (bf16_t*)(p.ws + WS_KNT) + (size_t)task * 8192 + k * 64 + tk0;
;         u32x4 o0, o1; o0.x = pk2(kv[0], kv[1]); o0.y = pk2(kv[2], kv[3]); o0.z = pk2(kv[4], kv[5]); o0.w = pk2(kv[6], kv[7]);
;         o1.x = pk2(kv[8], kv[9]); o1.y = pk2(kv[10], kv[11]); o1.z = pk2(kv[12], kv[13]); o1.w = pk2(kv[14], kv[15]);
;         *(u32x4*)kd = o0; *(u32x4*)(kd + 8) = o1;
;     }
;     __syncthreads();
.LBB0_644:
	s_or_b64 exec, exec, s[80:81]
	ds_read_u16 v2, v151
	ds_read_u16 v3, v151 offset:272
	ds_read_u16 v4, v151 offset:544
	ds_read_u16 v5, v151 offset:816
	ds_read_u16 v6, v151 offset:1088
	ds_read_u16 v7, v151 offset:1360
	ds_read_u16 v25, v151 offset:1632
	ds_read_u16 v26, v151 offset:1904
	s_waitcnt lgkmcnt(7)
	v_lshlrev_b32_e32 v2, 16, v2
	s_waitcnt lgkmcnt(3)
	v_lshlrev_b32_e32 v27, 16, v6
	s_waitcnt lgkmcnt(2)
	v_lshlrev_b32_e32 v28, 16, v7
	ds_read_u16 v6, v151 offset:2176
	ds_read_u16 v7, v151 offset:2448
	ds_read_u16 v29, v151 offset:2720
	ds_read_u16 v30, v151 offset:2992
	ds_read_u16 v31, v151 offset:3264
	ds_read_u16 v32, v151 offset:3536
	ds_read_u16 v33, v151 offset:3808
	ds_read_u16 v34, v151 offset:4080
	s_waitcnt lgkmcnt(7)
	v_lshlrev_b32_e32 v35, 16, v6
	s_waitcnt lgkmcnt(6)
	v_lshlrev_b32_e32 v36, 16, v7
	v_lshl_add_u64 v[6:7], s[44:45], 0, v[14:15]
	v_lshlrev_b32_e32 v3, 16, v3
	v_lshlrev_b32_e32 v4, 16, v4
	v_lshlrev_b32_e32 v5, 16, v5
	v_add_co_u32_e32 v6, vcc, 0xd900000, v6
	v_lshlrev_b32_e32 v25, 16, v25
	v_lshlrev_b32_e32 v26, 16, v26
	s_waitcnt lgkmcnt(5)
	v_lshlrev_b32_e32 v29, 16, v29
	v_cvt_pk_bf16_f32 v2, v2, v3
	v_cvt_pk_bf16_f32 v3, v4, v5
	v_cvt_pk_bf16_f32 v4, v27, v28
	v_cvt_pk_bf16_f32 v5, v25, v26
	v_addc_co_u32_e32 v7, vcc, 0, v7, vcc
	s_waitcnt lgkmcnt(4)
	v_lshlrev_b32_e32 v30, 16, v30
	s_waitcnt lgkmcnt(3)
	v_lshlrev_b32_e32 v31, 16, v31
	s_waitcnt lgkmcnt(2)
	v_lshlrev_b32_e32 v32, 16, v32
	s_waitcnt lgkmcnt(1)
	v_lshlrev_b32_e32 v33, 16, v33
	s_waitcnt lgkmcnt(0)
	v_lshlrev_b32_e32 v34, 16, v34
	v_cvt_pk_bf16_f32 v26, v35, v36
	v_cvt_pk_bf16_f32 v27, v29, v30
	v_cvt_pk_bf16_f32 v28, v31, v32
	v_cvt_pk_bf16_f32 v29, v33, v34
	global_store_dwordx4 v[6:7], v[2:5], off
	global_store_dwordx4 v[6:7], v[26:29], off offset:16
	s_barrier
	s_mov_b64 exec, -1
	v_readfirstlane_b32 s72, v144
	s_nop 3
	s_lshr_b32 s72, s72, 6
	s_cmp_gt_u32 s72, 3
	s_cbranch_scc1 .Lpz_join
	s_lshr_b32 s73, s72, 1
	s_and_b32 s74, s72, 1
	v_and_b32_e32 v25, 63, v144
	s_lshl_b32 s75, s74, 6
	v_add_u32_e32 v207, s75, v25
	s_mul_i32 s80, s72, 8192
	s_add_i32 s80, s80, 121344
	v_lshlrev_b32_e32 v244, 2, v25
	v_add_u32_e32 v244, s80, v244
	ds_write_b32 v244, v88 offset:0
	ds_write_b32 v244, v89 offset:256
	ds_write_b32 v244, v90 offset:512
	ds_write_b32 v244, v91 offset:768
	ds_write_b32 v244, v92 offset:1024
	ds_write_b32 v244, v93 offset:1280
	ds_write_b32 v244, v94 offset:1536
	ds_write_b32 v244, v95 offset:1792
	ds_write_b32 v244, v96 offset:2048
	ds_write_b32 v244, v97 offset:2304
	ds_write_b32 v244, v98 offset:2560
	ds_write_b32 v244, v99 offset:2816
	ds_write_b32 v244, v100 offset:3072
	ds_write_b32 v244, v101 offset:3328
	ds_write_b32 v244, v102 offset:3584
	ds_write_b32 v244, v103 offset:3840
	ds_write_b32 v244, v104 offset:4096
	ds_write_b32 v244, v105 offset:4352
	ds_write_b32 v244, v106 offset:4608
	ds_write_b32 v244, v107 offset:4864
	ds_write_b32 v244, v108 offset:5120
	ds_write_b32 v244, v109 offset:5376
	ds_write_b32 v244, v110 offset:5632
	ds_write_b32 v244, v111 offset:5888
	ds_write_b32 v244, v112 offset:6144
	ds_write_b32 v244, v113 offset:6400
	ds_write_b32 v244, v114 offset:6656
	ds_write_b32 v244, v115 offset:6912
	ds_write_b32 v244, v116 offset:7168
	ds_write_b32 v244, v117 offset:7424
	ds_write_b32 v244, v118 offset:7680
	ds_write_b32 v244, v119 offset:7936
	s_lshl_b32 s81, s73, 8
	s_add_i32 s82, s81, 68096
	v_lshlrev_b32_e32 v245, 2, v25
	v_add_u32_e32 v245, s82, v245
	ds_read_b32 v247, v245
	ds_read_b32 v246, v245 offset:512
	s_lshl_b32 s83, s72, 9
	s_add_i32 s83, s83, 119296
	v_mov_b32_e32 v243, s83
	v_lshl_add_u32 v245, v25, 3, v243
	v_lshlrev_b32_e32 v240, 1, v207
	v_add_u32_e32 v228, 101888, v240
	s_lshl_b32 s80, s73, 14
	s_add_i32 s81, s80, 69120
	v_mov_b32_e32 v241, s81
	s_add_i32 s81, s80, 34816
	v_add_u32_e32 v242, s81, v240
	s_waitcnt lgkmcnt(0)
	v_mul_f32_e32 v247, 0x3fb8aa3b, v247
	v_exp_f32_e32 v247, v247
	s_nop 0
	v_mul_f32_e32 v247, v246, v247
	ds_write_b64 v245, v[246:247]
	s_waitcnt lgkmcnt(0)
	s_cmp_eq_u32 s73, 0
	s_cbranch_scc0 .Lpz_init1
	ds_read_u16 v6, v228 offset:0
	ds_read_u16 v7, v240 offset:0
	ds_read_u16 v54, v228 offset:272
	ds_read_u16 v55, v240 offset:272
	ds_read_b128 v[2:5], v243 offset:0
	ds_read_u16 v56, v228 offset:544
	ds_read_u16 v57, v240 offset:544
	ds_read_u16 v58, v228 offset:816
	ds_read_u16 v59, v240 offset:816
	ds_read_b128 v[26:29], v243 offset:16
	ds_read_u16 v60, v228 offset:1088
	ds_read_u16 v61, v240 offset:1088
	ds_read_u16 v62, v228 offset:1360
	ds_read_u16 v63, v240 offset:1360
	ds_read_b128 v[30:33], v243 offset:32
	s_waitcnt lgkmcnt(10)
	v_lshlrev_b32_e32 v6, 16, v6
	v_lshlrev_b32_e32 v7, 16, v7
	v_lshlrev_b32_e32 v54, 16, v54
	v_lshlrev_b32_e32 v55, 16, v55
	v_pk_mul_f32 v[6:7], v[6:7], v[2:3]
	v_pk_mul_f32 v[54:55], v[54:55], v[4:5]
	ds_read_u16 v64, v228 offset:1632
	ds_read_u16 v65, v240 offset:1632
	ds_read_u16 v66, v228 offset:1904
	ds_read_u16 v67, v240 offset:1904
	ds_read_b128 v[34:37], v243 offset:48
	s_waitcnt lgkmcnt(10)
	v_lshlrev_b32_e32 v56, 16, v56
	v_lshlrev_b32_e32 v57, 16, v57
	v_lshlrev_b32_e32 v58, 16, v58
	v_lshlrev_b32_e32 v59, 16, v59
	v_pk_mul_f32 v[56:57], v[56:57], v[26:27]
	v_pk_mul_f32 v[58:59], v[58:59], v[28:29]
	ds_read_u16 v68, v228 offset:2176
	ds_read_u16 v69, v240 offset:2176
	ds_read_u16 v70, v228 offset:2448
	ds_read_u16 v71, v240 offset:2448
	ds_read_b128 v[38:41], v243 offset:64
	s_waitcnt lgkmcnt(10)
; template <int DIR>
; __device__ __forceinline__ void dn_solve(const P& p, int task, int m0, int h, int t2, const bf16_t* kn_s, const bf16_t* v_s, const float* gc, const float* be, float* L) {
;     ...
;         for (int cp = 0; cp < 64; ++cp) { const int tok = DIR ? 63 - cp : cp; x[cp] = bf2f(v_s[tok * 136 + t2]) * be[cp]; }
;     } else {
;         const int k = t2 - 128;
; #pragma unroll
;         for (int cp = 0; cp < 64; ++cp) { const int tok = DIR ? 63 - cp : cp; x[cp] = bf2f(kn_s[tok * 136 + k]) * be[cp] * __expf(gc[cp]); }
	v_lshlrev_b32_e32 v60, 16, v60
	v_lshlrev_b32_e32 v61, 16, v61
	v_lshlrev_b32_e32 v62, 16, v62
	v_lshlrev_b32_e32 v63, 16, v63
	v_pk_mul_f32 v[60:61], v[60:61], v[30:31]
	v_pk_mul_f32 v[62:63], v[62:63], v[32:33]
	ds_read_u16 v72, v228 offset:2720
	ds_read_u16 v73, v240 offset:2720
	ds_read_u16 v74, v228 offset:2992
	ds_read_u16 v75, v240 offset:2992
	ds_read_b128 v[42:45], v243 offset:80
	s_waitcnt lgkmcnt(10)
	v_lshlrev_b32_e32 v64, 16, v64
	v_lshlrev_b32_e32 v65, 16, v65
	v_lshlrev_b32_e32 v66, 16, v66
	v_lshlrev_b32_e32 v67, 16, v67
	v_pk_mul_f32 v[64:65], v[64:65], v[34:35]
	v_pk_mul_f32 v[66:67], v[66:67], v[36:37]
	ds_read_u16 v76, v228 offset:3264
	ds_read_u16 v77, v240 offset:3264
	ds_read_u16 v78, v228 offset:3536
	ds_read_u16 v79, v240 offset:3536
	ds_read_b128 v[46:49], v243 offset:96
	s_waitcnt lgkmcnt(10)
	v_lshlrev_b32_e32 v68, 16, v68
	v_lshlrev_b32_e32 v69, 16, v69
	v_lshlrev_b32_e32 v70, 16, v70
	v_lshlrev_b32_e32 v71, 16, v71
	v_pk_mul_f32 v[68:69], v[68:69], v[38:39]
	v_pk_mul_f32 v[70:71], v[70:71], v[40:41]
	ds_read_u16 v80, v228 offset:3808
	ds_read_u16 v81, v240 offset:3808
	ds_read_u16 v82, v228 offset:4080
	ds_read_u16 v83, v240 offset:4080
	ds_read_b128 v[50:53], v243 offset:112
	s_waitcnt lgkmcnt(10)
	v_lshlrev_b32_e32 v72, 16, v72
	v_lshlrev_b32_e32 v73, 16, v73
	v_lshlrev_b32_e32 v74, 16, v74
	v_lshlrev_b32_e32 v75, 16, v75
	v_pk_mul_f32 v[72:73], v[72:73], v[42:43]
	v_pk_mul_f32 v[74:75], v[74:75], v[44:45]
	ds_read_u16 v84, v228 offset:4352
	ds_read_u16 v85, v240 offset:4352
	ds_read_u16 v86, v228 offset:4624
	ds_read_u16 v87, v240 offset:4624
	ds_read_b128 v[2:5], v243 offset:128
	s_waitcnt lgkmcnt(10)
	v_lshlrev_b32_e32 v76, 16, v76
	v_lshlrev_b32_e32 v77, 16, v77
	v_lshlrev_b32_e32 v78, 16, v78
	v_lshlrev_b32_e32 v79, 16, v79
	v_pk_mul_f32 v[76:77], v[76:77], v[46:47]
	v_pk_mul_f32 v[78:79], v[78:79], v[48:49]
	ds_read_u16 v88, v228 offset:4896
	ds_read_u16 v89, v240 offset:4896
	ds_read_u16 v90, v228 offset:5168
	ds_read_u16 v91, v240 offset:5168
	ds_read_b128 v[26:29], v243 offset:144
	s_waitcnt lgkmcnt(10)
	v_lshlrev_b32_e32 v80, 16, v80
	v_lshlrev_b32_e32 v81, 16, v81
	v_lshlrev_b32_e32 v82, 16, v82
	v_lshlrev_b32_e32 v83, 16, v83
	v_pk_mul_f32 v[80:81], v[80:81], v[50:51]
	v_pk_mul_f32 v[82:83], v[82:83], v[52:53]
	ds_read_u16 v92, v228 offset:5440
	ds_read_u16 v93, v240 offset:5440
	ds_read_u16 v94, v228 offset:5712
	ds_read_u16 v95, v240 offset:5712
	ds_read_b128 v[30:33], v243 offset:160
	s_waitcnt lgkmcnt(10)
	v_lshlrev_b32_e32 v84, 16, v84
	v_lshlrev_b32_e32 v85, 16, v85
	v_lshlrev_b32_e32 v86, 16, v86
	v_lshlrev_b32_e32 v87, 16, v87
	v_pk_mul_f32 v[84:85], v[84:85], v[2:3]
	v_pk_mul_f32 v[86:87], v[86:87], v[4:5]
	ds_read_u16 v96, v228 offset:5984
	ds_read_u16 v97, v240 offset:5984
	ds_read_u16 v98, v228 offset:6256
	ds_read_u16 v99, v240 offset:6256
	ds_read_b128 v[34:37], v243 offset:176
	s_waitcnt lgkmcnt(10)
	v_lshlrev_b32_e32 v88, 16, v88
	v_lshlrev_b32_e32 v89, 16, v89
	v_lshlrev_b32_e32 v90, 16, v90
	v_lshlrev_b32_e32 v91, 16, v91
	v_pk_mul_f32 v[88:89], v[88:89], v[26:27]
	v_pk_mul_f32 v[90:91], v[90:91], v[28:29]
	ds_read_u16 v100, v228 offset:6528
	ds_read_u16 v101, v240 offset:6528
	ds_read_u16 v102, v228 offset:6800
	ds_read_u16 v103, v240 offset:6800
	ds_read_b128 v[38:41], v243 offset:192
	s_waitcnt lgkmcnt(10)
	v_lshlrev_b32_e32 v92, 16, v92
	v_lshlrev_b32_e32 v93, 16, v93
	v_lshlrev_b32_e32 v94, 16, v94
	v_lshlrev_b32_e32 v95, 16, v95
	v_pk_mul_f32 v[92:93], v[92:93], v[30:31]
	v_pk_mul_f32 v[94:95], v[94:95], v[32:33]
	ds_read_u16 v104, v228 offset:7072
	ds_read_u16 v105, v240 offset:7072
	ds_read_u16 v106, v228 offset:7344
	ds_read_u16 v107, v240 offset:7344
	ds_read_b128 v[42:45], v243 offset:208
	s_waitcnt lgkmcnt(10)
	v_lshlrev_b32_e32 v96, 16, v96
	v_lshlrev_b32_e32 v97, 16, v97
	v_lshlrev_b32_e32 v98, 16, v98
	v_lshlrev_b32_e32 v99, 16, v99
	v_pk_mul_f32 v[96:97], v[96:97], v[34:35]
	v_pk_mul_f32 v[98:99], v[98:99], v[36:37]
	ds_read_u16 v108, v228 offset:7616
	ds_read_u16 v109, v240 offset:7616
	ds_read_u16 v110, v228 offset:7888
	ds_read_u16 v111, v240 offset:7888
	ds_read_b128 v[46:49], v243 offset:224
	s_waitcnt lgkmcnt(10)
	v_lshlrev_b32_e32 v100, 16, v100
	v_lshlrev_b32_e32 v101, 16, v101
	v_lshlrev_b32_e32 v102, 16, v102
	v_lshlrev_b32_e32 v103, 16, v103
	v_pk_mul_f32 v[100:101], v[100:101], v[38:39]
	v_pk_mul_f32 v[102:103], v[102:103], v[40:41]
	ds_read_u16 v112, v228 offset:8160
	ds_read_u16 v113, v240 offset:8160
	ds_read_u16 v114, v228 offset:8432
	ds_read_u16 v115, v240 offset:8432
	ds_read_b128 v[50:53], v243 offset:240
	s_waitcnt lgkmcnt(10)
	v_lshlrev_b32_e32 v104, 16, v104
	v_lshlrev_b32_e32 v105, 16, v105
	v_lshlrev_b32_e32 v106, 16, v106
	v_lshlrev_b32_e32 v107, 16, v107
	v_pk_mul_f32 v[104:105], v[104:105], v[42:43]
	v_pk_mul_f32 v[106:107], v[106:107], v[44:45]
	ds_read_u16 v116, v228 offset:8704
	ds_read_u16 v117, v240 offset:8704
	ds_read_u16 v118, v228 offset:8976
	ds_read_u16 v119, v240 offset:8976
	ds_read_b128 v[2:5], v243 offset:256
	s_waitcnt lgkmcnt(10)
	v_lshlrev_b32_e32 v108, 16, v108
	v_lshlrev_b32_e32 v109, 16, v109
	v_lshlrev_b32_e32 v110, 16, v110
	v_lshlrev_b32_e32 v111, 16, v111
	v_pk_mul_f32 v[108:109], v[108:109], v[46:47]
	v_pk_mul_f32 v[110:111], v[110:111], v[48:49]
	ds_read_u16 v152, v228 offset:9248
	ds_read_u16 v153, v240 offset:9248
	ds_read_u16 v154, v228 offset:9520
	ds_read_u16 v155, v240 offset:9520
	ds_read_b128 v[26:29], v243 offset:272
	s_waitcnt lgkmcnt(10)
; template <int DIR>
; __device__ __forceinline__ void dn_solve(const P& p, int task, int m0, int h, int t2, const bf16_t* kn_s, const bf16_t* v_s, const float* gc, const float* be, float* L) {
;     ...
;         for (int cp = 0; cp < 64; ++cp) { const int tok = DIR ? 63 - cp : cp; x[cp] = bf2f(v_s[tok * 136 + t2]) * be[cp]; }
;     } else {
;         const int k = t2 - 128;
; #pragma unroll
;         for (int cp = 0; cp < 64; ++cp) { const int tok = DIR ? 63 - cp : cp; x[cp] = bf2f(kn_s[tok * 136 + k]) * be[cp] * __expf(gc[cp]); }
	v_lshlrev_b32_e32 v112, 16, v112
	v_lshlrev_b32_e32 v113, 16, v113
	v_lshlrev_b32_e32 v114, 16, v114
	v_lshlrev_b32_e32 v115, 16, v115
	v_pk_mul_f32 v[112:113], v[112:113], v[50:51]
	v_pk_mul_f32 v[114:115], v[114:115], v[52:53]
	ds_read_u16 v156, v228 offset:9792
	ds_read_u16 v157, v240 offset:9792
	ds_read_u16 v158, v228 offset:10064
	ds_read_u16 v159, v240 offset:10064
	ds_read_b128 v[30:33], v243 offset:288
	s_waitcnt lgkmcnt(10)
	v_lshlrev_b32_e32 v116, 16, v116
	v_lshlrev_b32_e32 v117, 16, v117
	v_lshlrev_b32_e32 v118, 16, v118
	v_lshlrev_b32_e32 v119, 16, v119
	v_pk_mul_f32 v[116:117], v[116:117], v[2:3]
	v_pk_mul_f32 v[118:119], v[118:119], v[4:5]
	ds_read_u16 v160, v228 offset:10336
	ds_read_u16 v161, v240 offset:10336
	ds_read_u16 v162, v228 offset:10608
	ds_read_u16 v163, v240 offset:10608
	ds_read_b128 v[34:37], v243 offset:304
	s_waitcnt lgkmcnt(10)
	v_lshlrev_b32_e32 v152, 16, v152
	v_lshlrev_b32_e32 v153, 16, v153
	v_lshlrev_b32_e32 v154, 16, v154
	v_lshlrev_b32_e32 v155, 16, v155
	v_pk_mul_f32 v[152:153], v[152:153], v[26:27]
	v_pk_mul_f32 v[154:155], v[154:155], v[28:29]
	ds_read_u16 v164, v228 offset:10880
	ds_read_u16 v165, v240 offset:10880
	ds_read_u16 v166, v228 offset:11152
	ds_read_u16 v167, v240 offset:11152
	ds_read_b128 v[38:41], v243 offset:320
	s_waitcnt lgkmcnt(10)
	v_lshlrev_b32_e32 v156, 16, v156
	v_lshlrev_b32_e32 v157, 16, v157
	v_lshlrev_b32_e32 v158, 16, v158
	v_lshlrev_b32_e32 v159, 16, v159
	v_pk_mul_f32 v[156:157], v[156:157], v[30:31]
	v_pk_mul_f32 v[158:159], v[158:159], v[32:33]
	ds_read_u16 v168, v228 offset:11424
	ds_read_u16 v169, v240 offset:11424
	ds_read_u16 v170, v228 offset:11696
	ds_read_u16 v171, v240 offset:11696
	ds_read_b128 v[42:45], v243 offset:336
	s_waitcnt lgkmcnt(10)
	v_lshlrev_b32_e32 v160, 16, v160
	v_lshlrev_b32_e32 v161, 16, v161
	v_lshlrev_b32_e32 v162, 16, v162
	v_lshlrev_b32_e32 v163, 16, v163
	v_pk_mul_f32 v[160:161], v[160:161], v[34:35]
	v_pk_mul_f32 v[162:163], v[162:163], v[36:37]
	ds_read_u16 v172, v228 offset:11968
	ds_read_u16 v173, v240 offset:11968
	ds_read_u16 v174, v228 offset:12240
	ds_read_u16 v175, v240 offset:12240
	ds_read_b128 v[46:49], v243 offset:352
	s_waitcnt lgkmcnt(10)
	v_lshlrev_b32_e32 v164, 16, v164
	v_lshlrev_b32_e32 v165, 16, v165
	v_lshlrev_b32_e32 v166, 16, v166
	v_lshlrev_b32_e32 v167, 16, v167
	v_pk_mul_f32 v[164:165], v[164:165], v[38:39]
	v_pk_mul_f32 v[166:167], v[166:167], v[40:41]
	ds_read_u16 v176, v228 offset:12512
	ds_read_u16 v177, v240 offset:12512
	ds_read_u16 v178, v228 offset:12784
	ds_read_u16 v179, v240 offset:12784
	ds_read_b128 v[50:53], v243 offset:368
	s_waitcnt lgkmcnt(10)
	v_lshlrev_b32_e32 v168, 16, v168
	v_lshlrev_b32_e32 v169, 16, v169
	v_lshlrev_b32_e32 v170, 16, v170
	v_lshlrev_b32_e32 v171, 16, v171
	v_pk_mul_f32 v[168:169], v[168:169], v[42:43]
	v_pk_mul_f32 v[170:171], v[170:171], v[44:45]
	ds_read_u16 v180, v228 offset:13056
	ds_read_u16 v181, v240 offset:13056
	ds_read_u16 v182, v228 offset:13328
	ds_read_u16 v183, v240 offset:13328
	ds_read_b128 v[2:5], v243 offset:384
	s_waitcnt lgkmcnt(10)
	v_lshlrev_b32_e32 v172, 16, v172
	v_lshlrev_b32_e32 v173, 16, v173
	v_lshlrev_b32_e32 v174, 16, v174
	v_lshlrev_b32_e32 v175, 16, v175
	v_pk_mul_f32 v[172:173], v[172:173], v[46:47]
	v_pk_mul_f32 v[174:175], v[174:175], v[48:49]
	ds_read_u16 v202, v228 offset:13600
	ds_read_u16 v203, v240 offset:13600
	ds_read_u16 v204, v228 offset:13872
	ds_read_u16 v205, v240 offset:13872
	ds_read_b128 v[26:29], v243 offset:400
	s_waitcnt lgkmcnt(10)
	v_lshlrev_b32_e32 v176, 16, v176
	v_lshlrev_b32_e32 v177, 16, v177
	v_lshlrev_b32_e32 v178, 16, v178
	v_lshlrev_b32_e32 v179, 16, v179
	v_pk_mul_f32 v[176:177], v[176:177], v[50:51]
	v_pk_mul_f32 v[178:179], v[178:179], v[52:53]
	ds_read_u16 v208, v228 offset:14144
	ds_read_u16 v209, v240 offset:14144
	ds_read_u16 v210, v228 offset:14416
	ds_read_u16 v211, v240 offset:14416
	ds_read_b128 v[30:33], v243 offset:416
	s_waitcnt lgkmcnt(10)
	v_lshlrev_b32_e32 v180, 16, v180
	v_lshlrev_b32_e32 v181, 16, v181
	v_lshlrev_b32_e32 v182, 16, v182
	v_lshlrev_b32_e32 v183, 16, v183
	v_pk_mul_f32 v[180:181], v[180:181], v[2:3]
	v_pk_mul_f32 v[182:183], v[182:183], v[4:5]
	ds_read_u16 v212, v228 offset:14688
	ds_read_u16 v213, v240 offset:14688
	ds_read_u16 v214, v228 offset:14960
	ds_read_u16 v215, v240 offset:14960
	ds_read_b128 v[34:37], v243 offset:432
	s_waitcnt lgkmcnt(10)
	v_lshlrev_b32_e32 v202, 16, v202
	v_lshlrev_b32_e32 v203, 16, v203
	v_lshlrev_b32_e32 v204, 16, v204
	v_lshlrev_b32_e32 v205, 16, v205
	v_pk_mul_f32 v[202:203], v[202:203], v[26:27]
	v_pk_mul_f32 v[204:205], v[204:205], v[28:29]
	ds_read_u16 v216, v228 offset:15232
	ds_read_u16 v217, v240 offset:15232
	ds_read_u16 v218, v228 offset:15504
	ds_read_u16 v219, v240 offset:15504
	ds_read_b128 v[38:41], v243 offset:448
	s_waitcnt lgkmcnt(10)
	v_lshlrev_b32_e32 v208, 16, v208
	v_lshlrev_b32_e32 v209, 16, v209
	v_lshlrev_b32_e32 v210, 16, v210
	v_lshlrev_b32_e32 v211, 16, v211
	v_pk_mul_f32 v[208:209], v[208:209], v[30:31]
	v_pk_mul_f32 v[210:211], v[210:211], v[32:33]
	ds_read_u16 v220, v228 offset:15776
	ds_read_u16 v221, v240 offset:15776
	ds_read_u16 v222, v228 offset:16048
	ds_read_u16 v223, v240 offset:16048
	ds_read_b128 v[42:45], v243 offset:464
	s_waitcnt lgkmcnt(10)
	v_lshlrev_b32_e32 v212, 16, v212
	v_lshlrev_b32_e32 v213, 16, v213
	v_lshlrev_b32_e32 v214, 16, v214
	v_lshlrev_b32_e32 v215, 16, v215
	v_pk_mul_f32 v[212:213], v[212:213], v[34:35]
	v_pk_mul_f32 v[214:215], v[214:215], v[36:37]
	ds_read_u16 v224, v228 offset:16320
	ds_read_u16 v225, v240 offset:16320
	ds_read_u16 v226, v228 offset:16592
	ds_read_u16 v227, v240 offset:16592
	ds_read_b128 v[46:49], v243 offset:480
	s_waitcnt lgkmcnt(10)
	v_lshlrev_b32_e32 v216, 16, v216
	v_lshlrev_b32_e32 v217, 16, v217
	v_lshlrev_b32_e32 v218, 16, v218
	v_lshlrev_b32_e32 v219, 16, v219
	v_pk_mul_f32 v[216:217], v[216:217], v[38:39]
	v_pk_mul_f32 v[218:219], v[218:219], v[40:41]
	ds_read_u16 v230, v228 offset:16864
	ds_read_u16 v231, v240 offset:16864
	ds_read_u16 v232, v228 offset:17136
	ds_read_u16 v233, v240 offset:17136
	ds_read_b128 v[50:53], v243 offset:496
	s_waitcnt lgkmcnt(10)
	v_lshlrev_b32_e32 v220, 16, v220
	v_lshlrev_b32_e32 v221, 16, v221
	v_lshlrev_b32_e32 v222, 16, v222
	v_lshlrev_b32_e32 v223, 16, v223
	v_pk_mul_f32 v[220:221], v[220:221], v[42:43]
	v_pk_mul_f32 v[222:223], v[222:223], v[44:45]
	s_waitcnt lgkmcnt(5)
	v_lshlrev_b32_e32 v224, 16, v224
	v_lshlrev_b32_e32 v225, 16, v225
	v_lshlrev_b32_e32 v226, 16, v226
	v_lshlrev_b32_e32 v227, 16, v227
	v_pk_mul_f32 v[224:225], v[224:225], v[46:47]
	v_pk_mul_f32 v[226:227], v[226:227], v[48:49]
	s_waitcnt lgkmcnt(0)
	v_lshlrev_b32_e32 v230, 16, v230
	v_lshlrev_b32_e32 v231, 16, v231
	v_lshlrev_b32_e32 v232, 16, v232
	v_lshlrev_b32_e32 v233, 16, v233
	v_pk_mul_f32 v[230:231], v[230:231], v[50:51]
	v_pk_mul_f32 v[232:233], v[232:233], v[52:53]
	s_branch .Lpz_solve
; template <int DIR>
; __device__ __forceinline__ void dn_solve(const P& p, int task, int m0, int h, int t2, const bf16_t* kn_s, const bf16_t* v_s, const float* gc, const float* be, float* L) {
;     ...
;         for (int cp = 0; cp < 64; ++cp) { const int tok = DIR ? 63 - cp : cp; x[cp] = bf2f(v_s[tok * 136 + t2]) * be[cp]; }
;     } else {
;         const int k = t2 - 128;
; #pragma unroll
;         for (int cp = 0; cp < 64; ++cp) { const int tok = DIR ? 63 - cp : cp; x[cp] = bf2f(kn_s[tok * 136 + k]) * be[cp] * __expf(gc[cp]); }
.Lpz_init1:
	ds_read_u16 v6, v228 offset:17136
	ds_read_u16 v7, v240 offset:17136
	ds_read_u16 v54, v228 offset:16864
	ds_read_u16 v55, v240 offset:16864
	ds_read_b128 v[2:5], v243 offset:0
	ds_read_u16 v56, v228 offset:16592
	ds_read_u16 v57, v240 offset:16592
	ds_read_u16 v58, v228 offset:16320
	ds_read_u16 v59, v240 offset:16320
	ds_read_b128 v[26:29], v243 offset:16
	ds_read_u16 v60, v228 offset:16048
	ds_read_u16 v61, v240 offset:16048
	ds_read_u16 v62, v228 offset:15776
	ds_read_u16 v63, v240 offset:15776
	ds_read_b128 v[30:33], v243 offset:32
	s_waitcnt lgkmcnt(10)
	v_lshlrev_b32_e32 v6, 16, v6
	v_lshlrev_b32_e32 v7, 16, v7
	v_lshlrev_b32_e32 v54, 16, v54
	v_lshlrev_b32_e32 v55, 16, v55
	v_pk_mul_f32 v[6:7], v[6:7], v[2:3]
	v_pk_mul_f32 v[54:55], v[54:55], v[4:5]
	ds_read_u16 v64, v228 offset:15504
	ds_read_u16 v65, v240 offset:15504
	ds_read_u16 v66, v228 offset:15232
	ds_read_u16 v67, v240 offset:15232
	ds_read_b128 v[34:37], v243 offset:48
	s_waitcnt lgkmcnt(10)
	v_lshlrev_b32_e32 v56, 16, v56
	v_lshlrev_b32_e32 v57, 16, v57
	v_lshlrev_b32_e32 v58, 16, v58
	v_lshlrev_b32_e32 v59, 16, v59
	v_pk_mul_f32 v[56:57], v[56:57], v[26:27]
	v_pk_mul_f32 v[58:59], v[58:59], v[28:29]
	ds_read_u16 v68, v228 offset:14960
	ds_read_u16 v69, v240 offset:14960
	ds_read_u16 v70, v228 offset:14688
	ds_read_u16 v71, v240 offset:14688
	ds_read_b128 v[38:41], v243 offset:64
	s_waitcnt lgkmcnt(10)
	v_lshlrev_b32_e32 v60, 16, v60
	v_lshlrev_b32_e32 v61, 16, v61
	v_lshlrev_b32_e32 v62, 16, v62
	v_lshlrev_b32_e32 v63, 16, v63
	v_pk_mul_f32 v[60:61], v[60:61], v[30:31]
	v_pk_mul_f32 v[62:63], v[62:63], v[32:33]
	ds_read_u16 v72, v228 offset:14416
	ds_read_u16 v73, v240 offset:14416
	ds_read_u16 v74, v228 offset:14144
	ds_read_u16 v75, v240 offset:14144
	ds_read_b128 v[42:45], v243 offset:80
	s_waitcnt lgkmcnt(10)
	v_lshlrev_b32_e32 v64, 16, v64
	v_lshlrev_b32_e32 v65, 16, v65
	v_lshlrev_b32_e32 v66, 16, v66
	v_lshlrev_b32_e32 v67, 16, v67
	v_pk_mul_f32 v[64:65], v[64:65], v[34:35]
	v_pk_mul_f32 v[66:67], v[66:67], v[36:37]
	ds_read_u16 v76, v228 offset:13872
	ds_read_u16 v77, v240 offset:13872
	ds_read_u16 v78, v228 offset:13600
	ds_read_u16 v79, v240 offset:13600
	ds_read_b128 v[46:49], v243 offset:96
	s_waitcnt lgkmcnt(10)
	v_lshlrev_b32_e32 v68, 16, v68
	v_lshlrev_b32_e32 v69, 16, v69
	v_lshlrev_b32_e32 v70, 16, v70
	v_lshlrev_b32_e32 v71, 16, v71
	v_pk_mul_f32 v[68:69], v[68:69], v[38:39]
	v_pk_mul_f32 v[70:71], v[70:71], v[40:41]
	ds_read_u16 v80, v228 offset:13328
	ds_read_u16 v81, v240 offset:13328
	ds_read_u16 v82, v228 offset:13056
	ds_read_u16 v83, v240 offset:13056
	ds_read_b128 v[50:53], v243 offset:112
	s_waitcnt lgkmcnt(10)
	v_lshlrev_b32_e32 v72, 16, v72
	v_lshlrev_b32_e32 v73, 16, v73
	v_lshlrev_b32_e32 v74, 16, v74
	v_lshlrev_b32_e32 v75, 16, v75
	v_pk_mul_f32 v[72:73], v[72:73], v[42:43]
	v_pk_mul_f32 v[74:75], v[74:75], v[44:45]
	ds_read_u16 v84, v228 offset:12784
	ds_read_u16 v85, v240 offset:12784
	ds_read_u16 v86, v228 offset:12512
	ds_read_u16 v87, v240 offset:12512
	ds_read_b128 v[2:5], v243 offset:128
	s_waitcnt lgkmcnt(10)
	v_lshlrev_b32_e32 v76, 16, v76
	v_lshlrev_b32_e32 v77, 16, v77
	v_lshlrev_b32_e32 v78, 16, v78
	v_lshlrev_b32_e32 v79, 16, v79
	v_pk_mul_f32 v[76:77], v[76:77], v[46:47]
	v_pk_mul_f32 v[78:79], v[78:79], v[48:49]
	ds_read_u16 v88, v228 offset:12240
	ds_read_u16 v89, v240 offset:12240
	ds_read_u16 v90, v228 offset:11968
	ds_read_u16 v91, v240 offset:11968
	ds_read_b128 v[26:29], v243 offset:144
	s_waitcnt lgkmcnt(10)
	v_lshlrev_b32_e32 v80, 16, v80
	v_lshlrev_b32_e32 v81, 16, v81
	v_lshlrev_b32_e32 v82, 16, v82
	v_lshlrev_b32_e32 v83, 16, v83
	v_pk_mul_f32 v[80:81], v[80:81], v[50:51]
	v_pk_mul_f32 v[82:83], v[82:83], v[52:53]
	ds_read_u16 v92, v228 offset:11696
	ds_read_u16 v93, v240 offset:11696
	ds_read_u16 v94, v228 offset:11424
	ds_read_u16 v95, v240 offset:11424
	ds_read_b128 v[30:33], v243 offset:160
	s_waitcnt lgkmcnt(10)
	v_lshlrev_b32_e32 v84, 16, v84
	v_lshlrev_b32_e32 v85, 16, v85
	v_lshlrev_b32_e32 v86, 16, v86
	v_lshlrev_b32_e32 v87, 16, v87
	v_pk_mul_f32 v[84:85], v[84:85], v[2:3]
	v_pk_mul_f32 v[86:87], v[86:87], v[4:5]
	ds_read_u16 v96, v228 offset:11152
	ds_read_u16 v97, v240 offset:11152
	ds_read_u16 v98, v228 offset:10880
	ds_read_u16 v99, v240 offset:10880
	ds_read_b128 v[34:37], v243 offset:176
	s_waitcnt lgkmcnt(10)
	v_lshlrev_b32_e32 v88, 16, v88
	v_lshlrev_b32_e32 v89, 16, v89
	v_lshlrev_b32_e32 v90, 16, v90
	v_lshlrev_b32_e32 v91, 16, v91
	v_pk_mul_f32 v[88:89], v[88:89], v[26:27]
	v_pk_mul_f32 v[90:91], v[90:91], v[28:29]
	ds_read_u16 v100, v228 offset:10608
	ds_read_u16 v101, v240 offset:10608
	ds_read_u16 v102, v228 offset:10336
	ds_read_u16 v103, v240 offset:10336
	ds_read_b128 v[38:41], v243 offset:192
	s_waitcnt lgkmcnt(10)
	v_lshlrev_b32_e32 v92, 16, v92
	v_lshlrev_b32_e32 v93, 16, v93
	v_lshlrev_b32_e32 v94, 16, v94
	v_lshlrev_b32_e32 v95, 16, v95
	v_pk_mul_f32 v[92:93], v[92:93], v[30:31]
	v_pk_mul_f32 v[94:95], v[94:95], v[32:33]
	ds_read_u16 v104, v228 offset:10064
	ds_read_u16 v105, v240 offset:10064
	ds_read_u16 v106, v228 offset:9792
	ds_read_u16 v107, v240 offset:9792
	ds_read_b128 v[42:45], v243 offset:208
	s_waitcnt lgkmcnt(10)
	v_lshlrev_b32_e32 v96, 16, v96
	v_lshlrev_b32_e32 v97, 16, v97
	v_lshlrev_b32_e32 v98, 16, v98
	v_lshlrev_b32_e32 v99, 16, v99
	v_pk_mul_f32 v[96:97], v[96:97], v[34:35]
	v_pk_mul_f32 v[98:99], v[98:99], v[36:37]
	ds_read_u16 v108, v228 offset:9520
	ds_read_u16 v109, v240 offset:9520
	ds_read_u16 v110, v228 offset:9248
	ds_read_u16 v111, v240 offset:9248
	ds_read_b128 v[46:49], v243 offset:224
	s_waitcnt lgkmcnt(10)
; template <int DIR>
; __device__ __forceinline__ void dn_solve(const P& p, int task, int m0, int h, int t2, const bf16_t* kn_s, const bf16_t* v_s, const float* gc, const float* be, float* L) {
;     ...
;         for (int cp = 0; cp < 64; ++cp) { const int tok = DIR ? 63 - cp : cp; x[cp] = bf2f(v_s[tok * 136 + t2]) * be[cp]; }
;     } else {
;         const int k = t2 - 128;
; #pragma unroll
;         for (int cp = 0; cp < 64; ++cp) { const int tok = DIR ? 63 - cp : cp; x[cp] = bf2f(kn_s[tok * 136 + k]) * be[cp] * __expf(gc[cp]); }
	v_lshlrev_b32_e32 v100, 16, v100
	v_lshlrev_b32_e32 v101, 16, v101
	v_lshlrev_b32_e32 v102, 16, v102
	v_lshlrev_b32_e32 v103, 16, v103
	v_pk_mul_f32 v[100:101], v[100:101], v[38:39]
	v_pk_mul_f32 v[102:103], v[102:103], v[40:41]
	ds_read_u16 v112, v228 offset:8976
	ds_read_u16 v113, v240 offset:8976
	ds_read_u16 v114, v228 offset:8704
	ds_read_u16 v115, v240 offset:8704
	ds_read_b128 v[50:53], v243 offset:240
	s_waitcnt lgkmcnt(10)
	v_lshlrev_b32_e32 v104, 16, v104
	v_lshlrev_b32_e32 v105, 16, v105
	v_lshlrev_b32_e32 v106, 16, v106
	v_lshlrev_b32_e32 v107, 16, v107
	v_pk_mul_f32 v[104:105], v[104:105], v[42:43]
	v_pk_mul_f32 v[106:107], v[106:107], v[44:45]
	ds_read_u16 v116, v228 offset:8432
	ds_read_u16 v117, v240 offset:8432
	ds_read_u16 v118, v228 offset:8160
	ds_read_u16 v119, v240 offset:8160
	ds_read_b128 v[2:5], v243 offset:256
	s_waitcnt lgkmcnt(10)
	v_lshlrev_b32_e32 v108, 16, v108
	v_lshlrev_b32_e32 v109, 16, v109
	v_lshlrev_b32_e32 v110, 16, v110
	v_lshlrev_b32_e32 v111, 16, v111
	v_pk_mul_f32 v[108:109], v[108:109], v[46:47]
	v_pk_mul_f32 v[110:111], v[110:111], v[48:49]
	ds_read_u16 v152, v228 offset:7888
	ds_read_u16 v153, v240 offset:7888
	ds_read_u16 v154, v228 offset:7616
	ds_read_u16 v155, v240 offset:7616
	ds_read_b128 v[26:29], v243 offset:272
	s_waitcnt lgkmcnt(10)
	v_lshlrev_b32_e32 v112, 16, v112
	v_lshlrev_b32_e32 v113, 16, v113
	v_lshlrev_b32_e32 v114, 16, v114
	v_lshlrev_b32_e32 v115, 16, v115
	v_pk_mul_f32 v[112:113], v[112:113], v[50:51]
	v_pk_mul_f32 v[114:115], v[114:115], v[52:53]
	ds_read_u16 v156, v228 offset:7344
	ds_read_u16 v157, v240 offset:7344
	ds_read_u16 v158, v228 offset:7072
	ds_read_u16 v159, v240 offset:7072
	ds_read_b128 v[30:33], v243 offset:288
	s_waitcnt lgkmcnt(10)
	v_lshlrev_b32_e32 v116, 16, v116
	v_lshlrev_b32_e32 v117, 16, v117
	v_lshlrev_b32_e32 v118, 16, v118
	v_lshlrev_b32_e32 v119, 16, v119
	v_pk_mul_f32 v[116:117], v[116:117], v[2:3]
	v_pk_mul_f32 v[118:119], v[118:119], v[4:5]
	ds_read_u16 v160, v228 offset:6800
	ds_read_u16 v161, v240 offset:6800
	ds_read_u16 v162, v228 offset:6528
	ds_read_u16 v163, v240 offset:6528
	ds_read_b128 v[34:37], v243 offset:304
	s_waitcnt lgkmcnt(10)
	v_lshlrev_b32_e32 v152, 16, v152
	v_lshlrev_b32_e32 v153, 16, v153
	v_lshlrev_b32_e32 v154, 16, v154
	v_lshlrev_b32_e32 v155, 16, v155
	v_pk_mul_f32 v[152:153], v[152:153], v[26:27]
	v_pk_mul_f32 v[154:155], v[154:155], v[28:29]
	ds_read_u16 v164, v228 offset:6256
	ds_read_u16 v165, v240 offset:6256
	ds_read_u16 v166, v228 offset:5984
	ds_read_u16 v167, v240 offset:5984
	ds_read_b128 v[38:41], v243 offset:320
	s_waitcnt lgkmcnt(10)
	v_lshlrev_b32_e32 v156, 16, v156
	v_lshlrev_b32_e32 v157, 16, v157
	v_lshlrev_b32_e32 v158, 16, v158
	v_lshlrev_b32_e32 v159, 16, v159
	v_pk_mul_f32 v[156:157], v[156:157], v[30:31]
	v_pk_mul_f32 v[158:159], v[158:159], v[32:33]
	ds_read_u16 v168, v228 offset:5712
	ds_read_u16 v169, v240 offset:5712
	ds_read_u16 v170, v228 offset:5440
	ds_read_u16 v171, v240 offset:5440
	ds_read_b128 v[42:45], v243 offset:336
	s_waitcnt lgkmcnt(10)
	v_lshlrev_b32_e32 v160, 16, v160
	v_lshlrev_b32_e32 v161, 16, v161
	v_lshlrev_b32_e32 v162, 16, v162
	v_lshlrev_b32_e32 v163, 16, v163
	v_pk_mul_f32 v[160:161], v[160:161], v[34:35]
	v_pk_mul_f32 v[162:163], v[162:163], v[36:37]
	ds_read_u16 v172, v228 offset:5168
	ds_read_u16 v173, v240 offset:5168
	ds_read_u16 v174, v228 offset:4896
	ds_read_u16 v175, v240 offset:4896
	ds_read_b128 v[46:49], v243 offset:352
	s_waitcnt lgkmcnt(10)
	v_lshlrev_b32_e32 v164, 16, v164
	v_lshlrev_b32_e32 v165, 16, v165
	v_lshlrev_b32_e32 v166, 16, v166
	v_lshlrev_b32_e32 v167, 16, v167
	v_pk_mul_f32 v[164:165], v[164:165], v[38:39]
	v_pk_mul_f32 v[166:167], v[166:167], v[40:41]
	ds_read_u16 v176, v228 offset:4624
	ds_read_u16 v177, v240 offset:4624
	ds_read_u16 v178, v228 offset:4352
	ds_read_u16 v179, v240 offset:4352
	ds_read_b128 v[50:53], v243 offset:368
	s_waitcnt lgkmcnt(10)
	v_lshlrev_b32_e32 v168, 16, v168
	v_lshlrev_b32_e32 v169, 16, v169
	v_lshlrev_b32_e32 v170, 16, v170
	v_lshlrev_b32_e32 v171, 16, v171
	v_pk_mul_f32 v[168:169], v[168:169], v[42:43]
	v_pk_mul_f32 v[170:171], v[170:171], v[44:45]
	ds_read_u16 v180, v228 offset:4080
	ds_read_u16 v181, v240 offset:4080
	ds_read_u16 v182, v228 offset:3808
	ds_read_u16 v183, v240 offset:3808
	ds_read_b128 v[2:5], v243 offset:384
	s_waitcnt lgkmcnt(10)
	v_lshlrev_b32_e32 v172, 16, v172
	v_lshlrev_b32_e32 v173, 16, v173
	v_lshlrev_b32_e32 v174, 16, v174
	v_lshlrev_b32_e32 v175, 16, v175
	v_pk_mul_f32 v[172:173], v[172:173], v[46:47]
	v_pk_mul_f32 v[174:175], v[174:175], v[48:49]
	ds_read_u16 v202, v228 offset:3536
	ds_read_u16 v203, v240 offset:3536
	ds_read_u16 v204, v228 offset:3264
	ds_read_u16 v205, v240 offset:3264
	ds_read_b128 v[26:29], v243 offset:400
	s_waitcnt lgkmcnt(10)
	v_lshlrev_b32_e32 v176, 16, v176
	v_lshlrev_b32_e32 v177, 16, v177
	v_lshlrev_b32_e32 v178, 16, v178
	v_lshlrev_b32_e32 v179, 16, v179
	v_pk_mul_f32 v[176:177], v[176:177], v[50:51]
	v_pk_mul_f32 v[178:179], v[178:179], v[52:53]
	ds_read_u16 v208, v228 offset:2992
	ds_read_u16 v209, v240 offset:2992
	ds_read_u16 v210, v228 offset:2720
	ds_read_u16 v211, v240 offset:2720
	ds_read_b128 v[30:33], v243 offset:416
	s_waitcnt lgkmcnt(10)
	v_lshlrev_b32_e32 v180, 16, v180
	v_lshlrev_b32_e32 v181, 16, v181
	v_lshlrev_b32_e32 v182, 16, v182
	v_lshlrev_b32_e32 v183, 16, v183
	v_pk_mul_f32 v[180:181], v[180:181], v[2:3]
	v_pk_mul_f32 v[182:183], v[182:183], v[4:5]
	ds_read_u16 v212, v228 offset:2448
	ds_read_u16 v213, v240 offset:2448
	ds_read_u16 v214, v228 offset:2176
	ds_read_u16 v215, v240 offset:2176
	ds_read_b128 v[34:37], v243 offset:432
	s_waitcnt lgkmcnt(10)
; template <int DIR>
; __device__ __forceinline__ void dn_solve(const P& p, int task, int m0, int h, int t2, const bf16_t* kn_s, const bf16_t* v_s, const float* gc, const float* be, float* L) {
;     float x[64];
;     if (t2 < 128) {
; #pragma unroll
;         for (int cp = 0; cp < 64; ++cp) { const int tok = DIR ? 63 - cp : cp; x[cp] = bf2f(v_s[tok * 136 + t2]) * be[cp]; }
;     } else {
;         const int k = t2 - 128;
; #pragma unroll
;         for (int cp = 0; cp < 64; ++cp) { const int tok = DIR ? 63 - cp : cp; x[cp] = bf2f(kn_s[tok * 136 + k]) * be[cp] * __expf(gc[cp]); }
;     }
; #pragma unroll
;     for (int cp = 1; cp < 64; ++cp) {
;         float a0 = 0.f, a1 = 0.f, a2 = 0.f, a3 = 0.f;
; #pragma unroll
;         for (int s4 = 0; s4 < cp; s4 += 4) { const f32x4 l4 = *(const f32x4*)(L + cp * 64 + s4); a0 += l4[0] * x[s4]; a1 += l4[1] * x[s4 + 1]; a2 += l4[2] * x[s4 + 2]; a3 += l4[3] * x[s4 + 3]; }
;         x[cp] -= (a0 + a1) + (a2 + a3);
;     }
	v_lshlrev_b32_e32 v202, 16, v202
	v_lshlrev_b32_e32 v203, 16, v203
	v_lshlrev_b32_e32 v204, 16, v204
	v_lshlrev_b32_e32 v205, 16, v205
	v_pk_mul_f32 v[202:203], v[202:203], v[26:27]
	v_pk_mul_f32 v[204:205], v[204:205], v[28:29]
	ds_read_u16 v216, v228 offset:1904
	ds_read_u16 v217, v240 offset:1904
	ds_read_u16 v218, v228 offset:1632
	ds_read_u16 v219, v240 offset:1632
	ds_read_b128 v[38:41], v243 offset:448
	s_waitcnt lgkmcnt(10)
	v_lshlrev_b32_e32 v208, 16, v208
	v_lshlrev_b32_e32 v209, 16, v209
	v_lshlrev_b32_e32 v210, 16, v210
	v_lshlrev_b32_e32 v211, 16, v211
	v_pk_mul_f32 v[208:209], v[208:209], v[30:31]
	v_pk_mul_f32 v[210:211], v[210:211], v[32:33]
	ds_read_u16 v220, v228 offset:1360
	ds_read_u16 v221, v240 offset:1360
	ds_read_u16 v222, v228 offset:1088
	ds_read_u16 v223, v240 offset:1088
	ds_read_b128 v[42:45], v243 offset:464
	s_waitcnt lgkmcnt(10)
	v_lshlrev_b32_e32 v212, 16, v212
	v_lshlrev_b32_e32 v213, 16, v213
	v_lshlrev_b32_e32 v214, 16, v214
	v_lshlrev_b32_e32 v215, 16, v215
	v_pk_mul_f32 v[212:213], v[212:213], v[34:35]
	v_pk_mul_f32 v[214:215], v[214:215], v[36:37]
	ds_read_u16 v224, v228 offset:816
	ds_read_u16 v225, v240 offset:816
	ds_read_u16 v226, v228 offset:544
	ds_read_u16 v227, v240 offset:544
	ds_read_b128 v[46:49], v243 offset:480
	s_waitcnt lgkmcnt(10)
	v_lshlrev_b32_e32 v216, 16, v216
	v_lshlrev_b32_e32 v217, 16, v217
	v_lshlrev_b32_e32 v218, 16, v218
	v_lshlrev_b32_e32 v219, 16, v219
	v_pk_mul_f32 v[216:217], v[216:217], v[38:39]
	v_pk_mul_f32 v[218:219], v[218:219], v[40:41]
	ds_read_u16 v230, v228 offset:272
	ds_read_u16 v231, v240 offset:272
	ds_read_u16 v232, v228 offset:0
	ds_read_u16 v233, v240 offset:0
	ds_read_b128 v[50:53], v243 offset:496
	s_waitcnt lgkmcnt(10)
	v_lshlrev_b32_e32 v220, 16, v220
	v_lshlrev_b32_e32 v221, 16, v221
	v_lshlrev_b32_e32 v222, 16, v222
	v_lshlrev_b32_e32 v223, 16, v223
	v_pk_mul_f32 v[220:221], v[220:221], v[42:43]
	v_pk_mul_f32 v[222:223], v[222:223], v[44:45]
	s_waitcnt lgkmcnt(5)
	v_lshlrev_b32_e32 v224, 16, v224
	v_lshlrev_b32_e32 v225, 16, v225
	v_lshlrev_b32_e32 v226, 16, v226
	v_lshlrev_b32_e32 v227, 16, v227
	v_pk_mul_f32 v[224:225], v[224:225], v[46:47]
	v_pk_mul_f32 v[226:227], v[226:227], v[48:49]
	s_waitcnt lgkmcnt(0)
	v_lshlrev_b32_e32 v230, 16, v230
	v_lshlrev_b32_e32 v231, 16, v231
	v_lshlrev_b32_e32 v232, 16, v232
	v_lshlrev_b32_e32 v233, 16, v233
	v_pk_mul_f32 v[230:231], v[230:231], v[50:51]
	v_pk_mul_f32 v[232:233], v[232:233], v[52:53]
.Lpz_solve:
	ds_read_b128 v[2:5], v241 offset:256
	ds_read_b128 v[26:29], v241 offset:512
	ds_read_b128 v[30:33], v241 offset:768
	ds_read_b128 v[34:37], v241 offset:1024
	ds_read_b128 v[38:41], v241 offset:1280
	ds_read_b128 v[42:45], v241 offset:1296
	ds_read_b128 v[46:49], v241 offset:1536
	ds_read_b128 v[50:53], v241 offset:1552
	s_waitcnt lgkmcnt(7)
	v_pk_fma_f32 v[54:55], v[2:3], v[6:7], v[54:55] op_sel:[0,0,0] op_sel_hi:[0,1,1] neg_lo:[1,0,0] neg_hi:[1,0,0]
	ds_read_b128 v[2:5], v241 offset:1792
	s_waitcnt lgkmcnt(7)
	v_pk_fma_f32 v[56:57], v[26:27], v[6:7], v[56:57] op_sel:[0,0,0] op_sel_hi:[0,1,1] neg_lo:[1,0,0] neg_hi:[1,0,0]
	v_pk_mul_f32 v[234:235], v[26:27], v[54:55] op_sel:[1,0] op_sel_hi:[1,1] neg_lo:[1,0] neg_hi:[1,0]
	v_pk_add_f32 v[56:57], v[56:57], v[234:235]
	ds_read_b128 v[26:29], v241 offset:1808
	s_waitcnt lgkmcnt(7)
	v_pk_fma_f32 v[58:59], v[30:31], v[6:7], v[58:59] op_sel:[0,0,0] op_sel_hi:[0,1,1] neg_lo:[1,0,0] neg_hi:[1,0,0]
	v_pk_mul_f32 v[234:235], v[30:31], v[54:55] op_sel:[1,0] op_sel_hi:[1,1] neg_lo:[1,0] neg_hi:[1,0]
	v_pk_mul_f32 v[236:237], v[32:33], v[56:57] op_sel:[0,0] op_sel_hi:[0,1] neg_lo:[1,0] neg_hi:[1,0]
	v_pk_add_f32 v[234:235], v[58:59], v[234:235]
	v_pk_add_f32 v[58:59], v[234:235], v[236:237]
	ds_read_b128 v[30:33], v241 offset:2048
	s_waitcnt lgkmcnt(7)
	v_pk_fma_f32 v[60:61], v[34:35], v[6:7], v[60:61] op_sel:[0,0,0] op_sel_hi:[0,1,1] neg_lo:[1,0,0] neg_hi:[1,0,0]
	v_pk_mul_f32 v[234:235], v[34:35], v[54:55] op_sel:[1,0] op_sel_hi:[1,1] neg_lo:[1,0] neg_hi:[1,0]
	v_pk_mul_f32 v[236:237], v[36:37], v[56:57] op_sel:[0,0] op_sel_hi:[0,1] neg_lo:[1,0] neg_hi:[1,0]
	v_pk_mul_f32 v[238:239], v[36:37], v[58:59] op_sel:[1,0] op_sel_hi:[1,1] neg_lo:[1,0] neg_hi:[1,0]
	v_pk_add_f32 v[234:235], v[60:61], v[234:235]
	v_pk_add_f32 v[234:235], v[234:235], v[236:237]
	v_pk_add_f32 v[60:61], v[234:235], v[238:239]
	ds_read_b128 v[34:37], v241 offset:2064
	s_waitcnt lgkmcnt(7)
	v_pk_fma_f32 v[62:63], v[38:39], v[6:7], v[62:63] op_sel:[0,0,0] op_sel_hi:[0,1,1] neg_lo:[1,0,0] neg_hi:[1,0,0]
	v_pk_mul_f32 v[234:235], v[38:39], v[54:55] op_sel:[1,0] op_sel_hi:[1,1] neg_lo:[1,0] neg_hi:[1,0]
	v_pk_mul_f32 v[236:237], v[40:41], v[56:57] op_sel:[0,0] op_sel_hi:[0,1] neg_lo:[1,0] neg_hi:[1,0]
	v_pk_mul_f32 v[238:239], v[40:41], v[58:59] op_sel:[1,0] op_sel_hi:[1,1] neg_lo:[1,0] neg_hi:[1,0]
	ds_read_b128 v[38:41], v241 offset:2304
	s_waitcnt lgkmcnt(7)
	v_pk_fma_f32 v[62:63], v[42:43], v[60:61], v[62:63] op_sel:[0,0,0] op_sel_hi:[0,1,1] neg_lo:[1,0,0] neg_hi:[1,0,0]
	v_pk_add_f32 v[234:235], v[234:235], v[236:237]
	v_pk_add_f32 v[234:235], v[234:235], v[238:239]
	v_pk_add_f32 v[62:63], v[234:235], v[62:63]
	ds_read_b128 v[42:45], v241 offset:2320
	s_waitcnt lgkmcnt(7)
	v_pk_fma_f32 v[64:65], v[46:47], v[6:7], v[64:65] op_sel:[0,0,0] op_sel_hi:[0,1,1] neg_lo:[1,0,0] neg_hi:[1,0,0]
	v_pk_mul_f32 v[234:235], v[46:47], v[54:55] op_sel:[1,0] op_sel_hi:[1,1] neg_lo:[1,0] neg_hi:[1,0]
	v_pk_mul_f32 v[236:237], v[48:49], v[56:57] op_sel:[0,0] op_sel_hi:[0,1] neg_lo:[1,0] neg_hi:[1,0]
	v_pk_mul_f32 v[238:239], v[48:49], v[58:59] op_sel:[1,0] op_sel_hi:[1,1] neg_lo:[1,0] neg_hi:[1,0]
	ds_read_b128 v[46:49], v241 offset:2336
	s_waitcnt lgkmcnt(7)
; template <int DIR>
; __device__ __forceinline__ void dn_solve(const P& p, int task, int m0, int h, int t2, const bf16_t* kn_s, const bf16_t* v_s, const float* gc, const float* be, float* L) {
;     ...
; #pragma unroll
;     for (int cp = 1; cp < 64; ++cp) {
;         float a0 = 0.f, a1 = 0.f, a2 = 0.f, a3 = 0.f;
; #pragma unroll
;         for (int s4 = 0; s4 < cp; s4 += 4) { const f32x4 l4 = *(const f32x4*)(L + cp * 64 + s4); a0 += l4[0] * x[s4]; a1 += l4[1] * x[s4 + 1]; a2 += l4[2] * x[s4 + 2]; a3 += l4[3] * x[s4 + 3]; }
;         x[cp] -= (a0 + a1) + (a2 + a3);
;     }
	v_pk_fma_f32 v[64:65], v[50:51], v[60:61], v[64:65] op_sel:[0,0,0] op_sel_hi:[0,1,1] neg_lo:[1,0,0] neg_hi:[1,0,0]
	v_pk_fma_f32 v[234:235], v[50:51], v[62:63], v[234:235] op_sel:[1,0,0] op_sel_hi:[1,1,1] neg_lo:[1,0,0] neg_hi:[1,0,0]
	v_pk_add_f32 v[236:237], v[64:65], v[236:237]
	v_pk_add_f32 v[236:237], v[236:237], v[238:239]
	v_pk_add_f32 v[64:65], v[236:237], v[234:235]
	ds_read_b128 v[50:53], v241 offset:2560
	s_waitcnt lgkmcnt(7)
	v_pk_fma_f32 v[66:67], v[2:3], v[6:7], v[66:67] op_sel:[0,0,0] op_sel_hi:[0,1,1] neg_lo:[1,0,0] neg_hi:[1,0,0]
	v_pk_mul_f32 v[234:235], v[2:3], v[54:55] op_sel:[1,0] op_sel_hi:[1,1] neg_lo:[1,0] neg_hi:[1,0]
	v_pk_mul_f32 v[236:237], v[4:5], v[56:57] op_sel:[0,0] op_sel_hi:[0,1] neg_lo:[1,0] neg_hi:[1,0]
	v_pk_mul_f32 v[238:239], v[4:5], v[58:59] op_sel:[1,0] op_sel_hi:[1,1] neg_lo:[1,0] neg_hi:[1,0]
	ds_read_b128 v[2:5], v241 offset:2576
	s_waitcnt lgkmcnt(7)
	v_pk_fma_f32 v[66:67], v[26:27], v[60:61], v[66:67] op_sel:[0,0,0] op_sel_hi:[0,1,1] neg_lo:[1,0,0] neg_hi:[1,0,0]
	v_pk_fma_f32 v[234:235], v[26:27], v[62:63], v[234:235] op_sel:[1,0,0] op_sel_hi:[1,1,1] neg_lo:[1,0,0] neg_hi:[1,0,0]
	v_pk_fma_f32 v[236:237], v[28:29], v[64:65], v[236:237] op_sel:[0,0,0] op_sel_hi:[0,1,1] neg_lo:[1,0,0] neg_hi:[1,0,0]
	v_pk_add_f32 v[234:235], v[66:67], v[234:235]
	v_pk_add_f32 v[234:235], v[234:235], v[238:239]
	v_pk_add_f32 v[66:67], v[234:235], v[236:237]
	ds_read_b128 v[26:29], v241 offset:2592
	s_waitcnt lgkmcnt(7)
	v_pk_fma_f32 v[68:69], v[30:31], v[6:7], v[68:69] op_sel:[0,0,0] op_sel_hi:[0,1,1] neg_lo:[1,0,0] neg_hi:[1,0,0]
	v_pk_mul_f32 v[234:235], v[30:31], v[54:55] op_sel:[1,0] op_sel_hi:[1,1] neg_lo:[1,0] neg_hi:[1,0]
	v_pk_mul_f32 v[236:237], v[32:33], v[56:57] op_sel:[0,0] op_sel_hi:[0,1] neg_lo:[1,0] neg_hi:[1,0]
	v_pk_mul_f32 v[238:239], v[32:33], v[58:59] op_sel:[1,0] op_sel_hi:[1,1] neg_lo:[1,0] neg_hi:[1,0]
	ds_read_b128 v[30:33], v241 offset:2816
	s_waitcnt lgkmcnt(7)
	v_pk_fma_f32 v[68:69], v[34:35], v[60:61], v[68:69] op_sel:[0,0,0] op_sel_hi:[0,1,1] neg_lo:[1,0,0] neg_hi:[1,0,0]
	v_pk_fma_f32 v[234:235], v[34:35], v[62:63], v[234:235] op_sel:[1,0,0] op_sel_hi:[1,1,1] neg_lo:[1,0,0] neg_hi:[1,0,0]
	v_pk_fma_f32 v[236:237], v[36:37], v[64:65], v[236:237] op_sel:[0,0,0] op_sel_hi:[0,1,1] neg_lo:[1,0,0] neg_hi:[1,0,0]
	v_pk_fma_f32 v[238:239], v[36:37], v[66:67], v[238:239] op_sel:[1,0,0] op_sel_hi:[1,1,1] neg_lo:[1,0,0] neg_hi:[1,0,0]
	v_pk_add_f32 v[234:235], v[68:69], v[234:235]
	v_pk_add_f32 v[234:235], v[234:235], v[236:237]
	v_pk_add_f32 v[68:69], v[234:235], v[238:239]
	ds_read_b128 v[34:37], v241 offset:2832
	s_waitcnt lgkmcnt(7)
	v_pk_fma_f32 v[70:71], v[38:39], v[6:7], v[70:71] op_sel:[0,0,0] op_sel_hi:[0,1,1] neg_lo:[1,0,0] neg_hi:[1,0,0]
	v_pk_mul_f32 v[234:235], v[38:39], v[54:55] op_sel:[1,0] op_sel_hi:[1,1] neg_lo:[1,0] neg_hi:[1,0]
	v_pk_mul_f32 v[236:237], v[40:41], v[56:57] op_sel:[0,0] op_sel_hi:[0,1] neg_lo:[1,0] neg_hi:[1,0]
	v_pk_mul_f32 v[238:239], v[40:41], v[58:59] op_sel:[1,0] op_sel_hi:[1,1] neg_lo:[1,0] neg_hi:[1,0]
	ds_read_b128 v[38:41], v241 offset:2848
	s_waitcnt lgkmcnt(7)
	v_pk_fma_f32 v[70:71], v[42:43], v[60:61], v[70:71] op_sel:[0,0,0] op_sel_hi:[0,1,1] neg_lo:[1,0,0] neg_hi:[1,0,0]
	v_pk_fma_f32 v[234:235], v[42:43], v[62:63], v[234:235] op_sel:[1,0,0] op_sel_hi:[1,1,1] neg_lo:[1,0,0] neg_hi:[1,0,0]
	v_pk_fma_f32 v[236:237], v[44:45], v[64:65], v[236:237] op_sel:[0,0,0] op_sel_hi:[0,1,1] neg_lo:[1,0,0] neg_hi:[1,0,0]
	v_pk_fma_f32 v[238:239], v[44:45], v[66:67], v[238:239] op_sel:[1,0,0] op_sel_hi:[1,1,1] neg_lo:[1,0,0] neg_hi:[1,0,0]
	ds_read_b128 v[42:45], v241 offset:3072
	s_waitcnt lgkmcnt(7)
	v_pk_fma_f32 v[70:71], v[46:47], v[68:69], v[70:71] op_sel:[0,0,0] op_sel_hi:[0,1,1] neg_lo:[1,0,0] neg_hi:[1,0,0]
	v_pk_add_f32 v[234:235], v[234:235], v[236:237]
	v_pk_add_f32 v[234:235], v[234:235], v[238:239]
	v_pk_add_f32 v[70:71], v[234:235], v[70:71]
	ds_read_b128 v[46:49], v241 offset:3088
	s_waitcnt lgkmcnt(7)
	v_pk_fma_f32 v[72:73], v[50:51], v[6:7], v[72:73] op_sel:[0,0,0] op_sel_hi:[0,1,1] neg_lo:[1,0,0] neg_hi:[1,0,0]
	v_pk_mul_f32 v[234:235], v[50:51], v[54:55] op_sel:[1,0] op_sel_hi:[1,1] neg_lo:[1,0] neg_hi:[1,0]
	v_pk_mul_f32 v[236:237], v[52:53], v[56:57] op_sel:[0,0] op_sel_hi:[0,1] neg_lo:[1,0] neg_hi:[1,0]
	v_pk_mul_f32 v[238:239], v[52:53], v[58:59] op_sel:[1,0] op_sel_hi:[1,1] neg_lo:[1,0] neg_hi:[1,0]
	ds_read_b128 v[50:53], v241 offset:3104
	s_waitcnt lgkmcnt(7)
	v_pk_fma_f32 v[72:73], v[2:3], v[60:61], v[72:73] op_sel:[0,0,0] op_sel_hi:[0,1,1] neg_lo:[1,0,0] neg_hi:[1,0,0]
	v_pk_fma_f32 v[234:235], v[2:3], v[62:63], v[234:235] op_sel:[1,0,0] op_sel_hi:[1,1,1] neg_lo:[1,0,0] neg_hi:[1,0,0]
	v_pk_fma_f32 v[236:237], v[4:5], v[64:65], v[236:237] op_sel:[0,0,0] op_sel_hi:[0,1,1] neg_lo:[1,0,0] neg_hi:[1,0,0]
	v_pk_fma_f32 v[238:239], v[4:5], v[66:67], v[238:239] op_sel:[1,0,0] op_sel_hi:[1,1,1] neg_lo:[1,0,0] neg_hi:[1,0,0]
	ds_read_b128 v[2:5], v241 offset:3328
	s_waitcnt lgkmcnt(7)
	v_pk_fma_f32 v[72:73], v[26:27], v[68:69], v[72:73] op_sel:[0,0,0] op_sel_hi:[0,1,1] neg_lo:[1,0,0] neg_hi:[1,0,0]
	v_pk_fma_f32 v[234:235], v[26:27], v[70:71], v[234:235] op_sel:[1,0,0] op_sel_hi:[1,1,1] neg_lo:[1,0,0] neg_hi:[1,0,0]
	v_pk_add_f32 v[236:237], v[72:73], v[236:237]
	v_pk_add_f32 v[236:237], v[236:237], v[238:239]
	v_pk_add_f32 v[72:73], v[236:237], v[234:235]
	ds_read_b128 v[26:29], v241 offset:3344
	s_waitcnt lgkmcnt(7)
; template <int DIR>
; __device__ __forceinline__ void dn_solve(const P& p, int task, int m0, int h, int t2, const bf16_t* kn_s, const bf16_t* v_s, const float* gc, const float* be, float* L) {
;     ...
; #pragma unroll
;     for (int cp = 1; cp < 64; ++cp) {
;         float a0 = 0.f, a1 = 0.f, a2 = 0.f, a3 = 0.f;
; #pragma unroll
;         for (int s4 = 0; s4 < cp; s4 += 4) { const f32x4 l4 = *(const f32x4*)(L + cp * 64 + s4); a0 += l4[0] * x[s4]; a1 += l4[1] * x[s4 + 1]; a2 += l4[2] * x[s4 + 2]; a3 += l4[3] * x[s4 + 3]; }
;         x[cp] -= (a0 + a1) + (a2 + a3);
;     }
	v_pk_fma_f32 v[74:75], v[30:31], v[6:7], v[74:75] op_sel:[0,0,0] op_sel_hi:[0,1,1] neg_lo:[1,0,0] neg_hi:[1,0,0]
	v_pk_mul_f32 v[234:235], v[30:31], v[54:55] op_sel:[1,0] op_sel_hi:[1,1] neg_lo:[1,0] neg_hi:[1,0]
	v_pk_mul_f32 v[236:237], v[32:33], v[56:57] op_sel:[0,0] op_sel_hi:[0,1] neg_lo:[1,0] neg_hi:[1,0]
	v_pk_mul_f32 v[238:239], v[32:33], v[58:59] op_sel:[1,0] op_sel_hi:[1,1] neg_lo:[1,0] neg_hi:[1,0]
	ds_read_b128 v[30:33], v241 offset:3360
	s_waitcnt lgkmcnt(7)
	v_pk_fma_f32 v[74:75], v[34:35], v[60:61], v[74:75] op_sel:[0,0,0] op_sel_hi:[0,1,1] neg_lo:[1,0,0] neg_hi:[1,0,0]
	v_pk_fma_f32 v[234:235], v[34:35], v[62:63], v[234:235] op_sel:[1,0,0] op_sel_hi:[1,1,1] neg_lo:[1,0,0] neg_hi:[1,0,0]
	v_pk_fma_f32 v[236:237], v[36:37], v[64:65], v[236:237] op_sel:[0,0,0] op_sel_hi:[0,1,1] neg_lo:[1,0,0] neg_hi:[1,0,0]
	v_pk_fma_f32 v[238:239], v[36:37], v[66:67], v[238:239] op_sel:[1,0,0] op_sel_hi:[1,1,1] neg_lo:[1,0,0] neg_hi:[1,0,0]
	ds_read_b128 v[34:37], v241 offset:3376
	s_waitcnt lgkmcnt(7)
	v_pk_fma_f32 v[74:75], v[38:39], v[68:69], v[74:75] op_sel:[0,0,0] op_sel_hi:[0,1,1] neg_lo:[1,0,0] neg_hi:[1,0,0]
	v_pk_fma_f32 v[234:235], v[38:39], v[70:71], v[234:235] op_sel:[1,0,0] op_sel_hi:[1,1,1] neg_lo:[1,0,0] neg_hi:[1,0,0]
	v_pk_fma_f32 v[236:237], v[40:41], v[72:73], v[236:237] op_sel:[0,0,0] op_sel_hi:[0,1,1] neg_lo:[1,0,0] neg_hi:[1,0,0]
	v_pk_add_f32 v[234:235], v[74:75], v[234:235]
	v_pk_add_f32 v[234:235], v[234:235], v[238:239]
	v_pk_add_f32 v[74:75], v[234:235], v[236:237]
	ds_read_b128 v[38:41], v241 offset:3584
	s_waitcnt lgkmcnt(7)
	v_pk_fma_f32 v[76:77], v[42:43], v[6:7], v[76:77] op_sel:[0,0,0] op_sel_hi:[0,1,1] neg_lo:[1,0,0] neg_hi:[1,0,0]
	v_pk_mul_f32 v[234:235], v[42:43], v[54:55] op_sel:[1,0] op_sel_hi:[1,1] neg_lo:[1,0] neg_hi:[1,0]
	v_pk_mul_f32 v[236:237], v[44:45], v[56:57] op_sel:[0,0] op_sel_hi:[0,1] neg_lo:[1,0] neg_hi:[1,0]
	v_pk_mul_f32 v[238:239], v[44:45], v[58:59] op_sel:[1,0] op_sel_hi:[1,1] neg_lo:[1,0] neg_hi:[1,0]
	ds_read_b128 v[42:45], v241 offset:3600
	s_waitcnt lgkmcnt(7)
	v_pk_fma_f32 v[76:77], v[46:47], v[60:61], v[76:77] op_sel:[0,0,0] op_sel_hi:[0,1,1] neg_lo:[1,0,0] neg_hi:[1,0,0]
	v_pk_fma_f32 v[234:235], v[46:47], v[62:63], v[234:235] op_sel:[1,0,0] op_sel_hi:[1,1,1] neg_lo:[1,0,0] neg_hi:[1,0,0]
	v_pk_fma_f32 v[236:237], v[48:49], v[64:65], v[236:237] op_sel:[0,0,0] op_sel_hi:[0,1,1] neg_lo:[1,0,0] neg_hi:[1,0,0]
	v_pk_fma_f32 v[238:239], v[48:49], v[66:67], v[238:239] op_sel:[1,0,0] op_sel_hi:[1,1,1] neg_lo:[1,0,0] neg_hi:[1,0,0]
	ds_read_b128 v[46:49], v241 offset:3616
	s_waitcnt lgkmcnt(7)
	v_pk_fma_f32 v[76:77], v[50:51], v[68:69], v[76:77] op_sel:[0,0,0] op_sel_hi:[0,1,1] neg_lo:[1,0,0] neg_hi:[1,0,0]
	v_pk_fma_f32 v[234:235], v[50:51], v[70:71], v[234:235] op_sel:[1,0,0] op_sel_hi:[1,1,1] neg_lo:[1,0,0] neg_hi:[1,0,0]
	v_pk_fma_f32 v[236:237], v[52:53], v[72:73], v[236:237] op_sel:[0,0,0] op_sel_hi:[0,1,1] neg_lo:[1,0,0] neg_hi:[1,0,0]
	v_pk_fma_f32 v[238:239], v[52:53], v[74:75], v[238:239] op_sel:[1,0,0] op_sel_hi:[1,1,1] neg_lo:[1,0,0] neg_hi:[1,0,0]
	v_pk_add_f32 v[234:235], v[76:77], v[234:235]
	v_pk_add_f32 v[234:235], v[234:235], v[236:237]
	v_pk_add_f32 v[76:77], v[234:235], v[238:239]
	ds_read_b128 v[50:53], v241 offset:3632
	s_waitcnt lgkmcnt(7)
	v_pk_fma_f32 v[78:79], v[2:3], v[6:7], v[78:79] op_sel:[0,0,0] op_sel_hi:[0,1,1] neg_lo:[1,0,0] neg_hi:[1,0,0]
	v_pk_mul_f32 v[234:235], v[2:3], v[54:55] op_sel:[1,0] op_sel_hi:[1,1] neg_lo:[1,0] neg_hi:[1,0]
	v_pk_mul_f32 v[236:237], v[4:5], v[56:57] op_sel:[0,0] op_sel_hi:[0,1] neg_lo:[1,0] neg_hi:[1,0]
	v_pk_mul_f32 v[238:239], v[4:5], v[58:59] op_sel:[1,0] op_sel_hi:[1,1] neg_lo:[1,0] neg_hi:[1,0]
	ds_read_b128 v[2:5], v241 offset:3840
	s_waitcnt lgkmcnt(7)
	v_pk_fma_f32 v[78:79], v[26:27], v[60:61], v[78:79] op_sel:[0,0,0] op_sel_hi:[0,1,1] neg_lo:[1,0,0] neg_hi:[1,0,0]
	v_pk_fma_f32 v[234:235], v[26:27], v[62:63], v[234:235] op_sel:[1,0,0] op_sel_hi:[1,1,1] neg_lo:[1,0,0] neg_hi:[1,0,0]
	v_pk_fma_f32 v[236:237], v[28:29], v[64:65], v[236:237] op_sel:[0,0,0] op_sel_hi:[0,1,1] neg_lo:[1,0,0] neg_hi:[1,0,0]
	v_pk_fma_f32 v[238:239], v[28:29], v[66:67], v[238:239] op_sel:[1,0,0] op_sel_hi:[1,1,1] neg_lo:[1,0,0] neg_hi:[1,0,0]
	ds_read_b128 v[26:29], v241 offset:3856
	s_waitcnt lgkmcnt(7)
	v_pk_fma_f32 v[78:79], v[30:31], v[68:69], v[78:79] op_sel:[0,0,0] op_sel_hi:[0,1,1] neg_lo:[1,0,0] neg_hi:[1,0,0]
	v_pk_fma_f32 v[234:235], v[30:31], v[70:71], v[234:235] op_sel:[1,0,0] op_sel_hi:[1,1,1] neg_lo:[1,0,0] neg_hi:[1,0,0]
	v_pk_fma_f32 v[236:237], v[32:33], v[72:73], v[236:237] op_sel:[0,0,0] op_sel_hi:[0,1,1] neg_lo:[1,0,0] neg_hi:[1,0,0]
	v_pk_fma_f32 v[238:239], v[32:33], v[74:75], v[238:239] op_sel:[1,0,0] op_sel_hi:[1,1,1] neg_lo:[1,0,0] neg_hi:[1,0,0]
	ds_read_b128 v[30:33], v241 offset:3872
	s_waitcnt lgkmcnt(7)
	v_pk_fma_f32 v[78:79], v[34:35], v[76:77], v[78:79] op_sel:[0,0,0] op_sel_hi:[0,1,1] neg_lo:[1,0,0] neg_hi:[1,0,0]
	v_pk_add_f32 v[234:235], v[234:235], v[236:237]
	v_pk_add_f32 v[234:235], v[234:235], v[238:239]
	v_pk_add_f32 v[78:79], v[234:235], v[78:79]
	ds_read_b128 v[34:37], v241 offset:3888
	s_waitcnt lgkmcnt(7)
	v_pk_fma_f32 v[80:81], v[38:39], v[6:7], v[80:81] op_sel:[0,0,0] op_sel_hi:[0,1,1] neg_lo:[1,0,0] neg_hi:[1,0,0]
	v_pk_mul_f32 v[234:235], v[38:39], v[54:55] op_sel:[1,0] op_sel_hi:[1,1] neg_lo:[1,0] neg_hi:[1,0]
	v_pk_mul_f32 v[236:237], v[40:41], v[56:57] op_sel:[0,0] op_sel_hi:[0,1] neg_lo:[1,0] neg_hi:[1,0]
	v_pk_mul_f32 v[238:239], v[40:41], v[58:59] op_sel:[1,0] op_sel_hi:[1,1] neg_lo:[1,0] neg_hi:[1,0]
	ds_read_b128 v[38:41], v241 offset:4096
	s_waitcnt lgkmcnt(7)
; template <int DIR>
; __device__ __forceinline__ void dn_solve(const P& p, int task, int m0, int h, int t2, const bf16_t* kn_s, const bf16_t* v_s, const float* gc, const float* be, float* L) {
;     ...
; #pragma unroll
;     for (int cp = 1; cp < 64; ++cp) {
;         float a0 = 0.f, a1 = 0.f, a2 = 0.f, a3 = 0.f;
; #pragma unroll
;         for (int s4 = 0; s4 < cp; s4 += 4) { const f32x4 l4 = *(const f32x4*)(L + cp * 64 + s4); a0 += l4[0] * x[s4]; a1 += l4[1] * x[s4 + 1]; a2 += l4[2] * x[s4 + 2]; a3 += l4[3] * x[s4 + 3]; }
;         x[cp] -= (a0 + a1) + (a2 + a3);
;     }
	v_pk_fma_f32 v[80:81], v[42:43], v[60:61], v[80:81] op_sel:[0,0,0] op_sel_hi:[0,1,1] neg_lo:[1,0,0] neg_hi:[1,0,0]
	v_pk_fma_f32 v[234:235], v[42:43], v[62:63], v[234:235] op_sel:[1,0,0] op_sel_hi:[1,1,1] neg_lo:[1,0,0] neg_hi:[1,0,0]
	v_pk_fma_f32 v[236:237], v[44:45], v[64:65], v[236:237] op_sel:[0,0,0] op_sel_hi:[0,1,1] neg_lo:[1,0,0] neg_hi:[1,0,0]
	v_pk_fma_f32 v[238:239], v[44:45], v[66:67], v[238:239] op_sel:[1,0,0] op_sel_hi:[1,1,1] neg_lo:[1,0,0] neg_hi:[1,0,0]
	ds_read_b128 v[42:45], v241 offset:4112
	s_waitcnt lgkmcnt(7)
	v_pk_fma_f32 v[80:81], v[46:47], v[68:69], v[80:81] op_sel:[0,0,0] op_sel_hi:[0,1,1] neg_lo:[1,0,0] neg_hi:[1,0,0]
	v_pk_fma_f32 v[234:235], v[46:47], v[70:71], v[234:235] op_sel:[1,0,0] op_sel_hi:[1,1,1] neg_lo:[1,0,0] neg_hi:[1,0,0]
	v_pk_fma_f32 v[236:237], v[48:49], v[72:73], v[236:237] op_sel:[0,0,0] op_sel_hi:[0,1,1] neg_lo:[1,0,0] neg_hi:[1,0,0]
	v_pk_fma_f32 v[238:239], v[48:49], v[74:75], v[238:239] op_sel:[1,0,0] op_sel_hi:[1,1,1] neg_lo:[1,0,0] neg_hi:[1,0,0]
	ds_read_b128 v[46:49], v241 offset:4128
	s_waitcnt lgkmcnt(7)
	v_pk_fma_f32 v[80:81], v[50:51], v[76:77], v[80:81] op_sel:[0,0,0] op_sel_hi:[0,1,1] neg_lo:[1,0,0] neg_hi:[1,0,0]
	v_pk_fma_f32 v[234:235], v[50:51], v[78:79], v[234:235] op_sel:[1,0,0] op_sel_hi:[1,1,1] neg_lo:[1,0,0] neg_hi:[1,0,0]
	v_pk_add_f32 v[236:237], v[80:81], v[236:237]
	v_pk_add_f32 v[236:237], v[236:237], v[238:239]
	v_pk_add_f32 v[80:81], v[236:237], v[234:235]
	ds_read_b128 v[50:53], v241 offset:4144
	s_waitcnt lgkmcnt(7)
	v_pk_fma_f32 v[82:83], v[2:3], v[6:7], v[82:83] op_sel:[0,0,0] op_sel_hi:[0,1,1] neg_lo:[1,0,0] neg_hi:[1,0,0]
	v_pk_mul_f32 v[234:235], v[2:3], v[54:55] op_sel:[1,0] op_sel_hi:[1,1] neg_lo:[1,0] neg_hi:[1,0]
	v_pk_mul_f32 v[236:237], v[4:5], v[56:57] op_sel:[0,0] op_sel_hi:[0,1] neg_lo:[1,0] neg_hi:[1,0]
	v_pk_mul_f32 v[238:239], v[4:5], v[58:59] op_sel:[1,0] op_sel_hi:[1,1] neg_lo:[1,0] neg_hi:[1,0]
	ds_read_b128 v[2:5], v241 offset:4352
	s_waitcnt lgkmcnt(7)
	v_pk_fma_f32 v[82:83], v[26:27], v[60:61], v[82:83] op_sel:[0,0,0] op_sel_hi:[0,1,1] neg_lo:[1,0,0] neg_hi:[1,0,0]
	v_pk_fma_f32 v[234:235], v[26:27], v[62:63], v[234:235] op_sel:[1,0,0] op_sel_hi:[1,1,1] neg_lo:[1,0,0] neg_hi:[1,0,0]
	v_pk_fma_f32 v[236:237], v[28:29], v[64:65], v[236:237] op_sel:[0,0,0] op_sel_hi:[0,1,1] neg_lo:[1,0,0] neg_hi:[1,0,0]
	v_pk_fma_f32 v[238:239], v[28:29], v[66:67], v[238:239] op_sel:[1,0,0] op_sel_hi:[1,1,1] neg_lo:[1,0,0] neg_hi:[1,0,0]
	ds_read_b128 v[26:29], v241 offset:4368
	s_waitcnt lgkmcnt(7)
	v_pk_fma_f32 v[82:83], v[30:31], v[68:69], v[82:83] op_sel:[0,0,0] op_sel_hi:[0,1,1] neg_lo:[1,0,0] neg_hi:[1,0,0]
	v_pk_fma_f32 v[234:235], v[30:31], v[70:71], v[234:235] op_sel:[1,0,0] op_sel_hi:[1,1,1] neg_lo:[1,0,0] neg_hi:[1,0,0]
	v_pk_fma_f32 v[236:237], v[32:33], v[72:73], v[236:237] op_sel:[0,0,0] op_sel_hi:[0,1,1] neg_lo:[1,0,0] neg_hi:[1,0,0]
	v_pk_fma_f32 v[238:239], v[32:33], v[74:75], v[238:239] op_sel:[1,0,0] op_sel_hi:[1,1,1] neg_lo:[1,0,0] neg_hi:[1,0,0]
	ds_read_b128 v[30:33], v241 offset:4384
	s_waitcnt lgkmcnt(7)
	v_pk_fma_f32 v[82:83], v[34:35], v[76:77], v[82:83] op_sel:[0,0,0] op_sel_hi:[0,1,1] neg_lo:[1,0,0] neg_hi:[1,0,0]
	v_pk_fma_f32 v[234:235], v[34:35], v[78:79], v[234:235] op_sel:[1,0,0] op_sel_hi:[1,1,1] neg_lo:[1,0,0] neg_hi:[1,0,0]
	v_pk_fma_f32 v[236:237], v[36:37], v[80:81], v[236:237] op_sel:[0,0,0] op_sel_hi:[0,1,1] neg_lo:[1,0,0] neg_hi:[1,0,0]
	v_pk_add_f32 v[234:235], v[82:83], v[234:235]
	v_pk_add_f32 v[234:235], v[234:235], v[238:239]
	v_pk_add_f32 v[82:83], v[234:235], v[236:237]
	ds_read_b128 v[34:37], v241 offset:4400
	s_waitcnt lgkmcnt(7)
	v_pk_fma_f32 v[84:85], v[38:39], v[6:7], v[84:85] op_sel:[0,0,0] op_sel_hi:[0,1,1] neg_lo:[1,0,0] neg_hi:[1,0,0]
	v_pk_mul_f32 v[234:235], v[38:39], v[54:55] op_sel:[1,0] op_sel_hi:[1,1] neg_lo:[1,0] neg_hi:[1,0]
	v_pk_mul_f32 v[236:237], v[40:41], v[56:57] op_sel:[0,0] op_sel_hi:[0,1] neg_lo:[1,0] neg_hi:[1,0]
	v_pk_mul_f32 v[238:239], v[40:41], v[58:59] op_sel:[1,0] op_sel_hi:[1,1] neg_lo:[1,0] neg_hi:[1,0]
	ds_read_b128 v[38:41], v241 offset:4416
	s_waitcnt lgkmcnt(7)
	v_pk_fma_f32 v[84:85], v[42:43], v[60:61], v[84:85] op_sel:[0,0,0] op_sel_hi:[0,1,1] neg_lo:[1,0,0] neg_hi:[1,0,0]
	v_pk_fma_f32 v[234:235], v[42:43], v[62:63], v[234:235] op_sel:[1,0,0] op_sel_hi:[1,1,1] neg_lo:[1,0,0] neg_hi:[1,0,0]
	v_pk_fma_f32 v[236:237], v[44:45], v[64:65], v[236:237] op_sel:[0,0,0] op_sel_hi:[0,1,1] neg_lo:[1,0,0] neg_hi:[1,0,0]
	v_pk_fma_f32 v[238:239], v[44:45], v[66:67], v[238:239] op_sel:[1,0,0] op_sel_hi:[1,1,1] neg_lo:[1,0,0] neg_hi:[1,0,0]
	ds_read_b128 v[42:45], v241 offset:4608
	s_waitcnt lgkmcnt(7)
	v_pk_fma_f32 v[84:85], v[46:47], v[68:69], v[84:85] op_sel:[0,0,0] op_sel_hi:[0,1,1] neg_lo:[1,0,0] neg_hi:[1,0,0]
	v_pk_fma_f32 v[234:235], v[46:47], v[70:71], v[234:235] op_sel:[1,0,0] op_sel_hi:[1,1,1] neg_lo:[1,0,0] neg_hi:[1,0,0]
	v_pk_fma_f32 v[236:237], v[48:49], v[72:73], v[236:237] op_sel:[0,0,0] op_sel_hi:[0,1,1] neg_lo:[1,0,0] neg_hi:[1,0,0]
	v_pk_fma_f32 v[238:239], v[48:49], v[74:75], v[238:239] op_sel:[1,0,0] op_sel_hi:[1,1,1] neg_lo:[1,0,0] neg_hi:[1,0,0]
	ds_read_b128 v[46:49], v241 offset:4624
	s_waitcnt lgkmcnt(7)
	v_pk_fma_f32 v[84:85], v[50:51], v[76:77], v[84:85] op_sel:[0,0,0] op_sel_hi:[0,1,1] neg_lo:[1,0,0] neg_hi:[1,0,0]
	v_pk_fma_f32 v[234:235], v[50:51], v[78:79], v[234:235] op_sel:[1,0,0] op_sel_hi:[1,1,1] neg_lo:[1,0,0] neg_hi:[1,0,0]
	v_pk_fma_f32 v[236:237], v[52:53], v[80:81], v[236:237] op_sel:[0,0,0] op_sel_hi:[0,1,1] neg_lo:[1,0,0] neg_hi:[1,0,0]
	v_pk_fma_f32 v[238:239], v[52:53], v[82:83], v[238:239] op_sel:[1,0,0] op_sel_hi:[1,1,1] neg_lo:[1,0,0] neg_hi:[1,0,0]
	v_pk_add_f32 v[234:235], v[84:85], v[234:235]
	v_pk_add_f32 v[234:235], v[234:235], v[236:237]
	v_pk_add_f32 v[84:85], v[234:235], v[238:239]
	ds_read_b128 v[50:53], v241 offset:4640
	s_waitcnt lgkmcnt(7)
; template <int DIR>
; __device__ __forceinline__ void dn_solve(const P& p, int task, int m0, int h, int t2, const bf16_t* kn_s, const bf16_t* v_s, const float* gc, const float* be, float* L) {
;     ...
; #pragma unroll
;     for (int cp = 1; cp < 64; ++cp) {
;         float a0 = 0.f, a1 = 0.f, a2 = 0.f, a3 = 0.f;
; #pragma unroll
;         for (int s4 = 0; s4 < cp; s4 += 4) { const f32x4 l4 = *(const f32x4*)(L + cp * 64 + s4); a0 += l4[0] * x[s4]; a1 += l4[1] * x[s4 + 1]; a2 += l4[2] * x[s4 + 2]; a3 += l4[3] * x[s4 + 3]; }
;         x[cp] -= (a0 + a1) + (a2 + a3);
;     }
	v_pk_fma_f32 v[86:87], v[2:3], v[6:7], v[86:87] op_sel:[0,0,0] op_sel_hi:[0,1,1] neg_lo:[1,0,0] neg_hi:[1,0,0]
	v_pk_mul_f32 v[234:235], v[2:3], v[54:55] op_sel:[1,0] op_sel_hi:[1,1] neg_lo:[1,0] neg_hi:[1,0]
	v_pk_mul_f32 v[236:237], v[4:5], v[56:57] op_sel:[0,0] op_sel_hi:[0,1] neg_lo:[1,0] neg_hi:[1,0]
	v_pk_mul_f32 v[238:239], v[4:5], v[58:59] op_sel:[1,0] op_sel_hi:[1,1] neg_lo:[1,0] neg_hi:[1,0]
	ds_read_b128 v[2:5], v241 offset:4656
	s_waitcnt lgkmcnt(7)
	v_pk_fma_f32 v[86:87], v[26:27], v[60:61], v[86:87] op_sel:[0,0,0] op_sel_hi:[0,1,1] neg_lo:[1,0,0] neg_hi:[1,0,0]
	v_pk_fma_f32 v[234:235], v[26:27], v[62:63], v[234:235] op_sel:[1,0,0] op_sel_hi:[1,1,1] neg_lo:[1,0,0] neg_hi:[1,0,0]
	v_pk_fma_f32 v[236:237], v[28:29], v[64:65], v[236:237] op_sel:[0,0,0] op_sel_hi:[0,1,1] neg_lo:[1,0,0] neg_hi:[1,0,0]
	v_pk_fma_f32 v[238:239], v[28:29], v[66:67], v[238:239] op_sel:[1,0,0] op_sel_hi:[1,1,1] neg_lo:[1,0,0] neg_hi:[1,0,0]
	ds_read_b128 v[26:29], v241 offset:4672
	s_waitcnt lgkmcnt(7)
	v_pk_fma_f32 v[86:87], v[30:31], v[68:69], v[86:87] op_sel:[0,0,0] op_sel_hi:[0,1,1] neg_lo:[1,0,0] neg_hi:[1,0,0]
	v_pk_fma_f32 v[234:235], v[30:31], v[70:71], v[234:235] op_sel:[1,0,0] op_sel_hi:[1,1,1] neg_lo:[1,0,0] neg_hi:[1,0,0]
	v_pk_fma_f32 v[236:237], v[32:33], v[72:73], v[236:237] op_sel:[0,0,0] op_sel_hi:[0,1,1] neg_lo:[1,0,0] neg_hi:[1,0,0]
	v_pk_fma_f32 v[238:239], v[32:33], v[74:75], v[238:239] op_sel:[1,0,0] op_sel_hi:[1,1,1] neg_lo:[1,0,0] neg_hi:[1,0,0]
	ds_read_b128 v[30:33], v241 offset:4864
	s_waitcnt lgkmcnt(7)
	v_pk_fma_f32 v[86:87], v[34:35], v[76:77], v[86:87] op_sel:[0,0,0] op_sel_hi:[0,1,1] neg_lo:[1,0,0] neg_hi:[1,0,0]
	v_pk_fma_f32 v[234:235], v[34:35], v[78:79], v[234:235] op_sel:[1,0,0] op_sel_hi:[1,1,1] neg_lo:[1,0,0] neg_hi:[1,0,0]
	v_pk_fma_f32 v[236:237], v[36:37], v[80:81], v[236:237] op_sel:[0,0,0] op_sel_hi:[0,1,1] neg_lo:[1,0,0] neg_hi:[1,0,0]
	v_pk_fma_f32 v[238:239], v[36:37], v[82:83], v[238:239] op_sel:[1,0,0] op_sel_hi:[1,1,1] neg_lo:[1,0,0] neg_hi:[1,0,0]
	ds_read_b128 v[34:37], v241 offset:4880
	s_waitcnt lgkmcnt(7)
	v_pk_fma_f32 v[86:87], v[38:39], v[84:85], v[86:87] op_sel:[0,0,0] op_sel_hi:[0,1,1] neg_lo:[1,0,0] neg_hi:[1,0,0]
	v_pk_add_f32 v[234:235], v[234:235], v[236:237]
	v_pk_add_f32 v[234:235], v[234:235], v[238:239]
	v_pk_add_f32 v[86:87], v[234:235], v[86:87]
	ds_read_b128 v[38:41], v241 offset:4896
	s_waitcnt lgkmcnt(7)
	v_pk_fma_f32 v[88:89], v[42:43], v[6:7], v[88:89] op_sel:[0,0,0] op_sel_hi:[0,1,1] neg_lo:[1,0,0] neg_hi:[1,0,0]
	v_pk_mul_f32 v[234:235], v[42:43], v[54:55] op_sel:[1,0] op_sel_hi:[1,1] neg_lo:[1,0] neg_hi:[1,0]
	v_pk_mul_f32 v[236:237], v[44:45], v[56:57] op_sel:[0,0] op_sel_hi:[0,1] neg_lo:[1,0] neg_hi:[1,0]
	v_pk_mul_f32 v[238:239], v[44:45], v[58:59] op_sel:[1,0] op_sel_hi:[1,1] neg_lo:[1,0] neg_hi:[1,0]
	ds_read_b128 v[42:45], v241 offset:4912
	s_waitcnt lgkmcnt(7)
	v_pk_fma_f32 v[88:89], v[46:47], v[60:61], v[88:89] op_sel:[0,0,0] op_sel_hi:[0,1,1] neg_lo:[1,0,0] neg_hi:[1,0,0]
	v_pk_fma_f32 v[234:235], v[46:47], v[62:63], v[234:235] op_sel:[1,0,0] op_sel_hi:[1,1,1] neg_lo:[1,0,0] neg_hi:[1,0,0]
	v_pk_fma_f32 v[236:237], v[48:49], v[64:65], v[236:237] op_sel:[0,0,0] op_sel_hi:[0,1,1] neg_lo:[1,0,0] neg_hi:[1,0,0]
	v_pk_fma_f32 v[238:239], v[48:49], v[66:67], v[238:239] op_sel:[1,0,0] op_sel_hi:[1,1,1] neg_lo:[1,0,0] neg_hi:[1,0,0]
	ds_read_b128 v[46:49], v241 offset:4928
	s_waitcnt lgkmcnt(7)
	v_pk_fma_f32 v[88:89], v[50:51], v[68:69], v[88:89] op_sel:[0,0,0] op_sel_hi:[0,1,1] neg_lo:[1,0,0] neg_hi:[1,0,0]
	v_pk_fma_f32 v[234:235], v[50:51], v[70:71], v[234:235] op_sel:[1,0,0] op_sel_hi:[1,1,1] neg_lo:[1,0,0] neg_hi:[1,0,0]
	v_pk_fma_f32 v[236:237], v[52:53], v[72:73], v[236:237] op_sel:[0,0,0] op_sel_hi:[0,1,1] neg_lo:[1,0,0] neg_hi:[1,0,0]
	v_pk_fma_f32 v[238:239], v[52:53], v[74:75], v[238:239] op_sel:[1,0,0] op_sel_hi:[1,1,1] neg_lo:[1,0,0] neg_hi:[1,0,0]
	ds_read_b128 v[50:53], v241 offset:5120
	s_waitcnt lgkmcnt(7)
	v_pk_fma_f32 v[88:89], v[2:3], v[76:77], v[88:89] op_sel:[0,0,0] op_sel_hi:[0,1,1] neg_lo:[1,0,0] neg_hi:[1,0,0]
	v_pk_fma_f32 v[234:235], v[2:3], v[78:79], v[234:235] op_sel:[1,0,0] op_sel_hi:[1,1,1] neg_lo:[1,0,0] neg_hi:[1,0,0]
	v_pk_fma_f32 v[236:237], v[4:5], v[80:81], v[236:237] op_sel:[0,0,0] op_sel_hi:[0,1,1] neg_lo:[1,0,0] neg_hi:[1,0,0]
	v_pk_fma_f32 v[238:239], v[4:5], v[82:83], v[238:239] op_sel:[1,0,0] op_sel_hi:[1,1,1] neg_lo:[1,0,0] neg_hi:[1,0,0]
	ds_read_b128 v[2:5], v241 offset:5136
	s_waitcnt lgkmcnt(7)
	v_pk_fma_f32 v[88:89], v[26:27], v[84:85], v[88:89] op_sel:[0,0,0] op_sel_hi:[0,1,1] neg_lo:[1,0,0] neg_hi:[1,0,0]
	v_pk_fma_f32 v[234:235], v[26:27], v[86:87], v[234:235] op_sel:[1,0,0] op_sel_hi:[1,1,1] neg_lo:[1,0,0] neg_hi:[1,0,0]
	v_pk_add_f32 v[236:237], v[88:89], v[236:237]
	v_pk_add_f32 v[236:237], v[236:237], v[238:239]
	v_pk_add_f32 v[88:89], v[236:237], v[234:235]
	ds_read_b128 v[26:29], v241 offset:5152
	s_waitcnt lgkmcnt(7)
	v_pk_fma_f32 v[90:91], v[30:31], v[6:7], v[90:91] op_sel:[0,0,0] op_sel_hi:[0,1,1] neg_lo:[1,0,0] neg_hi:[1,0,0]
	v_pk_mul_f32 v[234:235], v[30:31], v[54:55] op_sel:[1,0] op_sel_hi:[1,1] neg_lo:[1,0] neg_hi:[1,0]
	v_pk_mul_f32 v[236:237], v[32:33], v[56:57] op_sel:[0,0] op_sel_hi:[0,1] neg_lo:[1,0] neg_hi:[1,0]
	v_pk_mul_f32 v[238:239], v[32:33], v[58:59] op_sel:[1,0] op_sel_hi:[1,1] neg_lo:[1,0] neg_hi:[1,0]
	ds_read_b128 v[30:33], v241 offset:5168
	s_waitcnt lgkmcnt(7)
; template <int DIR>
; __device__ __forceinline__ void dn_solve(const P& p, int task, int m0, int h, int t2, const bf16_t* kn_s, const bf16_t* v_s, const float* gc, const float* be, float* L) {
;     ...
; #pragma unroll
;     for (int cp = 1; cp < 64; ++cp) {
;         float a0 = 0.f, a1 = 0.f, a2 = 0.f, a3 = 0.f;
; #pragma unroll
;         for (int s4 = 0; s4 < cp; s4 += 4) { const f32x4 l4 = *(const f32x4*)(L + cp * 64 + s4); a0 += l4[0] * x[s4]; a1 += l4[1] * x[s4 + 1]; a2 += l4[2] * x[s4 + 2]; a3 += l4[3] * x[s4 + 3]; }
;         x[cp] -= (a0 + a1) + (a2 + a3);
;     }
	v_pk_fma_f32 v[90:91], v[34:35], v[60:61], v[90:91] op_sel:[0,0,0] op_sel_hi:[0,1,1] neg_lo:[1,0,0] neg_hi:[1,0,0]
	v_pk_fma_f32 v[234:235], v[34:35], v[62:63], v[234:235] op_sel:[1,0,0] op_sel_hi:[1,1,1] neg_lo:[1,0,0] neg_hi:[1,0,0]
	v_pk_fma_f32 v[236:237], v[36:37], v[64:65], v[236:237] op_sel:[0,0,0] op_sel_hi:[0,1,1] neg_lo:[1,0,0] neg_hi:[1,0,0]
	v_pk_fma_f32 v[238:239], v[36:37], v[66:67], v[238:239] op_sel:[1,0,0] op_sel_hi:[1,1,1] neg_lo:[1,0,0] neg_hi:[1,0,0]
	ds_read_b128 v[34:37], v241 offset:5184
	s_waitcnt lgkmcnt(7)
	v_pk_fma_f32 v[90:91], v[38:39], v[68:69], v[90:91] op_sel:[0,0,0] op_sel_hi:[0,1,1] neg_lo:[1,0,0] neg_hi:[1,0,0]
	v_pk_fma_f32 v[234:235], v[38:39], v[70:71], v[234:235] op_sel:[1,0,0] op_sel_hi:[1,1,1] neg_lo:[1,0,0] neg_hi:[1,0,0]
	v_pk_fma_f32 v[236:237], v[40:41], v[72:73], v[236:237] op_sel:[0,0,0] op_sel_hi:[0,1,1] neg_lo:[1,0,0] neg_hi:[1,0,0]
	v_pk_fma_f32 v[238:239], v[40:41], v[74:75], v[238:239] op_sel:[1,0,0] op_sel_hi:[1,1,1] neg_lo:[1,0,0] neg_hi:[1,0,0]
	ds_read_b128 v[38:41], v241 offset:5376
	s_waitcnt lgkmcnt(7)
	v_pk_fma_f32 v[90:91], v[42:43], v[76:77], v[90:91] op_sel:[0,0,0] op_sel_hi:[0,1,1] neg_lo:[1,0,0] neg_hi:[1,0,0]
	v_pk_fma_f32 v[234:235], v[42:43], v[78:79], v[234:235] op_sel:[1,0,0] op_sel_hi:[1,1,1] neg_lo:[1,0,0] neg_hi:[1,0,0]
	v_pk_fma_f32 v[236:237], v[44:45], v[80:81], v[236:237] op_sel:[0,0,0] op_sel_hi:[0,1,1] neg_lo:[1,0,0] neg_hi:[1,0,0]
	v_pk_fma_f32 v[238:239], v[44:45], v[82:83], v[238:239] op_sel:[1,0,0] op_sel_hi:[1,1,1] neg_lo:[1,0,0] neg_hi:[1,0,0]
	ds_read_b128 v[42:45], v241 offset:5392
	s_waitcnt lgkmcnt(7)
	v_pk_fma_f32 v[90:91], v[46:47], v[84:85], v[90:91] op_sel:[0,0,0] op_sel_hi:[0,1,1] neg_lo:[1,0,0] neg_hi:[1,0,0]
	v_pk_fma_f32 v[234:235], v[46:47], v[86:87], v[234:235] op_sel:[1,0,0] op_sel_hi:[1,1,1] neg_lo:[1,0,0] neg_hi:[1,0,0]
	v_pk_fma_f32 v[236:237], v[48:49], v[88:89], v[236:237] op_sel:[0,0,0] op_sel_hi:[0,1,1] neg_lo:[1,0,0] neg_hi:[1,0,0]
	v_pk_add_f32 v[234:235], v[90:91], v[234:235]
	v_pk_add_f32 v[234:235], v[234:235], v[238:239]
	v_pk_add_f32 v[90:91], v[234:235], v[236:237]
	ds_read_b128 v[46:49], v241 offset:5408
	s_waitcnt lgkmcnt(7)
	v_pk_fma_f32 v[92:93], v[50:51], v[6:7], v[92:93] op_sel:[0,0,0] op_sel_hi:[0,1,1] neg_lo:[1,0,0] neg_hi:[1,0,0]
	v_pk_mul_f32 v[234:235], v[50:51], v[54:55] op_sel:[1,0] op_sel_hi:[1,1] neg_lo:[1,0] neg_hi:[1,0]
	v_pk_mul_f32 v[236:237], v[52:53], v[56:57] op_sel:[0,0] op_sel_hi:[0,1] neg_lo:[1,0] neg_hi:[1,0]
	v_pk_mul_f32 v[238:239], v[52:53], v[58:59] op_sel:[1,0] op_sel_hi:[1,1] neg_lo:[1,0] neg_hi:[1,0]
	ds_read_b128 v[50:53], v241 offset:5424
	s_waitcnt lgkmcnt(7)
	v_pk_fma_f32 v[92:93], v[2:3], v[60:61], v[92:93] op_sel:[0,0,0] op_sel_hi:[0,1,1] neg_lo:[1,0,0] neg_hi:[1,0,0]
	v_pk_fma_f32 v[234:235], v[2:3], v[62:63], v[234:235] op_sel:[1,0,0] op_sel_hi:[1,1,1] neg_lo:[1,0,0] neg_hi:[1,0,0]
	v_pk_fma_f32 v[236:237], v[4:5], v[64:65], v[236:237] op_sel:[0,0,0] op_sel_hi:[0,1,1] neg_lo:[1,0,0] neg_hi:[1,0,0]
	v_pk_fma_f32 v[238:239], v[4:5], v[66:67], v[238:239] op_sel:[1,0,0] op_sel_hi:[1,1,1] neg_lo:[1,0,0] neg_hi:[1,0,0]
	ds_read_b128 v[2:5], v241 offset:5440
	s_waitcnt lgkmcnt(7)
	v_pk_fma_f32 v[92:93], v[26:27], v[68:69], v[92:93] op_sel:[0,0,0] op_sel_hi:[0,1,1] neg_lo:[1,0,0] neg_hi:[1,0,0]
	v_pk_fma_f32 v[234:235], v[26:27], v[70:71], v[234:235] op_sel:[1,0,0] op_sel_hi:[1,1,1] neg_lo:[1,0,0] neg_hi:[1,0,0]
	v_pk_fma_f32 v[236:237], v[28:29], v[72:73], v[236:237] op_sel:[0,0,0] op_sel_hi:[0,1,1] neg_lo:[1,0,0] neg_hi:[1,0,0]
	v_pk_fma_f32 v[238:239], v[28:29], v[74:75], v[238:239] op_sel:[1,0,0] op_sel_hi:[1,1,1] neg_lo:[1,0,0] neg_hi:[1,0,0]
	ds_read_b128 v[26:29], v241 offset:5456
	s_waitcnt lgkmcnt(7)
	v_pk_fma_f32 v[92:93], v[30:31], v[76:77], v[92:93] op_sel:[0,0,0] op_sel_hi:[0,1,1] neg_lo:[1,0,0] neg_hi:[1,0,0]
	v_pk_fma_f32 v[234:235], v[30:31], v[78:79], v[234:235] op_sel:[1,0,0] op_sel_hi:[1,1,1] neg_lo:[1,0,0] neg_hi:[1,0,0]
	v_pk_fma_f32 v[236:237], v[32:33], v[80:81], v[236:237] op_sel:[0,0,0] op_sel_hi:[0,1,1] neg_lo:[1,0,0] neg_hi:[1,0,0]
	v_pk_fma_f32 v[238:239], v[32:33], v[82:83], v[238:239] op_sel:[1,0,0] op_sel_hi:[1,1,1] neg_lo:[1,0,0] neg_hi:[1,0,0]
	ds_read_b128 v[30:33], v241 offset:5632
	s_waitcnt lgkmcnt(7)
	v_pk_fma_f32 v[92:93], v[34:35], v[84:85], v[92:93] op_sel:[0,0,0] op_sel_hi:[0,1,1] neg_lo:[1,0,0] neg_hi:[1,0,0]
	v_pk_fma_f32 v[234:235], v[34:35], v[86:87], v[234:235] op_sel:[1,0,0] op_sel_hi:[1,1,1] neg_lo:[1,0,0] neg_hi:[1,0,0]
	v_pk_fma_f32 v[236:237], v[36:37], v[88:89], v[236:237] op_sel:[0,0,0] op_sel_hi:[0,1,1] neg_lo:[1,0,0] neg_hi:[1,0,0]
	v_pk_fma_f32 v[238:239], v[36:37], v[90:91], v[238:239] op_sel:[1,0,0] op_sel_hi:[1,1,1] neg_lo:[1,0,0] neg_hi:[1,0,0]
	v_pk_add_f32 v[234:235], v[92:93], v[234:235]
	v_pk_add_f32 v[234:235], v[234:235], v[236:237]
	v_pk_add_f32 v[92:93], v[234:235], v[238:239]
	ds_read_b128 v[34:37], v241 offset:5648
	s_waitcnt lgkmcnt(7)
	v_pk_fma_f32 v[94:95], v[38:39], v[6:7], v[94:95] op_sel:[0,0,0] op_sel_hi:[0,1,1] neg_lo:[1,0,0] neg_hi:[1,0,0]
	v_pk_mul_f32 v[234:235], v[38:39], v[54:55] op_sel:[1,0] op_sel_hi:[1,1] neg_lo:[1,0] neg_hi:[1,0]
	v_pk_mul_f32 v[236:237], v[40:41], v[56:57] op_sel:[0,0] op_sel_hi:[0,1] neg_lo:[1,0] neg_hi:[1,0]
	v_pk_mul_f32 v[238:239], v[40:41], v[58:59] op_sel:[1,0] op_sel_hi:[1,1] neg_lo:[1,0] neg_hi:[1,0]
	ds_read_b128 v[38:41], v241 offset:5664
	s_waitcnt lgkmcnt(7)
; template <int DIR>
; __device__ __forceinline__ void dn_solve(const P& p, int task, int m0, int h, int t2, const bf16_t* kn_s, const bf16_t* v_s, const float* gc, const float* be, float* L) {
;     ...
; #pragma unroll
;     for (int cp = 1; cp < 64; ++cp) {
;         float a0 = 0.f, a1 = 0.f, a2 = 0.f, a3 = 0.f;
; #pragma unroll
;         for (int s4 = 0; s4 < cp; s4 += 4) { const f32x4 l4 = *(const f32x4*)(L + cp * 64 + s4); a0 += l4[0] * x[s4]; a1 += l4[1] * x[s4 + 1]; a2 += l4[2] * x[s4 + 2]; a3 += l4[3] * x[s4 + 3]; }
;         x[cp] -= (a0 + a1) + (a2 + a3);
;     }
	v_pk_fma_f32 v[94:95], v[42:43], v[60:61], v[94:95] op_sel:[0,0,0] op_sel_hi:[0,1,1] neg_lo:[1,0,0] neg_hi:[1,0,0]
	v_pk_fma_f32 v[234:235], v[42:43], v[62:63], v[234:235] op_sel:[1,0,0] op_sel_hi:[1,1,1] neg_lo:[1,0,0] neg_hi:[1,0,0]
	v_pk_fma_f32 v[236:237], v[44:45], v[64:65], v[236:237] op_sel:[0,0,0] op_sel_hi:[0,1,1] neg_lo:[1,0,0] neg_hi:[1,0,0]
	v_pk_fma_f32 v[238:239], v[44:45], v[66:67], v[238:239] op_sel:[1,0,0] op_sel_hi:[1,1,1] neg_lo:[1,0,0] neg_hi:[1,0,0]
	ds_read_b128 v[42:45], v241 offset:5680
	s_waitcnt lgkmcnt(7)
	v_pk_fma_f32 v[94:95], v[46:47], v[68:69], v[94:95] op_sel:[0,0,0] op_sel_hi:[0,1,1] neg_lo:[1,0,0] neg_hi:[1,0,0]
	v_pk_fma_f32 v[234:235], v[46:47], v[70:71], v[234:235] op_sel:[1,0,0] op_sel_hi:[1,1,1] neg_lo:[1,0,0] neg_hi:[1,0,0]
	v_pk_fma_f32 v[236:237], v[48:49], v[72:73], v[236:237] op_sel:[0,0,0] op_sel_hi:[0,1,1] neg_lo:[1,0,0] neg_hi:[1,0,0]
	v_pk_fma_f32 v[238:239], v[48:49], v[74:75], v[238:239] op_sel:[1,0,0] op_sel_hi:[1,1,1] neg_lo:[1,0,0] neg_hi:[1,0,0]
	ds_read_b128 v[46:49], v241 offset:5696
	s_waitcnt lgkmcnt(7)
	v_pk_fma_f32 v[94:95], v[50:51], v[76:77], v[94:95] op_sel:[0,0,0] op_sel_hi:[0,1,1] neg_lo:[1,0,0] neg_hi:[1,0,0]
	v_pk_fma_f32 v[234:235], v[50:51], v[78:79], v[234:235] op_sel:[1,0,0] op_sel_hi:[1,1,1] neg_lo:[1,0,0] neg_hi:[1,0,0]
	v_pk_fma_f32 v[236:237], v[52:53], v[80:81], v[236:237] op_sel:[0,0,0] op_sel_hi:[0,1,1] neg_lo:[1,0,0] neg_hi:[1,0,0]
	v_pk_fma_f32 v[238:239], v[52:53], v[82:83], v[238:239] op_sel:[1,0,0] op_sel_hi:[1,1,1] neg_lo:[1,0,0] neg_hi:[1,0,0]
	ds_read_b128 v[50:53], v241 offset:5712
	s_waitcnt lgkmcnt(7)
	v_pk_fma_f32 v[94:95], v[2:3], v[84:85], v[94:95] op_sel:[0,0,0] op_sel_hi:[0,1,1] neg_lo:[1,0,0] neg_hi:[1,0,0]
	v_pk_fma_f32 v[234:235], v[2:3], v[86:87], v[234:235] op_sel:[1,0,0] op_sel_hi:[1,1,1] neg_lo:[1,0,0] neg_hi:[1,0,0]
	v_pk_fma_f32 v[236:237], v[4:5], v[88:89], v[236:237] op_sel:[0,0,0] op_sel_hi:[0,1,1] neg_lo:[1,0,0] neg_hi:[1,0,0]
	v_pk_fma_f32 v[238:239], v[4:5], v[90:91], v[238:239] op_sel:[1,0,0] op_sel_hi:[1,1,1] neg_lo:[1,0,0] neg_hi:[1,0,0]
	ds_read_b128 v[2:5], v241 offset:5888
	s_waitcnt lgkmcnt(7)
	v_pk_fma_f32 v[94:95], v[26:27], v[92:93], v[94:95] op_sel:[0,0,0] op_sel_hi:[0,1,1] neg_lo:[1,0,0] neg_hi:[1,0,0]
	v_pk_add_f32 v[234:235], v[234:235], v[236:237]
	v_pk_add_f32 v[234:235], v[234:235], v[238:239]
	v_pk_add_f32 v[94:95], v[234:235], v[94:95]
	ds_read_b128 v[26:29], v241 offset:5904
	s_waitcnt lgkmcnt(7)
	v_pk_fma_f32 v[96:97], v[30:31], v[6:7], v[96:97] op_sel:[0,0,0] op_sel_hi:[0,1,1] neg_lo:[1,0,0] neg_hi:[1,0,0]
	v_pk_mul_f32 v[234:235], v[30:31], v[54:55] op_sel:[1,0] op_sel_hi:[1,1] neg_lo:[1,0] neg_hi:[1,0]
	v_pk_mul_f32 v[236:237], v[32:33], v[56:57] op_sel:[0,0] op_sel_hi:[0,1] neg_lo:[1,0] neg_hi:[1,0]
	v_pk_mul_f32 v[238:239], v[32:33], v[58:59] op_sel:[1,0] op_sel_hi:[1,1] neg_lo:[1,0] neg_hi:[1,0]
	ds_read_b128 v[30:33], v241 offset:5920
	s_waitcnt lgkmcnt(7)
	v_pk_fma_f32 v[96:97], v[34:35], v[60:61], v[96:97] op_sel:[0,0,0] op_sel_hi:[0,1,1] neg_lo:[1,0,0] neg_hi:[1,0,0]
	v_pk_fma_f32 v[234:235], v[34:35], v[62:63], v[234:235] op_sel:[1,0,0] op_sel_hi:[1,1,1] neg_lo:[1,0,0] neg_hi:[1,0,0]
	v_pk_fma_f32 v[236:237], v[36:37], v[64:65], v[236:237] op_sel:[0,0,0] op_sel_hi:[0,1,1] neg_lo:[1,0,0] neg_hi:[1,0,0]
	v_pk_fma_f32 v[238:239], v[36:37], v[66:67], v[238:239] op_sel:[1,0,0] op_sel_hi:[1,1,1] neg_lo:[1,0,0] neg_hi:[1,0,0]
	ds_read_b128 v[34:37], v241 offset:5936
	s_waitcnt lgkmcnt(7)
	v_pk_fma_f32 v[96:97], v[38:39], v[68:69], v[96:97] op_sel:[0,0,0] op_sel_hi:[0,1,1] neg_lo:[1,0,0] neg_hi:[1,0,0]
	v_pk_fma_f32 v[234:235], v[38:39], v[70:71], v[234:235] op_sel:[1,0,0] op_sel_hi:[1,1,1] neg_lo:[1,0,0] neg_hi:[1,0,0]
	v_pk_fma_f32 v[236:237], v[40:41], v[72:73], v[236:237] op_sel:[0,0,0] op_sel_hi:[0,1,1] neg_lo:[1,0,0] neg_hi:[1,0,0]
	v_pk_fma_f32 v[238:239], v[40:41], v[74:75], v[238:239] op_sel:[1,0,0] op_sel_hi:[1,1,1] neg_lo:[1,0,0] neg_hi:[1,0,0]
	ds_read_b128 v[38:41], v241 offset:5952
	s_waitcnt lgkmcnt(7)
	v_pk_fma_f32 v[96:97], v[42:43], v[76:77], v[96:97] op_sel:[0,0,0] op_sel_hi:[0,1,1] neg_lo:[1,0,0] neg_hi:[1,0,0]
	v_pk_fma_f32 v[234:235], v[42:43], v[78:79], v[234:235] op_sel:[1,0,0] op_sel_hi:[1,1,1] neg_lo:[1,0,0] neg_hi:[1,0,0]
	v_pk_fma_f32 v[236:237], v[44:45], v[80:81], v[236:237] op_sel:[0,0,0] op_sel_hi:[0,1,1] neg_lo:[1,0,0] neg_hi:[1,0,0]
	v_pk_fma_f32 v[238:239], v[44:45], v[82:83], v[238:239] op_sel:[1,0,0] op_sel_hi:[1,1,1] neg_lo:[1,0,0] neg_hi:[1,0,0]
	ds_read_b128 v[42:45], v241 offset:5968
	s_waitcnt lgkmcnt(7)
	v_pk_fma_f32 v[96:97], v[46:47], v[84:85], v[96:97] op_sel:[0,0,0] op_sel_hi:[0,1,1] neg_lo:[1,0,0] neg_hi:[1,0,0]
	v_pk_fma_f32 v[234:235], v[46:47], v[86:87], v[234:235] op_sel:[1,0,0] op_sel_hi:[1,1,1] neg_lo:[1,0,0] neg_hi:[1,0,0]
	v_pk_fma_f32 v[236:237], v[48:49], v[88:89], v[236:237] op_sel:[0,0,0] op_sel_hi:[0,1,1] neg_lo:[1,0,0] neg_hi:[1,0,0]
	v_pk_fma_f32 v[238:239], v[48:49], v[90:91], v[238:239] op_sel:[1,0,0] op_sel_hi:[1,1,1] neg_lo:[1,0,0] neg_hi:[1,0,0]
	ds_read_b128 v[46:49], v241 offset:6144
	s_waitcnt lgkmcnt(7)
	v_pk_fma_f32 v[96:97], v[50:51], v[92:93], v[96:97] op_sel:[0,0,0] op_sel_hi:[0,1,1] neg_lo:[1,0,0] neg_hi:[1,0,0]
	v_pk_fma_f32 v[234:235], v[50:51], v[94:95], v[234:235] op_sel:[1,0,0] op_sel_hi:[1,1,1] neg_lo:[1,0,0] neg_hi:[1,0,0]
	v_pk_add_f32 v[236:237], v[96:97], v[236:237]
	v_pk_add_f32 v[236:237], v[236:237], v[238:239]
	v_pk_add_f32 v[96:97], v[236:237], v[234:235]
	ds_read_b128 v[50:53], v241 offset:6160
	s_waitcnt lgkmcnt(7)
; template <int DIR>
; __device__ __forceinline__ void dn_solve(const P& p, int task, int m0, int h, int t2, const bf16_t* kn_s, const bf16_t* v_s, const float* gc, const float* be, float* L) {
;     ...
; #pragma unroll
;     for (int cp = 1; cp < 64; ++cp) {
;         float a0 = 0.f, a1 = 0.f, a2 = 0.f, a3 = 0.f;
; #pragma unroll
;         for (int s4 = 0; s4 < cp; s4 += 4) { const f32x4 l4 = *(const f32x4*)(L + cp * 64 + s4); a0 += l4[0] * x[s4]; a1 += l4[1] * x[s4 + 1]; a2 += l4[2] * x[s4 + 2]; a3 += l4[3] * x[s4 + 3]; }
;         x[cp] -= (a0 + a1) + (a2 + a3);
;     }
	v_pk_fma_f32 v[98:99], v[2:3], v[6:7], v[98:99] op_sel:[0,0,0] op_sel_hi:[0,1,1] neg_lo:[1,0,0] neg_hi:[1,0,0]
	v_pk_mul_f32 v[234:235], v[2:3], v[54:55] op_sel:[1,0] op_sel_hi:[1,1] neg_lo:[1,0] neg_hi:[1,0]
	v_pk_mul_f32 v[236:237], v[4:5], v[56:57] op_sel:[0,0] op_sel_hi:[0,1] neg_lo:[1,0] neg_hi:[1,0]
	v_pk_mul_f32 v[238:239], v[4:5], v[58:59] op_sel:[1,0] op_sel_hi:[1,1] neg_lo:[1,0] neg_hi:[1,0]
	ds_read_b128 v[2:5], v241 offset:6176
	s_waitcnt lgkmcnt(7)
	v_pk_fma_f32 v[98:99], v[26:27], v[60:61], v[98:99] op_sel:[0,0,0] op_sel_hi:[0,1,1] neg_lo:[1,0,0] neg_hi:[1,0,0]
	v_pk_fma_f32 v[234:235], v[26:27], v[62:63], v[234:235] op_sel:[1,0,0] op_sel_hi:[1,1,1] neg_lo:[1,0,0] neg_hi:[1,0,0]
	v_pk_fma_f32 v[236:237], v[28:29], v[64:65], v[236:237] op_sel:[0,0,0] op_sel_hi:[0,1,1] neg_lo:[1,0,0] neg_hi:[1,0,0]
	v_pk_fma_f32 v[238:239], v[28:29], v[66:67], v[238:239] op_sel:[1,0,0] op_sel_hi:[1,1,1] neg_lo:[1,0,0] neg_hi:[1,0,0]
	ds_read_b128 v[26:29], v241 offset:6192
	s_waitcnt lgkmcnt(7)
	v_pk_fma_f32 v[98:99], v[30:31], v[68:69], v[98:99] op_sel:[0,0,0] op_sel_hi:[0,1,1] neg_lo:[1,0,0] neg_hi:[1,0,0]
	v_pk_fma_f32 v[234:235], v[30:31], v[70:71], v[234:235] op_sel:[1,0,0] op_sel_hi:[1,1,1] neg_lo:[1,0,0] neg_hi:[1,0,0]
	v_pk_fma_f32 v[236:237], v[32:33], v[72:73], v[236:237] op_sel:[0,0,0] op_sel_hi:[0,1,1] neg_lo:[1,0,0] neg_hi:[1,0,0]
	v_pk_fma_f32 v[238:239], v[32:33], v[74:75], v[238:239] op_sel:[1,0,0] op_sel_hi:[1,1,1] neg_lo:[1,0,0] neg_hi:[1,0,0]
	ds_read_b128 v[30:33], v241 offset:6208
	s_waitcnt lgkmcnt(7)
	v_pk_fma_f32 v[98:99], v[34:35], v[76:77], v[98:99] op_sel:[0,0,0] op_sel_hi:[0,1,1] neg_lo:[1,0,0] neg_hi:[1,0,0]
	v_pk_fma_f32 v[234:235], v[34:35], v[78:79], v[234:235] op_sel:[1,0,0] op_sel_hi:[1,1,1] neg_lo:[1,0,0] neg_hi:[1,0,0]
	v_pk_fma_f32 v[236:237], v[36:37], v[80:81], v[236:237] op_sel:[0,0,0] op_sel_hi:[0,1,1] neg_lo:[1,0,0] neg_hi:[1,0,0]
	v_pk_fma_f32 v[238:239], v[36:37], v[82:83], v[238:239] op_sel:[1,0,0] op_sel_hi:[1,1,1] neg_lo:[1,0,0] neg_hi:[1,0,0]
	ds_read_b128 v[34:37], v241 offset:6224
	s_waitcnt lgkmcnt(7)
	v_pk_fma_f32 v[98:99], v[38:39], v[84:85], v[98:99] op_sel:[0,0,0] op_sel_hi:[0,1,1] neg_lo:[1,0,0] neg_hi:[1,0,0]
	v_pk_fma_f32 v[234:235], v[38:39], v[86:87], v[234:235] op_sel:[1,0,0] op_sel_hi:[1,1,1] neg_lo:[1,0,0] neg_hi:[1,0,0]
	v_pk_fma_f32 v[236:237], v[40:41], v[88:89], v[236:237] op_sel:[0,0,0] op_sel_hi:[0,1,1] neg_lo:[1,0,0] neg_hi:[1,0,0]
	v_pk_fma_f32 v[238:239], v[40:41], v[90:91], v[238:239] op_sel:[1,0,0] op_sel_hi:[1,1,1] neg_lo:[1,0,0] neg_hi:[1,0,0]
	ds_read_b128 v[38:41], v241 offset:6400
	s_waitcnt lgkmcnt(7)
	v_pk_fma_f32 v[98:99], v[42:43], v[92:93], v[98:99] op_sel:[0,0,0] op_sel_hi:[0,1,1] neg_lo:[1,0,0] neg_hi:[1,0,0]
	v_pk_fma_f32 v[234:235], v[42:43], v[94:95], v[234:235] op_sel:[1,0,0] op_sel_hi:[1,1,1] neg_lo:[1,0,0] neg_hi:[1,0,0]
	v_pk_fma_f32 v[236:237], v[44:45], v[96:97], v[236:237] op_sel:[0,0,0] op_sel_hi:[0,1,1] neg_lo:[1,0,0] neg_hi:[1,0,0]
	v_pk_add_f32 v[234:235], v[98:99], v[234:235]
	v_pk_add_f32 v[234:235], v[234:235], v[238:239]
	v_pk_add_f32 v[98:99], v[234:235], v[236:237]
	ds_read_b128 v[42:45], v241 offset:6416
	s_waitcnt lgkmcnt(7)
	v_pk_fma_f32 v[100:101], v[46:47], v[6:7], v[100:101] op_sel:[0,0,0] op_sel_hi:[0,1,1] neg_lo:[1,0,0] neg_hi:[1,0,0]
	v_pk_mul_f32 v[234:235], v[46:47], v[54:55] op_sel:[1,0] op_sel_hi:[1,1] neg_lo:[1,0] neg_hi:[1,0]
	v_pk_mul_f32 v[236:237], v[48:49], v[56:57] op_sel:[0,0] op_sel_hi:[0,1] neg_lo:[1,0] neg_hi:[1,0]
	v_pk_mul_f32 v[238:239], v[48:49], v[58:59] op_sel:[1,0] op_sel_hi:[1,1] neg_lo:[1,0] neg_hi:[1,0]
	ds_read_b128 v[46:49], v241 offset:6432
	s_waitcnt lgkmcnt(7)
	v_pk_fma_f32 v[100:101], v[50:51], v[60:61], v[100:101] op_sel:[0,0,0] op_sel_hi:[0,1,1] neg_lo:[1,0,0] neg_hi:[1,0,0]
	v_pk_fma_f32 v[234:235], v[50:51], v[62:63], v[234:235] op_sel:[1,0,0] op_sel_hi:[1,1,1] neg_lo:[1,0,0] neg_hi:[1,0,0]
	v_pk_fma_f32 v[236:237], v[52:53], v[64:65], v[236:237] op_sel:[0,0,0] op_sel_hi:[0,1,1] neg_lo:[1,0,0] neg_hi:[1,0,0]
	v_pk_fma_f32 v[238:239], v[52:53], v[66:67], v[238:239] op_sel:[1,0,0] op_sel_hi:[1,1,1] neg_lo:[1,0,0] neg_hi:[1,0,0]
	ds_read_b128 v[50:53], v241 offset:6448
	s_waitcnt lgkmcnt(7)
	v_pk_fma_f32 v[100:101], v[2:3], v[68:69], v[100:101] op_sel:[0,0,0] op_sel_hi:[0,1,1] neg_lo:[1,0,0] neg_hi:[1,0,0]
	v_pk_fma_f32 v[234:235], v[2:3], v[70:71], v[234:235] op_sel:[1,0,0] op_sel_hi:[1,1,1] neg_lo:[1,0,0] neg_hi:[1,0,0]
	v_pk_fma_f32 v[236:237], v[4:5], v[72:73], v[236:237] op_sel:[0,0,0] op_sel_hi:[0,1,1] neg_lo:[1,0,0] neg_hi:[1,0,0]
	v_pk_fma_f32 v[238:239], v[4:5], v[74:75], v[238:239] op_sel:[1,0,0] op_sel_hi:[1,1,1] neg_lo:[1,0,0] neg_hi:[1,0,0]
	ds_read_b128 v[2:5], v241 offset:6464
	s_waitcnt lgkmcnt(7)
	v_pk_fma_f32 v[100:101], v[26:27], v[76:77], v[100:101] op_sel:[0,0,0] op_sel_hi:[0,1,1] neg_lo:[1,0,0] neg_hi:[1,0,0]
	v_pk_fma_f32 v[234:235], v[26:27], v[78:79], v[234:235] op_sel:[1,0,0] op_sel_hi:[1,1,1] neg_lo:[1,0,0] neg_hi:[1,0,0]
	v_pk_fma_f32 v[236:237], v[28:29], v[80:81], v[236:237] op_sel:[0,0,0] op_sel_hi:[0,1,1] neg_lo:[1,0,0] neg_hi:[1,0,0]
	v_pk_fma_f32 v[238:239], v[28:29], v[82:83], v[238:239] op_sel:[1,0,0] op_sel_hi:[1,1,1] neg_lo:[1,0,0] neg_hi:[1,0,0]
	ds_read_b128 v[26:29], v241 offset:6480
	s_waitcnt lgkmcnt(7)
	v_pk_fma_f32 v[100:101], v[30:31], v[84:85], v[100:101] op_sel:[0,0,0] op_sel_hi:[0,1,1] neg_lo:[1,0,0] neg_hi:[1,0,0]
	v_pk_fma_f32 v[234:235], v[30:31], v[86:87], v[234:235] op_sel:[1,0,0] op_sel_hi:[1,1,1] neg_lo:[1,0,0] neg_hi:[1,0,0]
	v_pk_fma_f32 v[236:237], v[32:33], v[88:89], v[236:237] op_sel:[0,0,0] op_sel_hi:[0,1,1] neg_lo:[1,0,0] neg_hi:[1,0,0]
	v_pk_fma_f32 v[238:239], v[32:33], v[90:91], v[238:239] op_sel:[1,0,0] op_sel_hi:[1,1,1] neg_lo:[1,0,0] neg_hi:[1,0,0]
	ds_read_b128 v[30:33], v241 offset:6496
	s_waitcnt lgkmcnt(7)
; template <int DIR>
; __device__ __forceinline__ void dn_solve(const P& p, int task, int m0, int h, int t2, const bf16_t* kn_s, const bf16_t* v_s, const float* gc, const float* be, float* L) {
;     ...
; #pragma unroll
;     for (int cp = 1; cp < 64; ++cp) {
;         float a0 = 0.f, a1 = 0.f, a2 = 0.f, a3 = 0.f;
; #pragma unroll
;         for (int s4 = 0; s4 < cp; s4 += 4) { const f32x4 l4 = *(const f32x4*)(L + cp * 64 + s4); a0 += l4[0] * x[s4]; a1 += l4[1] * x[s4 + 1]; a2 += l4[2] * x[s4 + 2]; a3 += l4[3] * x[s4 + 3]; }
;         x[cp] -= (a0 + a1) + (a2 + a3);
;     }
	v_pk_fma_f32 v[100:101], v[34:35], v[92:93], v[100:101] op_sel:[0,0,0] op_sel_hi:[0,1,1] neg_lo:[1,0,0] neg_hi:[1,0,0]
	v_pk_fma_f32 v[234:235], v[34:35], v[94:95], v[234:235] op_sel:[1,0,0] op_sel_hi:[1,1,1] neg_lo:[1,0,0] neg_hi:[1,0,0]
	v_pk_fma_f32 v[236:237], v[36:37], v[96:97], v[236:237] op_sel:[0,0,0] op_sel_hi:[0,1,1] neg_lo:[1,0,0] neg_hi:[1,0,0]
	v_pk_fma_f32 v[238:239], v[36:37], v[98:99], v[238:239] op_sel:[1,0,0] op_sel_hi:[1,1,1] neg_lo:[1,0,0] neg_hi:[1,0,0]
	v_pk_add_f32 v[234:235], v[100:101], v[234:235]
	v_pk_add_f32 v[234:235], v[234:235], v[236:237]
	v_pk_add_f32 v[100:101], v[234:235], v[238:239]
	ds_read_b128 v[34:37], v241 offset:6656
	s_waitcnt lgkmcnt(7)
	v_pk_fma_f32 v[102:103], v[38:39], v[6:7], v[102:103] op_sel:[0,0,0] op_sel_hi:[0,1,1] neg_lo:[1,0,0] neg_hi:[1,0,0]
	v_pk_mul_f32 v[234:235], v[38:39], v[54:55] op_sel:[1,0] op_sel_hi:[1,1] neg_lo:[1,0] neg_hi:[1,0]
	v_pk_mul_f32 v[236:237], v[40:41], v[56:57] op_sel:[0,0] op_sel_hi:[0,1] neg_lo:[1,0] neg_hi:[1,0]
	v_pk_mul_f32 v[238:239], v[40:41], v[58:59] op_sel:[1,0] op_sel_hi:[1,1] neg_lo:[1,0] neg_hi:[1,0]
	ds_read_b128 v[38:41], v241 offset:6672
	s_waitcnt lgkmcnt(7)
	v_pk_fma_f32 v[102:103], v[42:43], v[60:61], v[102:103] op_sel:[0,0,0] op_sel_hi:[0,1,1] neg_lo:[1,0,0] neg_hi:[1,0,0]
	v_pk_fma_f32 v[234:235], v[42:43], v[62:63], v[234:235] op_sel:[1,0,0] op_sel_hi:[1,1,1] neg_lo:[1,0,0] neg_hi:[1,0,0]
	v_pk_fma_f32 v[236:237], v[44:45], v[64:65], v[236:237] op_sel:[0,0,0] op_sel_hi:[0,1,1] neg_lo:[1,0,0] neg_hi:[1,0,0]
	v_pk_fma_f32 v[238:239], v[44:45], v[66:67], v[238:239] op_sel:[1,0,0] op_sel_hi:[1,1,1] neg_lo:[1,0,0] neg_hi:[1,0,0]
	ds_read_b128 v[42:45], v241 offset:6688
	s_waitcnt lgkmcnt(7)
	v_pk_fma_f32 v[102:103], v[46:47], v[68:69], v[102:103] op_sel:[0,0,0] op_sel_hi:[0,1,1] neg_lo:[1,0,0] neg_hi:[1,0,0]
	v_pk_fma_f32 v[234:235], v[46:47], v[70:71], v[234:235] op_sel:[1,0,0] op_sel_hi:[1,1,1] neg_lo:[1,0,0] neg_hi:[1,0,0]
	v_pk_fma_f32 v[236:237], v[48:49], v[72:73], v[236:237] op_sel:[0,0,0] op_sel_hi:[0,1,1] neg_lo:[1,0,0] neg_hi:[1,0,0]
	v_pk_fma_f32 v[238:239], v[48:49], v[74:75], v[238:239] op_sel:[1,0,0] op_sel_hi:[1,1,1] neg_lo:[1,0,0] neg_hi:[1,0,0]
	ds_read_b128 v[46:49], v241 offset:6704
	s_waitcnt lgkmcnt(7)
	v_pk_fma_f32 v[102:103], v[50:51], v[76:77], v[102:103] op_sel:[0,0,0] op_sel_hi:[0,1,1] neg_lo:[1,0,0] neg_hi:[1,0,0]
	v_pk_fma_f32 v[234:235], v[50:51], v[78:79], v[234:235] op_sel:[1,0,0] op_sel_hi:[1,1,1] neg_lo:[1,0,0] neg_hi:[1,0,0]
	v_pk_fma_f32 v[236:237], v[52:53], v[80:81], v[236:237] op_sel:[0,0,0] op_sel_hi:[0,1,1] neg_lo:[1,0,0] neg_hi:[1,0,0]
	v_pk_fma_f32 v[238:239], v[52:53], v[82:83], v[238:239] op_sel:[1,0,0] op_sel_hi:[1,1,1] neg_lo:[1,0,0] neg_hi:[1,0,0]
	ds_read_b128 v[50:53], v241 offset:6720
	s_waitcnt lgkmcnt(7)
	v_pk_fma_f32 v[102:103], v[2:3], v[84:85], v[102:103] op_sel:[0,0,0] op_sel_hi:[0,1,1] neg_lo:[1,0,0] neg_hi:[1,0,0]
	v_pk_fma_f32 v[234:235], v[2:3], v[86:87], v[234:235] op_sel:[1,0,0] op_sel_hi:[1,1,1] neg_lo:[1,0,0] neg_hi:[1,0,0]
	v_pk_fma_f32 v[236:237], v[4:5], v[88:89], v[236:237] op_sel:[0,0,0] op_sel_hi:[0,1,1] neg_lo:[1,0,0] neg_hi:[1,0,0]
	v_pk_fma_f32 v[238:239], v[4:5], v[90:91], v[238:239] op_sel:[1,0,0] op_sel_hi:[1,1,1] neg_lo:[1,0,0] neg_hi:[1,0,0]
	ds_read_b128 v[2:5], v241 offset:6736
	s_waitcnt lgkmcnt(7)
	v_pk_fma_f32 v[102:103], v[26:27], v[92:93], v[102:103] op_sel:[0,0,0] op_sel_hi:[0,1,1] neg_lo:[1,0,0] neg_hi:[1,0,0]
	v_pk_fma_f32 v[234:235], v[26:27], v[94:95], v[234:235] op_sel:[1,0,0] op_sel_hi:[1,1,1] neg_lo:[1,0,0] neg_hi:[1,0,0]
	v_pk_fma_f32 v[236:237], v[28:29], v[96:97], v[236:237] op_sel:[0,0,0] op_sel_hi:[0,1,1] neg_lo:[1,0,0] neg_hi:[1,0,0]
	v_pk_fma_f32 v[238:239], v[28:29], v[98:99], v[238:239] op_sel:[1,0,0] op_sel_hi:[1,1,1] neg_lo:[1,0,0] neg_hi:[1,0,0]
	ds_read_b128 v[26:29], v241 offset:6752
	s_waitcnt lgkmcnt(7)
	v_pk_fma_f32 v[102:103], v[30:31], v[100:101], v[102:103] op_sel:[0,0,0] op_sel_hi:[0,1,1] neg_lo:[1,0,0] neg_hi:[1,0,0]
	v_pk_add_f32 v[234:235], v[234:235], v[236:237]
	v_pk_add_f32 v[234:235], v[234:235], v[238:239]
	v_pk_add_f32 v[102:103], v[234:235], v[102:103]
	ds_read_b128 v[30:33], v241 offset:6912
	s_waitcnt lgkmcnt(7)
	v_pk_fma_f32 v[104:105], v[34:35], v[6:7], v[104:105] op_sel:[0,0,0] op_sel_hi:[0,1,1] neg_lo:[1,0,0] neg_hi:[1,0,0]
	v_pk_mul_f32 v[234:235], v[34:35], v[54:55] op_sel:[1,0] op_sel_hi:[1,1] neg_lo:[1,0] neg_hi:[1,0]
	v_pk_mul_f32 v[236:237], v[36:37], v[56:57] op_sel:[0,0] op_sel_hi:[0,1] neg_lo:[1,0] neg_hi:[1,0]
	v_pk_mul_f32 v[238:239], v[36:37], v[58:59] op_sel:[1,0] op_sel_hi:[1,1] neg_lo:[1,0] neg_hi:[1,0]
	ds_read_b128 v[34:37], v241 offset:6928
	s_waitcnt lgkmcnt(7)
	v_pk_fma_f32 v[104:105], v[38:39], v[60:61], v[104:105] op_sel:[0,0,0] op_sel_hi:[0,1,1] neg_lo:[1,0,0] neg_hi:[1,0,0]
	v_pk_fma_f32 v[234:235], v[38:39], v[62:63], v[234:235] op_sel:[1,0,0] op_sel_hi:[1,1,1] neg_lo:[1,0,0] neg_hi:[1,0,0]
	v_pk_fma_f32 v[236:237], v[40:41], v[64:65], v[236:237] op_sel:[0,0,0] op_sel_hi:[0,1,1] neg_lo:[1,0,0] neg_hi:[1,0,0]
	v_pk_fma_f32 v[238:239], v[40:41], v[66:67], v[238:239] op_sel:[1,0,0] op_sel_hi:[1,1,1] neg_lo:[1,0,0] neg_hi:[1,0,0]
	ds_read_b128 v[38:41], v241 offset:6944
	s_waitcnt lgkmcnt(7)
	v_pk_fma_f32 v[104:105], v[42:43], v[68:69], v[104:105] op_sel:[0,0,0] op_sel_hi:[0,1,1] neg_lo:[1,0,0] neg_hi:[1,0,0]
	v_pk_fma_f32 v[234:235], v[42:43], v[70:71], v[234:235] op_sel:[1,0,0] op_sel_hi:[1,1,1] neg_lo:[1,0,0] neg_hi:[1,0,0]
	v_pk_fma_f32 v[236:237], v[44:45], v[72:73], v[236:237] op_sel:[0,0,0] op_sel_hi:[0,1,1] neg_lo:[1,0,0] neg_hi:[1,0,0]
	v_pk_fma_f32 v[238:239], v[44:45], v[74:75], v[238:239] op_sel:[1,0,0] op_sel_hi:[1,1,1] neg_lo:[1,0,0] neg_hi:[1,0,0]
	ds_read_b128 v[42:45], v241 offset:6960
	s_waitcnt lgkmcnt(7)
; template <int DIR>
; __device__ __forceinline__ void dn_solve(const P& p, int task, int m0, int h, int t2, const bf16_t* kn_s, const bf16_t* v_s, const float* gc, const float* be, float* L) {
;     ...
; #pragma unroll
;     for (int cp = 1; cp < 64; ++cp) {
;         float a0 = 0.f, a1 = 0.f, a2 = 0.f, a3 = 0.f;
; #pragma unroll
;         for (int s4 = 0; s4 < cp; s4 += 4) { const f32x4 l4 = *(const f32x4*)(L + cp * 64 + s4); a0 += l4[0] * x[s4]; a1 += l4[1] * x[s4 + 1]; a2 += l4[2] * x[s4 + 2]; a3 += l4[3] * x[s4 + 3]; }
;         x[cp] -= (a0 + a1) + (a2 + a3);
;     }
	v_pk_fma_f32 v[104:105], v[46:47], v[76:77], v[104:105] op_sel:[0,0,0] op_sel_hi:[0,1,1] neg_lo:[1,0,0] neg_hi:[1,0,0]
	v_pk_fma_f32 v[234:235], v[46:47], v[78:79], v[234:235] op_sel:[1,0,0] op_sel_hi:[1,1,1] neg_lo:[1,0,0] neg_hi:[1,0,0]
	v_pk_fma_f32 v[236:237], v[48:49], v[80:81], v[236:237] op_sel:[0,0,0] op_sel_hi:[0,1,1] neg_lo:[1,0,0] neg_hi:[1,0,0]
	v_pk_fma_f32 v[238:239], v[48:49], v[82:83], v[238:239] op_sel:[1,0,0] op_sel_hi:[1,1,1] neg_lo:[1,0,0] neg_hi:[1,0,0]
	ds_read_b128 v[46:49], v241 offset:6976
	s_waitcnt lgkmcnt(7)
	v_pk_fma_f32 v[104:105], v[50:51], v[84:85], v[104:105] op_sel:[0,0,0] op_sel_hi:[0,1,1] neg_lo:[1,0,0] neg_hi:[1,0,0]
	v_pk_fma_f32 v[234:235], v[50:51], v[86:87], v[234:235] op_sel:[1,0,0] op_sel_hi:[1,1,1] neg_lo:[1,0,0] neg_hi:[1,0,0]
	v_pk_fma_f32 v[236:237], v[52:53], v[88:89], v[236:237] op_sel:[0,0,0] op_sel_hi:[0,1,1] neg_lo:[1,0,0] neg_hi:[1,0,0]
	v_pk_fma_f32 v[238:239], v[52:53], v[90:91], v[238:239] op_sel:[1,0,0] op_sel_hi:[1,1,1] neg_lo:[1,0,0] neg_hi:[1,0,0]
	ds_read_b128 v[50:53], v241 offset:6992
	s_waitcnt lgkmcnt(7)
	v_pk_fma_f32 v[104:105], v[2:3], v[92:93], v[104:105] op_sel:[0,0,0] op_sel_hi:[0,1,1] neg_lo:[1,0,0] neg_hi:[1,0,0]
	v_pk_fma_f32 v[234:235], v[2:3], v[94:95], v[234:235] op_sel:[1,0,0] op_sel_hi:[1,1,1] neg_lo:[1,0,0] neg_hi:[1,0,0]
	v_pk_fma_f32 v[236:237], v[4:5], v[96:97], v[236:237] op_sel:[0,0,0] op_sel_hi:[0,1,1] neg_lo:[1,0,0] neg_hi:[1,0,0]
	v_pk_fma_f32 v[238:239], v[4:5], v[98:99], v[238:239] op_sel:[1,0,0] op_sel_hi:[1,1,1] neg_lo:[1,0,0] neg_hi:[1,0,0]
	ds_read_b128 v[2:5], v241 offset:7008
	s_waitcnt lgkmcnt(7)
	v_pk_fma_f32 v[104:105], v[26:27], v[100:101], v[104:105] op_sel:[0,0,0] op_sel_hi:[0,1,1] neg_lo:[1,0,0] neg_hi:[1,0,0]
	v_pk_fma_f32 v[234:235], v[26:27], v[102:103], v[234:235] op_sel:[1,0,0] op_sel_hi:[1,1,1] neg_lo:[1,0,0] neg_hi:[1,0,0]
	v_pk_add_f32 v[236:237], v[104:105], v[236:237]
	v_pk_add_f32 v[236:237], v[236:237], v[238:239]
	v_pk_add_f32 v[104:105], v[236:237], v[234:235]
	ds_read_b128 v[26:29], v241 offset:7168
	s_waitcnt lgkmcnt(7)
	v_pk_fma_f32 v[106:107], v[30:31], v[6:7], v[106:107] op_sel:[0,0,0] op_sel_hi:[0,1,1] neg_lo:[1,0,0] neg_hi:[1,0,0]
	v_pk_mul_f32 v[234:235], v[30:31], v[54:55] op_sel:[1,0] op_sel_hi:[1,1] neg_lo:[1,0] neg_hi:[1,0]
	v_pk_mul_f32 v[236:237], v[32:33], v[56:57] op_sel:[0,0] op_sel_hi:[0,1] neg_lo:[1,0] neg_hi:[1,0]
	v_pk_mul_f32 v[238:239], v[32:33], v[58:59] op_sel:[1,0] op_sel_hi:[1,1] neg_lo:[1,0] neg_hi:[1,0]
	ds_read_b128 v[30:33], v241 offset:7184
	s_waitcnt lgkmcnt(7)
	v_pk_fma_f32 v[106:107], v[34:35], v[60:61], v[106:107] op_sel:[0,0,0] op_sel_hi:[0,1,1] neg_lo:[1,0,0] neg_hi:[1,0,0]
	v_pk_fma_f32 v[234:235], v[34:35], v[62:63], v[234:235] op_sel:[1,0,0] op_sel_hi:[1,1,1] neg_lo:[1,0,0] neg_hi:[1,0,0]
	v_pk_fma_f32 v[236:237], v[36:37], v[64:65], v[236:237] op_sel:[0,0,0] op_sel_hi:[0,1,1] neg_lo:[1,0,0] neg_hi:[1,0,0]
	v_pk_fma_f32 v[238:239], v[36:37], v[66:67], v[238:239] op_sel:[1,0,0] op_sel_hi:[1,1,1] neg_lo:[1,0,0] neg_hi:[1,0,0]
	ds_read_b128 v[34:37], v241 offset:7200
	s_waitcnt lgkmcnt(7)
	v_pk_fma_f32 v[106:107], v[38:39], v[68:69], v[106:107] op_sel:[0,0,0] op_sel_hi:[0,1,1] neg_lo:[1,0,0] neg_hi:[1,0,0]
	v_pk_fma_f32 v[234:235], v[38:39], v[70:71], v[234:235] op_sel:[1,0,0] op_sel_hi:[1,1,1] neg_lo:[1,0,0] neg_hi:[1,0,0]
	v_pk_fma_f32 v[236:237], v[40:41], v[72:73], v[236:237] op_sel:[0,0,0] op_sel_hi:[0,1,1] neg_lo:[1,0,0] neg_hi:[1,0,0]
	v_pk_fma_f32 v[238:239], v[40:41], v[74:75], v[238:239] op_sel:[1,0,0] op_sel_hi:[1,1,1] neg_lo:[1,0,0] neg_hi:[1,0,0]
	ds_read_b128 v[38:41], v241 offset:7216
	s_waitcnt lgkmcnt(7)
	v_pk_fma_f32 v[106:107], v[42:43], v[76:77], v[106:107] op_sel:[0,0,0] op_sel_hi:[0,1,1] neg_lo:[1,0,0] neg_hi:[1,0,0]
	v_pk_fma_f32 v[234:235], v[42:43], v[78:79], v[234:235] op_sel:[1,0,0] op_sel_hi:[1,1,1] neg_lo:[1,0,0] neg_hi:[1,0,0]
	v_pk_fma_f32 v[236:237], v[44:45], v[80:81], v[236:237] op_sel:[0,0,0] op_sel_hi:[0,1,1] neg_lo:[1,0,0] neg_hi:[1,0,0]
	v_pk_fma_f32 v[238:239], v[44:45], v[82:83], v[238:239] op_sel:[1,0,0] op_sel_hi:[1,1,1] neg_lo:[1,0,0] neg_hi:[1,0,0]
	ds_read_b128 v[42:45], v241 offset:7232
	s_waitcnt lgkmcnt(7)
	v_pk_fma_f32 v[106:107], v[46:47], v[84:85], v[106:107] op_sel:[0,0,0] op_sel_hi:[0,1,1] neg_lo:[1,0,0] neg_hi:[1,0,0]
	v_pk_fma_f32 v[234:235], v[46:47], v[86:87], v[234:235] op_sel:[1,0,0] op_sel_hi:[1,1,1] neg_lo:[1,0,0] neg_hi:[1,0,0]
	v_pk_fma_f32 v[236:237], v[48:49], v[88:89], v[236:237] op_sel:[0,0,0] op_sel_hi:[0,1,1] neg_lo:[1,0,0] neg_hi:[1,0,0]
	v_pk_fma_f32 v[238:239], v[48:49], v[90:91], v[238:239] op_sel:[1,0,0] op_sel_hi:[1,1,1] neg_lo:[1,0,0] neg_hi:[1,0,0]
	ds_read_b128 v[46:49], v241 offset:7248
	s_waitcnt lgkmcnt(7)
	v_pk_fma_f32 v[106:107], v[50:51], v[92:93], v[106:107] op_sel:[0,0,0] op_sel_hi:[0,1,1] neg_lo:[1,0,0] neg_hi:[1,0,0]
	v_pk_fma_f32 v[234:235], v[50:51], v[94:95], v[234:235] op_sel:[1,0,0] op_sel_hi:[1,1,1] neg_lo:[1,0,0] neg_hi:[1,0,0]
	v_pk_fma_f32 v[236:237], v[52:53], v[96:97], v[236:237] op_sel:[0,0,0] op_sel_hi:[0,1,1] neg_lo:[1,0,0] neg_hi:[1,0,0]
	v_pk_fma_f32 v[238:239], v[52:53], v[98:99], v[238:239] op_sel:[1,0,0] op_sel_hi:[1,1,1] neg_lo:[1,0,0] neg_hi:[1,0,0]
	ds_read_b128 v[50:53], v241 offset:7264
	s_waitcnt lgkmcnt(7)
	v_pk_fma_f32 v[106:107], v[2:3], v[100:101], v[106:107] op_sel:[0,0,0] op_sel_hi:[0,1,1] neg_lo:[1,0,0] neg_hi:[1,0,0]
	v_pk_fma_f32 v[234:235], v[2:3], v[102:103], v[234:235] op_sel:[1,0,0] op_sel_hi:[1,1,1] neg_lo:[1,0,0] neg_hi:[1,0,0]
	v_pk_fma_f32 v[236:237], v[4:5], v[104:105], v[236:237] op_sel:[0,0,0] op_sel_hi:[0,1,1] neg_lo:[1,0,0] neg_hi:[1,0,0]
	v_pk_add_f32 v[234:235], v[106:107], v[234:235]
	v_pk_add_f32 v[234:235], v[234:235], v[238:239]
	v_pk_add_f32 v[106:107], v[234:235], v[236:237]
	ds_read_b128 v[2:5], v241 offset:7424
	s_waitcnt lgkmcnt(7)
; template <int DIR>
; __device__ __forceinline__ void dn_solve(const P& p, int task, int m0, int h, int t2, const bf16_t* kn_s, const bf16_t* v_s, const float* gc, const float* be, float* L) {
;     ...
; #pragma unroll
;     for (int cp = 1; cp < 64; ++cp) {
;         float a0 = 0.f, a1 = 0.f, a2 = 0.f, a3 = 0.f;
; #pragma unroll
;         for (int s4 = 0; s4 < cp; s4 += 4) { const f32x4 l4 = *(const f32x4*)(L + cp * 64 + s4); a0 += l4[0] * x[s4]; a1 += l4[1] * x[s4 + 1]; a2 += l4[2] * x[s4 + 2]; a3 += l4[3] * x[s4 + 3]; }
;         x[cp] -= (a0 + a1) + (a2 + a3);
;     }
	v_pk_fma_f32 v[108:109], v[26:27], v[6:7], v[108:109] op_sel:[0,0,0] op_sel_hi:[0,1,1] neg_lo:[1,0,0] neg_hi:[1,0,0]
	v_pk_mul_f32 v[234:235], v[26:27], v[54:55] op_sel:[1,0] op_sel_hi:[1,1] neg_lo:[1,0] neg_hi:[1,0]
	v_pk_mul_f32 v[236:237], v[28:29], v[56:57] op_sel:[0,0] op_sel_hi:[0,1] neg_lo:[1,0] neg_hi:[1,0]
	v_pk_mul_f32 v[238:239], v[28:29], v[58:59] op_sel:[1,0] op_sel_hi:[1,1] neg_lo:[1,0] neg_hi:[1,0]
	ds_read_b128 v[26:29], v241 offset:7440
	s_waitcnt lgkmcnt(7)
	v_pk_fma_f32 v[108:109], v[30:31], v[60:61], v[108:109] op_sel:[0,0,0] op_sel_hi:[0,1,1] neg_lo:[1,0,0] neg_hi:[1,0,0]
	v_pk_fma_f32 v[234:235], v[30:31], v[62:63], v[234:235] op_sel:[1,0,0] op_sel_hi:[1,1,1] neg_lo:[1,0,0] neg_hi:[1,0,0]
	v_pk_fma_f32 v[236:237], v[32:33], v[64:65], v[236:237] op_sel:[0,0,0] op_sel_hi:[0,1,1] neg_lo:[1,0,0] neg_hi:[1,0,0]
	v_pk_fma_f32 v[238:239], v[32:33], v[66:67], v[238:239] op_sel:[1,0,0] op_sel_hi:[1,1,1] neg_lo:[1,0,0] neg_hi:[1,0,0]
	ds_read_b128 v[30:33], v241 offset:7456
	s_waitcnt lgkmcnt(7)
	v_pk_fma_f32 v[108:109], v[34:35], v[68:69], v[108:109] op_sel:[0,0,0] op_sel_hi:[0,1,1] neg_lo:[1,0,0] neg_hi:[1,0,0]
	v_pk_fma_f32 v[234:235], v[34:35], v[70:71], v[234:235] op_sel:[1,0,0] op_sel_hi:[1,1,1] neg_lo:[1,0,0] neg_hi:[1,0,0]
	v_pk_fma_f32 v[236:237], v[36:37], v[72:73], v[236:237] op_sel:[0,0,0] op_sel_hi:[0,1,1] neg_lo:[1,0,0] neg_hi:[1,0,0]
	v_pk_fma_f32 v[238:239], v[36:37], v[74:75], v[238:239] op_sel:[1,0,0] op_sel_hi:[1,1,1] neg_lo:[1,0,0] neg_hi:[1,0,0]
	ds_read_b128 v[34:37], v241 offset:7472
	s_waitcnt lgkmcnt(7)
	v_pk_fma_f32 v[108:109], v[38:39], v[76:77], v[108:109] op_sel:[0,0,0] op_sel_hi:[0,1,1] neg_lo:[1,0,0] neg_hi:[1,0,0]
	v_pk_fma_f32 v[234:235], v[38:39], v[78:79], v[234:235] op_sel:[1,0,0] op_sel_hi:[1,1,1] neg_lo:[1,0,0] neg_hi:[1,0,0]
	v_pk_fma_f32 v[236:237], v[40:41], v[80:81], v[236:237] op_sel:[0,0,0] op_sel_hi:[0,1,1] neg_lo:[1,0,0] neg_hi:[1,0,0]
	v_pk_fma_f32 v[238:239], v[40:41], v[82:83], v[238:239] op_sel:[1,0,0] op_sel_hi:[1,1,1] neg_lo:[1,0,0] neg_hi:[1,0,0]
	ds_read_b128 v[38:41], v241 offset:7488
	s_waitcnt lgkmcnt(7)
	v_pk_fma_f32 v[108:109], v[42:43], v[84:85], v[108:109] op_sel:[0,0,0] op_sel_hi:[0,1,1] neg_lo:[1,0,0] neg_hi:[1,0,0]
	v_pk_fma_f32 v[234:235], v[42:43], v[86:87], v[234:235] op_sel:[1,0,0] op_sel_hi:[1,1,1] neg_lo:[1,0,0] neg_hi:[1,0,0]
	v_pk_fma_f32 v[236:237], v[44:45], v[88:89], v[236:237] op_sel:[0,0,0] op_sel_hi:[0,1,1] neg_lo:[1,0,0] neg_hi:[1,0,0]
	v_pk_fma_f32 v[238:239], v[44:45], v[90:91], v[238:239] op_sel:[1,0,0] op_sel_hi:[1,1,1] neg_lo:[1,0,0] neg_hi:[1,0,0]
	ds_read_b128 v[42:45], v241 offset:7504
	s_waitcnt lgkmcnt(7)
	v_pk_fma_f32 v[108:109], v[46:47], v[92:93], v[108:109] op_sel:[0,0,0] op_sel_hi:[0,1,1] neg_lo:[1,0,0] neg_hi:[1,0,0]
	v_pk_fma_f32 v[234:235], v[46:47], v[94:95], v[234:235] op_sel:[1,0,0] op_sel_hi:[1,1,1] neg_lo:[1,0,0] neg_hi:[1,0,0]
	v_pk_fma_f32 v[236:237], v[48:49], v[96:97], v[236:237] op_sel:[0,0,0] op_sel_hi:[0,1,1] neg_lo:[1,0,0] neg_hi:[1,0,0]
	v_pk_fma_f32 v[238:239], v[48:49], v[98:99], v[238:239] op_sel:[1,0,0] op_sel_hi:[1,1,1] neg_lo:[1,0,0] neg_hi:[1,0,0]
	ds_read_b128 v[46:49], v241 offset:7520
	s_waitcnt lgkmcnt(7)
	v_pk_fma_f32 v[108:109], v[50:51], v[100:101], v[108:109] op_sel:[0,0,0] op_sel_hi:[0,1,1] neg_lo:[1,0,0] neg_hi:[1,0,0]
	v_pk_fma_f32 v[234:235], v[50:51], v[102:103], v[234:235] op_sel:[1,0,0] op_sel_hi:[1,1,1] neg_lo:[1,0,0] neg_hi:[1,0,0]
	v_pk_fma_f32 v[236:237], v[52:53], v[104:105], v[236:237] op_sel:[0,0,0] op_sel_hi:[0,1,1] neg_lo:[1,0,0] neg_hi:[1,0,0]
	v_pk_fma_f32 v[238:239], v[52:53], v[106:107], v[238:239] op_sel:[1,0,0] op_sel_hi:[1,1,1] neg_lo:[1,0,0] neg_hi:[1,0,0]
	v_pk_add_f32 v[234:235], v[108:109], v[234:235]
	v_pk_add_f32 v[234:235], v[234:235], v[236:237]
	v_pk_add_f32 v[108:109], v[234:235], v[238:239]
	ds_read_b128 v[50:53], v241 offset:7536
	s_waitcnt lgkmcnt(7)
	v_pk_fma_f32 v[110:111], v[2:3], v[6:7], v[110:111] op_sel:[0,0,0] op_sel_hi:[0,1,1] neg_lo:[1,0,0] neg_hi:[1,0,0]
	v_pk_mul_f32 v[234:235], v[2:3], v[54:55] op_sel:[1,0] op_sel_hi:[1,1] neg_lo:[1,0] neg_hi:[1,0]
	v_pk_mul_f32 v[236:237], v[4:5], v[56:57] op_sel:[0,0] op_sel_hi:[0,1] neg_lo:[1,0] neg_hi:[1,0]
	v_pk_mul_f32 v[238:239], v[4:5], v[58:59] op_sel:[1,0] op_sel_hi:[1,1] neg_lo:[1,0] neg_hi:[1,0]
	ds_read_b128 v[2:5], v241 offset:7680
	s_waitcnt lgkmcnt(7)
	v_pk_fma_f32 v[110:111], v[26:27], v[60:61], v[110:111] op_sel:[0,0,0] op_sel_hi:[0,1,1] neg_lo:[1,0,0] neg_hi:[1,0,0]
	v_pk_fma_f32 v[234:235], v[26:27], v[62:63], v[234:235] op_sel:[1,0,0] op_sel_hi:[1,1,1] neg_lo:[1,0,0] neg_hi:[1,0,0]
	v_pk_fma_f32 v[236:237], v[28:29], v[64:65], v[236:237] op_sel:[0,0,0] op_sel_hi:[0,1,1] neg_lo:[1,0,0] neg_hi:[1,0,0]
	v_pk_fma_f32 v[238:239], v[28:29], v[66:67], v[238:239] op_sel:[1,0,0] op_sel_hi:[1,1,1] neg_lo:[1,0,0] neg_hi:[1,0,0]
	ds_read_b128 v[26:29], v241 offset:7696
	s_waitcnt lgkmcnt(7)
	v_pk_fma_f32 v[110:111], v[30:31], v[68:69], v[110:111] op_sel:[0,0,0] op_sel_hi:[0,1,1] neg_lo:[1,0,0] neg_hi:[1,0,0]
	v_pk_fma_f32 v[234:235], v[30:31], v[70:71], v[234:235] op_sel:[1,0,0] op_sel_hi:[1,1,1] neg_lo:[1,0,0] neg_hi:[1,0,0]
	v_pk_fma_f32 v[236:237], v[32:33], v[72:73], v[236:237] op_sel:[0,0,0] op_sel_hi:[0,1,1] neg_lo:[1,0,0] neg_hi:[1,0,0]
	v_pk_fma_f32 v[238:239], v[32:33], v[74:75], v[238:239] op_sel:[1,0,0] op_sel_hi:[1,1,1] neg_lo:[1,0,0] neg_hi:[1,0,0]
	ds_read_b128 v[30:33], v241 offset:7712
	s_waitcnt lgkmcnt(7)
; template <int DIR>
; __device__ __forceinline__ void dn_solve(const P& p, int task, int m0, int h, int t2, const bf16_t* kn_s, const bf16_t* v_s, const float* gc, const float* be, float* L) {
;     ...
; #pragma unroll
;     for (int cp = 1; cp < 64; ++cp) {
;         float a0 = 0.f, a1 = 0.f, a2 = 0.f, a3 = 0.f;
; #pragma unroll
;         for (int s4 = 0; s4 < cp; s4 += 4) { const f32x4 l4 = *(const f32x4*)(L + cp * 64 + s4); a0 += l4[0] * x[s4]; a1 += l4[1] * x[s4 + 1]; a2 += l4[2] * x[s4 + 2]; a3 += l4[3] * x[s4 + 3]; }
;         x[cp] -= (a0 + a1) + (a2 + a3);
;     }
	v_pk_fma_f32 v[110:111], v[34:35], v[76:77], v[110:111] op_sel:[0,0,0] op_sel_hi:[0,1,1] neg_lo:[1,0,0] neg_hi:[1,0,0]
	v_pk_fma_f32 v[234:235], v[34:35], v[78:79], v[234:235] op_sel:[1,0,0] op_sel_hi:[1,1,1] neg_lo:[1,0,0] neg_hi:[1,0,0]
	v_pk_fma_f32 v[236:237], v[36:37], v[80:81], v[236:237] op_sel:[0,0,0] op_sel_hi:[0,1,1] neg_lo:[1,0,0] neg_hi:[1,0,0]
	v_pk_fma_f32 v[238:239], v[36:37], v[82:83], v[238:239] op_sel:[1,0,0] op_sel_hi:[1,1,1] neg_lo:[1,0,0] neg_hi:[1,0,0]
	ds_read_b128 v[34:37], v241 offset:7728
	s_waitcnt lgkmcnt(7)
	v_pk_fma_f32 v[110:111], v[38:39], v[84:85], v[110:111] op_sel:[0,0,0] op_sel_hi:[0,1,1] neg_lo:[1,0,0] neg_hi:[1,0,0]
	v_pk_fma_f32 v[234:235], v[38:39], v[86:87], v[234:235] op_sel:[1,0,0] op_sel_hi:[1,1,1] neg_lo:[1,0,0] neg_hi:[1,0,0]
	v_pk_fma_f32 v[236:237], v[40:41], v[88:89], v[236:237] op_sel:[0,0,0] op_sel_hi:[0,1,1] neg_lo:[1,0,0] neg_hi:[1,0,0]
	v_pk_fma_f32 v[238:239], v[40:41], v[90:91], v[238:239] op_sel:[1,0,0] op_sel_hi:[1,1,1] neg_lo:[1,0,0] neg_hi:[1,0,0]
	ds_read_b128 v[38:41], v241 offset:7744
	s_waitcnt lgkmcnt(7)
	v_pk_fma_f32 v[110:111], v[42:43], v[92:93], v[110:111] op_sel:[0,0,0] op_sel_hi:[0,1,1] neg_lo:[1,0,0] neg_hi:[1,0,0]
	v_pk_fma_f32 v[234:235], v[42:43], v[94:95], v[234:235] op_sel:[1,0,0] op_sel_hi:[1,1,1] neg_lo:[1,0,0] neg_hi:[1,0,0]
	v_pk_fma_f32 v[236:237], v[44:45], v[96:97], v[236:237] op_sel:[0,0,0] op_sel_hi:[0,1,1] neg_lo:[1,0,0] neg_hi:[1,0,0]
	v_pk_fma_f32 v[238:239], v[44:45], v[98:99], v[238:239] op_sel:[1,0,0] op_sel_hi:[1,1,1] neg_lo:[1,0,0] neg_hi:[1,0,0]
	ds_read_b128 v[42:45], v241 offset:7760
	s_waitcnt lgkmcnt(7)
	v_pk_fma_f32 v[110:111], v[46:47], v[100:101], v[110:111] op_sel:[0,0,0] op_sel_hi:[0,1,1] neg_lo:[1,0,0] neg_hi:[1,0,0]
	v_pk_fma_f32 v[234:235], v[46:47], v[102:103], v[234:235] op_sel:[1,0,0] op_sel_hi:[1,1,1] neg_lo:[1,0,0] neg_hi:[1,0,0]
	v_pk_fma_f32 v[236:237], v[48:49], v[104:105], v[236:237] op_sel:[0,0,0] op_sel_hi:[0,1,1] neg_lo:[1,0,0] neg_hi:[1,0,0]
	v_pk_fma_f32 v[238:239], v[48:49], v[106:107], v[238:239] op_sel:[1,0,0] op_sel_hi:[1,1,1] neg_lo:[1,0,0] neg_hi:[1,0,0]
	ds_read_b128 v[46:49], v241 offset:7776
	s_waitcnt lgkmcnt(7)
	v_pk_fma_f32 v[110:111], v[50:51], v[108:109], v[110:111] op_sel:[0,0,0] op_sel_hi:[0,1,1] neg_lo:[1,0,0] neg_hi:[1,0,0]
	v_pk_add_f32 v[234:235], v[234:235], v[236:237]
	v_pk_add_f32 v[234:235], v[234:235], v[238:239]
	v_pk_add_f32 v[110:111], v[234:235], v[110:111]
	ds_read_b128 v[50:53], v241 offset:7792
	s_waitcnt lgkmcnt(7)
	v_pk_fma_f32 v[112:113], v[2:3], v[6:7], v[112:113] op_sel:[0,0,0] op_sel_hi:[0,1,1] neg_lo:[1,0,0] neg_hi:[1,0,0]
	v_pk_mul_f32 v[234:235], v[2:3], v[54:55] op_sel:[1,0] op_sel_hi:[1,1] neg_lo:[1,0] neg_hi:[1,0]
	v_pk_mul_f32 v[236:237], v[4:5], v[56:57] op_sel:[0,0] op_sel_hi:[0,1] neg_lo:[1,0] neg_hi:[1,0]
	v_pk_mul_f32 v[238:239], v[4:5], v[58:59] op_sel:[1,0] op_sel_hi:[1,1] neg_lo:[1,0] neg_hi:[1,0]
	ds_read_b128 v[2:5], v241 offset:7936
	s_waitcnt lgkmcnt(7)
	v_pk_fma_f32 v[112:113], v[26:27], v[60:61], v[112:113] op_sel:[0,0,0] op_sel_hi:[0,1,1] neg_lo:[1,0,0] neg_hi:[1,0,0]
	v_pk_fma_f32 v[234:235], v[26:27], v[62:63], v[234:235] op_sel:[1,0,0] op_sel_hi:[1,1,1] neg_lo:[1,0,0] neg_hi:[1,0,0]
	v_pk_fma_f32 v[236:237], v[28:29], v[64:65], v[236:237] op_sel:[0,0,0] op_sel_hi:[0,1,1] neg_lo:[1,0,0] neg_hi:[1,0,0]
	v_pk_fma_f32 v[238:239], v[28:29], v[66:67], v[238:239] op_sel:[1,0,0] op_sel_hi:[1,1,1] neg_lo:[1,0,0] neg_hi:[1,0,0]
	ds_read_b128 v[26:29], v241 offset:7952
	s_waitcnt lgkmcnt(7)
	v_pk_fma_f32 v[112:113], v[30:31], v[68:69], v[112:113] op_sel:[0,0,0] op_sel_hi:[0,1,1] neg_lo:[1,0,0] neg_hi:[1,0,0]
	v_pk_fma_f32 v[234:235], v[30:31], v[70:71], v[234:235] op_sel:[1,0,0] op_sel_hi:[1,1,1] neg_lo:[1,0,0] neg_hi:[1,0,0]
	v_pk_fma_f32 v[236:237], v[32:33], v[72:73], v[236:237] op_sel:[0,0,0] op_sel_hi:[0,1,1] neg_lo:[1,0,0] neg_hi:[1,0,0]
	v_pk_fma_f32 v[238:239], v[32:33], v[74:75], v[238:239] op_sel:[1,0,0] op_sel_hi:[1,1,1] neg_lo:[1,0,0] neg_hi:[1,0,0]
	ds_read_b128 v[30:33], v241 offset:7968
	s_waitcnt lgkmcnt(7)
	v_pk_fma_f32 v[112:113], v[34:35], v[76:77], v[112:113] op_sel:[0,0,0] op_sel_hi:[0,1,1] neg_lo:[1,0,0] neg_hi:[1,0,0]
	v_pk_fma_f32 v[234:235], v[34:35], v[78:79], v[234:235] op_sel:[1,0,0] op_sel_hi:[1,1,1] neg_lo:[1,0,0] neg_hi:[1,0,0]
	v_pk_fma_f32 v[236:237], v[36:37], v[80:81], v[236:237] op_sel:[0,0,0] op_sel_hi:[0,1,1] neg_lo:[1,0,0] neg_hi:[1,0,0]
	v_pk_fma_f32 v[238:239], v[36:37], v[82:83], v[238:239] op_sel:[1,0,0] op_sel_hi:[1,1,1] neg_lo:[1,0,0] neg_hi:[1,0,0]
	ds_read_b128 v[34:37], v241 offset:7984
	s_waitcnt lgkmcnt(7)
	v_pk_fma_f32 v[112:113], v[38:39], v[84:85], v[112:113] op_sel:[0,0,0] op_sel_hi:[0,1,1] neg_lo:[1,0,0] neg_hi:[1,0,0]
	v_pk_fma_f32 v[234:235], v[38:39], v[86:87], v[234:235] op_sel:[1,0,0] op_sel_hi:[1,1,1] neg_lo:[1,0,0] neg_hi:[1,0,0]
	v_pk_fma_f32 v[236:237], v[40:41], v[88:89], v[236:237] op_sel:[0,0,0] op_sel_hi:[0,1,1] neg_lo:[1,0,0] neg_hi:[1,0,0]
	v_pk_fma_f32 v[238:239], v[40:41], v[90:91], v[238:239] op_sel:[1,0,0] op_sel_hi:[1,1,1] neg_lo:[1,0,0] neg_hi:[1,0,0]
	ds_read_b128 v[38:41], v241 offset:8000
	s_waitcnt lgkmcnt(7)
	v_pk_fma_f32 v[112:113], v[42:43], v[92:93], v[112:113] op_sel:[0,0,0] op_sel_hi:[0,1,1] neg_lo:[1,0,0] neg_hi:[1,0,0]
	v_pk_fma_f32 v[234:235], v[42:43], v[94:95], v[234:235] op_sel:[1,0,0] op_sel_hi:[1,1,1] neg_lo:[1,0,0] neg_hi:[1,0,0]
	v_pk_fma_f32 v[236:237], v[44:45], v[96:97], v[236:237] op_sel:[0,0,0] op_sel_hi:[0,1,1] neg_lo:[1,0,0] neg_hi:[1,0,0]
	v_pk_fma_f32 v[238:239], v[44:45], v[98:99], v[238:239] op_sel:[1,0,0] op_sel_hi:[1,1,1] neg_lo:[1,0,0] neg_hi:[1,0,0]
	ds_read_b128 v[42:45], v241 offset:8016
	s_waitcnt lgkmcnt(7)
; template <int DIR>
; __device__ __forceinline__ void dn_solve(const P& p, int task, int m0, int h, int t2, const bf16_t* kn_s, const bf16_t* v_s, const float* gc, const float* be, float* L) {
;     ...
; #pragma unroll
;     for (int cp = 1; cp < 64; ++cp) {
;         float a0 = 0.f, a1 = 0.f, a2 = 0.f, a3 = 0.f;
; #pragma unroll
;         for (int s4 = 0; s4 < cp; s4 += 4) { const f32x4 l4 = *(const f32x4*)(L + cp * 64 + s4); a0 += l4[0] * x[s4]; a1 += l4[1] * x[s4 + 1]; a2 += l4[2] * x[s4 + 2]; a3 += l4[3] * x[s4 + 3]; }
;         x[cp] -= (a0 + a1) + (a2 + a3);
;     }
	v_pk_fma_f32 v[112:113], v[46:47], v[100:101], v[112:113] op_sel:[0,0,0] op_sel_hi:[0,1,1] neg_lo:[1,0,0] neg_hi:[1,0,0]
	v_pk_fma_f32 v[234:235], v[46:47], v[102:103], v[234:235] op_sel:[1,0,0] op_sel_hi:[1,1,1] neg_lo:[1,0,0] neg_hi:[1,0,0]
	v_pk_fma_f32 v[236:237], v[48:49], v[104:105], v[236:237] op_sel:[0,0,0] op_sel_hi:[0,1,1] neg_lo:[1,0,0] neg_hi:[1,0,0]
	v_pk_fma_f32 v[238:239], v[48:49], v[106:107], v[238:239] op_sel:[1,0,0] op_sel_hi:[1,1,1] neg_lo:[1,0,0] neg_hi:[1,0,0]
	ds_read_b128 v[46:49], v241 offset:8032
	s_waitcnt lgkmcnt(7)
	v_pk_fma_f32 v[112:113], v[50:51], v[108:109], v[112:113] op_sel:[0,0,0] op_sel_hi:[0,1,1] neg_lo:[1,0,0] neg_hi:[1,0,0]
	v_pk_fma_f32 v[234:235], v[50:51], v[110:111], v[234:235] op_sel:[1,0,0] op_sel_hi:[1,1,1] neg_lo:[1,0,0] neg_hi:[1,0,0]
	v_pk_add_f32 v[236:237], v[112:113], v[236:237]
	v_pk_add_f32 v[236:237], v[236:237], v[238:239]
	v_pk_add_f32 v[112:113], v[236:237], v[234:235]
	ds_read_b128 v[50:53], v241 offset:8048
	s_waitcnt lgkmcnt(7)
	v_pk_fma_f32 v[114:115], v[2:3], v[6:7], v[114:115] op_sel:[0,0,0] op_sel_hi:[0,1,1] neg_lo:[1,0,0] neg_hi:[1,0,0]
	v_pk_mul_f32 v[234:235], v[2:3], v[54:55] op_sel:[1,0] op_sel_hi:[1,1] neg_lo:[1,0] neg_hi:[1,0]
	v_pk_mul_f32 v[236:237], v[4:5], v[56:57] op_sel:[0,0] op_sel_hi:[0,1] neg_lo:[1,0] neg_hi:[1,0]
	v_pk_mul_f32 v[238:239], v[4:5], v[58:59] op_sel:[1,0] op_sel_hi:[1,1] neg_lo:[1,0] neg_hi:[1,0]
	ds_read_b128 v[2:5], v241 offset:8192
	s_waitcnt lgkmcnt(7)
	v_pk_fma_f32 v[114:115], v[26:27], v[60:61], v[114:115] op_sel:[0,0,0] op_sel_hi:[0,1,1] neg_lo:[1,0,0] neg_hi:[1,0,0]
	v_pk_fma_f32 v[234:235], v[26:27], v[62:63], v[234:235] op_sel:[1,0,0] op_sel_hi:[1,1,1] neg_lo:[1,0,0] neg_hi:[1,0,0]
	v_pk_fma_f32 v[236:237], v[28:29], v[64:65], v[236:237] op_sel:[0,0,0] op_sel_hi:[0,1,1] neg_lo:[1,0,0] neg_hi:[1,0,0]
	v_pk_fma_f32 v[238:239], v[28:29], v[66:67], v[238:239] op_sel:[1,0,0] op_sel_hi:[1,1,1] neg_lo:[1,0,0] neg_hi:[1,0,0]
	ds_read_b128 v[26:29], v241 offset:8208
	s_waitcnt lgkmcnt(7)
	v_pk_fma_f32 v[114:115], v[30:31], v[68:69], v[114:115] op_sel:[0,0,0] op_sel_hi:[0,1,1] neg_lo:[1,0,0] neg_hi:[1,0,0]
	v_pk_fma_f32 v[234:235], v[30:31], v[70:71], v[234:235] op_sel:[1,0,0] op_sel_hi:[1,1,1] neg_lo:[1,0,0] neg_hi:[1,0,0]
	v_pk_fma_f32 v[236:237], v[32:33], v[72:73], v[236:237] op_sel:[0,0,0] op_sel_hi:[0,1,1] neg_lo:[1,0,0] neg_hi:[1,0,0]
	v_pk_fma_f32 v[238:239], v[32:33], v[74:75], v[238:239] op_sel:[1,0,0] op_sel_hi:[1,1,1] neg_lo:[1,0,0] neg_hi:[1,0,0]
	ds_read_b128 v[30:33], v241 offset:8224
	s_waitcnt lgkmcnt(7)
	v_pk_fma_f32 v[114:115], v[34:35], v[76:77], v[114:115] op_sel:[0,0,0] op_sel_hi:[0,1,1] neg_lo:[1,0,0] neg_hi:[1,0,0]
	v_pk_fma_f32 v[234:235], v[34:35], v[78:79], v[234:235] op_sel:[1,0,0] op_sel_hi:[1,1,1] neg_lo:[1,0,0] neg_hi:[1,0,0]
	v_pk_fma_f32 v[236:237], v[36:37], v[80:81], v[236:237] op_sel:[0,0,0] op_sel_hi:[0,1,1] neg_lo:[1,0,0] neg_hi:[1,0,0]
	v_pk_fma_f32 v[238:239], v[36:37], v[82:83], v[238:239] op_sel:[1,0,0] op_sel_hi:[1,1,1] neg_lo:[1,0,0] neg_hi:[1,0,0]
	ds_read_b128 v[34:37], v241 offset:8240
	s_waitcnt lgkmcnt(7)
	v_pk_fma_f32 v[114:115], v[38:39], v[84:85], v[114:115] op_sel:[0,0,0] op_sel_hi:[0,1,1] neg_lo:[1,0,0] neg_hi:[1,0,0]
	v_pk_fma_f32 v[234:235], v[38:39], v[86:87], v[234:235] op_sel:[1,0,0] op_sel_hi:[1,1,1] neg_lo:[1,0,0] neg_hi:[1,0,0]
	v_pk_fma_f32 v[236:237], v[40:41], v[88:89], v[236:237] op_sel:[0,0,0] op_sel_hi:[0,1,1] neg_lo:[1,0,0] neg_hi:[1,0,0]
	v_pk_fma_f32 v[238:239], v[40:41], v[90:91], v[238:239] op_sel:[1,0,0] op_sel_hi:[1,1,1] neg_lo:[1,0,0] neg_hi:[1,0,0]
	ds_read_b128 v[38:41], v241 offset:8256
	s_waitcnt lgkmcnt(7)
	v_pk_fma_f32 v[114:115], v[42:43], v[92:93], v[114:115] op_sel:[0,0,0] op_sel_hi:[0,1,1] neg_lo:[1,0,0] neg_hi:[1,0,0]
	v_pk_fma_f32 v[234:235], v[42:43], v[94:95], v[234:235] op_sel:[1,0,0] op_sel_hi:[1,1,1] neg_lo:[1,0,0] neg_hi:[1,0,0]
	v_pk_fma_f32 v[236:237], v[44:45], v[96:97], v[236:237] op_sel:[0,0,0] op_sel_hi:[0,1,1] neg_lo:[1,0,0] neg_hi:[1,0,0]
	v_pk_fma_f32 v[238:239], v[44:45], v[98:99], v[238:239] op_sel:[1,0,0] op_sel_hi:[1,1,1] neg_lo:[1,0,0] neg_hi:[1,0,0]
	ds_read_b128 v[42:45], v241 offset:8272
	s_waitcnt lgkmcnt(7)
	v_pk_fma_f32 v[114:115], v[46:47], v[100:101], v[114:115] op_sel:[0,0,0] op_sel_hi:[0,1,1] neg_lo:[1,0,0] neg_hi:[1,0,0]
	v_pk_fma_f32 v[234:235], v[46:47], v[102:103], v[234:235] op_sel:[1,0,0] op_sel_hi:[1,1,1] neg_lo:[1,0,0] neg_hi:[1,0,0]
	v_pk_fma_f32 v[236:237], v[48:49], v[104:105], v[236:237] op_sel:[0,0,0] op_sel_hi:[0,1,1] neg_lo:[1,0,0] neg_hi:[1,0,0]
	v_pk_fma_f32 v[238:239], v[48:49], v[106:107], v[238:239] op_sel:[1,0,0] op_sel_hi:[1,1,1] neg_lo:[1,0,0] neg_hi:[1,0,0]
	ds_read_b128 v[46:49], v241 offset:8288
	s_waitcnt lgkmcnt(7)
	v_pk_fma_f32 v[114:115], v[50:51], v[108:109], v[114:115] op_sel:[0,0,0] op_sel_hi:[0,1,1] neg_lo:[1,0,0] neg_hi:[1,0,0]
	v_pk_fma_f32 v[234:235], v[50:51], v[110:111], v[234:235] op_sel:[1,0,0] op_sel_hi:[1,1,1] neg_lo:[1,0,0] neg_hi:[1,0,0]
	v_pk_fma_f32 v[236:237], v[52:53], v[112:113], v[236:237] op_sel:[0,0,0] op_sel_hi:[0,1,1] neg_lo:[1,0,0] neg_hi:[1,0,0]
	v_pk_add_f32 v[234:235], v[114:115], v[234:235]
	v_pk_add_f32 v[234:235], v[234:235], v[238:239]
	v_pk_add_f32 v[114:115], v[234:235], v[236:237]
	ds_read_b128 v[50:53], v241 offset:8304
	s_waitcnt lgkmcnt(7)
	v_pk_fma_f32 v[116:117], v[2:3], v[6:7], v[116:117] op_sel:[0,0,0] op_sel_hi:[0,1,1] neg_lo:[1,0,0] neg_hi:[1,0,0]
	v_pk_mul_f32 v[234:235], v[2:3], v[54:55] op_sel:[1,0] op_sel_hi:[1,1] neg_lo:[1,0] neg_hi:[1,0]
	v_pk_mul_f32 v[236:237], v[4:5], v[56:57] op_sel:[0,0] op_sel_hi:[0,1] neg_lo:[1,0] neg_hi:[1,0]
	v_pk_mul_f32 v[238:239], v[4:5], v[58:59] op_sel:[1,0] op_sel_hi:[1,1] neg_lo:[1,0] neg_hi:[1,0]
	ds_read_b128 v[2:5], v241 offset:8448
	s_waitcnt lgkmcnt(7)
; template <int DIR>
; __device__ __forceinline__ void dn_solve(const P& p, int task, int m0, int h, int t2, const bf16_t* kn_s, const bf16_t* v_s, const float* gc, const float* be, float* L) {
;     ...
; #pragma unroll
;     for (int cp = 1; cp < 64; ++cp) {
;         float a0 = 0.f, a1 = 0.f, a2 = 0.f, a3 = 0.f;
; #pragma unroll
;         for (int s4 = 0; s4 < cp; s4 += 4) { const f32x4 l4 = *(const f32x4*)(L + cp * 64 + s4); a0 += l4[0] * x[s4]; a1 += l4[1] * x[s4 + 1]; a2 += l4[2] * x[s4 + 2]; a3 += l4[3] * x[s4 + 3]; }
;         x[cp] -= (a0 + a1) + (a2 + a3);
;     }
	v_pk_fma_f32 v[116:117], v[26:27], v[60:61], v[116:117] op_sel:[0,0,0] op_sel_hi:[0,1,1] neg_lo:[1,0,0] neg_hi:[1,0,0]
	v_pk_fma_f32 v[234:235], v[26:27], v[62:63], v[234:235] op_sel:[1,0,0] op_sel_hi:[1,1,1] neg_lo:[1,0,0] neg_hi:[1,0,0]
	v_pk_fma_f32 v[236:237], v[28:29], v[64:65], v[236:237] op_sel:[0,0,0] op_sel_hi:[0,1,1] neg_lo:[1,0,0] neg_hi:[1,0,0]
	v_pk_fma_f32 v[238:239], v[28:29], v[66:67], v[238:239] op_sel:[1,0,0] op_sel_hi:[1,1,1] neg_lo:[1,0,0] neg_hi:[1,0,0]
	ds_read_b128 v[26:29], v241 offset:8464
	s_waitcnt lgkmcnt(7)
	v_pk_fma_f32 v[116:117], v[30:31], v[68:69], v[116:117] op_sel:[0,0,0] op_sel_hi:[0,1,1] neg_lo:[1,0,0] neg_hi:[1,0,0]
	v_pk_fma_f32 v[234:235], v[30:31], v[70:71], v[234:235] op_sel:[1,0,0] op_sel_hi:[1,1,1] neg_lo:[1,0,0] neg_hi:[1,0,0]
	v_pk_fma_f32 v[236:237], v[32:33], v[72:73], v[236:237] op_sel:[0,0,0] op_sel_hi:[0,1,1] neg_lo:[1,0,0] neg_hi:[1,0,0]
	v_pk_fma_f32 v[238:239], v[32:33], v[74:75], v[238:239] op_sel:[1,0,0] op_sel_hi:[1,1,1] neg_lo:[1,0,0] neg_hi:[1,0,0]
	ds_read_b128 v[30:33], v241 offset:8480
	s_waitcnt lgkmcnt(7)
	v_pk_fma_f32 v[116:117], v[34:35], v[76:77], v[116:117] op_sel:[0,0,0] op_sel_hi:[0,1,1] neg_lo:[1,0,0] neg_hi:[1,0,0]
	v_pk_fma_f32 v[234:235], v[34:35], v[78:79], v[234:235] op_sel:[1,0,0] op_sel_hi:[1,1,1] neg_lo:[1,0,0] neg_hi:[1,0,0]
	v_pk_fma_f32 v[236:237], v[36:37], v[80:81], v[236:237] op_sel:[0,0,0] op_sel_hi:[0,1,1] neg_lo:[1,0,0] neg_hi:[1,0,0]
	v_pk_fma_f32 v[238:239], v[36:37], v[82:83], v[238:239] op_sel:[1,0,0] op_sel_hi:[1,1,1] neg_lo:[1,0,0] neg_hi:[1,0,0]
	ds_read_b128 v[34:37], v241 offset:8496
	s_waitcnt lgkmcnt(7)
	v_pk_fma_f32 v[116:117], v[38:39], v[84:85], v[116:117] op_sel:[0,0,0] op_sel_hi:[0,1,1] neg_lo:[1,0,0] neg_hi:[1,0,0]
	v_pk_fma_f32 v[234:235], v[38:39], v[86:87], v[234:235] op_sel:[1,0,0] op_sel_hi:[1,1,1] neg_lo:[1,0,0] neg_hi:[1,0,0]
	v_pk_fma_f32 v[236:237], v[40:41], v[88:89], v[236:237] op_sel:[0,0,0] op_sel_hi:[0,1,1] neg_lo:[1,0,0] neg_hi:[1,0,0]
	v_pk_fma_f32 v[238:239], v[40:41], v[90:91], v[238:239] op_sel:[1,0,0] op_sel_hi:[1,1,1] neg_lo:[1,0,0] neg_hi:[1,0,0]
	ds_read_b128 v[38:41], v241 offset:8512
	s_waitcnt lgkmcnt(7)
	v_pk_fma_f32 v[116:117], v[42:43], v[92:93], v[116:117] op_sel:[0,0,0] op_sel_hi:[0,1,1] neg_lo:[1,0,0] neg_hi:[1,0,0]
	v_pk_fma_f32 v[234:235], v[42:43], v[94:95], v[234:235] op_sel:[1,0,0] op_sel_hi:[1,1,1] neg_lo:[1,0,0] neg_hi:[1,0,0]
	v_pk_fma_f32 v[236:237], v[44:45], v[96:97], v[236:237] op_sel:[0,0,0] op_sel_hi:[0,1,1] neg_lo:[1,0,0] neg_hi:[1,0,0]
	v_pk_fma_f32 v[238:239], v[44:45], v[98:99], v[238:239] op_sel:[1,0,0] op_sel_hi:[1,1,1] neg_lo:[1,0,0] neg_hi:[1,0,0]
	ds_read_b128 v[42:45], v241 offset:8528
	s_waitcnt lgkmcnt(7)
	v_pk_fma_f32 v[116:117], v[46:47], v[100:101], v[116:117] op_sel:[0,0,0] op_sel_hi:[0,1,1] neg_lo:[1,0,0] neg_hi:[1,0,0]
	v_pk_fma_f32 v[234:235], v[46:47], v[102:103], v[234:235] op_sel:[1,0,0] op_sel_hi:[1,1,1] neg_lo:[1,0,0] neg_hi:[1,0,0]
	v_pk_fma_f32 v[236:237], v[48:49], v[104:105], v[236:237] op_sel:[0,0,0] op_sel_hi:[0,1,1] neg_lo:[1,0,0] neg_hi:[1,0,0]
	v_pk_fma_f32 v[238:239], v[48:49], v[106:107], v[238:239] op_sel:[1,0,0] op_sel_hi:[1,1,1] neg_lo:[1,0,0] neg_hi:[1,0,0]
	ds_read_b128 v[46:49], v241 offset:8544
	s_waitcnt lgkmcnt(7)
	v_pk_fma_f32 v[116:117], v[50:51], v[108:109], v[116:117] op_sel:[0,0,0] op_sel_hi:[0,1,1] neg_lo:[1,0,0] neg_hi:[1,0,0]
	v_pk_fma_f32 v[234:235], v[50:51], v[110:111], v[234:235] op_sel:[1,0,0] op_sel_hi:[1,1,1] neg_lo:[1,0,0] neg_hi:[1,0,0]
	v_pk_fma_f32 v[236:237], v[52:53], v[112:113], v[236:237] op_sel:[0,0,0] op_sel_hi:[0,1,1] neg_lo:[1,0,0] neg_hi:[1,0,0]
	v_pk_fma_f32 v[238:239], v[52:53], v[114:115], v[238:239] op_sel:[1,0,0] op_sel_hi:[1,1,1] neg_lo:[1,0,0] neg_hi:[1,0,0]
	v_pk_add_f32 v[234:235], v[116:117], v[234:235]
	v_pk_add_f32 v[234:235], v[234:235], v[236:237]
	v_pk_add_f32 v[116:117], v[234:235], v[238:239]
	ds_read_b128 v[50:53], v241 offset:8560
	s_waitcnt lgkmcnt(7)
	v_pk_fma_f32 v[118:119], v[2:3], v[6:7], v[118:119] op_sel:[0,0,0] op_sel_hi:[0,1,1] neg_lo:[1,0,0] neg_hi:[1,0,0]
	v_pk_mul_f32 v[234:235], v[2:3], v[54:55] op_sel:[1,0] op_sel_hi:[1,1] neg_lo:[1,0] neg_hi:[1,0]
	v_pk_mul_f32 v[236:237], v[4:5], v[56:57] op_sel:[0,0] op_sel_hi:[0,1] neg_lo:[1,0] neg_hi:[1,0]
	v_pk_mul_f32 v[238:239], v[4:5], v[58:59] op_sel:[1,0] op_sel_hi:[1,1] neg_lo:[1,0] neg_hi:[1,0]
	ds_read_b128 v[2:5], v241 offset:8576
	s_waitcnt lgkmcnt(7)
	v_pk_fma_f32 v[118:119], v[26:27], v[60:61], v[118:119] op_sel:[0,0,0] op_sel_hi:[0,1,1] neg_lo:[1,0,0] neg_hi:[1,0,0]
	v_pk_fma_f32 v[234:235], v[26:27], v[62:63], v[234:235] op_sel:[1,0,0] op_sel_hi:[1,1,1] neg_lo:[1,0,0] neg_hi:[1,0,0]
	v_pk_fma_f32 v[236:237], v[28:29], v[64:65], v[236:237] op_sel:[0,0,0] op_sel_hi:[0,1,1] neg_lo:[1,0,0] neg_hi:[1,0,0]
	v_pk_fma_f32 v[238:239], v[28:29], v[66:67], v[238:239] op_sel:[1,0,0] op_sel_hi:[1,1,1] neg_lo:[1,0,0] neg_hi:[1,0,0]
	ds_read_b128 v[26:29], v241 offset:8704
	s_waitcnt lgkmcnt(7)
	v_pk_fma_f32 v[118:119], v[30:31], v[68:69], v[118:119] op_sel:[0,0,0] op_sel_hi:[0,1,1] neg_lo:[1,0,0] neg_hi:[1,0,0]
	v_pk_fma_f32 v[234:235], v[30:31], v[70:71], v[234:235] op_sel:[1,0,0] op_sel_hi:[1,1,1] neg_lo:[1,0,0] neg_hi:[1,0,0]
	v_pk_fma_f32 v[236:237], v[32:33], v[72:73], v[236:237] op_sel:[0,0,0] op_sel_hi:[0,1,1] neg_lo:[1,0,0] neg_hi:[1,0,0]
	v_pk_fma_f32 v[238:239], v[32:33], v[74:75], v[238:239] op_sel:[1,0,0] op_sel_hi:[1,1,1] neg_lo:[1,0,0] neg_hi:[1,0,0]
	ds_read_b128 v[30:33], v241 offset:8720
	s_waitcnt lgkmcnt(7)
; template <int DIR>
; __device__ __forceinline__ void dn_solve(const P& p, int task, int m0, int h, int t2, const bf16_t* kn_s, const bf16_t* v_s, const float* gc, const float* be, float* L) {
;     ...
; #pragma unroll
;     for (int cp = 1; cp < 64; ++cp) {
;         float a0 = 0.f, a1 = 0.f, a2 = 0.f, a3 = 0.f;
; #pragma unroll
;         for (int s4 = 0; s4 < cp; s4 += 4) { const f32x4 l4 = *(const f32x4*)(L + cp * 64 + s4); a0 += l4[0] * x[s4]; a1 += l4[1] * x[s4 + 1]; a2 += l4[2] * x[s4 + 2]; a3 += l4[3] * x[s4 + 3]; }
;         x[cp] -= (a0 + a1) + (a2 + a3);
;     }
	v_pk_fma_f32 v[118:119], v[34:35], v[76:77], v[118:119] op_sel:[0,0,0] op_sel_hi:[0,1,1] neg_lo:[1,0,0] neg_hi:[1,0,0]
	v_pk_fma_f32 v[234:235], v[34:35], v[78:79], v[234:235] op_sel:[1,0,0] op_sel_hi:[1,1,1] neg_lo:[1,0,0] neg_hi:[1,0,0]
	v_pk_fma_f32 v[236:237], v[36:37], v[80:81], v[236:237] op_sel:[0,0,0] op_sel_hi:[0,1,1] neg_lo:[1,0,0] neg_hi:[1,0,0]
	v_pk_fma_f32 v[238:239], v[36:37], v[82:83], v[238:239] op_sel:[1,0,0] op_sel_hi:[1,1,1] neg_lo:[1,0,0] neg_hi:[1,0,0]
	ds_read_b128 v[34:37], v241 offset:8736
	s_waitcnt lgkmcnt(7)
	v_pk_fma_f32 v[118:119], v[38:39], v[84:85], v[118:119] op_sel:[0,0,0] op_sel_hi:[0,1,1] neg_lo:[1,0,0] neg_hi:[1,0,0]
	v_pk_fma_f32 v[234:235], v[38:39], v[86:87], v[234:235] op_sel:[1,0,0] op_sel_hi:[1,1,1] neg_lo:[1,0,0] neg_hi:[1,0,0]
	v_pk_fma_f32 v[236:237], v[40:41], v[88:89], v[236:237] op_sel:[0,0,0] op_sel_hi:[0,1,1] neg_lo:[1,0,0] neg_hi:[1,0,0]
	v_pk_fma_f32 v[238:239], v[40:41], v[90:91], v[238:239] op_sel:[1,0,0] op_sel_hi:[1,1,1] neg_lo:[1,0,0] neg_hi:[1,0,0]
	ds_read_b128 v[38:41], v241 offset:8752
	s_waitcnt lgkmcnt(7)
	v_pk_fma_f32 v[118:119], v[42:43], v[92:93], v[118:119] op_sel:[0,0,0] op_sel_hi:[0,1,1] neg_lo:[1,0,0] neg_hi:[1,0,0]
	v_pk_fma_f32 v[234:235], v[42:43], v[94:95], v[234:235] op_sel:[1,0,0] op_sel_hi:[1,1,1] neg_lo:[1,0,0] neg_hi:[1,0,0]
	v_pk_fma_f32 v[236:237], v[44:45], v[96:97], v[236:237] op_sel:[0,0,0] op_sel_hi:[0,1,1] neg_lo:[1,0,0] neg_hi:[1,0,0]
	v_pk_fma_f32 v[238:239], v[44:45], v[98:99], v[238:239] op_sel:[1,0,0] op_sel_hi:[1,1,1] neg_lo:[1,0,0] neg_hi:[1,0,0]
	ds_read_b128 v[42:45], v241 offset:8768
	s_waitcnt lgkmcnt(7)
	v_pk_fma_f32 v[118:119], v[46:47], v[100:101], v[118:119] op_sel:[0,0,0] op_sel_hi:[0,1,1] neg_lo:[1,0,0] neg_hi:[1,0,0]
	v_pk_fma_f32 v[234:235], v[46:47], v[102:103], v[234:235] op_sel:[1,0,0] op_sel_hi:[1,1,1] neg_lo:[1,0,0] neg_hi:[1,0,0]
	v_pk_fma_f32 v[236:237], v[48:49], v[104:105], v[236:237] op_sel:[0,0,0] op_sel_hi:[0,1,1] neg_lo:[1,0,0] neg_hi:[1,0,0]
	v_pk_fma_f32 v[238:239], v[48:49], v[106:107], v[238:239] op_sel:[1,0,0] op_sel_hi:[1,1,1] neg_lo:[1,0,0] neg_hi:[1,0,0]
	ds_read_b128 v[46:49], v241 offset:8784
	s_waitcnt lgkmcnt(7)
	v_pk_fma_f32 v[118:119], v[50:51], v[108:109], v[118:119] op_sel:[0,0,0] op_sel_hi:[0,1,1] neg_lo:[1,0,0] neg_hi:[1,0,0]
	v_pk_fma_f32 v[234:235], v[50:51], v[110:111], v[234:235] op_sel:[1,0,0] op_sel_hi:[1,1,1] neg_lo:[1,0,0] neg_hi:[1,0,0]
	v_pk_fma_f32 v[236:237], v[52:53], v[112:113], v[236:237] op_sel:[0,0,0] op_sel_hi:[0,1,1] neg_lo:[1,0,0] neg_hi:[1,0,0]
	v_pk_fma_f32 v[238:239], v[52:53], v[114:115], v[238:239] op_sel:[1,0,0] op_sel_hi:[1,1,1] neg_lo:[1,0,0] neg_hi:[1,0,0]
	ds_read_b128 v[50:53], v241 offset:8800
	s_waitcnt lgkmcnt(7)
	v_pk_fma_f32 v[118:119], v[2:3], v[116:117], v[118:119] op_sel:[0,0,0] op_sel_hi:[0,1,1] neg_lo:[1,0,0] neg_hi:[1,0,0]
	v_pk_add_f32 v[234:235], v[234:235], v[236:237]
	v_pk_add_f32 v[234:235], v[234:235], v[238:239]
	v_pk_add_f32 v[118:119], v[234:235], v[118:119]
	ds_read_b128 v[2:5], v241 offset:8816
	s_waitcnt lgkmcnt(7)
	v_pk_fma_f32 v[152:153], v[26:27], v[6:7], v[152:153] op_sel:[0,0,0] op_sel_hi:[0,1,1] neg_lo:[1,0,0] neg_hi:[1,0,0]
	v_pk_mul_f32 v[234:235], v[26:27], v[54:55] op_sel:[1,0] op_sel_hi:[1,1] neg_lo:[1,0] neg_hi:[1,0]
	v_pk_mul_f32 v[236:237], v[28:29], v[56:57] op_sel:[0,0] op_sel_hi:[0,1] neg_lo:[1,0] neg_hi:[1,0]
	v_pk_mul_f32 v[238:239], v[28:29], v[58:59] op_sel:[1,0] op_sel_hi:[1,1] neg_lo:[1,0] neg_hi:[1,0]
	ds_read_b128 v[26:29], v241 offset:8832
	s_waitcnt lgkmcnt(7)
	v_pk_fma_f32 v[152:153], v[30:31], v[60:61], v[152:153] op_sel:[0,0,0] op_sel_hi:[0,1,1] neg_lo:[1,0,0] neg_hi:[1,0,0]
	v_pk_fma_f32 v[234:235], v[30:31], v[62:63], v[234:235] op_sel:[1,0,0] op_sel_hi:[1,1,1] neg_lo:[1,0,0] neg_hi:[1,0,0]
	v_pk_fma_f32 v[236:237], v[32:33], v[64:65], v[236:237] op_sel:[0,0,0] op_sel_hi:[0,1,1] neg_lo:[1,0,0] neg_hi:[1,0,0]
	v_pk_fma_f32 v[238:239], v[32:33], v[66:67], v[238:239] op_sel:[1,0,0] op_sel_hi:[1,1,1] neg_lo:[1,0,0] neg_hi:[1,0,0]
	ds_read_b128 v[30:33], v241 offset:8960
	s_waitcnt lgkmcnt(7)
	v_pk_fma_f32 v[152:153], v[34:35], v[68:69], v[152:153] op_sel:[0,0,0] op_sel_hi:[0,1,1] neg_lo:[1,0,0] neg_hi:[1,0,0]
	v_pk_fma_f32 v[234:235], v[34:35], v[70:71], v[234:235] op_sel:[1,0,0] op_sel_hi:[1,1,1] neg_lo:[1,0,0] neg_hi:[1,0,0]
	v_pk_fma_f32 v[236:237], v[36:37], v[72:73], v[236:237] op_sel:[0,0,0] op_sel_hi:[0,1,1] neg_lo:[1,0,0] neg_hi:[1,0,0]
	v_pk_fma_f32 v[238:239], v[36:37], v[74:75], v[238:239] op_sel:[1,0,0] op_sel_hi:[1,1,1] neg_lo:[1,0,0] neg_hi:[1,0,0]
	ds_read_b128 v[34:37], v241 offset:8976
	s_waitcnt lgkmcnt(7)
	v_pk_fma_f32 v[152:153], v[38:39], v[76:77], v[152:153] op_sel:[0,0,0] op_sel_hi:[0,1,1] neg_lo:[1,0,0] neg_hi:[1,0,0]
	v_pk_fma_f32 v[234:235], v[38:39], v[78:79], v[234:235] op_sel:[1,0,0] op_sel_hi:[1,1,1] neg_lo:[1,0,0] neg_hi:[1,0,0]
	v_pk_fma_f32 v[236:237], v[40:41], v[80:81], v[236:237] op_sel:[0,0,0] op_sel_hi:[0,1,1] neg_lo:[1,0,0] neg_hi:[1,0,0]
	v_pk_fma_f32 v[238:239], v[40:41], v[82:83], v[238:239] op_sel:[1,0,0] op_sel_hi:[1,1,1] neg_lo:[1,0,0] neg_hi:[1,0,0]
	ds_read_b128 v[38:41], v241 offset:8992
	s_waitcnt lgkmcnt(7)
	v_pk_fma_f32 v[152:153], v[42:43], v[84:85], v[152:153] op_sel:[0,0,0] op_sel_hi:[0,1,1] neg_lo:[1,0,0] neg_hi:[1,0,0]
	v_pk_fma_f32 v[234:235], v[42:43], v[86:87], v[234:235] op_sel:[1,0,0] op_sel_hi:[1,1,1] neg_lo:[1,0,0] neg_hi:[1,0,0]
	v_pk_fma_f32 v[236:237], v[44:45], v[88:89], v[236:237] op_sel:[0,0,0] op_sel_hi:[0,1,1] neg_lo:[1,0,0] neg_hi:[1,0,0]
	v_pk_fma_f32 v[238:239], v[44:45], v[90:91], v[238:239] op_sel:[1,0,0] op_sel_hi:[1,1,1] neg_lo:[1,0,0] neg_hi:[1,0,0]
	ds_read_b128 v[42:45], v241 offset:9008
	s_waitcnt lgkmcnt(7)
; template <int DIR>
; __device__ __forceinline__ void dn_solve(const P& p, int task, int m0, int h, int t2, const bf16_t* kn_s, const bf16_t* v_s, const float* gc, const float* be, float* L) {
;     ...
; #pragma unroll
;     for (int cp = 1; cp < 64; ++cp) {
;         float a0 = 0.f, a1 = 0.f, a2 = 0.f, a3 = 0.f;
; #pragma unroll
;         for (int s4 = 0; s4 < cp; s4 += 4) { const f32x4 l4 = *(const f32x4*)(L + cp * 64 + s4); a0 += l4[0] * x[s4]; a1 += l4[1] * x[s4 + 1]; a2 += l4[2] * x[s4 + 2]; a3 += l4[3] * x[s4 + 3]; }
;         x[cp] -= (a0 + a1) + (a2 + a3);
;     }
	v_pk_fma_f32 v[152:153], v[46:47], v[92:93], v[152:153] op_sel:[0,0,0] op_sel_hi:[0,1,1] neg_lo:[1,0,0] neg_hi:[1,0,0]
	v_pk_fma_f32 v[234:235], v[46:47], v[94:95], v[234:235] op_sel:[1,0,0] op_sel_hi:[1,1,1] neg_lo:[1,0,0] neg_hi:[1,0,0]
	v_pk_fma_f32 v[236:237], v[48:49], v[96:97], v[236:237] op_sel:[0,0,0] op_sel_hi:[0,1,1] neg_lo:[1,0,0] neg_hi:[1,0,0]
	v_pk_fma_f32 v[238:239], v[48:49], v[98:99], v[238:239] op_sel:[1,0,0] op_sel_hi:[1,1,1] neg_lo:[1,0,0] neg_hi:[1,0,0]
	ds_read_b128 v[46:49], v241 offset:9024
	s_waitcnt lgkmcnt(7)
	v_pk_fma_f32 v[152:153], v[50:51], v[100:101], v[152:153] op_sel:[0,0,0] op_sel_hi:[0,1,1] neg_lo:[1,0,0] neg_hi:[1,0,0]
	v_pk_fma_f32 v[234:235], v[50:51], v[102:103], v[234:235] op_sel:[1,0,0] op_sel_hi:[1,1,1] neg_lo:[1,0,0] neg_hi:[1,0,0]
	v_pk_fma_f32 v[236:237], v[52:53], v[104:105], v[236:237] op_sel:[0,0,0] op_sel_hi:[0,1,1] neg_lo:[1,0,0] neg_hi:[1,0,0]
	v_pk_fma_f32 v[238:239], v[52:53], v[106:107], v[238:239] op_sel:[1,0,0] op_sel_hi:[1,1,1] neg_lo:[1,0,0] neg_hi:[1,0,0]
	ds_read_b128 v[50:53], v241 offset:9040
	s_waitcnt lgkmcnt(7)
	v_pk_fma_f32 v[152:153], v[2:3], v[108:109], v[152:153] op_sel:[0,0,0] op_sel_hi:[0,1,1] neg_lo:[1,0,0] neg_hi:[1,0,0]
	v_pk_fma_f32 v[234:235], v[2:3], v[110:111], v[234:235] op_sel:[1,0,0] op_sel_hi:[1,1,1] neg_lo:[1,0,0] neg_hi:[1,0,0]
	v_pk_fma_f32 v[236:237], v[4:5], v[112:113], v[236:237] op_sel:[0,0,0] op_sel_hi:[0,1,1] neg_lo:[1,0,0] neg_hi:[1,0,0]
	v_pk_fma_f32 v[238:239], v[4:5], v[114:115], v[238:239] op_sel:[1,0,0] op_sel_hi:[1,1,1] neg_lo:[1,0,0] neg_hi:[1,0,0]
	ds_read_b128 v[2:5], v241 offset:9056
	s_waitcnt lgkmcnt(7)
	v_pk_fma_f32 v[152:153], v[26:27], v[116:117], v[152:153] op_sel:[0,0,0] op_sel_hi:[0,1,1] neg_lo:[1,0,0] neg_hi:[1,0,0]
	v_pk_fma_f32 v[234:235], v[26:27], v[118:119], v[234:235] op_sel:[1,0,0] op_sel_hi:[1,1,1] neg_lo:[1,0,0] neg_hi:[1,0,0]
	v_pk_add_f32 v[236:237], v[152:153], v[236:237]
	v_pk_add_f32 v[236:237], v[236:237], v[238:239]
	v_pk_add_f32 v[152:153], v[236:237], v[234:235]
	ds_read_b128 v[26:29], v241 offset:9072
	s_waitcnt lgkmcnt(7)
	v_pk_fma_f32 v[154:155], v[30:31], v[6:7], v[154:155] op_sel:[0,0,0] op_sel_hi:[0,1,1] neg_lo:[1,0,0] neg_hi:[1,0,0]
	v_pk_mul_f32 v[234:235], v[30:31], v[54:55] op_sel:[1,0] op_sel_hi:[1,1] neg_lo:[1,0] neg_hi:[1,0]
	v_pk_mul_f32 v[236:237], v[32:33], v[56:57] op_sel:[0,0] op_sel_hi:[0,1] neg_lo:[1,0] neg_hi:[1,0]
	v_pk_mul_f32 v[238:239], v[32:33], v[58:59] op_sel:[1,0] op_sel_hi:[1,1] neg_lo:[1,0] neg_hi:[1,0]
	ds_read_b128 v[30:33], v241 offset:9088
	s_waitcnt lgkmcnt(7)
	v_pk_fma_f32 v[154:155], v[34:35], v[60:61], v[154:155] op_sel:[0,0,0] op_sel_hi:[0,1,1] neg_lo:[1,0,0] neg_hi:[1,0,0]
	v_pk_fma_f32 v[234:235], v[34:35], v[62:63], v[234:235] op_sel:[1,0,0] op_sel_hi:[1,1,1] neg_lo:[1,0,0] neg_hi:[1,0,0]
	v_pk_fma_f32 v[236:237], v[36:37], v[64:65], v[236:237] op_sel:[0,0,0] op_sel_hi:[0,1,1] neg_lo:[1,0,0] neg_hi:[1,0,0]
	v_pk_fma_f32 v[238:239], v[36:37], v[66:67], v[238:239] op_sel:[1,0,0] op_sel_hi:[1,1,1] neg_lo:[1,0,0] neg_hi:[1,0,0]
	ds_read_b128 v[34:37], v241 offset:9216
	s_waitcnt lgkmcnt(7)
	v_pk_fma_f32 v[154:155], v[38:39], v[68:69], v[154:155] op_sel:[0,0,0] op_sel_hi:[0,1,1] neg_lo:[1,0,0] neg_hi:[1,0,0]
	v_pk_fma_f32 v[234:235], v[38:39], v[70:71], v[234:235] op_sel:[1,0,0] op_sel_hi:[1,1,1] neg_lo:[1,0,0] neg_hi:[1,0,0]
	v_pk_fma_f32 v[236:237], v[40:41], v[72:73], v[236:237] op_sel:[0,0,0] op_sel_hi:[0,1,1] neg_lo:[1,0,0] neg_hi:[1,0,0]
	v_pk_fma_f32 v[238:239], v[40:41], v[74:75], v[238:239] op_sel:[1,0,0] op_sel_hi:[1,1,1] neg_lo:[1,0,0] neg_hi:[1,0,0]
	ds_read_b128 v[38:41], v241 offset:9232
	s_waitcnt lgkmcnt(7)
	v_pk_fma_f32 v[154:155], v[42:43], v[76:77], v[154:155] op_sel:[0,0,0] op_sel_hi:[0,1,1] neg_lo:[1,0,0] neg_hi:[1,0,0]
	v_pk_fma_f32 v[234:235], v[42:43], v[78:79], v[234:235] op_sel:[1,0,0] op_sel_hi:[1,1,1] neg_lo:[1,0,0] neg_hi:[1,0,0]
	v_pk_fma_f32 v[236:237], v[44:45], v[80:81], v[236:237] op_sel:[0,0,0] op_sel_hi:[0,1,1] neg_lo:[1,0,0] neg_hi:[1,0,0]
	v_pk_fma_f32 v[238:239], v[44:45], v[82:83], v[238:239] op_sel:[1,0,0] op_sel_hi:[1,1,1] neg_lo:[1,0,0] neg_hi:[1,0,0]
	ds_read_b128 v[42:45], v241 offset:9248
	s_waitcnt lgkmcnt(7)
	v_pk_fma_f32 v[154:155], v[46:47], v[84:85], v[154:155] op_sel:[0,0,0] op_sel_hi:[0,1,1] neg_lo:[1,0,0] neg_hi:[1,0,0]
	v_pk_fma_f32 v[234:235], v[46:47], v[86:87], v[234:235] op_sel:[1,0,0] op_sel_hi:[1,1,1] neg_lo:[1,0,0] neg_hi:[1,0,0]
	v_pk_fma_f32 v[236:237], v[48:49], v[88:89], v[236:237] op_sel:[0,0,0] op_sel_hi:[0,1,1] neg_lo:[1,0,0] neg_hi:[1,0,0]
	v_pk_fma_f32 v[238:239], v[48:49], v[90:91], v[238:239] op_sel:[1,0,0] op_sel_hi:[1,1,1] neg_lo:[1,0,0] neg_hi:[1,0,0]
	ds_read_b128 v[46:49], v241 offset:9264
	s_waitcnt lgkmcnt(7)
	v_pk_fma_f32 v[154:155], v[50:51], v[92:93], v[154:155] op_sel:[0,0,0] op_sel_hi:[0,1,1] neg_lo:[1,0,0] neg_hi:[1,0,0]
	v_pk_fma_f32 v[234:235], v[50:51], v[94:95], v[234:235] op_sel:[1,0,0] op_sel_hi:[1,1,1] neg_lo:[1,0,0] neg_hi:[1,0,0]
	v_pk_fma_f32 v[236:237], v[52:53], v[96:97], v[236:237] op_sel:[0,0,0] op_sel_hi:[0,1,1] neg_lo:[1,0,0] neg_hi:[1,0,0]
	v_pk_fma_f32 v[238:239], v[52:53], v[98:99], v[238:239] op_sel:[1,0,0] op_sel_hi:[1,1,1] neg_lo:[1,0,0] neg_hi:[1,0,0]
	ds_read_b128 v[50:53], v241 offset:9280
	s_waitcnt lgkmcnt(7)
	v_pk_fma_f32 v[154:155], v[2:3], v[100:101], v[154:155] op_sel:[0,0,0] op_sel_hi:[0,1,1] neg_lo:[1,0,0] neg_hi:[1,0,0]
	v_pk_fma_f32 v[234:235], v[2:3], v[102:103], v[234:235] op_sel:[1,0,0] op_sel_hi:[1,1,1] neg_lo:[1,0,0] neg_hi:[1,0,0]
	v_pk_fma_f32 v[236:237], v[4:5], v[104:105], v[236:237] op_sel:[0,0,0] op_sel_hi:[0,1,1] neg_lo:[1,0,0] neg_hi:[1,0,0]
	v_pk_fma_f32 v[238:239], v[4:5], v[106:107], v[238:239] op_sel:[1,0,0] op_sel_hi:[1,1,1] neg_lo:[1,0,0] neg_hi:[1,0,0]
	ds_read_b128 v[2:5], v241 offset:9296
	s_waitcnt lgkmcnt(7)
; template <int DIR>
; __device__ __forceinline__ void dn_solve(const P& p, int task, int m0, int h, int t2, const bf16_t* kn_s, const bf16_t* v_s, const float* gc, const float* be, float* L) {
;     ...
; #pragma unroll
;     for (int cp = 1; cp < 64; ++cp) {
;         float a0 = 0.f, a1 = 0.f, a2 = 0.f, a3 = 0.f;
; #pragma unroll
;         for (int s4 = 0; s4 < cp; s4 += 4) { const f32x4 l4 = *(const f32x4*)(L + cp * 64 + s4); a0 += l4[0] * x[s4]; a1 += l4[1] * x[s4 + 1]; a2 += l4[2] * x[s4 + 2]; a3 += l4[3] * x[s4 + 3]; }
;         x[cp] -= (a0 + a1) + (a2 + a3);
;     }
	v_pk_fma_f32 v[154:155], v[26:27], v[108:109], v[154:155] op_sel:[0,0,0] op_sel_hi:[0,1,1] neg_lo:[1,0,0] neg_hi:[1,0,0]
	v_pk_fma_f32 v[234:235], v[26:27], v[110:111], v[234:235] op_sel:[1,0,0] op_sel_hi:[1,1,1] neg_lo:[1,0,0] neg_hi:[1,0,0]
	v_pk_fma_f32 v[236:237], v[28:29], v[112:113], v[236:237] op_sel:[0,0,0] op_sel_hi:[0,1,1] neg_lo:[1,0,0] neg_hi:[1,0,0]
	v_pk_fma_f32 v[238:239], v[28:29], v[114:115], v[238:239] op_sel:[1,0,0] op_sel_hi:[1,1,1] neg_lo:[1,0,0] neg_hi:[1,0,0]
	ds_read_b128 v[26:29], v241 offset:9312
	s_waitcnt lgkmcnt(7)
	v_pk_fma_f32 v[154:155], v[30:31], v[116:117], v[154:155] op_sel:[0,0,0] op_sel_hi:[0,1,1] neg_lo:[1,0,0] neg_hi:[1,0,0]
	v_pk_fma_f32 v[234:235], v[30:31], v[118:119], v[234:235] op_sel:[1,0,0] op_sel_hi:[1,1,1] neg_lo:[1,0,0] neg_hi:[1,0,0]
	v_pk_fma_f32 v[236:237], v[32:33], v[152:153], v[236:237] op_sel:[0,0,0] op_sel_hi:[0,1,1] neg_lo:[1,0,0] neg_hi:[1,0,0]
	v_pk_add_f32 v[234:235], v[154:155], v[234:235]
	v_pk_add_f32 v[234:235], v[234:235], v[238:239]
	v_pk_add_f32 v[154:155], v[234:235], v[236:237]
	ds_read_b128 v[30:33], v241 offset:9328
	s_waitcnt lgkmcnt(7)
	v_pk_fma_f32 v[156:157], v[34:35], v[6:7], v[156:157] op_sel:[0,0,0] op_sel_hi:[0,1,1] neg_lo:[1,0,0] neg_hi:[1,0,0]
	v_pk_mul_f32 v[234:235], v[34:35], v[54:55] op_sel:[1,0] op_sel_hi:[1,1] neg_lo:[1,0] neg_hi:[1,0]
	v_pk_mul_f32 v[236:237], v[36:37], v[56:57] op_sel:[0,0] op_sel_hi:[0,1] neg_lo:[1,0] neg_hi:[1,0]
	v_pk_mul_f32 v[238:239], v[36:37], v[58:59] op_sel:[1,0] op_sel_hi:[1,1] neg_lo:[1,0] neg_hi:[1,0]
	ds_read_b128 v[34:37], v241 offset:9344
	s_waitcnt lgkmcnt(7)
	v_pk_fma_f32 v[156:157], v[38:39], v[60:61], v[156:157] op_sel:[0,0,0] op_sel_hi:[0,1,1] neg_lo:[1,0,0] neg_hi:[1,0,0]
	v_pk_fma_f32 v[234:235], v[38:39], v[62:63], v[234:235] op_sel:[1,0,0] op_sel_hi:[1,1,1] neg_lo:[1,0,0] neg_hi:[1,0,0]
	v_pk_fma_f32 v[236:237], v[40:41], v[64:65], v[236:237] op_sel:[0,0,0] op_sel_hi:[0,1,1] neg_lo:[1,0,0] neg_hi:[1,0,0]
	v_pk_fma_f32 v[238:239], v[40:41], v[66:67], v[238:239] op_sel:[1,0,0] op_sel_hi:[1,1,1] neg_lo:[1,0,0] neg_hi:[1,0,0]
	ds_read_b128 v[38:41], v241 offset:9472
	s_waitcnt lgkmcnt(7)
	v_pk_fma_f32 v[156:157], v[42:43], v[68:69], v[156:157] op_sel:[0,0,0] op_sel_hi:[0,1,1] neg_lo:[1,0,0] neg_hi:[1,0,0]
	v_pk_fma_f32 v[234:235], v[42:43], v[70:71], v[234:235] op_sel:[1,0,0] op_sel_hi:[1,1,1] neg_lo:[1,0,0] neg_hi:[1,0,0]
	v_pk_fma_f32 v[236:237], v[44:45], v[72:73], v[236:237] op_sel:[0,0,0] op_sel_hi:[0,1,1] neg_lo:[1,0,0] neg_hi:[1,0,0]
	v_pk_fma_f32 v[238:239], v[44:45], v[74:75], v[238:239] op_sel:[1,0,0] op_sel_hi:[1,1,1] neg_lo:[1,0,0] neg_hi:[1,0,0]
	ds_read_b128 v[42:45], v241 offset:9488
	s_waitcnt lgkmcnt(7)
	v_pk_fma_f32 v[156:157], v[46:47], v[76:77], v[156:157] op_sel:[0,0,0] op_sel_hi:[0,1,1] neg_lo:[1,0,0] neg_hi:[1,0,0]
	v_pk_fma_f32 v[234:235], v[46:47], v[78:79], v[234:235] op_sel:[1,0,0] op_sel_hi:[1,1,1] neg_lo:[1,0,0] neg_hi:[1,0,0]
	v_pk_fma_f32 v[236:237], v[48:49], v[80:81], v[236:237] op_sel:[0,0,0] op_sel_hi:[0,1,1] neg_lo:[1,0,0] neg_hi:[1,0,0]
	v_pk_fma_f32 v[238:239], v[48:49], v[82:83], v[238:239] op_sel:[1,0,0] op_sel_hi:[1,1,1] neg_lo:[1,0,0] neg_hi:[1,0,0]
	ds_read_b128 v[46:49], v241 offset:9504
	s_waitcnt lgkmcnt(7)
	v_pk_fma_f32 v[156:157], v[50:51], v[84:85], v[156:157] op_sel:[0,0,0] op_sel_hi:[0,1,1] neg_lo:[1,0,0] neg_hi:[1,0,0]
	v_pk_fma_f32 v[234:235], v[50:51], v[86:87], v[234:235] op_sel:[1,0,0] op_sel_hi:[1,1,1] neg_lo:[1,0,0] neg_hi:[1,0,0]
	v_pk_fma_f32 v[236:237], v[52:53], v[88:89], v[236:237] op_sel:[0,0,0] op_sel_hi:[0,1,1] neg_lo:[1,0,0] neg_hi:[1,0,0]
	v_pk_fma_f32 v[238:239], v[52:53], v[90:91], v[238:239] op_sel:[1,0,0] op_sel_hi:[1,1,1] neg_lo:[1,0,0] neg_hi:[1,0,0]
	ds_read_b128 v[50:53], v241 offset:9520
	s_waitcnt lgkmcnt(7)
	v_pk_fma_f32 v[156:157], v[2:3], v[92:93], v[156:157] op_sel:[0,0,0] op_sel_hi:[0,1,1] neg_lo:[1,0,0] neg_hi:[1,0,0]
	v_pk_fma_f32 v[234:235], v[2:3], v[94:95], v[234:235] op_sel:[1,0,0] op_sel_hi:[1,1,1] neg_lo:[1,0,0] neg_hi:[1,0,0]
	v_pk_fma_f32 v[236:237], v[4:5], v[96:97], v[236:237] op_sel:[0,0,0] op_sel_hi:[0,1,1] neg_lo:[1,0,0] neg_hi:[1,0,0]
	v_pk_fma_f32 v[238:239], v[4:5], v[98:99], v[238:239] op_sel:[1,0,0] op_sel_hi:[1,1,1] neg_lo:[1,0,0] neg_hi:[1,0,0]
	ds_read_b128 v[2:5], v241 offset:9536
	s_waitcnt lgkmcnt(7)
	v_pk_fma_f32 v[156:157], v[26:27], v[100:101], v[156:157] op_sel:[0,0,0] op_sel_hi:[0,1,1] neg_lo:[1,0,0] neg_hi:[1,0,0]
	v_pk_fma_f32 v[234:235], v[26:27], v[102:103], v[234:235] op_sel:[1,0,0] op_sel_hi:[1,1,1] neg_lo:[1,0,0] neg_hi:[1,0,0]
	v_pk_fma_f32 v[236:237], v[28:29], v[104:105], v[236:237] op_sel:[0,0,0] op_sel_hi:[0,1,1] neg_lo:[1,0,0] neg_hi:[1,0,0]
	v_pk_fma_f32 v[238:239], v[28:29], v[106:107], v[238:239] op_sel:[1,0,0] op_sel_hi:[1,1,1] neg_lo:[1,0,0] neg_hi:[1,0,0]
	ds_read_b128 v[26:29], v241 offset:9552
	s_waitcnt lgkmcnt(7)
	v_pk_fma_f32 v[156:157], v[30:31], v[108:109], v[156:157] op_sel:[0,0,0] op_sel_hi:[0,1,1] neg_lo:[1,0,0] neg_hi:[1,0,0]
	v_pk_fma_f32 v[234:235], v[30:31], v[110:111], v[234:235] op_sel:[1,0,0] op_sel_hi:[1,1,1] neg_lo:[1,0,0] neg_hi:[1,0,0]
	v_pk_fma_f32 v[236:237], v[32:33], v[112:113], v[236:237] op_sel:[0,0,0] op_sel_hi:[0,1,1] neg_lo:[1,0,0] neg_hi:[1,0,0]
	v_pk_fma_f32 v[238:239], v[32:33], v[114:115], v[238:239] op_sel:[1,0,0] op_sel_hi:[1,1,1] neg_lo:[1,0,0] neg_hi:[1,0,0]
	ds_read_b128 v[30:33], v241 offset:9568
	s_waitcnt lgkmcnt(7)
; template <int DIR>
; __device__ __forceinline__ void dn_solve(const P& p, int task, int m0, int h, int t2, const bf16_t* kn_s, const bf16_t* v_s, const float* gc, const float* be, float* L) {
;     ...
; #pragma unroll
;     for (int cp = 1; cp < 64; ++cp) {
;         float a0 = 0.f, a1 = 0.f, a2 = 0.f, a3 = 0.f;
; #pragma unroll
;         for (int s4 = 0; s4 < cp; s4 += 4) { const f32x4 l4 = *(const f32x4*)(L + cp * 64 + s4); a0 += l4[0] * x[s4]; a1 += l4[1] * x[s4 + 1]; a2 += l4[2] * x[s4 + 2]; a3 += l4[3] * x[s4 + 3]; }
;         x[cp] -= (a0 + a1) + (a2 + a3);
;     }
	v_pk_fma_f32 v[156:157], v[34:35], v[116:117], v[156:157] op_sel:[0,0,0] op_sel_hi:[0,1,1] neg_lo:[1,0,0] neg_hi:[1,0,0]
	v_pk_fma_f32 v[234:235], v[34:35], v[118:119], v[234:235] op_sel:[1,0,0] op_sel_hi:[1,1,1] neg_lo:[1,0,0] neg_hi:[1,0,0]
	v_pk_fma_f32 v[236:237], v[36:37], v[152:153], v[236:237] op_sel:[0,0,0] op_sel_hi:[0,1,1] neg_lo:[1,0,0] neg_hi:[1,0,0]
	v_pk_fma_f32 v[238:239], v[36:37], v[154:155], v[238:239] op_sel:[1,0,0] op_sel_hi:[1,1,1] neg_lo:[1,0,0] neg_hi:[1,0,0]
	v_pk_add_f32 v[234:235], v[156:157], v[234:235]
	v_pk_add_f32 v[234:235], v[234:235], v[236:237]
	v_pk_add_f32 v[156:157], v[234:235], v[238:239]
	ds_read_b128 v[34:37], v241 offset:9584
	s_waitcnt lgkmcnt(7)
	v_pk_fma_f32 v[158:159], v[38:39], v[6:7], v[158:159] op_sel:[0,0,0] op_sel_hi:[0,1,1] neg_lo:[1,0,0] neg_hi:[1,0,0]
	v_pk_mul_f32 v[234:235], v[38:39], v[54:55] op_sel:[1,0] op_sel_hi:[1,1] neg_lo:[1,0] neg_hi:[1,0]
	v_pk_mul_f32 v[236:237], v[40:41], v[56:57] op_sel:[0,0] op_sel_hi:[0,1] neg_lo:[1,0] neg_hi:[1,0]
	v_pk_mul_f32 v[238:239], v[40:41], v[58:59] op_sel:[1,0] op_sel_hi:[1,1] neg_lo:[1,0] neg_hi:[1,0]
	ds_read_b128 v[38:41], v241 offset:9600
	s_waitcnt lgkmcnt(7)
	v_pk_fma_f32 v[158:159], v[42:43], v[60:61], v[158:159] op_sel:[0,0,0] op_sel_hi:[0,1,1] neg_lo:[1,0,0] neg_hi:[1,0,0]
	v_pk_fma_f32 v[234:235], v[42:43], v[62:63], v[234:235] op_sel:[1,0,0] op_sel_hi:[1,1,1] neg_lo:[1,0,0] neg_hi:[1,0,0]
	v_pk_fma_f32 v[236:237], v[44:45], v[64:65], v[236:237] op_sel:[0,0,0] op_sel_hi:[0,1,1] neg_lo:[1,0,0] neg_hi:[1,0,0]
	v_pk_fma_f32 v[238:239], v[44:45], v[66:67], v[238:239] op_sel:[1,0,0] op_sel_hi:[1,1,1] neg_lo:[1,0,0] neg_hi:[1,0,0]
	ds_read_b128 v[42:45], v241 offset:9616
	s_waitcnt lgkmcnt(7)
	v_pk_fma_f32 v[158:159], v[46:47], v[68:69], v[158:159] op_sel:[0,0,0] op_sel_hi:[0,1,1] neg_lo:[1,0,0] neg_hi:[1,0,0]
	v_pk_fma_f32 v[234:235], v[46:47], v[70:71], v[234:235] op_sel:[1,0,0] op_sel_hi:[1,1,1] neg_lo:[1,0,0] neg_hi:[1,0,0]
	v_pk_fma_f32 v[236:237], v[48:49], v[72:73], v[236:237] op_sel:[0,0,0] op_sel_hi:[0,1,1] neg_lo:[1,0,0] neg_hi:[1,0,0]
	v_pk_fma_f32 v[238:239], v[48:49], v[74:75], v[238:239] op_sel:[1,0,0] op_sel_hi:[1,1,1] neg_lo:[1,0,0] neg_hi:[1,0,0]
	ds_read_b128 v[46:49], v241 offset:9728
	s_waitcnt lgkmcnt(7)
	v_pk_fma_f32 v[158:159], v[50:51], v[76:77], v[158:159] op_sel:[0,0,0] op_sel_hi:[0,1,1] neg_lo:[1,0,0] neg_hi:[1,0,0]
	v_pk_fma_f32 v[234:235], v[50:51], v[78:79], v[234:235] op_sel:[1,0,0] op_sel_hi:[1,1,1] neg_lo:[1,0,0] neg_hi:[1,0,0]
	v_pk_fma_f32 v[236:237], v[52:53], v[80:81], v[236:237] op_sel:[0,0,0] op_sel_hi:[0,1,1] neg_lo:[1,0,0] neg_hi:[1,0,0]
	v_pk_fma_f32 v[238:239], v[52:53], v[82:83], v[238:239] op_sel:[1,0,0] op_sel_hi:[1,1,1] neg_lo:[1,0,0] neg_hi:[1,0,0]
	ds_read_b128 v[50:53], v241 offset:9744
	s_waitcnt lgkmcnt(7)
	v_pk_fma_f32 v[158:159], v[2:3], v[84:85], v[158:159] op_sel:[0,0,0] op_sel_hi:[0,1,1] neg_lo:[1,0,0] neg_hi:[1,0,0]
	v_pk_fma_f32 v[234:235], v[2:3], v[86:87], v[234:235] op_sel:[1,0,0] op_sel_hi:[1,1,1] neg_lo:[1,0,0] neg_hi:[1,0,0]
	v_pk_fma_f32 v[236:237], v[4:5], v[88:89], v[236:237] op_sel:[0,0,0] op_sel_hi:[0,1,1] neg_lo:[1,0,0] neg_hi:[1,0,0]
	v_pk_fma_f32 v[238:239], v[4:5], v[90:91], v[238:239] op_sel:[1,0,0] op_sel_hi:[1,1,1] neg_lo:[1,0,0] neg_hi:[1,0,0]
	ds_read_b128 v[2:5], v241 offset:9760
	s_waitcnt lgkmcnt(7)
	v_pk_fma_f32 v[158:159], v[26:27], v[92:93], v[158:159] op_sel:[0,0,0] op_sel_hi:[0,1,1] neg_lo:[1,0,0] neg_hi:[1,0,0]
	v_pk_fma_f32 v[234:235], v[26:27], v[94:95], v[234:235] op_sel:[1,0,0] op_sel_hi:[1,1,1] neg_lo:[1,0,0] neg_hi:[1,0,0]
	v_pk_fma_f32 v[236:237], v[28:29], v[96:97], v[236:237] op_sel:[0,0,0] op_sel_hi:[0,1,1] neg_lo:[1,0,0] neg_hi:[1,0,0]
	v_pk_fma_f32 v[238:239], v[28:29], v[98:99], v[238:239] op_sel:[1,0,0] op_sel_hi:[1,1,1] neg_lo:[1,0,0] neg_hi:[1,0,0]
	ds_read_b128 v[26:29], v241 offset:9776
	s_waitcnt lgkmcnt(7)
	v_pk_fma_f32 v[158:159], v[30:31], v[100:101], v[158:159] op_sel:[0,0,0] op_sel_hi:[0,1,1] neg_lo:[1,0,0] neg_hi:[1,0,0]
	v_pk_fma_f32 v[234:235], v[30:31], v[102:103], v[234:235] op_sel:[1,0,0] op_sel_hi:[1,1,1] neg_lo:[1,0,0] neg_hi:[1,0,0]
	v_pk_fma_f32 v[236:237], v[32:33], v[104:105], v[236:237] op_sel:[0,0,0] op_sel_hi:[0,1,1] neg_lo:[1,0,0] neg_hi:[1,0,0]
	v_pk_fma_f32 v[238:239], v[32:33], v[106:107], v[238:239] op_sel:[1,0,0] op_sel_hi:[1,1,1] neg_lo:[1,0,0] neg_hi:[1,0,0]
	ds_read_b128 v[30:33], v241 offset:9792
	s_waitcnt lgkmcnt(7)
	v_pk_fma_f32 v[158:159], v[34:35], v[108:109], v[158:159] op_sel:[0,0,0] op_sel_hi:[0,1,1] neg_lo:[1,0,0] neg_hi:[1,0,0]
	v_pk_fma_f32 v[234:235], v[34:35], v[110:111], v[234:235] op_sel:[1,0,0] op_sel_hi:[1,1,1] neg_lo:[1,0,0] neg_hi:[1,0,0]
	v_pk_fma_f32 v[236:237], v[36:37], v[112:113], v[236:237] op_sel:[0,0,0] op_sel_hi:[0,1,1] neg_lo:[1,0,0] neg_hi:[1,0,0]
	v_pk_fma_f32 v[238:239], v[36:37], v[114:115], v[238:239] op_sel:[1,0,0] op_sel_hi:[1,1,1] neg_lo:[1,0,0] neg_hi:[1,0,0]
	ds_read_b128 v[34:37], v241 offset:9808
	s_waitcnt lgkmcnt(7)
	v_pk_fma_f32 v[158:159], v[38:39], v[116:117], v[158:159] op_sel:[0,0,0] op_sel_hi:[0,1,1] neg_lo:[1,0,0] neg_hi:[1,0,0]
	v_pk_fma_f32 v[234:235], v[38:39], v[118:119], v[234:235] op_sel:[1,0,0] op_sel_hi:[1,1,1] neg_lo:[1,0,0] neg_hi:[1,0,0]
	v_pk_fma_f32 v[236:237], v[40:41], v[152:153], v[236:237] op_sel:[0,0,0] op_sel_hi:[0,1,1] neg_lo:[1,0,0] neg_hi:[1,0,0]
	v_pk_fma_f32 v[238:239], v[40:41], v[154:155], v[238:239] op_sel:[1,0,0] op_sel_hi:[1,1,1] neg_lo:[1,0,0] neg_hi:[1,0,0]
	ds_read_b128 v[38:41], v241 offset:9824
	s_waitcnt lgkmcnt(7)
; template <int DIR>
; __device__ __forceinline__ void dn_solve(const P& p, int task, int m0, int h, int t2, const bf16_t* kn_s, const bf16_t* v_s, const float* gc, const float* be, float* L) {
;     ...
; #pragma unroll
;     for (int cp = 1; cp < 64; ++cp) {
;         float a0 = 0.f, a1 = 0.f, a2 = 0.f, a3 = 0.f;
; #pragma unroll
;         for (int s4 = 0; s4 < cp; s4 += 4) { const f32x4 l4 = *(const f32x4*)(L + cp * 64 + s4); a0 += l4[0] * x[s4]; a1 += l4[1] * x[s4 + 1]; a2 += l4[2] * x[s4 + 2]; a3 += l4[3] * x[s4 + 3]; }
;         x[cp] -= (a0 + a1) + (a2 + a3);
;     }
	v_pk_fma_f32 v[158:159], v[42:43], v[156:157], v[158:159] op_sel:[0,0,0] op_sel_hi:[0,1,1] neg_lo:[1,0,0] neg_hi:[1,0,0]
	v_pk_add_f32 v[234:235], v[234:235], v[236:237]
	v_pk_add_f32 v[234:235], v[234:235], v[238:239]
	v_pk_add_f32 v[158:159], v[234:235], v[158:159]
	ds_read_b128 v[42:45], v241 offset:9840
	s_waitcnt lgkmcnt(7)
	v_pk_fma_f32 v[160:161], v[46:47], v[6:7], v[160:161] op_sel:[0,0,0] op_sel_hi:[0,1,1] neg_lo:[1,0,0] neg_hi:[1,0,0]
	v_pk_mul_f32 v[234:235], v[46:47], v[54:55] op_sel:[1,0] op_sel_hi:[1,1] neg_lo:[1,0] neg_hi:[1,0]
	v_pk_mul_f32 v[236:237], v[48:49], v[56:57] op_sel:[0,0] op_sel_hi:[0,1] neg_lo:[1,0] neg_hi:[1,0]
	v_pk_mul_f32 v[238:239], v[48:49], v[58:59] op_sel:[1,0] op_sel_hi:[1,1] neg_lo:[1,0] neg_hi:[1,0]
	ds_read_b128 v[46:49], v241 offset:9856
	s_waitcnt lgkmcnt(7)
	v_pk_fma_f32 v[160:161], v[50:51], v[60:61], v[160:161] op_sel:[0,0,0] op_sel_hi:[0,1,1] neg_lo:[1,0,0] neg_hi:[1,0,0]
	v_pk_fma_f32 v[234:235], v[50:51], v[62:63], v[234:235] op_sel:[1,0,0] op_sel_hi:[1,1,1] neg_lo:[1,0,0] neg_hi:[1,0,0]
	v_pk_fma_f32 v[236:237], v[52:53], v[64:65], v[236:237] op_sel:[0,0,0] op_sel_hi:[0,1,1] neg_lo:[1,0,0] neg_hi:[1,0,0]
	v_pk_fma_f32 v[238:239], v[52:53], v[66:67], v[238:239] op_sel:[1,0,0] op_sel_hi:[1,1,1] neg_lo:[1,0,0] neg_hi:[1,0,0]
	ds_read_b128 v[50:53], v241 offset:9872
	s_waitcnt lgkmcnt(7)
	v_pk_fma_f32 v[160:161], v[2:3], v[68:69], v[160:161] op_sel:[0,0,0] op_sel_hi:[0,1,1] neg_lo:[1,0,0] neg_hi:[1,0,0]
	v_pk_fma_f32 v[234:235], v[2:3], v[70:71], v[234:235] op_sel:[1,0,0] op_sel_hi:[1,1,1] neg_lo:[1,0,0] neg_hi:[1,0,0]
	v_pk_fma_f32 v[236:237], v[4:5], v[72:73], v[236:237] op_sel:[0,0,0] op_sel_hi:[0,1,1] neg_lo:[1,0,0] neg_hi:[1,0,0]
	v_pk_fma_f32 v[238:239], v[4:5], v[74:75], v[238:239] op_sel:[1,0,0] op_sel_hi:[1,1,1] neg_lo:[1,0,0] neg_hi:[1,0,0]
	ds_read_b128 v[2:5], v241 offset:9984
	s_waitcnt lgkmcnt(7)
	v_pk_fma_f32 v[160:161], v[26:27], v[76:77], v[160:161] op_sel:[0,0,0] op_sel_hi:[0,1,1] neg_lo:[1,0,0] neg_hi:[1,0,0]
	v_pk_fma_f32 v[234:235], v[26:27], v[78:79], v[234:235] op_sel:[1,0,0] op_sel_hi:[1,1,1] neg_lo:[1,0,0] neg_hi:[1,0,0]
	v_pk_fma_f32 v[236:237], v[28:29], v[80:81], v[236:237] op_sel:[0,0,0] op_sel_hi:[0,1,1] neg_lo:[1,0,0] neg_hi:[1,0,0]
	v_pk_fma_f32 v[238:239], v[28:29], v[82:83], v[238:239] op_sel:[1,0,0] op_sel_hi:[1,1,1] neg_lo:[1,0,0] neg_hi:[1,0,0]
	ds_read_b128 v[26:29], v241 offset:10000
	s_waitcnt lgkmcnt(7)
	v_pk_fma_f32 v[160:161], v[30:31], v[84:85], v[160:161] op_sel:[0,0,0] op_sel_hi:[0,1,1] neg_lo:[1,0,0] neg_hi:[1,0,0]
	v_pk_fma_f32 v[234:235], v[30:31], v[86:87], v[234:235] op_sel:[1,0,0] op_sel_hi:[1,1,1] neg_lo:[1,0,0] neg_hi:[1,0,0]
	v_pk_fma_f32 v[236:237], v[32:33], v[88:89], v[236:237] op_sel:[0,0,0] op_sel_hi:[0,1,1] neg_lo:[1,0,0] neg_hi:[1,0,0]
	v_pk_fma_f32 v[238:239], v[32:33], v[90:91], v[238:239] op_sel:[1,0,0] op_sel_hi:[1,1,1] neg_lo:[1,0,0] neg_hi:[1,0,0]
	ds_read_b128 v[30:33], v241 offset:10016
	s_waitcnt lgkmcnt(7)
	v_pk_fma_f32 v[160:161], v[34:35], v[92:93], v[160:161] op_sel:[0,0,0] op_sel_hi:[0,1,1] neg_lo:[1,0,0] neg_hi:[1,0,0]
	v_pk_fma_f32 v[234:235], v[34:35], v[94:95], v[234:235] op_sel:[1,0,0] op_sel_hi:[1,1,1] neg_lo:[1,0,0] neg_hi:[1,0,0]
	v_pk_fma_f32 v[236:237], v[36:37], v[96:97], v[236:237] op_sel:[0,0,0] op_sel_hi:[0,1,1] neg_lo:[1,0,0] neg_hi:[1,0,0]
	v_pk_fma_f32 v[238:239], v[36:37], v[98:99], v[238:239] op_sel:[1,0,0] op_sel_hi:[1,1,1] neg_lo:[1,0,0] neg_hi:[1,0,0]
	ds_read_b128 v[34:37], v241 offset:10032
	s_waitcnt lgkmcnt(7)
	v_pk_fma_f32 v[160:161], v[38:39], v[100:101], v[160:161] op_sel:[0,0,0] op_sel_hi:[0,1,1] neg_lo:[1,0,0] neg_hi:[1,0,0]
	v_pk_fma_f32 v[234:235], v[38:39], v[102:103], v[234:235] op_sel:[1,0,0] op_sel_hi:[1,1,1] neg_lo:[1,0,0] neg_hi:[1,0,0]
	v_pk_fma_f32 v[236:237], v[40:41], v[104:105], v[236:237] op_sel:[0,0,0] op_sel_hi:[0,1,1] neg_lo:[1,0,0] neg_hi:[1,0,0]
	v_pk_fma_f32 v[238:239], v[40:41], v[106:107], v[238:239] op_sel:[1,0,0] op_sel_hi:[1,1,1] neg_lo:[1,0,0] neg_hi:[1,0,0]
	ds_read_b128 v[38:41], v241 offset:10048
	s_waitcnt lgkmcnt(7)
	v_pk_fma_f32 v[160:161], v[42:43], v[108:109], v[160:161] op_sel:[0,0,0] op_sel_hi:[0,1,1] neg_lo:[1,0,0] neg_hi:[1,0,0]
	v_pk_fma_f32 v[234:235], v[42:43], v[110:111], v[234:235] op_sel:[1,0,0] op_sel_hi:[1,1,1] neg_lo:[1,0,0] neg_hi:[1,0,0]
	v_pk_fma_f32 v[236:237], v[44:45], v[112:113], v[236:237] op_sel:[0,0,0] op_sel_hi:[0,1,1] neg_lo:[1,0,0] neg_hi:[1,0,0]
	v_pk_fma_f32 v[238:239], v[44:45], v[114:115], v[238:239] op_sel:[1,0,0] op_sel_hi:[1,1,1] neg_lo:[1,0,0] neg_hi:[1,0,0]
	ds_read_b128 v[42:45], v241 offset:10064
	s_waitcnt lgkmcnt(7)
	v_pk_fma_f32 v[160:161], v[46:47], v[116:117], v[160:161] op_sel:[0,0,0] op_sel_hi:[0,1,1] neg_lo:[1,0,0] neg_hi:[1,0,0]
	v_pk_fma_f32 v[234:235], v[46:47], v[118:119], v[234:235] op_sel:[1,0,0] op_sel_hi:[1,1,1] neg_lo:[1,0,0] neg_hi:[1,0,0]
	v_pk_fma_f32 v[236:237], v[48:49], v[152:153], v[236:237] op_sel:[0,0,0] op_sel_hi:[0,1,1] neg_lo:[1,0,0] neg_hi:[1,0,0]
	v_pk_fma_f32 v[238:239], v[48:49], v[154:155], v[238:239] op_sel:[1,0,0] op_sel_hi:[1,1,1] neg_lo:[1,0,0] neg_hi:[1,0,0]
	ds_read_b128 v[46:49], v241 offset:10080
	s_waitcnt lgkmcnt(7)
	v_pk_fma_f32 v[160:161], v[50:51], v[156:157], v[160:161] op_sel:[0,0,0] op_sel_hi:[0,1,1] neg_lo:[1,0,0] neg_hi:[1,0,0]
	v_pk_fma_f32 v[234:235], v[50:51], v[158:159], v[234:235] op_sel:[1,0,0] op_sel_hi:[1,1,1] neg_lo:[1,0,0] neg_hi:[1,0,0]
	v_pk_add_f32 v[236:237], v[160:161], v[236:237]
	v_pk_add_f32 v[236:237], v[236:237], v[238:239]
	v_pk_add_f32 v[160:161], v[236:237], v[234:235]
	ds_read_b128 v[50:53], v241 offset:10096
	s_waitcnt lgkmcnt(7)
; template <int DIR>
; __device__ __forceinline__ void dn_solve(const P& p, int task, int m0, int h, int t2, const bf16_t* kn_s, const bf16_t* v_s, const float* gc, const float* be, float* L) {
;     ...
; #pragma unroll
;     for (int cp = 1; cp < 64; ++cp) {
;         float a0 = 0.f, a1 = 0.f, a2 = 0.f, a3 = 0.f;
; #pragma unroll
;         for (int s4 = 0; s4 < cp; s4 += 4) { const f32x4 l4 = *(const f32x4*)(L + cp * 64 + s4); a0 += l4[0] * x[s4]; a1 += l4[1] * x[s4 + 1]; a2 += l4[2] * x[s4 + 2]; a3 += l4[3] * x[s4 + 3]; }
;         x[cp] -= (a0 + a1) + (a2 + a3);
;     }
	v_pk_fma_f32 v[162:163], v[2:3], v[6:7], v[162:163] op_sel:[0,0,0] op_sel_hi:[0,1,1] neg_lo:[1,0,0] neg_hi:[1,0,0]
	v_pk_mul_f32 v[234:235], v[2:3], v[54:55] op_sel:[1,0] op_sel_hi:[1,1] neg_lo:[1,0] neg_hi:[1,0]
	v_pk_mul_f32 v[236:237], v[4:5], v[56:57] op_sel:[0,0] op_sel_hi:[0,1] neg_lo:[1,0] neg_hi:[1,0]
	v_pk_mul_f32 v[238:239], v[4:5], v[58:59] op_sel:[1,0] op_sel_hi:[1,1] neg_lo:[1,0] neg_hi:[1,0]
	ds_read_b128 v[2:5], v241 offset:10112
	s_waitcnt lgkmcnt(7)
	v_pk_fma_f32 v[162:163], v[26:27], v[60:61], v[162:163] op_sel:[0,0,0] op_sel_hi:[0,1,1] neg_lo:[1,0,0] neg_hi:[1,0,0]
	v_pk_fma_f32 v[234:235], v[26:27], v[62:63], v[234:235] op_sel:[1,0,0] op_sel_hi:[1,1,1] neg_lo:[1,0,0] neg_hi:[1,0,0]
	v_pk_fma_f32 v[236:237], v[28:29], v[64:65], v[236:237] op_sel:[0,0,0] op_sel_hi:[0,1,1] neg_lo:[1,0,0] neg_hi:[1,0,0]
	v_pk_fma_f32 v[238:239], v[28:29], v[66:67], v[238:239] op_sel:[1,0,0] op_sel_hi:[1,1,1] neg_lo:[1,0,0] neg_hi:[1,0,0]
	ds_read_b128 v[26:29], v241 offset:10128
	s_waitcnt lgkmcnt(7)
	v_pk_fma_f32 v[162:163], v[30:31], v[68:69], v[162:163] op_sel:[0,0,0] op_sel_hi:[0,1,1] neg_lo:[1,0,0] neg_hi:[1,0,0]
	v_pk_fma_f32 v[234:235], v[30:31], v[70:71], v[234:235] op_sel:[1,0,0] op_sel_hi:[1,1,1] neg_lo:[1,0,0] neg_hi:[1,0,0]
	v_pk_fma_f32 v[236:237], v[32:33], v[72:73], v[236:237] op_sel:[0,0,0] op_sel_hi:[0,1,1] neg_lo:[1,0,0] neg_hi:[1,0,0]
	v_pk_fma_f32 v[238:239], v[32:33], v[74:75], v[238:239] op_sel:[1,0,0] op_sel_hi:[1,1,1] neg_lo:[1,0,0] neg_hi:[1,0,0]
	ds_read_b128 v[30:33], v241 offset:10240
	s_waitcnt lgkmcnt(7)
	v_pk_fma_f32 v[162:163], v[34:35], v[76:77], v[162:163] op_sel:[0,0,0] op_sel_hi:[0,1,1] neg_lo:[1,0,0] neg_hi:[1,0,0]
	v_pk_fma_f32 v[234:235], v[34:35], v[78:79], v[234:235] op_sel:[1,0,0] op_sel_hi:[1,1,1] neg_lo:[1,0,0] neg_hi:[1,0,0]
	v_pk_fma_f32 v[236:237], v[36:37], v[80:81], v[236:237] op_sel:[0,0,0] op_sel_hi:[0,1,1] neg_lo:[1,0,0] neg_hi:[1,0,0]
	v_pk_fma_f32 v[238:239], v[36:37], v[82:83], v[238:239] op_sel:[1,0,0] op_sel_hi:[1,1,1] neg_lo:[1,0,0] neg_hi:[1,0,0]
	ds_read_b128 v[34:37], v241 offset:10256
	s_waitcnt lgkmcnt(7)
	v_pk_fma_f32 v[162:163], v[38:39], v[84:85], v[162:163] op_sel:[0,0,0] op_sel_hi:[0,1,1] neg_lo:[1,0,0] neg_hi:[1,0,0]
	v_pk_fma_f32 v[234:235], v[38:39], v[86:87], v[234:235] op_sel:[1,0,0] op_sel_hi:[1,1,1] neg_lo:[1,0,0] neg_hi:[1,0,0]
	v_pk_fma_f32 v[236:237], v[40:41], v[88:89], v[236:237] op_sel:[0,0,0] op_sel_hi:[0,1,1] neg_lo:[1,0,0] neg_hi:[1,0,0]
	v_pk_fma_f32 v[238:239], v[40:41], v[90:91], v[238:239] op_sel:[1,0,0] op_sel_hi:[1,1,1] neg_lo:[1,0,0] neg_hi:[1,0,0]
	ds_read_b128 v[38:41], v241 offset:10272
	s_waitcnt lgkmcnt(7)
	v_pk_fma_f32 v[162:163], v[42:43], v[92:93], v[162:163] op_sel:[0,0,0] op_sel_hi:[0,1,1] neg_lo:[1,0,0] neg_hi:[1,0,0]
	v_pk_fma_f32 v[234:235], v[42:43], v[94:95], v[234:235] op_sel:[1,0,0] op_sel_hi:[1,1,1] neg_lo:[1,0,0] neg_hi:[1,0,0]
	v_pk_fma_f32 v[236:237], v[44:45], v[96:97], v[236:237] op_sel:[0,0,0] op_sel_hi:[0,1,1] neg_lo:[1,0,0] neg_hi:[1,0,0]
	v_pk_fma_f32 v[238:239], v[44:45], v[98:99], v[238:239] op_sel:[1,0,0] op_sel_hi:[1,1,1] neg_lo:[1,0,0] neg_hi:[1,0,0]
	ds_read_b128 v[42:45], v241 offset:10288
	s_waitcnt lgkmcnt(7)
	v_pk_fma_f32 v[162:163], v[46:47], v[100:101], v[162:163] op_sel:[0,0,0] op_sel_hi:[0,1,1] neg_lo:[1,0,0] neg_hi:[1,0,0]
	v_pk_fma_f32 v[234:235], v[46:47], v[102:103], v[234:235] op_sel:[1,0,0] op_sel_hi:[1,1,1] neg_lo:[1,0,0] neg_hi:[1,0,0]
	v_pk_fma_f32 v[236:237], v[48:49], v[104:105], v[236:237] op_sel:[0,0,0] op_sel_hi:[0,1,1] neg_lo:[1,0,0] neg_hi:[1,0,0]
	v_pk_fma_f32 v[238:239], v[48:49], v[106:107], v[238:239] op_sel:[1,0,0] op_sel_hi:[1,1,1] neg_lo:[1,0,0] neg_hi:[1,0,0]
	ds_read_b128 v[46:49], v241 offset:10304
	s_waitcnt lgkmcnt(7)
	v_pk_fma_f32 v[162:163], v[50:51], v[108:109], v[162:163] op_sel:[0,0,0] op_sel_hi:[0,1,1] neg_lo:[1,0,0] neg_hi:[1,0,0]
	v_pk_fma_f32 v[234:235], v[50:51], v[110:111], v[234:235] op_sel:[1,0,0] op_sel_hi:[1,1,1] neg_lo:[1,0,0] neg_hi:[1,0,0]
	v_pk_fma_f32 v[236:237], v[52:53], v[112:113], v[236:237] op_sel:[0,0,0] op_sel_hi:[0,1,1] neg_lo:[1,0,0] neg_hi:[1,0,0]
	v_pk_fma_f32 v[238:239], v[52:53], v[114:115], v[238:239] op_sel:[1,0,0] op_sel_hi:[1,1,1] neg_lo:[1,0,0] neg_hi:[1,0,0]
	ds_read_b128 v[50:53], v241 offset:10320
	s_waitcnt lgkmcnt(7)
	v_pk_fma_f32 v[162:163], v[2:3], v[116:117], v[162:163] op_sel:[0,0,0] op_sel_hi:[0,1,1] neg_lo:[1,0,0] neg_hi:[1,0,0]
	v_pk_fma_f32 v[234:235], v[2:3], v[118:119], v[234:235] op_sel:[1,0,0] op_sel_hi:[1,1,1] neg_lo:[1,0,0] neg_hi:[1,0,0]
	v_pk_fma_f32 v[236:237], v[4:5], v[152:153], v[236:237] op_sel:[0,0,0] op_sel_hi:[0,1,1] neg_lo:[1,0,0] neg_hi:[1,0,0]
	v_pk_fma_f32 v[238:239], v[4:5], v[154:155], v[238:239] op_sel:[1,0,0] op_sel_hi:[1,1,1] neg_lo:[1,0,0] neg_hi:[1,0,0]
	ds_read_b128 v[2:5], v241 offset:10336
	s_waitcnt lgkmcnt(7)
	v_pk_fma_f32 v[162:163], v[26:27], v[156:157], v[162:163] op_sel:[0,0,0] op_sel_hi:[0,1,1] neg_lo:[1,0,0] neg_hi:[1,0,0]
	v_pk_fma_f32 v[234:235], v[26:27], v[158:159], v[234:235] op_sel:[1,0,0] op_sel_hi:[1,1,1] neg_lo:[1,0,0] neg_hi:[1,0,0]
	v_pk_fma_f32 v[236:237], v[28:29], v[160:161], v[236:237] op_sel:[0,0,0] op_sel_hi:[0,1,1] neg_lo:[1,0,0] neg_hi:[1,0,0]
	v_pk_add_f32 v[234:235], v[162:163], v[234:235]
	v_pk_add_f32 v[234:235], v[234:235], v[238:239]
	v_pk_add_f32 v[162:163], v[234:235], v[236:237]
	ds_read_b128 v[26:29], v241 offset:10352
	s_waitcnt lgkmcnt(7)
; template <int DIR>
; __device__ __forceinline__ void dn_solve(const P& p, int task, int m0, int h, int t2, const bf16_t* kn_s, const bf16_t* v_s, const float* gc, const float* be, float* L) {
;     ...
; #pragma unroll
;     for (int cp = 1; cp < 64; ++cp) {
;         float a0 = 0.f, a1 = 0.f, a2 = 0.f, a3 = 0.f;
; #pragma unroll
;         for (int s4 = 0; s4 < cp; s4 += 4) { const f32x4 l4 = *(const f32x4*)(L + cp * 64 + s4); a0 += l4[0] * x[s4]; a1 += l4[1] * x[s4 + 1]; a2 += l4[2] * x[s4 + 2]; a3 += l4[3] * x[s4 + 3]; }
;         x[cp] -= (a0 + a1) + (a2 + a3);
;     }
	v_pk_fma_f32 v[164:165], v[30:31], v[6:7], v[164:165] op_sel:[0,0,0] op_sel_hi:[0,1,1] neg_lo:[1,0,0] neg_hi:[1,0,0]
	v_pk_mul_f32 v[234:235], v[30:31], v[54:55] op_sel:[1,0] op_sel_hi:[1,1] neg_lo:[1,0] neg_hi:[1,0]
	v_pk_mul_f32 v[236:237], v[32:33], v[56:57] op_sel:[0,0] op_sel_hi:[0,1] neg_lo:[1,0] neg_hi:[1,0]
	v_pk_mul_f32 v[238:239], v[32:33], v[58:59] op_sel:[1,0] op_sel_hi:[1,1] neg_lo:[1,0] neg_hi:[1,0]
	ds_read_b128 v[30:33], v241 offset:10368
	s_waitcnt lgkmcnt(7)
	v_pk_fma_f32 v[164:165], v[34:35], v[60:61], v[164:165] op_sel:[0,0,0] op_sel_hi:[0,1,1] neg_lo:[1,0,0] neg_hi:[1,0,0]
	v_pk_fma_f32 v[234:235], v[34:35], v[62:63], v[234:235] op_sel:[1,0,0] op_sel_hi:[1,1,1] neg_lo:[1,0,0] neg_hi:[1,0,0]
	v_pk_fma_f32 v[236:237], v[36:37], v[64:65], v[236:237] op_sel:[0,0,0] op_sel_hi:[0,1,1] neg_lo:[1,0,0] neg_hi:[1,0,0]
	v_pk_fma_f32 v[238:239], v[36:37], v[66:67], v[238:239] op_sel:[1,0,0] op_sel_hi:[1,1,1] neg_lo:[1,0,0] neg_hi:[1,0,0]
	ds_read_b128 v[34:37], v241 offset:10384
	s_waitcnt lgkmcnt(7)
	v_pk_fma_f32 v[164:165], v[38:39], v[68:69], v[164:165] op_sel:[0,0,0] op_sel_hi:[0,1,1] neg_lo:[1,0,0] neg_hi:[1,0,0]
	v_pk_fma_f32 v[234:235], v[38:39], v[70:71], v[234:235] op_sel:[1,0,0] op_sel_hi:[1,1,1] neg_lo:[1,0,0] neg_hi:[1,0,0]
	v_pk_fma_f32 v[236:237], v[40:41], v[72:73], v[236:237] op_sel:[0,0,0] op_sel_hi:[0,1,1] neg_lo:[1,0,0] neg_hi:[1,0,0]
	v_pk_fma_f32 v[238:239], v[40:41], v[74:75], v[238:239] op_sel:[1,0,0] op_sel_hi:[1,1,1] neg_lo:[1,0,0] neg_hi:[1,0,0]
	ds_read_b128 v[38:41], v241 offset:10496
	s_waitcnt lgkmcnt(7)
	v_pk_fma_f32 v[164:165], v[42:43], v[76:77], v[164:165] op_sel:[0,0,0] op_sel_hi:[0,1,1] neg_lo:[1,0,0] neg_hi:[1,0,0]
	v_pk_fma_f32 v[234:235], v[42:43], v[78:79], v[234:235] op_sel:[1,0,0] op_sel_hi:[1,1,1] neg_lo:[1,0,0] neg_hi:[1,0,0]
	v_pk_fma_f32 v[236:237], v[44:45], v[80:81], v[236:237] op_sel:[0,0,0] op_sel_hi:[0,1,1] neg_lo:[1,0,0] neg_hi:[1,0,0]
	v_pk_fma_f32 v[238:239], v[44:45], v[82:83], v[238:239] op_sel:[1,0,0] op_sel_hi:[1,1,1] neg_lo:[1,0,0] neg_hi:[1,0,0]
	ds_read_b128 v[42:45], v241 offset:10512
	s_waitcnt lgkmcnt(7)
	v_pk_fma_f32 v[164:165], v[46:47], v[84:85], v[164:165] op_sel:[0,0,0] op_sel_hi:[0,1,1] neg_lo:[1,0,0] neg_hi:[1,0,0]
	v_pk_fma_f32 v[234:235], v[46:47], v[86:87], v[234:235] op_sel:[1,0,0] op_sel_hi:[1,1,1] neg_lo:[1,0,0] neg_hi:[1,0,0]
	v_pk_fma_f32 v[236:237], v[48:49], v[88:89], v[236:237] op_sel:[0,0,0] op_sel_hi:[0,1,1] neg_lo:[1,0,0] neg_hi:[1,0,0]
	v_pk_fma_f32 v[238:239], v[48:49], v[90:91], v[238:239] op_sel:[1,0,0] op_sel_hi:[1,1,1] neg_lo:[1,0,0] neg_hi:[1,0,0]
	ds_read_b128 v[46:49], v241 offset:10528
	s_waitcnt lgkmcnt(7)
	v_pk_fma_f32 v[164:165], v[50:51], v[92:93], v[164:165] op_sel:[0,0,0] op_sel_hi:[0,1,1] neg_lo:[1,0,0] neg_hi:[1,0,0]
	v_pk_fma_f32 v[234:235], v[50:51], v[94:95], v[234:235] op_sel:[1,0,0] op_sel_hi:[1,1,1] neg_lo:[1,0,0] neg_hi:[1,0,0]
	v_pk_fma_f32 v[236:237], v[52:53], v[96:97], v[236:237] op_sel:[0,0,0] op_sel_hi:[0,1,1] neg_lo:[1,0,0] neg_hi:[1,0,0]
	v_pk_fma_f32 v[238:239], v[52:53], v[98:99], v[238:239] op_sel:[1,0,0] op_sel_hi:[1,1,1] neg_lo:[1,0,0] neg_hi:[1,0,0]
	ds_read_b128 v[50:53], v241 offset:10544
	s_waitcnt lgkmcnt(7)
	v_pk_fma_f32 v[164:165], v[2:3], v[100:101], v[164:165] op_sel:[0,0,0] op_sel_hi:[0,1,1] neg_lo:[1,0,0] neg_hi:[1,0,0]
	v_pk_fma_f32 v[234:235], v[2:3], v[102:103], v[234:235] op_sel:[1,0,0] op_sel_hi:[1,1,1] neg_lo:[1,0,0] neg_hi:[1,0,0]
	v_pk_fma_f32 v[236:237], v[4:5], v[104:105], v[236:237] op_sel:[0,0,0] op_sel_hi:[0,1,1] neg_lo:[1,0,0] neg_hi:[1,0,0]
	v_pk_fma_f32 v[238:239], v[4:5], v[106:107], v[238:239] op_sel:[1,0,0] op_sel_hi:[1,1,1] neg_lo:[1,0,0] neg_hi:[1,0,0]
	ds_read_b128 v[2:5], v241 offset:10560
	s_waitcnt lgkmcnt(7)
	v_pk_fma_f32 v[164:165], v[26:27], v[108:109], v[164:165] op_sel:[0,0,0] op_sel_hi:[0,1,1] neg_lo:[1,0,0] neg_hi:[1,0,0]
	v_pk_fma_f32 v[234:235], v[26:27], v[110:111], v[234:235] op_sel:[1,0,0] op_sel_hi:[1,1,1] neg_lo:[1,0,0] neg_hi:[1,0,0]
	v_pk_fma_f32 v[236:237], v[28:29], v[112:113], v[236:237] op_sel:[0,0,0] op_sel_hi:[0,1,1] neg_lo:[1,0,0] neg_hi:[1,0,0]
	v_pk_fma_f32 v[238:239], v[28:29], v[114:115], v[238:239] op_sel:[1,0,0] op_sel_hi:[1,1,1] neg_lo:[1,0,0] neg_hi:[1,0,0]
	ds_read_b128 v[26:29], v241 offset:10576
	s_waitcnt lgkmcnt(7)
	v_pk_fma_f32 v[164:165], v[30:31], v[116:117], v[164:165] op_sel:[0,0,0] op_sel_hi:[0,1,1] neg_lo:[1,0,0] neg_hi:[1,0,0]
	v_pk_fma_f32 v[234:235], v[30:31], v[118:119], v[234:235] op_sel:[1,0,0] op_sel_hi:[1,1,1] neg_lo:[1,0,0] neg_hi:[1,0,0]
	v_pk_fma_f32 v[236:237], v[32:33], v[152:153], v[236:237] op_sel:[0,0,0] op_sel_hi:[0,1,1] neg_lo:[1,0,0] neg_hi:[1,0,0]
	v_pk_fma_f32 v[238:239], v[32:33], v[154:155], v[238:239] op_sel:[1,0,0] op_sel_hi:[1,1,1] neg_lo:[1,0,0] neg_hi:[1,0,0]
	ds_read_b128 v[30:33], v241 offset:10592
	s_waitcnt lgkmcnt(7)
	v_pk_fma_f32 v[164:165], v[34:35], v[156:157], v[164:165] op_sel:[0,0,0] op_sel_hi:[0,1,1] neg_lo:[1,0,0] neg_hi:[1,0,0]
	v_pk_fma_f32 v[234:235], v[34:35], v[158:159], v[234:235] op_sel:[1,0,0] op_sel_hi:[1,1,1] neg_lo:[1,0,0] neg_hi:[1,0,0]
	v_pk_fma_f32 v[236:237], v[36:37], v[160:161], v[236:237] op_sel:[0,0,0] op_sel_hi:[0,1,1] neg_lo:[1,0,0] neg_hi:[1,0,0]
	v_pk_fma_f32 v[238:239], v[36:37], v[162:163], v[238:239] op_sel:[1,0,0] op_sel_hi:[1,1,1] neg_lo:[1,0,0] neg_hi:[1,0,0]
	v_pk_add_f32 v[234:235], v[164:165], v[234:235]
	v_pk_add_f32 v[234:235], v[234:235], v[236:237]
	v_pk_add_f32 v[164:165], v[234:235], v[238:239]
	ds_read_b128 v[34:37], v241 offset:10608
	s_waitcnt lgkmcnt(7)
; template <int DIR>
; __device__ __forceinline__ void dn_solve(const P& p, int task, int m0, int h, int t2, const bf16_t* kn_s, const bf16_t* v_s, const float* gc, const float* be, float* L) {
;     ...
; #pragma unroll
;     for (int cp = 1; cp < 64; ++cp) {
;         float a0 = 0.f, a1 = 0.f, a2 = 0.f, a3 = 0.f;
; #pragma unroll
;         for (int s4 = 0; s4 < cp; s4 += 4) { const f32x4 l4 = *(const f32x4*)(L + cp * 64 + s4); a0 += l4[0] * x[s4]; a1 += l4[1] * x[s4 + 1]; a2 += l4[2] * x[s4 + 2]; a3 += l4[3] * x[s4 + 3]; }
;         x[cp] -= (a0 + a1) + (a2 + a3);
;     }
	v_pk_fma_f32 v[166:167], v[38:39], v[6:7], v[166:167] op_sel:[0,0,0] op_sel_hi:[0,1,1] neg_lo:[1,0,0] neg_hi:[1,0,0]
	v_pk_mul_f32 v[234:235], v[38:39], v[54:55] op_sel:[1,0] op_sel_hi:[1,1] neg_lo:[1,0] neg_hi:[1,0]
	v_pk_mul_f32 v[236:237], v[40:41], v[56:57] op_sel:[0,0] op_sel_hi:[0,1] neg_lo:[1,0] neg_hi:[1,0]
	v_pk_mul_f32 v[238:239], v[40:41], v[58:59] op_sel:[1,0] op_sel_hi:[1,1] neg_lo:[1,0] neg_hi:[1,0]
	ds_read_b128 v[38:41], v241 offset:10624
	s_waitcnt lgkmcnt(7)
	v_pk_fma_f32 v[166:167], v[42:43], v[60:61], v[166:167] op_sel:[0,0,0] op_sel_hi:[0,1,1] neg_lo:[1,0,0] neg_hi:[1,0,0]
	v_pk_fma_f32 v[234:235], v[42:43], v[62:63], v[234:235] op_sel:[1,0,0] op_sel_hi:[1,1,1] neg_lo:[1,0,0] neg_hi:[1,0,0]
	v_pk_fma_f32 v[236:237], v[44:45], v[64:65], v[236:237] op_sel:[0,0,0] op_sel_hi:[0,1,1] neg_lo:[1,0,0] neg_hi:[1,0,0]
	v_pk_fma_f32 v[238:239], v[44:45], v[66:67], v[238:239] op_sel:[1,0,0] op_sel_hi:[1,1,1] neg_lo:[1,0,0] neg_hi:[1,0,0]
	ds_read_b128 v[42:45], v241 offset:10640
	s_waitcnt lgkmcnt(7)
	v_pk_fma_f32 v[166:167], v[46:47], v[68:69], v[166:167] op_sel:[0,0,0] op_sel_hi:[0,1,1] neg_lo:[1,0,0] neg_hi:[1,0,0]
	v_pk_fma_f32 v[234:235], v[46:47], v[70:71], v[234:235] op_sel:[1,0,0] op_sel_hi:[1,1,1] neg_lo:[1,0,0] neg_hi:[1,0,0]
	v_pk_fma_f32 v[236:237], v[48:49], v[72:73], v[236:237] op_sel:[0,0,0] op_sel_hi:[0,1,1] neg_lo:[1,0,0] neg_hi:[1,0,0]
	v_pk_fma_f32 v[238:239], v[48:49], v[74:75], v[238:239] op_sel:[1,0,0] op_sel_hi:[1,1,1] neg_lo:[1,0,0] neg_hi:[1,0,0]
	ds_read_b128 v[46:49], v241 offset:10656
	s_waitcnt lgkmcnt(7)
	v_pk_fma_f32 v[166:167], v[50:51], v[76:77], v[166:167] op_sel:[0,0,0] op_sel_hi:[0,1,1] neg_lo:[1,0,0] neg_hi:[1,0,0]
	v_pk_fma_f32 v[234:235], v[50:51], v[78:79], v[234:235] op_sel:[1,0,0] op_sel_hi:[1,1,1] neg_lo:[1,0,0] neg_hi:[1,0,0]
	v_pk_fma_f32 v[236:237], v[52:53], v[80:81], v[236:237] op_sel:[0,0,0] op_sel_hi:[0,1,1] neg_lo:[1,0,0] neg_hi:[1,0,0]
	v_pk_fma_f32 v[238:239], v[52:53], v[82:83], v[238:239] op_sel:[1,0,0] op_sel_hi:[1,1,1] neg_lo:[1,0,0] neg_hi:[1,0,0]
	ds_read_b128 v[50:53], v241 offset:10752
	s_waitcnt lgkmcnt(7)
	v_pk_fma_f32 v[166:167], v[2:3], v[84:85], v[166:167] op_sel:[0,0,0] op_sel_hi:[0,1,1] neg_lo:[1,0,0] neg_hi:[1,0,0]
	v_pk_fma_f32 v[234:235], v[2:3], v[86:87], v[234:235] op_sel:[1,0,0] op_sel_hi:[1,1,1] neg_lo:[1,0,0] neg_hi:[1,0,0]
	v_pk_fma_f32 v[236:237], v[4:5], v[88:89], v[236:237] op_sel:[0,0,0] op_sel_hi:[0,1,1] neg_lo:[1,0,0] neg_hi:[1,0,0]
	v_pk_fma_f32 v[238:239], v[4:5], v[90:91], v[238:239] op_sel:[1,0,0] op_sel_hi:[1,1,1] neg_lo:[1,0,0] neg_hi:[1,0,0]
	ds_read_b128 v[2:5], v241 offset:10768
	s_waitcnt lgkmcnt(7)
	v_pk_fma_f32 v[166:167], v[26:27], v[92:93], v[166:167] op_sel:[0,0,0] op_sel_hi:[0,1,1] neg_lo:[1,0,0] neg_hi:[1,0,0]
	v_pk_fma_f32 v[234:235], v[26:27], v[94:95], v[234:235] op_sel:[1,0,0] op_sel_hi:[1,1,1] neg_lo:[1,0,0] neg_hi:[1,0,0]
	v_pk_fma_f32 v[236:237], v[28:29], v[96:97], v[236:237] op_sel:[0,0,0] op_sel_hi:[0,1,1] neg_lo:[1,0,0] neg_hi:[1,0,0]
	v_pk_fma_f32 v[238:239], v[28:29], v[98:99], v[238:239] op_sel:[1,0,0] op_sel_hi:[1,1,1] neg_lo:[1,0,0] neg_hi:[1,0,0]
	ds_read_b128 v[26:29], v241 offset:10784
	s_waitcnt lgkmcnt(7)
	v_pk_fma_f32 v[166:167], v[30:31], v[100:101], v[166:167] op_sel:[0,0,0] op_sel_hi:[0,1,1] neg_lo:[1,0,0] neg_hi:[1,0,0]
	v_pk_fma_f32 v[234:235], v[30:31], v[102:103], v[234:235] op_sel:[1,0,0] op_sel_hi:[1,1,1] neg_lo:[1,0,0] neg_hi:[1,0,0]
	v_pk_fma_f32 v[236:237], v[32:33], v[104:105], v[236:237] op_sel:[0,0,0] op_sel_hi:[0,1,1] neg_lo:[1,0,0] neg_hi:[1,0,0]
	v_pk_fma_f32 v[238:239], v[32:33], v[106:107], v[238:239] op_sel:[1,0,0] op_sel_hi:[1,1,1] neg_lo:[1,0,0] neg_hi:[1,0,0]
	ds_read_b128 v[30:33], v241 offset:10800
	s_waitcnt lgkmcnt(7)
	v_pk_fma_f32 v[166:167], v[34:35], v[108:109], v[166:167] op_sel:[0,0,0] op_sel_hi:[0,1,1] neg_lo:[1,0,0] neg_hi:[1,0,0]
	v_pk_fma_f32 v[234:235], v[34:35], v[110:111], v[234:235] op_sel:[1,0,0] op_sel_hi:[1,1,1] neg_lo:[1,0,0] neg_hi:[1,0,0]
	v_pk_fma_f32 v[236:237], v[36:37], v[112:113], v[236:237] op_sel:[0,0,0] op_sel_hi:[0,1,1] neg_lo:[1,0,0] neg_hi:[1,0,0]
	v_pk_fma_f32 v[238:239], v[36:37], v[114:115], v[238:239] op_sel:[1,0,0] op_sel_hi:[1,1,1] neg_lo:[1,0,0] neg_hi:[1,0,0]
	ds_read_b128 v[34:37], v241 offset:10816
	s_waitcnt lgkmcnt(7)
	v_pk_fma_f32 v[166:167], v[38:39], v[116:117], v[166:167] op_sel:[0,0,0] op_sel_hi:[0,1,1] neg_lo:[1,0,0] neg_hi:[1,0,0]
	v_pk_fma_f32 v[234:235], v[38:39], v[118:119], v[234:235] op_sel:[1,0,0] op_sel_hi:[1,1,1] neg_lo:[1,0,0] neg_hi:[1,0,0]
	v_pk_fma_f32 v[236:237], v[40:41], v[152:153], v[236:237] op_sel:[0,0,0] op_sel_hi:[0,1,1] neg_lo:[1,0,0] neg_hi:[1,0,0]
	v_pk_fma_f32 v[238:239], v[40:41], v[154:155], v[238:239] op_sel:[1,0,0] op_sel_hi:[1,1,1] neg_lo:[1,0,0] neg_hi:[1,0,0]
	ds_read_b128 v[38:41], v241 offset:10832
	s_waitcnt lgkmcnt(7)
	v_pk_fma_f32 v[166:167], v[42:43], v[156:157], v[166:167] op_sel:[0,0,0] op_sel_hi:[0,1,1] neg_lo:[1,0,0] neg_hi:[1,0,0]
	v_pk_fma_f32 v[234:235], v[42:43], v[158:159], v[234:235] op_sel:[1,0,0] op_sel_hi:[1,1,1] neg_lo:[1,0,0] neg_hi:[1,0,0]
	v_pk_fma_f32 v[236:237], v[44:45], v[160:161], v[236:237] op_sel:[0,0,0] op_sel_hi:[0,1,1] neg_lo:[1,0,0] neg_hi:[1,0,0]
	v_pk_fma_f32 v[238:239], v[44:45], v[162:163], v[238:239] op_sel:[1,0,0] op_sel_hi:[1,1,1] neg_lo:[1,0,0] neg_hi:[1,0,0]
	ds_read_b128 v[42:45], v241 offset:10848
	s_waitcnt lgkmcnt(7)
	v_pk_fma_f32 v[166:167], v[46:47], v[164:165], v[166:167] op_sel:[0,0,0] op_sel_hi:[0,1,1] neg_lo:[1,0,0] neg_hi:[1,0,0]
	v_pk_add_f32 v[234:235], v[234:235], v[236:237]
	v_pk_add_f32 v[234:235], v[234:235], v[238:239]
	v_pk_add_f32 v[166:167], v[234:235], v[166:167]
	ds_read_b128 v[46:49], v241 offset:10864
	s_waitcnt lgkmcnt(7)
; template <int DIR>
; __device__ __forceinline__ void dn_solve(const P& p, int task, int m0, int h, int t2, const bf16_t* kn_s, const bf16_t* v_s, const float* gc, const float* be, float* L) {
;     ...
; #pragma unroll
;     for (int cp = 1; cp < 64; ++cp) {
;         float a0 = 0.f, a1 = 0.f, a2 = 0.f, a3 = 0.f;
; #pragma unroll
;         for (int s4 = 0; s4 < cp; s4 += 4) { const f32x4 l4 = *(const f32x4*)(L + cp * 64 + s4); a0 += l4[0] * x[s4]; a1 += l4[1] * x[s4 + 1]; a2 += l4[2] * x[s4 + 2]; a3 += l4[3] * x[s4 + 3]; }
;         x[cp] -= (a0 + a1) + (a2 + a3);
;     }
	v_pk_fma_f32 v[168:169], v[50:51], v[6:7], v[168:169] op_sel:[0,0,0] op_sel_hi:[0,1,1] neg_lo:[1,0,0] neg_hi:[1,0,0]
	v_pk_mul_f32 v[234:235], v[50:51], v[54:55] op_sel:[1,0] op_sel_hi:[1,1] neg_lo:[1,0] neg_hi:[1,0]
	v_pk_mul_f32 v[236:237], v[52:53], v[56:57] op_sel:[0,0] op_sel_hi:[0,1] neg_lo:[1,0] neg_hi:[1,0]
	v_pk_mul_f32 v[238:239], v[52:53], v[58:59] op_sel:[1,0] op_sel_hi:[1,1] neg_lo:[1,0] neg_hi:[1,0]
	ds_read_b128 v[50:53], v241 offset:10880
	s_waitcnt lgkmcnt(7)
	v_pk_fma_f32 v[168:169], v[2:3], v[60:61], v[168:169] op_sel:[0,0,0] op_sel_hi:[0,1,1] neg_lo:[1,0,0] neg_hi:[1,0,0]
	v_pk_fma_f32 v[234:235], v[2:3], v[62:63], v[234:235] op_sel:[1,0,0] op_sel_hi:[1,1,1] neg_lo:[1,0,0] neg_hi:[1,0,0]
	v_pk_fma_f32 v[236:237], v[4:5], v[64:65], v[236:237] op_sel:[0,0,0] op_sel_hi:[0,1,1] neg_lo:[1,0,0] neg_hi:[1,0,0]
	v_pk_fma_f32 v[238:239], v[4:5], v[66:67], v[238:239] op_sel:[1,0,0] op_sel_hi:[1,1,1] neg_lo:[1,0,0] neg_hi:[1,0,0]
	ds_read_b128 v[2:5], v241 offset:10896
	s_waitcnt lgkmcnt(7)
	v_pk_fma_f32 v[168:169], v[26:27], v[68:69], v[168:169] op_sel:[0,0,0] op_sel_hi:[0,1,1] neg_lo:[1,0,0] neg_hi:[1,0,0]
	v_pk_fma_f32 v[234:235], v[26:27], v[70:71], v[234:235] op_sel:[1,0,0] op_sel_hi:[1,1,1] neg_lo:[1,0,0] neg_hi:[1,0,0]
	v_pk_fma_f32 v[236:237], v[28:29], v[72:73], v[236:237] op_sel:[0,0,0] op_sel_hi:[0,1,1] neg_lo:[1,0,0] neg_hi:[1,0,0]
	v_pk_fma_f32 v[238:239], v[28:29], v[74:75], v[238:239] op_sel:[1,0,0] op_sel_hi:[1,1,1] neg_lo:[1,0,0] neg_hi:[1,0,0]
	ds_read_b128 v[26:29], v241 offset:10912
	s_waitcnt lgkmcnt(7)
	v_pk_fma_f32 v[168:169], v[30:31], v[76:77], v[168:169] op_sel:[0,0,0] op_sel_hi:[0,1,1] neg_lo:[1,0,0] neg_hi:[1,0,0]
	v_pk_fma_f32 v[234:235], v[30:31], v[78:79], v[234:235] op_sel:[1,0,0] op_sel_hi:[1,1,1] neg_lo:[1,0,0] neg_hi:[1,0,0]
	v_pk_fma_f32 v[236:237], v[32:33], v[80:81], v[236:237] op_sel:[0,0,0] op_sel_hi:[0,1,1] neg_lo:[1,0,0] neg_hi:[1,0,0]
	v_pk_fma_f32 v[238:239], v[32:33], v[82:83], v[238:239] op_sel:[1,0,0] op_sel_hi:[1,1,1] neg_lo:[1,0,0] neg_hi:[1,0,0]
	ds_read_b128 v[30:33], v241 offset:11008
	s_waitcnt lgkmcnt(7)
	v_pk_fma_f32 v[168:169], v[34:35], v[84:85], v[168:169] op_sel:[0,0,0] op_sel_hi:[0,1,1] neg_lo:[1,0,0] neg_hi:[1,0,0]
	v_pk_fma_f32 v[234:235], v[34:35], v[86:87], v[234:235] op_sel:[1,0,0] op_sel_hi:[1,1,1] neg_lo:[1,0,0] neg_hi:[1,0,0]
	v_pk_fma_f32 v[236:237], v[36:37], v[88:89], v[236:237] op_sel:[0,0,0] op_sel_hi:[0,1,1] neg_lo:[1,0,0] neg_hi:[1,0,0]
	v_pk_fma_f32 v[238:239], v[36:37], v[90:91], v[238:239] op_sel:[1,0,0] op_sel_hi:[1,1,1] neg_lo:[1,0,0] neg_hi:[1,0,0]
	ds_read_b128 v[34:37], v241 offset:11024
	s_waitcnt lgkmcnt(7)
	v_pk_fma_f32 v[168:169], v[38:39], v[92:93], v[168:169] op_sel:[0,0,0] op_sel_hi:[0,1,1] neg_lo:[1,0,0] neg_hi:[1,0,0]
	v_pk_fma_f32 v[234:235], v[38:39], v[94:95], v[234:235] op_sel:[1,0,0] op_sel_hi:[1,1,1] neg_lo:[1,0,0] neg_hi:[1,0,0]
	v_pk_fma_f32 v[236:237], v[40:41], v[96:97], v[236:237] op_sel:[0,0,0] op_sel_hi:[0,1,1] neg_lo:[1,0,0] neg_hi:[1,0,0]
	v_pk_fma_f32 v[238:239], v[40:41], v[98:99], v[238:239] op_sel:[1,0,0] op_sel_hi:[1,1,1] neg_lo:[1,0,0] neg_hi:[1,0,0]
	ds_read_b128 v[38:41], v241 offset:11040
	s_waitcnt lgkmcnt(7)
	v_pk_fma_f32 v[168:169], v[42:43], v[100:101], v[168:169] op_sel:[0,0,0] op_sel_hi:[0,1,1] neg_lo:[1,0,0] neg_hi:[1,0,0]
	v_pk_fma_f32 v[234:235], v[42:43], v[102:103], v[234:235] op_sel:[1,0,0] op_sel_hi:[1,1,1] neg_lo:[1,0,0] neg_hi:[1,0,0]
	v_pk_fma_f32 v[236:237], v[44:45], v[104:105], v[236:237] op_sel:[0,0,0] op_sel_hi:[0,1,1] neg_lo:[1,0,0] neg_hi:[1,0,0]
	v_pk_fma_f32 v[238:239], v[44:45], v[106:107], v[238:239] op_sel:[1,0,0] op_sel_hi:[1,1,1] neg_lo:[1,0,0] neg_hi:[1,0,0]
	ds_read_b128 v[42:45], v241 offset:11056
	s_waitcnt lgkmcnt(7)
	v_pk_fma_f32 v[168:169], v[46:47], v[108:109], v[168:169] op_sel:[0,0,0] op_sel_hi:[0,1,1] neg_lo:[1,0,0] neg_hi:[1,0,0]
	v_pk_fma_f32 v[234:235], v[46:47], v[110:111], v[234:235] op_sel:[1,0,0] op_sel_hi:[1,1,1] neg_lo:[1,0,0] neg_hi:[1,0,0]
	v_pk_fma_f32 v[236:237], v[48:49], v[112:113], v[236:237] op_sel:[0,0,0] op_sel_hi:[0,1,1] neg_lo:[1,0,0] neg_hi:[1,0,0]
	v_pk_fma_f32 v[238:239], v[48:49], v[114:115], v[238:239] op_sel:[1,0,0] op_sel_hi:[1,1,1] neg_lo:[1,0,0] neg_hi:[1,0,0]
	ds_read_b128 v[46:49], v241 offset:11072
	s_waitcnt lgkmcnt(7)
	v_pk_fma_f32 v[168:169], v[50:51], v[116:117], v[168:169] op_sel:[0,0,0] op_sel_hi:[0,1,1] neg_lo:[1,0,0] neg_hi:[1,0,0]
	v_pk_fma_f32 v[234:235], v[50:51], v[118:119], v[234:235] op_sel:[1,0,0] op_sel_hi:[1,1,1] neg_lo:[1,0,0] neg_hi:[1,0,0]
	v_pk_fma_f32 v[236:237], v[52:53], v[152:153], v[236:237] op_sel:[0,0,0] op_sel_hi:[0,1,1] neg_lo:[1,0,0] neg_hi:[1,0,0]
	v_pk_fma_f32 v[238:239], v[52:53], v[154:155], v[238:239] op_sel:[1,0,0] op_sel_hi:[1,1,1] neg_lo:[1,0,0] neg_hi:[1,0,0]
	ds_read_b128 v[50:53], v241 offset:11088
	s_waitcnt lgkmcnt(7)
	v_pk_fma_f32 v[168:169], v[2:3], v[156:157], v[168:169] op_sel:[0,0,0] op_sel_hi:[0,1,1] neg_lo:[1,0,0] neg_hi:[1,0,0]
	v_pk_fma_f32 v[234:235], v[2:3], v[158:159], v[234:235] op_sel:[1,0,0] op_sel_hi:[1,1,1] neg_lo:[1,0,0] neg_hi:[1,0,0]
	v_pk_fma_f32 v[236:237], v[4:5], v[160:161], v[236:237] op_sel:[0,0,0] op_sel_hi:[0,1,1] neg_lo:[1,0,0] neg_hi:[1,0,0]
	v_pk_fma_f32 v[238:239], v[4:5], v[162:163], v[238:239] op_sel:[1,0,0] op_sel_hi:[1,1,1] neg_lo:[1,0,0] neg_hi:[1,0,0]
	ds_read_b128 v[2:5], v241 offset:11104
	s_waitcnt lgkmcnt(7)
	v_pk_fma_f32 v[168:169], v[26:27], v[164:165], v[168:169] op_sel:[0,0,0] op_sel_hi:[0,1,1] neg_lo:[1,0,0] neg_hi:[1,0,0]
	v_pk_fma_f32 v[234:235], v[26:27], v[166:167], v[234:235] op_sel:[1,0,0] op_sel_hi:[1,1,1] neg_lo:[1,0,0] neg_hi:[1,0,0]
	v_pk_add_f32 v[236:237], v[168:169], v[236:237]
	v_pk_add_f32 v[236:237], v[236:237], v[238:239]
	v_pk_add_f32 v[168:169], v[236:237], v[234:235]
	ds_read_b128 v[26:29], v241 offset:11120
	s_waitcnt lgkmcnt(7)
; template <int DIR>
; __device__ __forceinline__ void dn_solve(const P& p, int task, int m0, int h, int t2, const bf16_t* kn_s, const bf16_t* v_s, const float* gc, const float* be, float* L) {
;     ...
; #pragma unroll
;     for (int cp = 1; cp < 64; ++cp) {
;         float a0 = 0.f, a1 = 0.f, a2 = 0.f, a3 = 0.f;
; #pragma unroll
;         for (int s4 = 0; s4 < cp; s4 += 4) { const f32x4 l4 = *(const f32x4*)(L + cp * 64 + s4); a0 += l4[0] * x[s4]; a1 += l4[1] * x[s4 + 1]; a2 += l4[2] * x[s4 + 2]; a3 += l4[3] * x[s4 + 3]; }
;         x[cp] -= (a0 + a1) + (a2 + a3);
;     }
	v_pk_fma_f32 v[170:171], v[30:31], v[6:7], v[170:171] op_sel:[0,0,0] op_sel_hi:[0,1,1] neg_lo:[1,0,0] neg_hi:[1,0,0]
	v_pk_mul_f32 v[234:235], v[30:31], v[54:55] op_sel:[1,0] op_sel_hi:[1,1] neg_lo:[1,0] neg_hi:[1,0]
	v_pk_mul_f32 v[236:237], v[32:33], v[56:57] op_sel:[0,0] op_sel_hi:[0,1] neg_lo:[1,0] neg_hi:[1,0]
	v_pk_mul_f32 v[238:239], v[32:33], v[58:59] op_sel:[1,0] op_sel_hi:[1,1] neg_lo:[1,0] neg_hi:[1,0]
	ds_read_b128 v[30:33], v241 offset:11136
	s_waitcnt lgkmcnt(7)
	v_pk_fma_f32 v[170:171], v[34:35], v[60:61], v[170:171] op_sel:[0,0,0] op_sel_hi:[0,1,1] neg_lo:[1,0,0] neg_hi:[1,0,0]
	v_pk_fma_f32 v[234:235], v[34:35], v[62:63], v[234:235] op_sel:[1,0,0] op_sel_hi:[1,1,1] neg_lo:[1,0,0] neg_hi:[1,0,0]
	v_pk_fma_f32 v[236:237], v[36:37], v[64:65], v[236:237] op_sel:[0,0,0] op_sel_hi:[0,1,1] neg_lo:[1,0,0] neg_hi:[1,0,0]
	v_pk_fma_f32 v[238:239], v[36:37], v[66:67], v[238:239] op_sel:[1,0,0] op_sel_hi:[1,1,1] neg_lo:[1,0,0] neg_hi:[1,0,0]
	ds_read_b128 v[34:37], v241 offset:11152
	s_waitcnt lgkmcnt(7)
	v_pk_fma_f32 v[170:171], v[38:39], v[68:69], v[170:171] op_sel:[0,0,0] op_sel_hi:[0,1,1] neg_lo:[1,0,0] neg_hi:[1,0,0]
	v_pk_fma_f32 v[234:235], v[38:39], v[70:71], v[234:235] op_sel:[1,0,0] op_sel_hi:[1,1,1] neg_lo:[1,0,0] neg_hi:[1,0,0]
	v_pk_fma_f32 v[236:237], v[40:41], v[72:73], v[236:237] op_sel:[0,0,0] op_sel_hi:[0,1,1] neg_lo:[1,0,0] neg_hi:[1,0,0]
	v_pk_fma_f32 v[238:239], v[40:41], v[74:75], v[238:239] op_sel:[1,0,0] op_sel_hi:[1,1,1] neg_lo:[1,0,0] neg_hi:[1,0,0]
	ds_read_b128 v[38:41], v241 offset:11168
	s_waitcnt lgkmcnt(7)
	v_pk_fma_f32 v[170:171], v[42:43], v[76:77], v[170:171] op_sel:[0,0,0] op_sel_hi:[0,1,1] neg_lo:[1,0,0] neg_hi:[1,0,0]
	v_pk_fma_f32 v[234:235], v[42:43], v[78:79], v[234:235] op_sel:[1,0,0] op_sel_hi:[1,1,1] neg_lo:[1,0,0] neg_hi:[1,0,0]
	v_pk_fma_f32 v[236:237], v[44:45], v[80:81], v[236:237] op_sel:[0,0,0] op_sel_hi:[0,1,1] neg_lo:[1,0,0] neg_hi:[1,0,0]
	v_pk_fma_f32 v[238:239], v[44:45], v[82:83], v[238:239] op_sel:[1,0,0] op_sel_hi:[1,1,1] neg_lo:[1,0,0] neg_hi:[1,0,0]
	ds_read_b128 v[42:45], v241 offset:11264
	s_waitcnt lgkmcnt(7)
	v_pk_fma_f32 v[170:171], v[46:47], v[84:85], v[170:171] op_sel:[0,0,0] op_sel_hi:[0,1,1] neg_lo:[1,0,0] neg_hi:[1,0,0]
	v_pk_fma_f32 v[234:235], v[46:47], v[86:87], v[234:235] op_sel:[1,0,0] op_sel_hi:[1,1,1] neg_lo:[1,0,0] neg_hi:[1,0,0]
	v_pk_fma_f32 v[236:237], v[48:49], v[88:89], v[236:237] op_sel:[0,0,0] op_sel_hi:[0,1,1] neg_lo:[1,0,0] neg_hi:[1,0,0]
	v_pk_fma_f32 v[238:239], v[48:49], v[90:91], v[238:239] op_sel:[1,0,0] op_sel_hi:[1,1,1] neg_lo:[1,0,0] neg_hi:[1,0,0]
	ds_read_b128 v[46:49], v241 offset:11280
	s_waitcnt lgkmcnt(7)
	v_pk_fma_f32 v[170:171], v[50:51], v[92:93], v[170:171] op_sel:[0,0,0] op_sel_hi:[0,1,1] neg_lo:[1,0,0] neg_hi:[1,0,0]
	v_pk_fma_f32 v[234:235], v[50:51], v[94:95], v[234:235] op_sel:[1,0,0] op_sel_hi:[1,1,1] neg_lo:[1,0,0] neg_hi:[1,0,0]
	v_pk_fma_f32 v[236:237], v[52:53], v[96:97], v[236:237] op_sel:[0,0,0] op_sel_hi:[0,1,1] neg_lo:[1,0,0] neg_hi:[1,0,0]
	v_pk_fma_f32 v[238:239], v[52:53], v[98:99], v[238:239] op_sel:[1,0,0] op_sel_hi:[1,1,1] neg_lo:[1,0,0] neg_hi:[1,0,0]
	ds_read_b128 v[50:53], v241 offset:11296
	s_waitcnt lgkmcnt(7)
	v_pk_fma_f32 v[170:171], v[2:3], v[100:101], v[170:171] op_sel:[0,0,0] op_sel_hi:[0,1,1] neg_lo:[1,0,0] neg_hi:[1,0,0]
	v_pk_fma_f32 v[234:235], v[2:3], v[102:103], v[234:235] op_sel:[1,0,0] op_sel_hi:[1,1,1] neg_lo:[1,0,0] neg_hi:[1,0,0]
	v_pk_fma_f32 v[236:237], v[4:5], v[104:105], v[236:237] op_sel:[0,0,0] op_sel_hi:[0,1,1] neg_lo:[1,0,0] neg_hi:[1,0,0]
	v_pk_fma_f32 v[238:239], v[4:5], v[106:107], v[238:239] op_sel:[1,0,0] op_sel_hi:[1,1,1] neg_lo:[1,0,0] neg_hi:[1,0,0]
	ds_read_b128 v[2:5], v241 offset:11312
	s_waitcnt lgkmcnt(7)
	v_pk_fma_f32 v[170:171], v[26:27], v[108:109], v[170:171] op_sel:[0,0,0] op_sel_hi:[0,1,1] neg_lo:[1,0,0] neg_hi:[1,0,0]
	v_pk_fma_f32 v[234:235], v[26:27], v[110:111], v[234:235] op_sel:[1,0,0] op_sel_hi:[1,1,1] neg_lo:[1,0,0] neg_hi:[1,0,0]
	v_pk_fma_f32 v[236:237], v[28:29], v[112:113], v[236:237] op_sel:[0,0,0] op_sel_hi:[0,1,1] neg_lo:[1,0,0] neg_hi:[1,0,0]
	v_pk_fma_f32 v[238:239], v[28:29], v[114:115], v[238:239] op_sel:[1,0,0] op_sel_hi:[1,1,1] neg_lo:[1,0,0] neg_hi:[1,0,0]
	ds_read_b128 v[26:29], v241 offset:11328
	s_waitcnt lgkmcnt(7)
	v_pk_fma_f32 v[170:171], v[30:31], v[116:117], v[170:171] op_sel:[0,0,0] op_sel_hi:[0,1,1] neg_lo:[1,0,0] neg_hi:[1,0,0]
	v_pk_fma_f32 v[234:235], v[30:31], v[118:119], v[234:235] op_sel:[1,0,0] op_sel_hi:[1,1,1] neg_lo:[1,0,0] neg_hi:[1,0,0]
	v_pk_fma_f32 v[236:237], v[32:33], v[152:153], v[236:237] op_sel:[0,0,0] op_sel_hi:[0,1,1] neg_lo:[1,0,0] neg_hi:[1,0,0]
	v_pk_fma_f32 v[238:239], v[32:33], v[154:155], v[238:239] op_sel:[1,0,0] op_sel_hi:[1,1,1] neg_lo:[1,0,0] neg_hi:[1,0,0]
	ds_read_b128 v[30:33], v241 offset:11344
	s_waitcnt lgkmcnt(7)
	v_pk_fma_f32 v[170:171], v[34:35], v[156:157], v[170:171] op_sel:[0,0,0] op_sel_hi:[0,1,1] neg_lo:[1,0,0] neg_hi:[1,0,0]
	v_pk_fma_f32 v[234:235], v[34:35], v[158:159], v[234:235] op_sel:[1,0,0] op_sel_hi:[1,1,1] neg_lo:[1,0,0] neg_hi:[1,0,0]
	v_pk_fma_f32 v[236:237], v[36:37], v[160:161], v[236:237] op_sel:[0,0,0] op_sel_hi:[0,1,1] neg_lo:[1,0,0] neg_hi:[1,0,0]
	v_pk_fma_f32 v[238:239], v[36:37], v[162:163], v[238:239] op_sel:[1,0,0] op_sel_hi:[1,1,1] neg_lo:[1,0,0] neg_hi:[1,0,0]
	ds_read_b128 v[34:37], v241 offset:11360
	s_waitcnt lgkmcnt(7)
; template <int DIR>
; __device__ __forceinline__ void dn_solve(const P& p, int task, int m0, int h, int t2, const bf16_t* kn_s, const bf16_t* v_s, const float* gc, const float* be, float* L) {
;     ...
; #pragma unroll
;     for (int cp = 1; cp < 64; ++cp) {
;         float a0 = 0.f, a1 = 0.f, a2 = 0.f, a3 = 0.f;
; #pragma unroll
;         for (int s4 = 0; s4 < cp; s4 += 4) { const f32x4 l4 = *(const f32x4*)(L + cp * 64 + s4); a0 += l4[0] * x[s4]; a1 += l4[1] * x[s4 + 1]; a2 += l4[2] * x[s4 + 2]; a3 += l4[3] * x[s4 + 3]; }
;         x[cp] -= (a0 + a1) + (a2 + a3);
;     }
	v_pk_fma_f32 v[170:171], v[38:39], v[164:165], v[170:171] op_sel:[0,0,0] op_sel_hi:[0,1,1] neg_lo:[1,0,0] neg_hi:[1,0,0]
	v_pk_fma_f32 v[234:235], v[38:39], v[166:167], v[234:235] op_sel:[1,0,0] op_sel_hi:[1,1,1] neg_lo:[1,0,0] neg_hi:[1,0,0]
	v_pk_fma_f32 v[236:237], v[40:41], v[168:169], v[236:237] op_sel:[0,0,0] op_sel_hi:[0,1,1] neg_lo:[1,0,0] neg_hi:[1,0,0]
	v_pk_add_f32 v[234:235], v[170:171], v[234:235]
	v_pk_add_f32 v[234:235], v[234:235], v[238:239]
	v_pk_add_f32 v[170:171], v[234:235], v[236:237]
	ds_read_b128 v[38:41], v241 offset:11376
	s_waitcnt lgkmcnt(7)
	v_pk_fma_f32 v[172:173], v[42:43], v[6:7], v[172:173] op_sel:[0,0,0] op_sel_hi:[0,1,1] neg_lo:[1,0,0] neg_hi:[1,0,0]
	v_pk_mul_f32 v[234:235], v[42:43], v[54:55] op_sel:[1,0] op_sel_hi:[1,1] neg_lo:[1,0] neg_hi:[1,0]
	v_pk_mul_f32 v[236:237], v[44:45], v[56:57] op_sel:[0,0] op_sel_hi:[0,1] neg_lo:[1,0] neg_hi:[1,0]
	v_pk_mul_f32 v[238:239], v[44:45], v[58:59] op_sel:[1,0] op_sel_hi:[1,1] neg_lo:[1,0] neg_hi:[1,0]
	ds_read_b128 v[42:45], v241 offset:11392
	s_waitcnt lgkmcnt(7)
	v_pk_fma_f32 v[172:173], v[46:47], v[60:61], v[172:173] op_sel:[0,0,0] op_sel_hi:[0,1,1] neg_lo:[1,0,0] neg_hi:[1,0,0]
	v_pk_fma_f32 v[234:235], v[46:47], v[62:63], v[234:235] op_sel:[1,0,0] op_sel_hi:[1,1,1] neg_lo:[1,0,0] neg_hi:[1,0,0]
	v_pk_fma_f32 v[236:237], v[48:49], v[64:65], v[236:237] op_sel:[0,0,0] op_sel_hi:[0,1,1] neg_lo:[1,0,0] neg_hi:[1,0,0]
	v_pk_fma_f32 v[238:239], v[48:49], v[66:67], v[238:239] op_sel:[1,0,0] op_sel_hi:[1,1,1] neg_lo:[1,0,0] neg_hi:[1,0,0]
	ds_read_b128 v[46:49], v241 offset:11408
	s_waitcnt lgkmcnt(7)
	v_pk_fma_f32 v[172:173], v[50:51], v[68:69], v[172:173] op_sel:[0,0,0] op_sel_hi:[0,1,1] neg_lo:[1,0,0] neg_hi:[1,0,0]
	v_pk_fma_f32 v[234:235], v[50:51], v[70:71], v[234:235] op_sel:[1,0,0] op_sel_hi:[1,1,1] neg_lo:[1,0,0] neg_hi:[1,0,0]
	v_pk_fma_f32 v[236:237], v[52:53], v[72:73], v[236:237] op_sel:[0,0,0] op_sel_hi:[0,1,1] neg_lo:[1,0,0] neg_hi:[1,0,0]
	v_pk_fma_f32 v[238:239], v[52:53], v[74:75], v[238:239] op_sel:[1,0,0] op_sel_hi:[1,1,1] neg_lo:[1,0,0] neg_hi:[1,0,0]
	ds_read_b128 v[50:53], v241 offset:11424
	s_waitcnt lgkmcnt(7)
	v_pk_fma_f32 v[172:173], v[2:3], v[76:77], v[172:173] op_sel:[0,0,0] op_sel_hi:[0,1,1] neg_lo:[1,0,0] neg_hi:[1,0,0]
	v_pk_fma_f32 v[234:235], v[2:3], v[78:79], v[234:235] op_sel:[1,0,0] op_sel_hi:[1,1,1] neg_lo:[1,0,0] neg_hi:[1,0,0]
	v_pk_fma_f32 v[236:237], v[4:5], v[80:81], v[236:237] op_sel:[0,0,0] op_sel_hi:[0,1,1] neg_lo:[1,0,0] neg_hi:[1,0,0]
	v_pk_fma_f32 v[238:239], v[4:5], v[82:83], v[238:239] op_sel:[1,0,0] op_sel_hi:[1,1,1] neg_lo:[1,0,0] neg_hi:[1,0,0]
	ds_read_b128 v[2:5], v241 offset:11520
	s_waitcnt lgkmcnt(7)
	v_pk_fma_f32 v[172:173], v[26:27], v[84:85], v[172:173] op_sel:[0,0,0] op_sel_hi:[0,1,1] neg_lo:[1,0,0] neg_hi:[1,0,0]
	v_pk_fma_f32 v[234:235], v[26:27], v[86:87], v[234:235] op_sel:[1,0,0] op_sel_hi:[1,1,1] neg_lo:[1,0,0] neg_hi:[1,0,0]
	v_pk_fma_f32 v[236:237], v[28:29], v[88:89], v[236:237] op_sel:[0,0,0] op_sel_hi:[0,1,1] neg_lo:[1,0,0] neg_hi:[1,0,0]
	v_pk_fma_f32 v[238:239], v[28:29], v[90:91], v[238:239] op_sel:[1,0,0] op_sel_hi:[1,1,1] neg_lo:[1,0,0] neg_hi:[1,0,0]
	ds_read_b128 v[26:29], v241 offset:11536
	s_waitcnt lgkmcnt(7)
	v_pk_fma_f32 v[172:173], v[30:31], v[92:93], v[172:173] op_sel:[0,0,0] op_sel_hi:[0,1,1] neg_lo:[1,0,0] neg_hi:[1,0,0]
	v_pk_fma_f32 v[234:235], v[30:31], v[94:95], v[234:235] op_sel:[1,0,0] op_sel_hi:[1,1,1] neg_lo:[1,0,0] neg_hi:[1,0,0]
	v_pk_fma_f32 v[236:237], v[32:33], v[96:97], v[236:237] op_sel:[0,0,0] op_sel_hi:[0,1,1] neg_lo:[1,0,0] neg_hi:[1,0,0]
	v_pk_fma_f32 v[238:239], v[32:33], v[98:99], v[238:239] op_sel:[1,0,0] op_sel_hi:[1,1,1] neg_lo:[1,0,0] neg_hi:[1,0,0]
	ds_read_b128 v[30:33], v241 offset:11552
	s_waitcnt lgkmcnt(7)
	v_pk_fma_f32 v[172:173], v[34:35], v[100:101], v[172:173] op_sel:[0,0,0] op_sel_hi:[0,1,1] neg_lo:[1,0,0] neg_hi:[1,0,0]
	v_pk_fma_f32 v[234:235], v[34:35], v[102:103], v[234:235] op_sel:[1,0,0] op_sel_hi:[1,1,1] neg_lo:[1,0,0] neg_hi:[1,0,0]
	v_pk_fma_f32 v[236:237], v[36:37], v[104:105], v[236:237] op_sel:[0,0,0] op_sel_hi:[0,1,1] neg_lo:[1,0,0] neg_hi:[1,0,0]
	v_pk_fma_f32 v[238:239], v[36:37], v[106:107], v[238:239] op_sel:[1,0,0] op_sel_hi:[1,1,1] neg_lo:[1,0,0] neg_hi:[1,0,0]
	ds_read_b128 v[34:37], v241 offset:11568
	s_waitcnt lgkmcnt(7)
	v_pk_fma_f32 v[172:173], v[38:39], v[108:109], v[172:173] op_sel:[0,0,0] op_sel_hi:[0,1,1] neg_lo:[1,0,0] neg_hi:[1,0,0]
	v_pk_fma_f32 v[234:235], v[38:39], v[110:111], v[234:235] op_sel:[1,0,0] op_sel_hi:[1,1,1] neg_lo:[1,0,0] neg_hi:[1,0,0]
	v_pk_fma_f32 v[236:237], v[40:41], v[112:113], v[236:237] op_sel:[0,0,0] op_sel_hi:[0,1,1] neg_lo:[1,0,0] neg_hi:[1,0,0]
	v_pk_fma_f32 v[238:239], v[40:41], v[114:115], v[238:239] op_sel:[1,0,0] op_sel_hi:[1,1,1] neg_lo:[1,0,0] neg_hi:[1,0,0]
	ds_read_b128 v[38:41], v241 offset:11584
	s_waitcnt lgkmcnt(7)
	v_pk_fma_f32 v[172:173], v[42:43], v[116:117], v[172:173] op_sel:[0,0,0] op_sel_hi:[0,1,1] neg_lo:[1,0,0] neg_hi:[1,0,0]
	v_pk_fma_f32 v[234:235], v[42:43], v[118:119], v[234:235] op_sel:[1,0,0] op_sel_hi:[1,1,1] neg_lo:[1,0,0] neg_hi:[1,0,0]
	v_pk_fma_f32 v[236:237], v[44:45], v[152:153], v[236:237] op_sel:[0,0,0] op_sel_hi:[0,1,1] neg_lo:[1,0,0] neg_hi:[1,0,0]
	v_pk_fma_f32 v[238:239], v[44:45], v[154:155], v[238:239] op_sel:[1,0,0] op_sel_hi:[1,1,1] neg_lo:[1,0,0] neg_hi:[1,0,0]
	ds_read_b128 v[42:45], v241 offset:11600
	s_waitcnt lgkmcnt(7)
; template <int DIR>
; __device__ __forceinline__ void dn_solve(const P& p, int task, int m0, int h, int t2, const bf16_t* kn_s, const bf16_t* v_s, const float* gc, const float* be, float* L) {
;     ...
; #pragma unroll
;     for (int cp = 1; cp < 64; ++cp) {
;         float a0 = 0.f, a1 = 0.f, a2 = 0.f, a3 = 0.f;
; #pragma unroll
;         for (int s4 = 0; s4 < cp; s4 += 4) { const f32x4 l4 = *(const f32x4*)(L + cp * 64 + s4); a0 += l4[0] * x[s4]; a1 += l4[1] * x[s4 + 1]; a2 += l4[2] * x[s4 + 2]; a3 += l4[3] * x[s4 + 3]; }
;         x[cp] -= (a0 + a1) + (a2 + a3);
;     }
	v_pk_fma_f32 v[172:173], v[46:47], v[156:157], v[172:173] op_sel:[0,0,0] op_sel_hi:[0,1,1] neg_lo:[1,0,0] neg_hi:[1,0,0]
	v_pk_fma_f32 v[234:235], v[46:47], v[158:159], v[234:235] op_sel:[1,0,0] op_sel_hi:[1,1,1] neg_lo:[1,0,0] neg_hi:[1,0,0]
	v_pk_fma_f32 v[236:237], v[48:49], v[160:161], v[236:237] op_sel:[0,0,0] op_sel_hi:[0,1,1] neg_lo:[1,0,0] neg_hi:[1,0,0]
	v_pk_fma_f32 v[238:239], v[48:49], v[162:163], v[238:239] op_sel:[1,0,0] op_sel_hi:[1,1,1] neg_lo:[1,0,0] neg_hi:[1,0,0]
	ds_read_b128 v[46:49], v241 offset:11616
	s_waitcnt lgkmcnt(7)
	v_pk_fma_f32 v[172:173], v[50:51], v[164:165], v[172:173] op_sel:[0,0,0] op_sel_hi:[0,1,1] neg_lo:[1,0,0] neg_hi:[1,0,0]
	v_pk_fma_f32 v[234:235], v[50:51], v[166:167], v[234:235] op_sel:[1,0,0] op_sel_hi:[1,1,1] neg_lo:[1,0,0] neg_hi:[1,0,0]
	v_pk_fma_f32 v[236:237], v[52:53], v[168:169], v[236:237] op_sel:[0,0,0] op_sel_hi:[0,1,1] neg_lo:[1,0,0] neg_hi:[1,0,0]
	v_pk_fma_f32 v[238:239], v[52:53], v[170:171], v[238:239] op_sel:[1,0,0] op_sel_hi:[1,1,1] neg_lo:[1,0,0] neg_hi:[1,0,0]
	v_pk_add_f32 v[234:235], v[172:173], v[234:235]
	v_pk_add_f32 v[234:235], v[234:235], v[236:237]
	v_pk_add_f32 v[172:173], v[234:235], v[238:239]
	ds_read_b128 v[50:53], v241 offset:11632
	s_waitcnt lgkmcnt(7)
	v_pk_fma_f32 v[174:175], v[2:3], v[6:7], v[174:175] op_sel:[0,0,0] op_sel_hi:[0,1,1] neg_lo:[1,0,0] neg_hi:[1,0,0]
	v_pk_mul_f32 v[234:235], v[2:3], v[54:55] op_sel:[1,0] op_sel_hi:[1,1] neg_lo:[1,0] neg_hi:[1,0]
	v_pk_mul_f32 v[236:237], v[4:5], v[56:57] op_sel:[0,0] op_sel_hi:[0,1] neg_lo:[1,0] neg_hi:[1,0]
	v_pk_mul_f32 v[238:239], v[4:5], v[58:59] op_sel:[1,0] op_sel_hi:[1,1] neg_lo:[1,0] neg_hi:[1,0]
	ds_read_b128 v[2:5], v241 offset:11648
	s_waitcnt lgkmcnt(7)
	v_pk_fma_f32 v[174:175], v[26:27], v[60:61], v[174:175] op_sel:[0,0,0] op_sel_hi:[0,1,1] neg_lo:[1,0,0] neg_hi:[1,0,0]
	v_pk_fma_f32 v[234:235], v[26:27], v[62:63], v[234:235] op_sel:[1,0,0] op_sel_hi:[1,1,1] neg_lo:[1,0,0] neg_hi:[1,0,0]
	v_pk_fma_f32 v[236:237], v[28:29], v[64:65], v[236:237] op_sel:[0,0,0] op_sel_hi:[0,1,1] neg_lo:[1,0,0] neg_hi:[1,0,0]
	v_pk_fma_f32 v[238:239], v[28:29], v[66:67], v[238:239] op_sel:[1,0,0] op_sel_hi:[1,1,1] neg_lo:[1,0,0] neg_hi:[1,0,0]
	ds_read_b128 v[26:29], v241 offset:11664
	s_waitcnt lgkmcnt(7)
	v_pk_fma_f32 v[174:175], v[30:31], v[68:69], v[174:175] op_sel:[0,0,0] op_sel_hi:[0,1,1] neg_lo:[1,0,0] neg_hi:[1,0,0]
	v_pk_fma_f32 v[234:235], v[30:31], v[70:71], v[234:235] op_sel:[1,0,0] op_sel_hi:[1,1,1] neg_lo:[1,0,0] neg_hi:[1,0,0]
	v_pk_fma_f32 v[236:237], v[32:33], v[72:73], v[236:237] op_sel:[0,0,0] op_sel_hi:[0,1,1] neg_lo:[1,0,0] neg_hi:[1,0,0]
	v_pk_fma_f32 v[238:239], v[32:33], v[74:75], v[238:239] op_sel:[1,0,0] op_sel_hi:[1,1,1] neg_lo:[1,0,0] neg_hi:[1,0,0]
	ds_read_b128 v[30:33], v241 offset:11680
	s_waitcnt lgkmcnt(7)
	v_pk_fma_f32 v[174:175], v[34:35], v[76:77], v[174:175] op_sel:[0,0,0] op_sel_hi:[0,1,1] neg_lo:[1,0,0] neg_hi:[1,0,0]
	v_pk_fma_f32 v[234:235], v[34:35], v[78:79], v[234:235] op_sel:[1,0,0] op_sel_hi:[1,1,1] neg_lo:[1,0,0] neg_hi:[1,0,0]
	v_pk_fma_f32 v[236:237], v[36:37], v[80:81], v[236:237] op_sel:[0,0,0] op_sel_hi:[0,1,1] neg_lo:[1,0,0] neg_hi:[1,0,0]
	v_pk_fma_f32 v[238:239], v[36:37], v[82:83], v[238:239] op_sel:[1,0,0] op_sel_hi:[1,1,1] neg_lo:[1,0,0] neg_hi:[1,0,0]
	ds_read_b128 v[34:37], v241 offset:11696
	s_waitcnt lgkmcnt(7)
	v_pk_fma_f32 v[174:175], v[38:39], v[84:85], v[174:175] op_sel:[0,0,0] op_sel_hi:[0,1,1] neg_lo:[1,0,0] neg_hi:[1,0,0]
	v_pk_fma_f32 v[234:235], v[38:39], v[86:87], v[234:235] op_sel:[1,0,0] op_sel_hi:[1,1,1] neg_lo:[1,0,0] neg_hi:[1,0,0]
	v_pk_fma_f32 v[236:237], v[40:41], v[88:89], v[236:237] op_sel:[0,0,0] op_sel_hi:[0,1,1] neg_lo:[1,0,0] neg_hi:[1,0,0]
	v_pk_fma_f32 v[238:239], v[40:41], v[90:91], v[238:239] op_sel:[1,0,0] op_sel_hi:[1,1,1] neg_lo:[1,0,0] neg_hi:[1,0,0]
	ds_read_b128 v[38:41], v241 offset:11776
	s_waitcnt lgkmcnt(7)
	v_pk_fma_f32 v[174:175], v[42:43], v[92:93], v[174:175] op_sel:[0,0,0] op_sel_hi:[0,1,1] neg_lo:[1,0,0] neg_hi:[1,0,0]
	v_pk_fma_f32 v[234:235], v[42:43], v[94:95], v[234:235] op_sel:[1,0,0] op_sel_hi:[1,1,1] neg_lo:[1,0,0] neg_hi:[1,0,0]
	v_pk_fma_f32 v[236:237], v[44:45], v[96:97], v[236:237] op_sel:[0,0,0] op_sel_hi:[0,1,1] neg_lo:[1,0,0] neg_hi:[1,0,0]
	v_pk_fma_f32 v[238:239], v[44:45], v[98:99], v[238:239] op_sel:[1,0,0] op_sel_hi:[1,1,1] neg_lo:[1,0,0] neg_hi:[1,0,0]
	ds_read_b128 v[42:45], v241 offset:11792
	s_waitcnt lgkmcnt(7)
	v_pk_fma_f32 v[174:175], v[46:47], v[100:101], v[174:175] op_sel:[0,0,0] op_sel_hi:[0,1,1] neg_lo:[1,0,0] neg_hi:[1,0,0]
	v_pk_fma_f32 v[234:235], v[46:47], v[102:103], v[234:235] op_sel:[1,0,0] op_sel_hi:[1,1,1] neg_lo:[1,0,0] neg_hi:[1,0,0]
	v_pk_fma_f32 v[236:237], v[48:49], v[104:105], v[236:237] op_sel:[0,0,0] op_sel_hi:[0,1,1] neg_lo:[1,0,0] neg_hi:[1,0,0]
	v_pk_fma_f32 v[238:239], v[48:49], v[106:107], v[238:239] op_sel:[1,0,0] op_sel_hi:[1,1,1] neg_lo:[1,0,0] neg_hi:[1,0,0]
	ds_read_b128 v[46:49], v241 offset:11808
	s_waitcnt lgkmcnt(7)
	v_pk_fma_f32 v[174:175], v[50:51], v[108:109], v[174:175] op_sel:[0,0,0] op_sel_hi:[0,1,1] neg_lo:[1,0,0] neg_hi:[1,0,0]
	v_pk_fma_f32 v[234:235], v[50:51], v[110:111], v[234:235] op_sel:[1,0,0] op_sel_hi:[1,1,1] neg_lo:[1,0,0] neg_hi:[1,0,0]
	v_pk_fma_f32 v[236:237], v[52:53], v[112:113], v[236:237] op_sel:[0,0,0] op_sel_hi:[0,1,1] neg_lo:[1,0,0] neg_hi:[1,0,0]
	v_pk_fma_f32 v[238:239], v[52:53], v[114:115], v[238:239] op_sel:[1,0,0] op_sel_hi:[1,1,1] neg_lo:[1,0,0] neg_hi:[1,0,0]
	ds_read_b128 v[50:53], v241 offset:11824
	s_waitcnt lgkmcnt(7)
; template <int DIR>
; __device__ __forceinline__ void dn_solve(const P& p, int task, int m0, int h, int t2, const bf16_t* kn_s, const bf16_t* v_s, const float* gc, const float* be, float* L) {
;     ...
; #pragma unroll
;     for (int cp = 1; cp < 64; ++cp) {
;         float a0 = 0.f, a1 = 0.f, a2 = 0.f, a3 = 0.f;
; #pragma unroll
;         for (int s4 = 0; s4 < cp; s4 += 4) { const f32x4 l4 = *(const f32x4*)(L + cp * 64 + s4); a0 += l4[0] * x[s4]; a1 += l4[1] * x[s4 + 1]; a2 += l4[2] * x[s4 + 2]; a3 += l4[3] * x[s4 + 3]; }
;         x[cp] -= (a0 + a1) + (a2 + a3);
;     }
	v_pk_fma_f32 v[174:175], v[2:3], v[116:117], v[174:175] op_sel:[0,0,0] op_sel_hi:[0,1,1] neg_lo:[1,0,0] neg_hi:[1,0,0]
	v_pk_fma_f32 v[234:235], v[2:3], v[118:119], v[234:235] op_sel:[1,0,0] op_sel_hi:[1,1,1] neg_lo:[1,0,0] neg_hi:[1,0,0]
	v_pk_fma_f32 v[236:237], v[4:5], v[152:153], v[236:237] op_sel:[0,0,0] op_sel_hi:[0,1,1] neg_lo:[1,0,0] neg_hi:[1,0,0]
	v_pk_fma_f32 v[238:239], v[4:5], v[154:155], v[238:239] op_sel:[1,0,0] op_sel_hi:[1,1,1] neg_lo:[1,0,0] neg_hi:[1,0,0]
	ds_read_b128 v[2:5], v241 offset:11840
	s_waitcnt lgkmcnt(7)
	v_pk_fma_f32 v[174:175], v[26:27], v[156:157], v[174:175] op_sel:[0,0,0] op_sel_hi:[0,1,1] neg_lo:[1,0,0] neg_hi:[1,0,0]
	v_pk_fma_f32 v[234:235], v[26:27], v[158:159], v[234:235] op_sel:[1,0,0] op_sel_hi:[1,1,1] neg_lo:[1,0,0] neg_hi:[1,0,0]
	v_pk_fma_f32 v[236:237], v[28:29], v[160:161], v[236:237] op_sel:[0,0,0] op_sel_hi:[0,1,1] neg_lo:[1,0,0] neg_hi:[1,0,0]
	v_pk_fma_f32 v[238:239], v[28:29], v[162:163], v[238:239] op_sel:[1,0,0] op_sel_hi:[1,1,1] neg_lo:[1,0,0] neg_hi:[1,0,0]
	ds_read_b128 v[26:29], v241 offset:11856
	s_waitcnt lgkmcnt(7)
	v_pk_fma_f32 v[174:175], v[30:31], v[164:165], v[174:175] op_sel:[0,0,0] op_sel_hi:[0,1,1] neg_lo:[1,0,0] neg_hi:[1,0,0]
	v_pk_fma_f32 v[234:235], v[30:31], v[166:167], v[234:235] op_sel:[1,0,0] op_sel_hi:[1,1,1] neg_lo:[1,0,0] neg_hi:[1,0,0]
	v_pk_fma_f32 v[236:237], v[32:33], v[168:169], v[236:237] op_sel:[0,0,0] op_sel_hi:[0,1,1] neg_lo:[1,0,0] neg_hi:[1,0,0]
	v_pk_fma_f32 v[238:239], v[32:33], v[170:171], v[238:239] op_sel:[1,0,0] op_sel_hi:[1,1,1] neg_lo:[1,0,0] neg_hi:[1,0,0]
	ds_read_b128 v[30:33], v241 offset:11872
	s_waitcnt lgkmcnt(7)
	v_pk_fma_f32 v[174:175], v[34:35], v[172:173], v[174:175] op_sel:[0,0,0] op_sel_hi:[0,1,1] neg_lo:[1,0,0] neg_hi:[1,0,0]
	v_pk_add_f32 v[234:235], v[234:235], v[236:237]
	v_pk_add_f32 v[234:235], v[234:235], v[238:239]
	v_pk_add_f32 v[174:175], v[234:235], v[174:175]
	ds_read_b128 v[34:37], v241 offset:11888
	s_waitcnt lgkmcnt(7)
	v_pk_fma_f32 v[176:177], v[38:39], v[6:7], v[176:177] op_sel:[0,0,0] op_sel_hi:[0,1,1] neg_lo:[1,0,0] neg_hi:[1,0,0]
	v_pk_mul_f32 v[234:235], v[38:39], v[54:55] op_sel:[1,0] op_sel_hi:[1,1] neg_lo:[1,0] neg_hi:[1,0]
	v_pk_mul_f32 v[236:237], v[40:41], v[56:57] op_sel:[0,0] op_sel_hi:[0,1] neg_lo:[1,0] neg_hi:[1,0]
	v_pk_mul_f32 v[238:239], v[40:41], v[58:59] op_sel:[1,0] op_sel_hi:[1,1] neg_lo:[1,0] neg_hi:[1,0]
	ds_read_b128 v[38:41], v241 offset:11904
	s_waitcnt lgkmcnt(7)
	v_pk_fma_f32 v[176:177], v[42:43], v[60:61], v[176:177] op_sel:[0,0,0] op_sel_hi:[0,1,1] neg_lo:[1,0,0] neg_hi:[1,0,0]
	v_pk_fma_f32 v[234:235], v[42:43], v[62:63], v[234:235] op_sel:[1,0,0] op_sel_hi:[1,1,1] neg_lo:[1,0,0] neg_hi:[1,0,0]
	v_pk_fma_f32 v[236:237], v[44:45], v[64:65], v[236:237] op_sel:[0,0,0] op_sel_hi:[0,1,1] neg_lo:[1,0,0] neg_hi:[1,0,0]
	v_pk_fma_f32 v[238:239], v[44:45], v[66:67], v[238:239] op_sel:[1,0,0] op_sel_hi:[1,1,1] neg_lo:[1,0,0] neg_hi:[1,0,0]
	ds_read_b128 v[42:45], v241 offset:11920
	s_waitcnt lgkmcnt(7)
	v_pk_fma_f32 v[176:177], v[46:47], v[68:69], v[176:177] op_sel:[0,0,0] op_sel_hi:[0,1,1] neg_lo:[1,0,0] neg_hi:[1,0,0]
	v_pk_fma_f32 v[234:235], v[46:47], v[70:71], v[234:235] op_sel:[1,0,0] op_sel_hi:[1,1,1] neg_lo:[1,0,0] neg_hi:[1,0,0]
	v_pk_fma_f32 v[236:237], v[48:49], v[72:73], v[236:237] op_sel:[0,0,0] op_sel_hi:[0,1,1] neg_lo:[1,0,0] neg_hi:[1,0,0]
	v_pk_fma_f32 v[238:239], v[48:49], v[74:75], v[238:239] op_sel:[1,0,0] op_sel_hi:[1,1,1] neg_lo:[1,0,0] neg_hi:[1,0,0]
	ds_read_b128 v[46:49], v241 offset:11936
	s_waitcnt lgkmcnt(7)
	v_pk_fma_f32 v[176:177], v[50:51], v[76:77], v[176:177] op_sel:[0,0,0] op_sel_hi:[0,1,1] neg_lo:[1,0,0] neg_hi:[1,0,0]
	v_pk_fma_f32 v[234:235], v[50:51], v[78:79], v[234:235] op_sel:[1,0,0] op_sel_hi:[1,1,1] neg_lo:[1,0,0] neg_hi:[1,0,0]
	v_pk_fma_f32 v[236:237], v[52:53], v[80:81], v[236:237] op_sel:[0,0,0] op_sel_hi:[0,1,1] neg_lo:[1,0,0] neg_hi:[1,0,0]
	v_pk_fma_f32 v[238:239], v[52:53], v[82:83], v[238:239] op_sel:[1,0,0] op_sel_hi:[1,1,1] neg_lo:[1,0,0] neg_hi:[1,0,0]
	ds_read_b128 v[50:53], v241 offset:11952
	s_waitcnt lgkmcnt(7)
	v_pk_fma_f32 v[176:177], v[2:3], v[84:85], v[176:177] op_sel:[0,0,0] op_sel_hi:[0,1,1] neg_lo:[1,0,0] neg_hi:[1,0,0]
	v_pk_fma_f32 v[234:235], v[2:3], v[86:87], v[234:235] op_sel:[1,0,0] op_sel_hi:[1,1,1] neg_lo:[1,0,0] neg_hi:[1,0,0]
	v_pk_fma_f32 v[236:237], v[4:5], v[88:89], v[236:237] op_sel:[0,0,0] op_sel_hi:[0,1,1] neg_lo:[1,0,0] neg_hi:[1,0,0]
	v_pk_fma_f32 v[238:239], v[4:5], v[90:91], v[238:239] op_sel:[1,0,0] op_sel_hi:[1,1,1] neg_lo:[1,0,0] neg_hi:[1,0,0]
	ds_read_b128 v[2:5], v241 offset:12032
	s_waitcnt lgkmcnt(7)
	v_pk_fma_f32 v[176:177], v[26:27], v[92:93], v[176:177] op_sel:[0,0,0] op_sel_hi:[0,1,1] neg_lo:[1,0,0] neg_hi:[1,0,0]
	v_pk_fma_f32 v[234:235], v[26:27], v[94:95], v[234:235] op_sel:[1,0,0] op_sel_hi:[1,1,1] neg_lo:[1,0,0] neg_hi:[1,0,0]
	v_pk_fma_f32 v[236:237], v[28:29], v[96:97], v[236:237] op_sel:[0,0,0] op_sel_hi:[0,1,1] neg_lo:[1,0,0] neg_hi:[1,0,0]
	v_pk_fma_f32 v[238:239], v[28:29], v[98:99], v[238:239] op_sel:[1,0,0] op_sel_hi:[1,1,1] neg_lo:[1,0,0] neg_hi:[1,0,0]
	ds_read_b128 v[26:29], v241 offset:12048
	s_waitcnt lgkmcnt(7)
	v_pk_fma_f32 v[176:177], v[30:31], v[100:101], v[176:177] op_sel:[0,0,0] op_sel_hi:[0,1,1] neg_lo:[1,0,0] neg_hi:[1,0,0]
	v_pk_fma_f32 v[234:235], v[30:31], v[102:103], v[234:235] op_sel:[1,0,0] op_sel_hi:[1,1,1] neg_lo:[1,0,0] neg_hi:[1,0,0]
	v_pk_fma_f32 v[236:237], v[32:33], v[104:105], v[236:237] op_sel:[0,0,0] op_sel_hi:[0,1,1] neg_lo:[1,0,0] neg_hi:[1,0,0]
	v_pk_fma_f32 v[238:239], v[32:33], v[106:107], v[238:239] op_sel:[1,0,0] op_sel_hi:[1,1,1] neg_lo:[1,0,0] neg_hi:[1,0,0]
	ds_read_b128 v[30:33], v241 offset:12064
	s_waitcnt lgkmcnt(7)
; template <int DIR>
; __device__ __forceinline__ void dn_solve(const P& p, int task, int m0, int h, int t2, const bf16_t* kn_s, const bf16_t* v_s, const float* gc, const float* be, float* L) {
;     ...
; #pragma unroll
;     for (int cp = 1; cp < 64; ++cp) {
;         float a0 = 0.f, a1 = 0.f, a2 = 0.f, a3 = 0.f;
; #pragma unroll
;         for (int s4 = 0; s4 < cp; s4 += 4) { const f32x4 l4 = *(const f32x4*)(L + cp * 64 + s4); a0 += l4[0] * x[s4]; a1 += l4[1] * x[s4 + 1]; a2 += l4[2] * x[s4 + 2]; a3 += l4[3] * x[s4 + 3]; }
;         x[cp] -= (a0 + a1) + (a2 + a3);
;     }
	v_pk_fma_f32 v[176:177], v[34:35], v[108:109], v[176:177] op_sel:[0,0,0] op_sel_hi:[0,1,1] neg_lo:[1,0,0] neg_hi:[1,0,0]
	v_pk_fma_f32 v[234:235], v[34:35], v[110:111], v[234:235] op_sel:[1,0,0] op_sel_hi:[1,1,1] neg_lo:[1,0,0] neg_hi:[1,0,0]
	v_pk_fma_f32 v[236:237], v[36:37], v[112:113], v[236:237] op_sel:[0,0,0] op_sel_hi:[0,1,1] neg_lo:[1,0,0] neg_hi:[1,0,0]
	v_pk_fma_f32 v[238:239], v[36:37], v[114:115], v[238:239] op_sel:[1,0,0] op_sel_hi:[1,1,1] neg_lo:[1,0,0] neg_hi:[1,0,0]
	ds_read_b128 v[34:37], v241 offset:12080
	s_waitcnt lgkmcnt(7)
	v_pk_fma_f32 v[176:177], v[38:39], v[116:117], v[176:177] op_sel:[0,0,0] op_sel_hi:[0,1,1] neg_lo:[1,0,0] neg_hi:[1,0,0]
	v_pk_fma_f32 v[234:235], v[38:39], v[118:119], v[234:235] op_sel:[1,0,0] op_sel_hi:[1,1,1] neg_lo:[1,0,0] neg_hi:[1,0,0]
	v_pk_fma_f32 v[236:237], v[40:41], v[152:153], v[236:237] op_sel:[0,0,0] op_sel_hi:[0,1,1] neg_lo:[1,0,0] neg_hi:[1,0,0]
	v_pk_fma_f32 v[238:239], v[40:41], v[154:155], v[238:239] op_sel:[1,0,0] op_sel_hi:[1,1,1] neg_lo:[1,0,0] neg_hi:[1,0,0]
	ds_read_b128 v[38:41], v241 offset:12096
	s_waitcnt lgkmcnt(7)
	v_pk_fma_f32 v[176:177], v[42:43], v[156:157], v[176:177] op_sel:[0,0,0] op_sel_hi:[0,1,1] neg_lo:[1,0,0] neg_hi:[1,0,0]
	v_pk_fma_f32 v[234:235], v[42:43], v[158:159], v[234:235] op_sel:[1,0,0] op_sel_hi:[1,1,1] neg_lo:[1,0,0] neg_hi:[1,0,0]
	v_pk_fma_f32 v[236:237], v[44:45], v[160:161], v[236:237] op_sel:[0,0,0] op_sel_hi:[0,1,1] neg_lo:[1,0,0] neg_hi:[1,0,0]
	v_pk_fma_f32 v[238:239], v[44:45], v[162:163], v[238:239] op_sel:[1,0,0] op_sel_hi:[1,1,1] neg_lo:[1,0,0] neg_hi:[1,0,0]
	ds_read_b128 v[42:45], v241 offset:12112
	s_waitcnt lgkmcnt(7)
	v_pk_fma_f32 v[176:177], v[46:47], v[164:165], v[176:177] op_sel:[0,0,0] op_sel_hi:[0,1,1] neg_lo:[1,0,0] neg_hi:[1,0,0]
	v_pk_fma_f32 v[234:235], v[46:47], v[166:167], v[234:235] op_sel:[1,0,0] op_sel_hi:[1,1,1] neg_lo:[1,0,0] neg_hi:[1,0,0]
	v_pk_fma_f32 v[236:237], v[48:49], v[168:169], v[236:237] op_sel:[0,0,0] op_sel_hi:[0,1,1] neg_lo:[1,0,0] neg_hi:[1,0,0]
	v_pk_fma_f32 v[238:239], v[48:49], v[170:171], v[238:239] op_sel:[1,0,0] op_sel_hi:[1,1,1] neg_lo:[1,0,0] neg_hi:[1,0,0]
	ds_read_b128 v[46:49], v241 offset:12128
	s_waitcnt lgkmcnt(7)
	v_pk_fma_f32 v[176:177], v[50:51], v[172:173], v[176:177] op_sel:[0,0,0] op_sel_hi:[0,1,1] neg_lo:[1,0,0] neg_hi:[1,0,0]
	v_pk_fma_f32 v[234:235], v[50:51], v[174:175], v[234:235] op_sel:[1,0,0] op_sel_hi:[1,1,1] neg_lo:[1,0,0] neg_hi:[1,0,0]
	v_pk_add_f32 v[236:237], v[176:177], v[236:237]
	v_pk_add_f32 v[236:237], v[236:237], v[238:239]
	v_pk_add_f32 v[176:177], v[236:237], v[234:235]
	ds_read_b128 v[50:53], v241 offset:12144
	s_waitcnt lgkmcnt(7)
	v_pk_fma_f32 v[178:179], v[2:3], v[6:7], v[178:179] op_sel:[0,0,0] op_sel_hi:[0,1,1] neg_lo:[1,0,0] neg_hi:[1,0,0]
	v_pk_mul_f32 v[234:235], v[2:3], v[54:55] op_sel:[1,0] op_sel_hi:[1,1] neg_lo:[1,0] neg_hi:[1,0]
	v_pk_mul_f32 v[236:237], v[4:5], v[56:57] op_sel:[0,0] op_sel_hi:[0,1] neg_lo:[1,0] neg_hi:[1,0]
	v_pk_mul_f32 v[238:239], v[4:5], v[58:59] op_sel:[1,0] op_sel_hi:[1,1] neg_lo:[1,0] neg_hi:[1,0]
	ds_read_b128 v[2:5], v241 offset:12160
	s_waitcnt lgkmcnt(7)
	v_pk_fma_f32 v[178:179], v[26:27], v[60:61], v[178:179] op_sel:[0,0,0] op_sel_hi:[0,1,1] neg_lo:[1,0,0] neg_hi:[1,0,0]
	v_pk_fma_f32 v[234:235], v[26:27], v[62:63], v[234:235] op_sel:[1,0,0] op_sel_hi:[1,1,1] neg_lo:[1,0,0] neg_hi:[1,0,0]
	v_pk_fma_f32 v[236:237], v[28:29], v[64:65], v[236:237] op_sel:[0,0,0] op_sel_hi:[0,1,1] neg_lo:[1,0,0] neg_hi:[1,0,0]
	v_pk_fma_f32 v[238:239], v[28:29], v[66:67], v[238:239] op_sel:[1,0,0] op_sel_hi:[1,1,1] neg_lo:[1,0,0] neg_hi:[1,0,0]
	ds_read_b128 v[26:29], v241 offset:12176
	s_waitcnt lgkmcnt(7)
	v_pk_fma_f32 v[178:179], v[30:31], v[68:69], v[178:179] op_sel:[0,0,0] op_sel_hi:[0,1,1] neg_lo:[1,0,0] neg_hi:[1,0,0]
	v_pk_fma_f32 v[234:235], v[30:31], v[70:71], v[234:235] op_sel:[1,0,0] op_sel_hi:[1,1,1] neg_lo:[1,0,0] neg_hi:[1,0,0]
	v_pk_fma_f32 v[236:237], v[32:33], v[72:73], v[236:237] op_sel:[0,0,0] op_sel_hi:[0,1,1] neg_lo:[1,0,0] neg_hi:[1,0,0]
	v_pk_fma_f32 v[238:239], v[32:33], v[74:75], v[238:239] op_sel:[1,0,0] op_sel_hi:[1,1,1] neg_lo:[1,0,0] neg_hi:[1,0,0]
	ds_read_b128 v[30:33], v241 offset:12192
	s_waitcnt lgkmcnt(7)
	v_pk_fma_f32 v[178:179], v[34:35], v[76:77], v[178:179] op_sel:[0,0,0] op_sel_hi:[0,1,1] neg_lo:[1,0,0] neg_hi:[1,0,0]
	v_pk_fma_f32 v[234:235], v[34:35], v[78:79], v[234:235] op_sel:[1,0,0] op_sel_hi:[1,1,1] neg_lo:[1,0,0] neg_hi:[1,0,0]
	v_pk_fma_f32 v[236:237], v[36:37], v[80:81], v[236:237] op_sel:[0,0,0] op_sel_hi:[0,1,1] neg_lo:[1,0,0] neg_hi:[1,0,0]
	v_pk_fma_f32 v[238:239], v[36:37], v[82:83], v[238:239] op_sel:[1,0,0] op_sel_hi:[1,1,1] neg_lo:[1,0,0] neg_hi:[1,0,0]
	ds_read_b128 v[34:37], v241 offset:12208
	s_waitcnt lgkmcnt(7)
	v_pk_fma_f32 v[178:179], v[38:39], v[84:85], v[178:179] op_sel:[0,0,0] op_sel_hi:[0,1,1] neg_lo:[1,0,0] neg_hi:[1,0,0]
	v_pk_fma_f32 v[234:235], v[38:39], v[86:87], v[234:235] op_sel:[1,0,0] op_sel_hi:[1,1,1] neg_lo:[1,0,0] neg_hi:[1,0,0]
	v_pk_fma_f32 v[236:237], v[40:41], v[88:89], v[236:237] op_sel:[0,0,0] op_sel_hi:[0,1,1] neg_lo:[1,0,0] neg_hi:[1,0,0]
	v_pk_fma_f32 v[238:239], v[40:41], v[90:91], v[238:239] op_sel:[1,0,0] op_sel_hi:[1,1,1] neg_lo:[1,0,0] neg_hi:[1,0,0]
	ds_read_b128 v[38:41], v241 offset:12288
	s_waitcnt lgkmcnt(7)
	v_pk_fma_f32 v[178:179], v[42:43], v[92:93], v[178:179] op_sel:[0,0,0] op_sel_hi:[0,1,1] neg_lo:[1,0,0] neg_hi:[1,0,0]
	v_pk_fma_f32 v[234:235], v[42:43], v[94:95], v[234:235] op_sel:[1,0,0] op_sel_hi:[1,1,1] neg_lo:[1,0,0] neg_hi:[1,0,0]
	v_pk_fma_f32 v[236:237], v[44:45], v[96:97], v[236:237] op_sel:[0,0,0] op_sel_hi:[0,1,1] neg_lo:[1,0,0] neg_hi:[1,0,0]
	v_pk_fma_f32 v[238:239], v[44:45], v[98:99], v[238:239] op_sel:[1,0,0] op_sel_hi:[1,1,1] neg_lo:[1,0,0] neg_hi:[1,0,0]
	ds_read_b128 v[42:45], v241 offset:12304
	s_waitcnt lgkmcnt(7)
; template <int DIR>
; __device__ __forceinline__ void dn_solve(const P& p, int task, int m0, int h, int t2, const bf16_t* kn_s, const bf16_t* v_s, const float* gc, const float* be, float* L) {
;     ...
; #pragma unroll
;     for (int cp = 1; cp < 64; ++cp) {
;         float a0 = 0.f, a1 = 0.f, a2 = 0.f, a3 = 0.f;
; #pragma unroll
;         for (int s4 = 0; s4 < cp; s4 += 4) { const f32x4 l4 = *(const f32x4*)(L + cp * 64 + s4); a0 += l4[0] * x[s4]; a1 += l4[1] * x[s4 + 1]; a2 += l4[2] * x[s4 + 2]; a3 += l4[3] * x[s4 + 3]; }
;         x[cp] -= (a0 + a1) + (a2 + a3);
;     }
	v_pk_fma_f32 v[178:179], v[46:47], v[100:101], v[178:179] op_sel:[0,0,0] op_sel_hi:[0,1,1] neg_lo:[1,0,0] neg_hi:[1,0,0]
	v_pk_fma_f32 v[234:235], v[46:47], v[102:103], v[234:235] op_sel:[1,0,0] op_sel_hi:[1,1,1] neg_lo:[1,0,0] neg_hi:[1,0,0]
	v_pk_fma_f32 v[236:237], v[48:49], v[104:105], v[236:237] op_sel:[0,0,0] op_sel_hi:[0,1,1] neg_lo:[1,0,0] neg_hi:[1,0,0]
	v_pk_fma_f32 v[238:239], v[48:49], v[106:107], v[238:239] op_sel:[1,0,0] op_sel_hi:[1,1,1] neg_lo:[1,0,0] neg_hi:[1,0,0]
	ds_read_b128 v[46:49], v241 offset:12320
	s_waitcnt lgkmcnt(7)
	v_pk_fma_f32 v[178:179], v[50:51], v[108:109], v[178:179] op_sel:[0,0,0] op_sel_hi:[0,1,1] neg_lo:[1,0,0] neg_hi:[1,0,0]
	v_pk_fma_f32 v[234:235], v[50:51], v[110:111], v[234:235] op_sel:[1,0,0] op_sel_hi:[1,1,1] neg_lo:[1,0,0] neg_hi:[1,0,0]
	v_pk_fma_f32 v[236:237], v[52:53], v[112:113], v[236:237] op_sel:[0,0,0] op_sel_hi:[0,1,1] neg_lo:[1,0,0] neg_hi:[1,0,0]
	v_pk_fma_f32 v[238:239], v[52:53], v[114:115], v[238:239] op_sel:[1,0,0] op_sel_hi:[1,1,1] neg_lo:[1,0,0] neg_hi:[1,0,0]
	ds_read_b128 v[50:53], v241 offset:12336
	s_waitcnt lgkmcnt(7)
	v_pk_fma_f32 v[178:179], v[2:3], v[116:117], v[178:179] op_sel:[0,0,0] op_sel_hi:[0,1,1] neg_lo:[1,0,0] neg_hi:[1,0,0]
	v_pk_fma_f32 v[234:235], v[2:3], v[118:119], v[234:235] op_sel:[1,0,0] op_sel_hi:[1,1,1] neg_lo:[1,0,0] neg_hi:[1,0,0]
	v_pk_fma_f32 v[236:237], v[4:5], v[152:153], v[236:237] op_sel:[0,0,0] op_sel_hi:[0,1,1] neg_lo:[1,0,0] neg_hi:[1,0,0]
	v_pk_fma_f32 v[238:239], v[4:5], v[154:155], v[238:239] op_sel:[1,0,0] op_sel_hi:[1,1,1] neg_lo:[1,0,0] neg_hi:[1,0,0]
	ds_read_b128 v[2:5], v241 offset:12352
	s_waitcnt lgkmcnt(7)
	v_pk_fma_f32 v[178:179], v[26:27], v[156:157], v[178:179] op_sel:[0,0,0] op_sel_hi:[0,1,1] neg_lo:[1,0,0] neg_hi:[1,0,0]
	v_pk_fma_f32 v[234:235], v[26:27], v[158:159], v[234:235] op_sel:[1,0,0] op_sel_hi:[1,1,1] neg_lo:[1,0,0] neg_hi:[1,0,0]
	v_pk_fma_f32 v[236:237], v[28:29], v[160:161], v[236:237] op_sel:[0,0,0] op_sel_hi:[0,1,1] neg_lo:[1,0,0] neg_hi:[1,0,0]
	v_pk_fma_f32 v[238:239], v[28:29], v[162:163], v[238:239] op_sel:[1,0,0] op_sel_hi:[1,1,1] neg_lo:[1,0,0] neg_hi:[1,0,0]
	ds_read_b128 v[26:29], v241 offset:12368
	s_waitcnt lgkmcnt(7)
	v_pk_fma_f32 v[178:179], v[30:31], v[164:165], v[178:179] op_sel:[0,0,0] op_sel_hi:[0,1,1] neg_lo:[1,0,0] neg_hi:[1,0,0]
	v_pk_fma_f32 v[234:235], v[30:31], v[166:167], v[234:235] op_sel:[1,0,0] op_sel_hi:[1,1,1] neg_lo:[1,0,0] neg_hi:[1,0,0]
	v_pk_fma_f32 v[236:237], v[32:33], v[168:169], v[236:237] op_sel:[0,0,0] op_sel_hi:[0,1,1] neg_lo:[1,0,0] neg_hi:[1,0,0]
	v_pk_fma_f32 v[238:239], v[32:33], v[170:171], v[238:239] op_sel:[1,0,0] op_sel_hi:[1,1,1] neg_lo:[1,0,0] neg_hi:[1,0,0]
	ds_read_b128 v[30:33], v241 offset:12384
	s_waitcnt lgkmcnt(7)
	v_pk_fma_f32 v[178:179], v[34:35], v[172:173], v[178:179] op_sel:[0,0,0] op_sel_hi:[0,1,1] neg_lo:[1,0,0] neg_hi:[1,0,0]
	v_pk_fma_f32 v[234:235], v[34:35], v[174:175], v[234:235] op_sel:[1,0,0] op_sel_hi:[1,1,1] neg_lo:[1,0,0] neg_hi:[1,0,0]
	v_pk_fma_f32 v[236:237], v[36:37], v[176:177], v[236:237] op_sel:[0,0,0] op_sel_hi:[0,1,1] neg_lo:[1,0,0] neg_hi:[1,0,0]
	v_pk_add_f32 v[234:235], v[178:179], v[234:235]
	v_pk_add_f32 v[234:235], v[234:235], v[238:239]
	v_pk_add_f32 v[178:179], v[234:235], v[236:237]
	ds_read_b128 v[34:37], v241 offset:12400
	s_waitcnt lgkmcnt(7)
	v_pk_fma_f32 v[180:181], v[38:39], v[6:7], v[180:181] op_sel:[0,0,0] op_sel_hi:[0,1,1] neg_lo:[1,0,0] neg_hi:[1,0,0]
	v_pk_mul_f32 v[234:235], v[38:39], v[54:55] op_sel:[1,0] op_sel_hi:[1,1] neg_lo:[1,0] neg_hi:[1,0]
	v_pk_mul_f32 v[236:237], v[40:41], v[56:57] op_sel:[0,0] op_sel_hi:[0,1] neg_lo:[1,0] neg_hi:[1,0]
	v_pk_mul_f32 v[238:239], v[40:41], v[58:59] op_sel:[1,0] op_sel_hi:[1,1] neg_lo:[1,0] neg_hi:[1,0]
	ds_read_b128 v[38:41], v241 offset:12416
	s_waitcnt lgkmcnt(7)
	v_pk_fma_f32 v[180:181], v[42:43], v[60:61], v[180:181] op_sel:[0,0,0] op_sel_hi:[0,1,1] neg_lo:[1,0,0] neg_hi:[1,0,0]
	v_pk_fma_f32 v[234:235], v[42:43], v[62:63], v[234:235] op_sel:[1,0,0] op_sel_hi:[1,1,1] neg_lo:[1,0,0] neg_hi:[1,0,0]
	v_pk_fma_f32 v[236:237], v[44:45], v[64:65], v[236:237] op_sel:[0,0,0] op_sel_hi:[0,1,1] neg_lo:[1,0,0] neg_hi:[1,0,0]
	v_pk_fma_f32 v[238:239], v[44:45], v[66:67], v[238:239] op_sel:[1,0,0] op_sel_hi:[1,1,1] neg_lo:[1,0,0] neg_hi:[1,0,0]
	ds_read_b128 v[42:45], v241 offset:12432
	s_waitcnt lgkmcnt(7)
	v_pk_fma_f32 v[180:181], v[46:47], v[68:69], v[180:181] op_sel:[0,0,0] op_sel_hi:[0,1,1] neg_lo:[1,0,0] neg_hi:[1,0,0]
	v_pk_fma_f32 v[234:235], v[46:47], v[70:71], v[234:235] op_sel:[1,0,0] op_sel_hi:[1,1,1] neg_lo:[1,0,0] neg_hi:[1,0,0]
	v_pk_fma_f32 v[236:237], v[48:49], v[72:73], v[236:237] op_sel:[0,0,0] op_sel_hi:[0,1,1] neg_lo:[1,0,0] neg_hi:[1,0,0]
	v_pk_fma_f32 v[238:239], v[48:49], v[74:75], v[238:239] op_sel:[1,0,0] op_sel_hi:[1,1,1] neg_lo:[1,0,0] neg_hi:[1,0,0]
	ds_read_b128 v[46:49], v241 offset:12448
	s_waitcnt lgkmcnt(7)
	v_pk_fma_f32 v[180:181], v[50:51], v[76:77], v[180:181] op_sel:[0,0,0] op_sel_hi:[0,1,1] neg_lo:[1,0,0] neg_hi:[1,0,0]
	v_pk_fma_f32 v[234:235], v[50:51], v[78:79], v[234:235] op_sel:[1,0,0] op_sel_hi:[1,1,1] neg_lo:[1,0,0] neg_hi:[1,0,0]
	v_pk_fma_f32 v[236:237], v[52:53], v[80:81], v[236:237] op_sel:[0,0,0] op_sel_hi:[0,1,1] neg_lo:[1,0,0] neg_hi:[1,0,0]
	v_pk_fma_f32 v[238:239], v[52:53], v[82:83], v[238:239] op_sel:[1,0,0] op_sel_hi:[1,1,1] neg_lo:[1,0,0] neg_hi:[1,0,0]
	ds_read_b128 v[50:53], v241 offset:12464
	s_waitcnt lgkmcnt(7)
; template <int DIR>
; __device__ __forceinline__ void dn_solve(const P& p, int task, int m0, int h, int t2, const bf16_t* kn_s, const bf16_t* v_s, const float* gc, const float* be, float* L) {
;     ...
; #pragma unroll
;     for (int cp = 1; cp < 64; ++cp) {
;         float a0 = 0.f, a1 = 0.f, a2 = 0.f, a3 = 0.f;
; #pragma unroll
;         for (int s4 = 0; s4 < cp; s4 += 4) { const f32x4 l4 = *(const f32x4*)(L + cp * 64 + s4); a0 += l4[0] * x[s4]; a1 += l4[1] * x[s4 + 1]; a2 += l4[2] * x[s4 + 2]; a3 += l4[3] * x[s4 + 3]; }
;         x[cp] -= (a0 + a1) + (a2 + a3);
;     }
	v_pk_fma_f32 v[180:181], v[2:3], v[84:85], v[180:181] op_sel:[0,0,0] op_sel_hi:[0,1,1] neg_lo:[1,0,0] neg_hi:[1,0,0]
	v_pk_fma_f32 v[234:235], v[2:3], v[86:87], v[234:235] op_sel:[1,0,0] op_sel_hi:[1,1,1] neg_lo:[1,0,0] neg_hi:[1,0,0]
	v_pk_fma_f32 v[236:237], v[4:5], v[88:89], v[236:237] op_sel:[0,0,0] op_sel_hi:[0,1,1] neg_lo:[1,0,0] neg_hi:[1,0,0]
	v_pk_fma_f32 v[238:239], v[4:5], v[90:91], v[238:239] op_sel:[1,0,0] op_sel_hi:[1,1,1] neg_lo:[1,0,0] neg_hi:[1,0,0]
	ds_read_b128 v[2:5], v241 offset:12544
	s_waitcnt lgkmcnt(7)
	v_pk_fma_f32 v[180:181], v[26:27], v[92:93], v[180:181] op_sel:[0,0,0] op_sel_hi:[0,1,1] neg_lo:[1,0,0] neg_hi:[1,0,0]
	v_pk_fma_f32 v[234:235], v[26:27], v[94:95], v[234:235] op_sel:[1,0,0] op_sel_hi:[1,1,1] neg_lo:[1,0,0] neg_hi:[1,0,0]
	v_pk_fma_f32 v[236:237], v[28:29], v[96:97], v[236:237] op_sel:[0,0,0] op_sel_hi:[0,1,1] neg_lo:[1,0,0] neg_hi:[1,0,0]
	v_pk_fma_f32 v[238:239], v[28:29], v[98:99], v[238:239] op_sel:[1,0,0] op_sel_hi:[1,1,1] neg_lo:[1,0,0] neg_hi:[1,0,0]
	ds_read_b128 v[26:29], v241 offset:12560
	s_waitcnt lgkmcnt(7)
	v_pk_fma_f32 v[180:181], v[30:31], v[100:101], v[180:181] op_sel:[0,0,0] op_sel_hi:[0,1,1] neg_lo:[1,0,0] neg_hi:[1,0,0]
	v_pk_fma_f32 v[234:235], v[30:31], v[102:103], v[234:235] op_sel:[1,0,0] op_sel_hi:[1,1,1] neg_lo:[1,0,0] neg_hi:[1,0,0]
	v_pk_fma_f32 v[236:237], v[32:33], v[104:105], v[236:237] op_sel:[0,0,0] op_sel_hi:[0,1,1] neg_lo:[1,0,0] neg_hi:[1,0,0]
	v_pk_fma_f32 v[238:239], v[32:33], v[106:107], v[238:239] op_sel:[1,0,0] op_sel_hi:[1,1,1] neg_lo:[1,0,0] neg_hi:[1,0,0]
	ds_read_b128 v[30:33], v241 offset:12576
	s_waitcnt lgkmcnt(7)
	v_pk_fma_f32 v[180:181], v[34:35], v[108:109], v[180:181] op_sel:[0,0,0] op_sel_hi:[0,1,1] neg_lo:[1,0,0] neg_hi:[1,0,0]
	v_pk_fma_f32 v[234:235], v[34:35], v[110:111], v[234:235] op_sel:[1,0,0] op_sel_hi:[1,1,1] neg_lo:[1,0,0] neg_hi:[1,0,0]
	v_pk_fma_f32 v[236:237], v[36:37], v[112:113], v[236:237] op_sel:[0,0,0] op_sel_hi:[0,1,1] neg_lo:[1,0,0] neg_hi:[1,0,0]
	v_pk_fma_f32 v[238:239], v[36:37], v[114:115], v[238:239] op_sel:[1,0,0] op_sel_hi:[1,1,1] neg_lo:[1,0,0] neg_hi:[1,0,0]
	ds_read_b128 v[34:37], v241 offset:12592
	s_waitcnt lgkmcnt(7)
	v_pk_fma_f32 v[180:181], v[38:39], v[116:117], v[180:181] op_sel:[0,0,0] op_sel_hi:[0,1,1] neg_lo:[1,0,0] neg_hi:[1,0,0]
	v_pk_fma_f32 v[234:235], v[38:39], v[118:119], v[234:235] op_sel:[1,0,0] op_sel_hi:[1,1,1] neg_lo:[1,0,0] neg_hi:[1,0,0]
	v_pk_fma_f32 v[236:237], v[40:41], v[152:153], v[236:237] op_sel:[0,0,0] op_sel_hi:[0,1,1] neg_lo:[1,0,0] neg_hi:[1,0,0]
	v_pk_fma_f32 v[238:239], v[40:41], v[154:155], v[238:239] op_sel:[1,0,0] op_sel_hi:[1,1,1] neg_lo:[1,0,0] neg_hi:[1,0,0]
	ds_read_b128 v[38:41], v241 offset:12608
	s_waitcnt lgkmcnt(7)
	v_pk_fma_f32 v[180:181], v[42:43], v[156:157], v[180:181] op_sel:[0,0,0] op_sel_hi:[0,1,1] neg_lo:[1,0,0] neg_hi:[1,0,0]
	v_pk_fma_f32 v[234:235], v[42:43], v[158:159], v[234:235] op_sel:[1,0,0] op_sel_hi:[1,1,1] neg_lo:[1,0,0] neg_hi:[1,0,0]
	v_pk_fma_f32 v[236:237], v[44:45], v[160:161], v[236:237] op_sel:[0,0,0] op_sel_hi:[0,1,1] neg_lo:[1,0,0] neg_hi:[1,0,0]
	v_pk_fma_f32 v[238:239], v[44:45], v[162:163], v[238:239] op_sel:[1,0,0] op_sel_hi:[1,1,1] neg_lo:[1,0,0] neg_hi:[1,0,0]
	ds_read_b128 v[42:45], v241 offset:12624
	s_waitcnt lgkmcnt(7)
	v_pk_fma_f32 v[180:181], v[46:47], v[164:165], v[180:181] op_sel:[0,0,0] op_sel_hi:[0,1,1] neg_lo:[1,0,0] neg_hi:[1,0,0]
	v_pk_fma_f32 v[234:235], v[46:47], v[166:167], v[234:235] op_sel:[1,0,0] op_sel_hi:[1,1,1] neg_lo:[1,0,0] neg_hi:[1,0,0]
	v_pk_fma_f32 v[236:237], v[48:49], v[168:169], v[236:237] op_sel:[0,0,0] op_sel_hi:[0,1,1] neg_lo:[1,0,0] neg_hi:[1,0,0]
	v_pk_fma_f32 v[238:239], v[48:49], v[170:171], v[238:239] op_sel:[1,0,0] op_sel_hi:[1,1,1] neg_lo:[1,0,0] neg_hi:[1,0,0]
	ds_read_b128 v[46:49], v241 offset:12640
	s_waitcnt lgkmcnt(7)
	v_pk_fma_f32 v[180:181], v[50:51], v[172:173], v[180:181] op_sel:[0,0,0] op_sel_hi:[0,1,1] neg_lo:[1,0,0] neg_hi:[1,0,0]
	v_pk_fma_f32 v[234:235], v[50:51], v[174:175], v[234:235] op_sel:[1,0,0] op_sel_hi:[1,1,1] neg_lo:[1,0,0] neg_hi:[1,0,0]
	v_pk_fma_f32 v[236:237], v[52:53], v[176:177], v[236:237] op_sel:[0,0,0] op_sel_hi:[0,1,1] neg_lo:[1,0,0] neg_hi:[1,0,0]
	v_pk_fma_f32 v[238:239], v[52:53], v[178:179], v[238:239] op_sel:[1,0,0] op_sel_hi:[1,1,1] neg_lo:[1,0,0] neg_hi:[1,0,0]
	v_pk_add_f32 v[234:235], v[180:181], v[234:235]
	v_pk_add_f32 v[234:235], v[234:235], v[236:237]
	v_pk_add_f32 v[180:181], v[234:235], v[238:239]
	ds_read_b128 v[50:53], v241 offset:12656
	s_waitcnt lgkmcnt(7)
	v_pk_fma_f32 v[182:183], v[2:3], v[6:7], v[182:183] op_sel:[0,0,0] op_sel_hi:[0,1,1] neg_lo:[1,0,0] neg_hi:[1,0,0]
	v_pk_mul_f32 v[234:235], v[2:3], v[54:55] op_sel:[1,0] op_sel_hi:[1,1] neg_lo:[1,0] neg_hi:[1,0]
	v_pk_mul_f32 v[236:237], v[4:5], v[56:57] op_sel:[0,0] op_sel_hi:[0,1] neg_lo:[1,0] neg_hi:[1,0]
	v_pk_mul_f32 v[238:239], v[4:5], v[58:59] op_sel:[1,0] op_sel_hi:[1,1] neg_lo:[1,0] neg_hi:[1,0]
	ds_read_b128 v[2:5], v241 offset:12672
	s_waitcnt lgkmcnt(7)
	v_pk_fma_f32 v[182:183], v[26:27], v[60:61], v[182:183] op_sel:[0,0,0] op_sel_hi:[0,1,1] neg_lo:[1,0,0] neg_hi:[1,0,0]
	v_pk_fma_f32 v[234:235], v[26:27], v[62:63], v[234:235] op_sel:[1,0,0] op_sel_hi:[1,1,1] neg_lo:[1,0,0] neg_hi:[1,0,0]
	v_pk_fma_f32 v[236:237], v[28:29], v[64:65], v[236:237] op_sel:[0,0,0] op_sel_hi:[0,1,1] neg_lo:[1,0,0] neg_hi:[1,0,0]
	v_pk_fma_f32 v[238:239], v[28:29], v[66:67], v[238:239] op_sel:[1,0,0] op_sel_hi:[1,1,1] neg_lo:[1,0,0] neg_hi:[1,0,0]
	ds_read_b128 v[26:29], v241 offset:12688
	s_waitcnt lgkmcnt(7)
; template <int DIR>
; __device__ __forceinline__ void dn_solve(const P& p, int task, int m0, int h, int t2, const bf16_t* kn_s, const bf16_t* v_s, const float* gc, const float* be, float* L) {
;     ...
; #pragma unroll
;     for (int cp = 1; cp < 64; ++cp) {
;         float a0 = 0.f, a1 = 0.f, a2 = 0.f, a3 = 0.f;
; #pragma unroll
;         for (int s4 = 0; s4 < cp; s4 += 4) { const f32x4 l4 = *(const f32x4*)(L + cp * 64 + s4); a0 += l4[0] * x[s4]; a1 += l4[1] * x[s4 + 1]; a2 += l4[2] * x[s4 + 2]; a3 += l4[3] * x[s4 + 3]; }
;         x[cp] -= (a0 + a1) + (a2 + a3);
;     }
	v_pk_fma_f32 v[182:183], v[30:31], v[68:69], v[182:183] op_sel:[0,0,0] op_sel_hi:[0,1,1] neg_lo:[1,0,0] neg_hi:[1,0,0]
	v_pk_fma_f32 v[234:235], v[30:31], v[70:71], v[234:235] op_sel:[1,0,0] op_sel_hi:[1,1,1] neg_lo:[1,0,0] neg_hi:[1,0,0]
	v_pk_fma_f32 v[236:237], v[32:33], v[72:73], v[236:237] op_sel:[0,0,0] op_sel_hi:[0,1,1] neg_lo:[1,0,0] neg_hi:[1,0,0]
	v_pk_fma_f32 v[238:239], v[32:33], v[74:75], v[238:239] op_sel:[1,0,0] op_sel_hi:[1,1,1] neg_lo:[1,0,0] neg_hi:[1,0,0]
	ds_read_b128 v[30:33], v241 offset:12704
	s_waitcnt lgkmcnt(7)
	v_pk_fma_f32 v[182:183], v[34:35], v[76:77], v[182:183] op_sel:[0,0,0] op_sel_hi:[0,1,1] neg_lo:[1,0,0] neg_hi:[1,0,0]
	v_pk_fma_f32 v[234:235], v[34:35], v[78:79], v[234:235] op_sel:[1,0,0] op_sel_hi:[1,1,1] neg_lo:[1,0,0] neg_hi:[1,0,0]
	v_pk_fma_f32 v[236:237], v[36:37], v[80:81], v[236:237] op_sel:[0,0,0] op_sel_hi:[0,1,1] neg_lo:[1,0,0] neg_hi:[1,0,0]
	v_pk_fma_f32 v[238:239], v[36:37], v[82:83], v[238:239] op_sel:[1,0,0] op_sel_hi:[1,1,1] neg_lo:[1,0,0] neg_hi:[1,0,0]
	ds_read_b128 v[34:37], v241 offset:12720
	s_waitcnt lgkmcnt(7)
	v_pk_fma_f32 v[182:183], v[38:39], v[84:85], v[182:183] op_sel:[0,0,0] op_sel_hi:[0,1,1] neg_lo:[1,0,0] neg_hi:[1,0,0]
	v_pk_fma_f32 v[234:235], v[38:39], v[86:87], v[234:235] op_sel:[1,0,0] op_sel_hi:[1,1,1] neg_lo:[1,0,0] neg_hi:[1,0,0]
	v_pk_fma_f32 v[236:237], v[40:41], v[88:89], v[236:237] op_sel:[0,0,0] op_sel_hi:[0,1,1] neg_lo:[1,0,0] neg_hi:[1,0,0]
	v_pk_fma_f32 v[238:239], v[40:41], v[90:91], v[238:239] op_sel:[1,0,0] op_sel_hi:[1,1,1] neg_lo:[1,0,0] neg_hi:[1,0,0]
	ds_read_b128 v[38:41], v241 offset:12736
	s_waitcnt lgkmcnt(7)
	v_pk_fma_f32 v[182:183], v[42:43], v[92:93], v[182:183] op_sel:[0,0,0] op_sel_hi:[0,1,1] neg_lo:[1,0,0] neg_hi:[1,0,0]
	v_pk_fma_f32 v[234:235], v[42:43], v[94:95], v[234:235] op_sel:[1,0,0] op_sel_hi:[1,1,1] neg_lo:[1,0,0] neg_hi:[1,0,0]
	v_pk_fma_f32 v[236:237], v[44:45], v[96:97], v[236:237] op_sel:[0,0,0] op_sel_hi:[0,1,1] neg_lo:[1,0,0] neg_hi:[1,0,0]
	v_pk_fma_f32 v[238:239], v[44:45], v[98:99], v[238:239] op_sel:[1,0,0] op_sel_hi:[1,1,1] neg_lo:[1,0,0] neg_hi:[1,0,0]
	ds_read_b128 v[42:45], v241 offset:12800
	s_waitcnt lgkmcnt(7)
	v_pk_fma_f32 v[182:183], v[46:47], v[100:101], v[182:183] op_sel:[0,0,0] op_sel_hi:[0,1,1] neg_lo:[1,0,0] neg_hi:[1,0,0]
	v_pk_fma_f32 v[234:235], v[46:47], v[102:103], v[234:235] op_sel:[1,0,0] op_sel_hi:[1,1,1] neg_lo:[1,0,0] neg_hi:[1,0,0]
	v_pk_fma_f32 v[236:237], v[48:49], v[104:105], v[236:237] op_sel:[0,0,0] op_sel_hi:[0,1,1] neg_lo:[1,0,0] neg_hi:[1,0,0]
	v_pk_fma_f32 v[238:239], v[48:49], v[106:107], v[238:239] op_sel:[1,0,0] op_sel_hi:[1,1,1] neg_lo:[1,0,0] neg_hi:[1,0,0]
	ds_read_b128 v[46:49], v241 offset:12816
	s_waitcnt lgkmcnt(7)
	v_pk_fma_f32 v[182:183], v[50:51], v[108:109], v[182:183] op_sel:[0,0,0] op_sel_hi:[0,1,1] neg_lo:[1,0,0] neg_hi:[1,0,0]
	v_pk_fma_f32 v[234:235], v[50:51], v[110:111], v[234:235] op_sel:[1,0,0] op_sel_hi:[1,1,1] neg_lo:[1,0,0] neg_hi:[1,0,0]
	v_pk_fma_f32 v[236:237], v[52:53], v[112:113], v[236:237] op_sel:[0,0,0] op_sel_hi:[0,1,1] neg_lo:[1,0,0] neg_hi:[1,0,0]
	v_pk_fma_f32 v[238:239], v[52:53], v[114:115], v[238:239] op_sel:[1,0,0] op_sel_hi:[1,1,1] neg_lo:[1,0,0] neg_hi:[1,0,0]
	ds_read_b128 v[50:53], v241 offset:12832
	s_waitcnt lgkmcnt(7)
	v_pk_fma_f32 v[182:183], v[2:3], v[116:117], v[182:183] op_sel:[0,0,0] op_sel_hi:[0,1,1] neg_lo:[1,0,0] neg_hi:[1,0,0]
	v_pk_fma_f32 v[234:235], v[2:3], v[118:119], v[234:235] op_sel:[1,0,0] op_sel_hi:[1,1,1] neg_lo:[1,0,0] neg_hi:[1,0,0]
	v_pk_fma_f32 v[236:237], v[4:5], v[152:153], v[236:237] op_sel:[0,0,0] op_sel_hi:[0,1,1] neg_lo:[1,0,0] neg_hi:[1,0,0]
	v_pk_fma_f32 v[238:239], v[4:5], v[154:155], v[238:239] op_sel:[1,0,0] op_sel_hi:[1,1,1] neg_lo:[1,0,0] neg_hi:[1,0,0]
	ds_read_b128 v[2:5], v241 offset:12848
	s_waitcnt lgkmcnt(7)
	v_pk_fma_f32 v[182:183], v[26:27], v[156:157], v[182:183] op_sel:[0,0,0] op_sel_hi:[0,1,1] neg_lo:[1,0,0] neg_hi:[1,0,0]
	v_pk_fma_f32 v[234:235], v[26:27], v[158:159], v[234:235] op_sel:[1,0,0] op_sel_hi:[1,1,1] neg_lo:[1,0,0] neg_hi:[1,0,0]
	v_pk_fma_f32 v[236:237], v[28:29], v[160:161], v[236:237] op_sel:[0,0,0] op_sel_hi:[0,1,1] neg_lo:[1,0,0] neg_hi:[1,0,0]
	v_pk_fma_f32 v[238:239], v[28:29], v[162:163], v[238:239] op_sel:[1,0,0] op_sel_hi:[1,1,1] neg_lo:[1,0,0] neg_hi:[1,0,0]
	ds_read_b128 v[26:29], v241 offset:12864
	s_waitcnt lgkmcnt(7)
	v_pk_fma_f32 v[182:183], v[30:31], v[164:165], v[182:183] op_sel:[0,0,0] op_sel_hi:[0,1,1] neg_lo:[1,0,0] neg_hi:[1,0,0]
	v_pk_fma_f32 v[234:235], v[30:31], v[166:167], v[234:235] op_sel:[1,0,0] op_sel_hi:[1,1,1] neg_lo:[1,0,0] neg_hi:[1,0,0]
	v_pk_fma_f32 v[236:237], v[32:33], v[168:169], v[236:237] op_sel:[0,0,0] op_sel_hi:[0,1,1] neg_lo:[1,0,0] neg_hi:[1,0,0]
	v_pk_fma_f32 v[238:239], v[32:33], v[170:171], v[238:239] op_sel:[1,0,0] op_sel_hi:[1,1,1] neg_lo:[1,0,0] neg_hi:[1,0,0]
	ds_read_b128 v[30:33], v241 offset:12880
	s_waitcnt lgkmcnt(7)
	v_pk_fma_f32 v[182:183], v[34:35], v[172:173], v[182:183] op_sel:[0,0,0] op_sel_hi:[0,1,1] neg_lo:[1,0,0] neg_hi:[1,0,0]
	v_pk_fma_f32 v[234:235], v[34:35], v[174:175], v[234:235] op_sel:[1,0,0] op_sel_hi:[1,1,1] neg_lo:[1,0,0] neg_hi:[1,0,0]
	v_pk_fma_f32 v[236:237], v[36:37], v[176:177], v[236:237] op_sel:[0,0,0] op_sel_hi:[0,1,1] neg_lo:[1,0,0] neg_hi:[1,0,0]
	v_pk_fma_f32 v[238:239], v[36:37], v[178:179], v[238:239] op_sel:[1,0,0] op_sel_hi:[1,1,1] neg_lo:[1,0,0] neg_hi:[1,0,0]
	ds_read_b128 v[34:37], v241 offset:12896
	s_waitcnt lgkmcnt(7)
; template <int DIR>
; __device__ __forceinline__ void dn_solve(const P& p, int task, int m0, int h, int t2, const bf16_t* kn_s, const bf16_t* v_s, const float* gc, const float* be, float* L) {
;     ...
; #pragma unroll
;     for (int cp = 1; cp < 64; ++cp) {
;         float a0 = 0.f, a1 = 0.f, a2 = 0.f, a3 = 0.f;
; #pragma unroll
;         for (int s4 = 0; s4 < cp; s4 += 4) { const f32x4 l4 = *(const f32x4*)(L + cp * 64 + s4); a0 += l4[0] * x[s4]; a1 += l4[1] * x[s4 + 1]; a2 += l4[2] * x[s4 + 2]; a3 += l4[3] * x[s4 + 3]; }
;         x[cp] -= (a0 + a1) + (a2 + a3);
;     }
	v_pk_fma_f32 v[182:183], v[38:39], v[180:181], v[182:183] op_sel:[0,0,0] op_sel_hi:[0,1,1] neg_lo:[1,0,0] neg_hi:[1,0,0]
	v_pk_add_f32 v[234:235], v[234:235], v[236:237]
	v_pk_add_f32 v[234:235], v[234:235], v[238:239]
	v_pk_add_f32 v[182:183], v[234:235], v[182:183]
	ds_read_b128 v[38:41], v241 offset:12912
	s_waitcnt lgkmcnt(7)
	v_pk_fma_f32 v[202:203], v[42:43], v[6:7], v[202:203] op_sel:[0,0,0] op_sel_hi:[0,1,1] neg_lo:[1,0,0] neg_hi:[1,0,0]
	v_pk_mul_f32 v[234:235], v[42:43], v[54:55] op_sel:[1,0] op_sel_hi:[1,1] neg_lo:[1,0] neg_hi:[1,0]
	v_pk_mul_f32 v[236:237], v[44:45], v[56:57] op_sel:[0,0] op_sel_hi:[0,1] neg_lo:[1,0] neg_hi:[1,0]
	v_pk_mul_f32 v[238:239], v[44:45], v[58:59] op_sel:[1,0] op_sel_hi:[1,1] neg_lo:[1,0] neg_hi:[1,0]
	ds_read_b128 v[42:45], v241 offset:12928
	s_waitcnt lgkmcnt(7)
	v_pk_fma_f32 v[202:203], v[46:47], v[60:61], v[202:203] op_sel:[0,0,0] op_sel_hi:[0,1,1] neg_lo:[1,0,0] neg_hi:[1,0,0]
	v_pk_fma_f32 v[234:235], v[46:47], v[62:63], v[234:235] op_sel:[1,0,0] op_sel_hi:[1,1,1] neg_lo:[1,0,0] neg_hi:[1,0,0]
	v_pk_fma_f32 v[236:237], v[48:49], v[64:65], v[236:237] op_sel:[0,0,0] op_sel_hi:[0,1,1] neg_lo:[1,0,0] neg_hi:[1,0,0]
	v_pk_fma_f32 v[238:239], v[48:49], v[66:67], v[238:239] op_sel:[1,0,0] op_sel_hi:[1,1,1] neg_lo:[1,0,0] neg_hi:[1,0,0]
	ds_read_b128 v[46:49], v241 offset:12944
	s_waitcnt lgkmcnt(7)
	v_pk_fma_f32 v[202:203], v[50:51], v[68:69], v[202:203] op_sel:[0,0,0] op_sel_hi:[0,1,1] neg_lo:[1,0,0] neg_hi:[1,0,0]
	v_pk_fma_f32 v[234:235], v[50:51], v[70:71], v[234:235] op_sel:[1,0,0] op_sel_hi:[1,1,1] neg_lo:[1,0,0] neg_hi:[1,0,0]
	v_pk_fma_f32 v[236:237], v[52:53], v[72:73], v[236:237] op_sel:[0,0,0] op_sel_hi:[0,1,1] neg_lo:[1,0,0] neg_hi:[1,0,0]
	v_pk_fma_f32 v[238:239], v[52:53], v[74:75], v[238:239] op_sel:[1,0,0] op_sel_hi:[1,1,1] neg_lo:[1,0,0] neg_hi:[1,0,0]
	ds_read_b128 v[50:53], v241 offset:12960
	s_waitcnt lgkmcnt(7)
	v_pk_fma_f32 v[202:203], v[2:3], v[76:77], v[202:203] op_sel:[0,0,0] op_sel_hi:[0,1,1] neg_lo:[1,0,0] neg_hi:[1,0,0]
	v_pk_fma_f32 v[234:235], v[2:3], v[78:79], v[234:235] op_sel:[1,0,0] op_sel_hi:[1,1,1] neg_lo:[1,0,0] neg_hi:[1,0,0]
	v_pk_fma_f32 v[236:237], v[4:5], v[80:81], v[236:237] op_sel:[0,0,0] op_sel_hi:[0,1,1] neg_lo:[1,0,0] neg_hi:[1,0,0]
	v_pk_fma_f32 v[238:239], v[4:5], v[82:83], v[238:239] op_sel:[1,0,0] op_sel_hi:[1,1,1] neg_lo:[1,0,0] neg_hi:[1,0,0]
	ds_read_b128 v[2:5], v241 offset:12976
	s_waitcnt lgkmcnt(7)
	v_pk_fma_f32 v[202:203], v[26:27], v[84:85], v[202:203] op_sel:[0,0,0] op_sel_hi:[0,1,1] neg_lo:[1,0,0] neg_hi:[1,0,0]
	v_pk_fma_f32 v[234:235], v[26:27], v[86:87], v[234:235] op_sel:[1,0,0] op_sel_hi:[1,1,1] neg_lo:[1,0,0] neg_hi:[1,0,0]
	v_pk_fma_f32 v[236:237], v[28:29], v[88:89], v[236:237] op_sel:[0,0,0] op_sel_hi:[0,1,1] neg_lo:[1,0,0] neg_hi:[1,0,0]
	v_pk_fma_f32 v[238:239], v[28:29], v[90:91], v[238:239] op_sel:[1,0,0] op_sel_hi:[1,1,1] neg_lo:[1,0,0] neg_hi:[1,0,0]
	ds_read_b128 v[26:29], v241 offset:12992
	s_waitcnt lgkmcnt(7)
	v_pk_fma_f32 v[202:203], v[30:31], v[92:93], v[202:203] op_sel:[0,0,0] op_sel_hi:[0,1,1] neg_lo:[1,0,0] neg_hi:[1,0,0]
	v_pk_fma_f32 v[234:235], v[30:31], v[94:95], v[234:235] op_sel:[1,0,0] op_sel_hi:[1,1,1] neg_lo:[1,0,0] neg_hi:[1,0,0]
	v_pk_fma_f32 v[236:237], v[32:33], v[96:97], v[236:237] op_sel:[0,0,0] op_sel_hi:[0,1,1] neg_lo:[1,0,0] neg_hi:[1,0,0]
	v_pk_fma_f32 v[238:239], v[32:33], v[98:99], v[238:239] op_sel:[1,0,0] op_sel_hi:[1,1,1] neg_lo:[1,0,0] neg_hi:[1,0,0]
	ds_read_b128 v[30:33], v241 offset:13056
	s_waitcnt lgkmcnt(7)
	v_pk_fma_f32 v[202:203], v[34:35], v[100:101], v[202:203] op_sel:[0,0,0] op_sel_hi:[0,1,1] neg_lo:[1,0,0] neg_hi:[1,0,0]
	v_pk_fma_f32 v[234:235], v[34:35], v[102:103], v[234:235] op_sel:[1,0,0] op_sel_hi:[1,1,1] neg_lo:[1,0,0] neg_hi:[1,0,0]
	v_pk_fma_f32 v[236:237], v[36:37], v[104:105], v[236:237] op_sel:[0,0,0] op_sel_hi:[0,1,1] neg_lo:[1,0,0] neg_hi:[1,0,0]
	v_pk_fma_f32 v[238:239], v[36:37], v[106:107], v[238:239] op_sel:[1,0,0] op_sel_hi:[1,1,1] neg_lo:[1,0,0] neg_hi:[1,0,0]
	ds_read_b128 v[34:37], v241 offset:13072
	s_waitcnt lgkmcnt(7)
	v_pk_fma_f32 v[202:203], v[38:39], v[108:109], v[202:203] op_sel:[0,0,0] op_sel_hi:[0,1,1] neg_lo:[1,0,0] neg_hi:[1,0,0]
	v_pk_fma_f32 v[234:235], v[38:39], v[110:111], v[234:235] op_sel:[1,0,0] op_sel_hi:[1,1,1] neg_lo:[1,0,0] neg_hi:[1,0,0]
	v_pk_fma_f32 v[236:237], v[40:41], v[112:113], v[236:237] op_sel:[0,0,0] op_sel_hi:[0,1,1] neg_lo:[1,0,0] neg_hi:[1,0,0]
	v_pk_fma_f32 v[238:239], v[40:41], v[114:115], v[238:239] op_sel:[1,0,0] op_sel_hi:[1,1,1] neg_lo:[1,0,0] neg_hi:[1,0,0]
	ds_read_b128 v[38:41], v241 offset:13088
	s_waitcnt lgkmcnt(7)
	v_pk_fma_f32 v[202:203], v[42:43], v[116:117], v[202:203] op_sel:[0,0,0] op_sel_hi:[0,1,1] neg_lo:[1,0,0] neg_hi:[1,0,0]
	v_pk_fma_f32 v[234:235], v[42:43], v[118:119], v[234:235] op_sel:[1,0,0] op_sel_hi:[1,1,1] neg_lo:[1,0,0] neg_hi:[1,0,0]
	v_pk_fma_f32 v[236:237], v[44:45], v[152:153], v[236:237] op_sel:[0,0,0] op_sel_hi:[0,1,1] neg_lo:[1,0,0] neg_hi:[1,0,0]
	v_pk_fma_f32 v[238:239], v[44:45], v[154:155], v[238:239] op_sel:[1,0,0] op_sel_hi:[1,1,1] neg_lo:[1,0,0] neg_hi:[1,0,0]
	ds_read_b128 v[42:45], v241 offset:13104
	s_waitcnt lgkmcnt(7)
	v_pk_fma_f32 v[202:203], v[46:47], v[156:157], v[202:203] op_sel:[0,0,0] op_sel_hi:[0,1,1] neg_lo:[1,0,0] neg_hi:[1,0,0]
	v_pk_fma_f32 v[234:235], v[46:47], v[158:159], v[234:235] op_sel:[1,0,0] op_sel_hi:[1,1,1] neg_lo:[1,0,0] neg_hi:[1,0,0]
	v_pk_fma_f32 v[236:237], v[48:49], v[160:161], v[236:237] op_sel:[0,0,0] op_sel_hi:[0,1,1] neg_lo:[1,0,0] neg_hi:[1,0,0]
	v_pk_fma_f32 v[238:239], v[48:49], v[162:163], v[238:239] op_sel:[1,0,0] op_sel_hi:[1,1,1] neg_lo:[1,0,0] neg_hi:[1,0,0]
	ds_read_b128 v[46:49], v241 offset:13120
	s_waitcnt lgkmcnt(7)
; template <int DIR>
; __device__ __forceinline__ void dn_solve(const P& p, int task, int m0, int h, int t2, const bf16_t* kn_s, const bf16_t* v_s, const float* gc, const float* be, float* L) {
;     ...
; #pragma unroll
;     for (int cp = 1; cp < 64; ++cp) {
;         float a0 = 0.f, a1 = 0.f, a2 = 0.f, a3 = 0.f;
; #pragma unroll
;         for (int s4 = 0; s4 < cp; s4 += 4) { const f32x4 l4 = *(const f32x4*)(L + cp * 64 + s4); a0 += l4[0] * x[s4]; a1 += l4[1] * x[s4 + 1]; a2 += l4[2] * x[s4 + 2]; a3 += l4[3] * x[s4 + 3]; }
;         x[cp] -= (a0 + a1) + (a2 + a3);
;     }
	v_pk_fma_f32 v[202:203], v[50:51], v[164:165], v[202:203] op_sel:[0,0,0] op_sel_hi:[0,1,1] neg_lo:[1,0,0] neg_hi:[1,0,0]
	v_pk_fma_f32 v[234:235], v[50:51], v[166:167], v[234:235] op_sel:[1,0,0] op_sel_hi:[1,1,1] neg_lo:[1,0,0] neg_hi:[1,0,0]
	v_pk_fma_f32 v[236:237], v[52:53], v[168:169], v[236:237] op_sel:[0,0,0] op_sel_hi:[0,1,1] neg_lo:[1,0,0] neg_hi:[1,0,0]
	v_pk_fma_f32 v[238:239], v[52:53], v[170:171], v[238:239] op_sel:[1,0,0] op_sel_hi:[1,1,1] neg_lo:[1,0,0] neg_hi:[1,0,0]
	ds_read_b128 v[50:53], v241 offset:13136
	s_waitcnt lgkmcnt(7)
	v_pk_fma_f32 v[202:203], v[2:3], v[172:173], v[202:203] op_sel:[0,0,0] op_sel_hi:[0,1,1] neg_lo:[1,0,0] neg_hi:[1,0,0]
	v_pk_fma_f32 v[234:235], v[2:3], v[174:175], v[234:235] op_sel:[1,0,0] op_sel_hi:[1,1,1] neg_lo:[1,0,0] neg_hi:[1,0,0]
	v_pk_fma_f32 v[236:237], v[4:5], v[176:177], v[236:237] op_sel:[0,0,0] op_sel_hi:[0,1,1] neg_lo:[1,0,0] neg_hi:[1,0,0]
	v_pk_fma_f32 v[238:239], v[4:5], v[178:179], v[238:239] op_sel:[1,0,0] op_sel_hi:[1,1,1] neg_lo:[1,0,0] neg_hi:[1,0,0]
	ds_read_b128 v[2:5], v241 offset:13152
	s_waitcnt lgkmcnt(7)
	v_pk_fma_f32 v[202:203], v[26:27], v[180:181], v[202:203] op_sel:[0,0,0] op_sel_hi:[0,1,1] neg_lo:[1,0,0] neg_hi:[1,0,0]
	v_pk_fma_f32 v[234:235], v[26:27], v[182:183], v[234:235] op_sel:[1,0,0] op_sel_hi:[1,1,1] neg_lo:[1,0,0] neg_hi:[1,0,0]
	v_pk_add_f32 v[236:237], v[202:203], v[236:237]
	v_pk_add_f32 v[236:237], v[236:237], v[238:239]
	v_pk_add_f32 v[202:203], v[236:237], v[234:235]
	ds_read_b128 v[26:29], v241 offset:13168
	s_waitcnt lgkmcnt(7)
	v_pk_fma_f32 v[204:205], v[30:31], v[6:7], v[204:205] op_sel:[0,0,0] op_sel_hi:[0,1,1] neg_lo:[1,0,0] neg_hi:[1,0,0]
	v_pk_mul_f32 v[234:235], v[30:31], v[54:55] op_sel:[1,0] op_sel_hi:[1,1] neg_lo:[1,0] neg_hi:[1,0]
	v_pk_mul_f32 v[236:237], v[32:33], v[56:57] op_sel:[0,0] op_sel_hi:[0,1] neg_lo:[1,0] neg_hi:[1,0]
	v_pk_mul_f32 v[238:239], v[32:33], v[58:59] op_sel:[1,0] op_sel_hi:[1,1] neg_lo:[1,0] neg_hi:[1,0]
	ds_read_b128 v[30:33], v241 offset:13184
	s_waitcnt lgkmcnt(7)
	v_pk_fma_f32 v[204:205], v[34:35], v[60:61], v[204:205] op_sel:[0,0,0] op_sel_hi:[0,1,1] neg_lo:[1,0,0] neg_hi:[1,0,0]
	v_pk_fma_f32 v[234:235], v[34:35], v[62:63], v[234:235] op_sel:[1,0,0] op_sel_hi:[1,1,1] neg_lo:[1,0,0] neg_hi:[1,0,0]
	v_pk_fma_f32 v[236:237], v[36:37], v[64:65], v[236:237] op_sel:[0,0,0] op_sel_hi:[0,1,1] neg_lo:[1,0,0] neg_hi:[1,0,0]
	v_pk_fma_f32 v[238:239], v[36:37], v[66:67], v[238:239] op_sel:[1,0,0] op_sel_hi:[1,1,1] neg_lo:[1,0,0] neg_hi:[1,0,0]
	ds_read_b128 v[34:37], v241 offset:13200
	s_waitcnt lgkmcnt(7)
	v_pk_fma_f32 v[204:205], v[38:39], v[68:69], v[204:205] op_sel:[0,0,0] op_sel_hi:[0,1,1] neg_lo:[1,0,0] neg_hi:[1,0,0]
	v_pk_fma_f32 v[234:235], v[38:39], v[70:71], v[234:235] op_sel:[1,0,0] op_sel_hi:[1,1,1] neg_lo:[1,0,0] neg_hi:[1,0,0]
	v_pk_fma_f32 v[236:237], v[40:41], v[72:73], v[236:237] op_sel:[0,0,0] op_sel_hi:[0,1,1] neg_lo:[1,0,0] neg_hi:[1,0,0]
	v_pk_fma_f32 v[238:239], v[40:41], v[74:75], v[238:239] op_sel:[1,0,0] op_sel_hi:[1,1,1] neg_lo:[1,0,0] neg_hi:[1,0,0]
	ds_read_b128 v[38:41], v241 offset:13216
	s_waitcnt lgkmcnt(7)
	v_pk_fma_f32 v[204:205], v[42:43], v[76:77], v[204:205] op_sel:[0,0,0] op_sel_hi:[0,1,1] neg_lo:[1,0,0] neg_hi:[1,0,0]
	v_pk_fma_f32 v[234:235], v[42:43], v[78:79], v[234:235] op_sel:[1,0,0] op_sel_hi:[1,1,1] neg_lo:[1,0,0] neg_hi:[1,0,0]
	v_pk_fma_f32 v[236:237], v[44:45], v[80:81], v[236:237] op_sel:[0,0,0] op_sel_hi:[0,1,1] neg_lo:[1,0,0] neg_hi:[1,0,0]
	v_pk_fma_f32 v[238:239], v[44:45], v[82:83], v[238:239] op_sel:[1,0,0] op_sel_hi:[1,1,1] neg_lo:[1,0,0] neg_hi:[1,0,0]
	ds_read_b128 v[42:45], v241 offset:13232
	s_waitcnt lgkmcnt(7)
	v_pk_fma_f32 v[204:205], v[46:47], v[84:85], v[204:205] op_sel:[0,0,0] op_sel_hi:[0,1,1] neg_lo:[1,0,0] neg_hi:[1,0,0]
	v_pk_fma_f32 v[234:235], v[46:47], v[86:87], v[234:235] op_sel:[1,0,0] op_sel_hi:[1,1,1] neg_lo:[1,0,0] neg_hi:[1,0,0]
	v_pk_fma_f32 v[236:237], v[48:49], v[88:89], v[236:237] op_sel:[0,0,0] op_sel_hi:[0,1,1] neg_lo:[1,0,0] neg_hi:[1,0,0]
	v_pk_fma_f32 v[238:239], v[48:49], v[90:91], v[238:239] op_sel:[1,0,0] op_sel_hi:[1,1,1] neg_lo:[1,0,0] neg_hi:[1,0,0]
	ds_read_b128 v[46:49], v241 offset:13248
	s_waitcnt lgkmcnt(7)
	v_pk_fma_f32 v[204:205], v[50:51], v[92:93], v[204:205] op_sel:[0,0,0] op_sel_hi:[0,1,1] neg_lo:[1,0,0] neg_hi:[1,0,0]
	v_pk_fma_f32 v[234:235], v[50:51], v[94:95], v[234:235] op_sel:[1,0,0] op_sel_hi:[1,1,1] neg_lo:[1,0,0] neg_hi:[1,0,0]
	v_pk_fma_f32 v[236:237], v[52:53], v[96:97], v[236:237] op_sel:[0,0,0] op_sel_hi:[0,1,1] neg_lo:[1,0,0] neg_hi:[1,0,0]
	v_pk_fma_f32 v[238:239], v[52:53], v[98:99], v[238:239] op_sel:[1,0,0] op_sel_hi:[1,1,1] neg_lo:[1,0,0] neg_hi:[1,0,0]
	ds_read_b128 v[50:53], v241 offset:13312
	s_waitcnt lgkmcnt(7)
	v_pk_fma_f32 v[204:205], v[2:3], v[100:101], v[204:205] op_sel:[0,0,0] op_sel_hi:[0,1,1] neg_lo:[1,0,0] neg_hi:[1,0,0]
	v_pk_fma_f32 v[234:235], v[2:3], v[102:103], v[234:235] op_sel:[1,0,0] op_sel_hi:[1,1,1] neg_lo:[1,0,0] neg_hi:[1,0,0]
	v_pk_fma_f32 v[236:237], v[4:5], v[104:105], v[236:237] op_sel:[0,0,0] op_sel_hi:[0,1,1] neg_lo:[1,0,0] neg_hi:[1,0,0]
	v_pk_fma_f32 v[238:239], v[4:5], v[106:107], v[238:239] op_sel:[1,0,0] op_sel_hi:[1,1,1] neg_lo:[1,0,0] neg_hi:[1,0,0]
	ds_read_b128 v[2:5], v241 offset:13328
	s_waitcnt lgkmcnt(7)
	v_pk_fma_f32 v[204:205], v[26:27], v[108:109], v[204:205] op_sel:[0,0,0] op_sel_hi:[0,1,1] neg_lo:[1,0,0] neg_hi:[1,0,0]
	v_pk_fma_f32 v[234:235], v[26:27], v[110:111], v[234:235] op_sel:[1,0,0] op_sel_hi:[1,1,1] neg_lo:[1,0,0] neg_hi:[1,0,0]
	v_pk_fma_f32 v[236:237], v[28:29], v[112:113], v[236:237] op_sel:[0,0,0] op_sel_hi:[0,1,1] neg_lo:[1,0,0] neg_hi:[1,0,0]
	v_pk_fma_f32 v[238:239], v[28:29], v[114:115], v[238:239] op_sel:[1,0,0] op_sel_hi:[1,1,1] neg_lo:[1,0,0] neg_hi:[1,0,0]
	ds_read_b128 v[26:29], v241 offset:13344
	s_waitcnt lgkmcnt(7)
; template <int DIR>
; __device__ __forceinline__ void dn_solve(const P& p, int task, int m0, int h, int t2, const bf16_t* kn_s, const bf16_t* v_s, const float* gc, const float* be, float* L) {
;     ...
; #pragma unroll
;     for (int cp = 1; cp < 64; ++cp) {
;         float a0 = 0.f, a1 = 0.f, a2 = 0.f, a3 = 0.f;
; #pragma unroll
;         for (int s4 = 0; s4 < cp; s4 += 4) { const f32x4 l4 = *(const f32x4*)(L + cp * 64 + s4); a0 += l4[0] * x[s4]; a1 += l4[1] * x[s4 + 1]; a2 += l4[2] * x[s4 + 2]; a3 += l4[3] * x[s4 + 3]; }
;         x[cp] -= (a0 + a1) + (a2 + a3);
;     }
	v_pk_fma_f32 v[204:205], v[30:31], v[116:117], v[204:205] op_sel:[0,0,0] op_sel_hi:[0,1,1] neg_lo:[1,0,0] neg_hi:[1,0,0]
	v_pk_fma_f32 v[234:235], v[30:31], v[118:119], v[234:235] op_sel:[1,0,0] op_sel_hi:[1,1,1] neg_lo:[1,0,0] neg_hi:[1,0,0]
	v_pk_fma_f32 v[236:237], v[32:33], v[152:153], v[236:237] op_sel:[0,0,0] op_sel_hi:[0,1,1] neg_lo:[1,0,0] neg_hi:[1,0,0]
	v_pk_fma_f32 v[238:239], v[32:33], v[154:155], v[238:239] op_sel:[1,0,0] op_sel_hi:[1,1,1] neg_lo:[1,0,0] neg_hi:[1,0,0]
	ds_read_b128 v[30:33], v241 offset:13360
	s_waitcnt lgkmcnt(7)
	v_pk_fma_f32 v[204:205], v[34:35], v[156:157], v[204:205] op_sel:[0,0,0] op_sel_hi:[0,1,1] neg_lo:[1,0,0] neg_hi:[1,0,0]
	v_pk_fma_f32 v[234:235], v[34:35], v[158:159], v[234:235] op_sel:[1,0,0] op_sel_hi:[1,1,1] neg_lo:[1,0,0] neg_hi:[1,0,0]
	v_pk_fma_f32 v[236:237], v[36:37], v[160:161], v[236:237] op_sel:[0,0,0] op_sel_hi:[0,1,1] neg_lo:[1,0,0] neg_hi:[1,0,0]
	v_pk_fma_f32 v[238:239], v[36:37], v[162:163], v[238:239] op_sel:[1,0,0] op_sel_hi:[1,1,1] neg_lo:[1,0,0] neg_hi:[1,0,0]
	ds_read_b128 v[34:37], v241 offset:13376
	s_waitcnt lgkmcnt(7)
	v_pk_fma_f32 v[204:205], v[38:39], v[164:165], v[204:205] op_sel:[0,0,0] op_sel_hi:[0,1,1] neg_lo:[1,0,0] neg_hi:[1,0,0]
	v_pk_fma_f32 v[234:235], v[38:39], v[166:167], v[234:235] op_sel:[1,0,0] op_sel_hi:[1,1,1] neg_lo:[1,0,0] neg_hi:[1,0,0]
	v_pk_fma_f32 v[236:237], v[40:41], v[168:169], v[236:237] op_sel:[0,0,0] op_sel_hi:[0,1,1] neg_lo:[1,0,0] neg_hi:[1,0,0]
	v_pk_fma_f32 v[238:239], v[40:41], v[170:171], v[238:239] op_sel:[1,0,0] op_sel_hi:[1,1,1] neg_lo:[1,0,0] neg_hi:[1,0,0]
	ds_read_b128 v[38:41], v241 offset:13392
	s_waitcnt lgkmcnt(7)
	v_pk_fma_f32 v[204:205], v[42:43], v[172:173], v[204:205] op_sel:[0,0,0] op_sel_hi:[0,1,1] neg_lo:[1,0,0] neg_hi:[1,0,0]
	v_pk_fma_f32 v[234:235], v[42:43], v[174:175], v[234:235] op_sel:[1,0,0] op_sel_hi:[1,1,1] neg_lo:[1,0,0] neg_hi:[1,0,0]
	v_pk_fma_f32 v[236:237], v[44:45], v[176:177], v[236:237] op_sel:[0,0,0] op_sel_hi:[0,1,1] neg_lo:[1,0,0] neg_hi:[1,0,0]
	v_pk_fma_f32 v[238:239], v[44:45], v[178:179], v[238:239] op_sel:[1,0,0] op_sel_hi:[1,1,1] neg_lo:[1,0,0] neg_hi:[1,0,0]
	ds_read_b128 v[42:45], v241 offset:13408
	s_waitcnt lgkmcnt(7)
	v_pk_fma_f32 v[204:205], v[46:47], v[180:181], v[204:205] op_sel:[0,0,0] op_sel_hi:[0,1,1] neg_lo:[1,0,0] neg_hi:[1,0,0]
	v_pk_fma_f32 v[234:235], v[46:47], v[182:183], v[234:235] op_sel:[1,0,0] op_sel_hi:[1,1,1] neg_lo:[1,0,0] neg_hi:[1,0,0]
	v_pk_fma_f32 v[236:237], v[48:49], v[202:203], v[236:237] op_sel:[0,0,0] op_sel_hi:[0,1,1] neg_lo:[1,0,0] neg_hi:[1,0,0]
	v_pk_add_f32 v[234:235], v[204:205], v[234:235]
	v_pk_add_f32 v[234:235], v[234:235], v[238:239]
	v_pk_add_f32 v[204:205], v[234:235], v[236:237]
	ds_read_b128 v[46:49], v241 offset:13424
	s_waitcnt lgkmcnt(7)
	v_pk_fma_f32 v[208:209], v[50:51], v[6:7], v[208:209] op_sel:[0,0,0] op_sel_hi:[0,1,1] neg_lo:[1,0,0] neg_hi:[1,0,0]
	v_pk_mul_f32 v[234:235], v[50:51], v[54:55] op_sel:[1,0] op_sel_hi:[1,1] neg_lo:[1,0] neg_hi:[1,0]
	v_pk_mul_f32 v[236:237], v[52:53], v[56:57] op_sel:[0,0] op_sel_hi:[0,1] neg_lo:[1,0] neg_hi:[1,0]
	v_pk_mul_f32 v[238:239], v[52:53], v[58:59] op_sel:[1,0] op_sel_hi:[1,1] neg_lo:[1,0] neg_hi:[1,0]
	ds_read_b128 v[50:53], v241 offset:13440
	s_waitcnt lgkmcnt(7)
	v_pk_fma_f32 v[208:209], v[2:3], v[60:61], v[208:209] op_sel:[0,0,0] op_sel_hi:[0,1,1] neg_lo:[1,0,0] neg_hi:[1,0,0]
	v_pk_fma_f32 v[234:235], v[2:3], v[62:63], v[234:235] op_sel:[1,0,0] op_sel_hi:[1,1,1] neg_lo:[1,0,0] neg_hi:[1,0,0]
	v_pk_fma_f32 v[236:237], v[4:5], v[64:65], v[236:237] op_sel:[0,0,0] op_sel_hi:[0,1,1] neg_lo:[1,0,0] neg_hi:[1,0,0]
	v_pk_fma_f32 v[238:239], v[4:5], v[66:67], v[238:239] op_sel:[1,0,0] op_sel_hi:[1,1,1] neg_lo:[1,0,0] neg_hi:[1,0,0]
	ds_read_b128 v[2:5], v241 offset:13456
	s_waitcnt lgkmcnt(7)
	v_pk_fma_f32 v[208:209], v[26:27], v[68:69], v[208:209] op_sel:[0,0,0] op_sel_hi:[0,1,1] neg_lo:[1,0,0] neg_hi:[1,0,0]
	v_pk_fma_f32 v[234:235], v[26:27], v[70:71], v[234:235] op_sel:[1,0,0] op_sel_hi:[1,1,1] neg_lo:[1,0,0] neg_hi:[1,0,0]
	v_pk_fma_f32 v[236:237], v[28:29], v[72:73], v[236:237] op_sel:[0,0,0] op_sel_hi:[0,1,1] neg_lo:[1,0,0] neg_hi:[1,0,0]
	v_pk_fma_f32 v[238:239], v[28:29], v[74:75], v[238:239] op_sel:[1,0,0] op_sel_hi:[1,1,1] neg_lo:[1,0,0] neg_hi:[1,0,0]
	ds_read_b128 v[26:29], v241 offset:13472
	s_waitcnt lgkmcnt(7)
	v_pk_fma_f32 v[208:209], v[30:31], v[76:77], v[208:209] op_sel:[0,0,0] op_sel_hi:[0,1,1] neg_lo:[1,0,0] neg_hi:[1,0,0]
	v_pk_fma_f32 v[234:235], v[30:31], v[78:79], v[234:235] op_sel:[1,0,0] op_sel_hi:[1,1,1] neg_lo:[1,0,0] neg_hi:[1,0,0]
	v_pk_fma_f32 v[236:237], v[32:33], v[80:81], v[236:237] op_sel:[0,0,0] op_sel_hi:[0,1,1] neg_lo:[1,0,0] neg_hi:[1,0,0]
	v_pk_fma_f32 v[238:239], v[32:33], v[82:83], v[238:239] op_sel:[1,0,0] op_sel_hi:[1,1,1] neg_lo:[1,0,0] neg_hi:[1,0,0]
	ds_read_b128 v[30:33], v241 offset:13488
	s_waitcnt lgkmcnt(7)
	v_pk_fma_f32 v[208:209], v[34:35], v[84:85], v[208:209] op_sel:[0,0,0] op_sel_hi:[0,1,1] neg_lo:[1,0,0] neg_hi:[1,0,0]
	v_pk_fma_f32 v[234:235], v[34:35], v[86:87], v[234:235] op_sel:[1,0,0] op_sel_hi:[1,1,1] neg_lo:[1,0,0] neg_hi:[1,0,0]
	v_pk_fma_f32 v[236:237], v[36:37], v[88:89], v[236:237] op_sel:[0,0,0] op_sel_hi:[0,1,1] neg_lo:[1,0,0] neg_hi:[1,0,0]
	v_pk_fma_f32 v[238:239], v[36:37], v[90:91], v[238:239] op_sel:[1,0,0] op_sel_hi:[1,1,1] neg_lo:[1,0,0] neg_hi:[1,0,0]
	ds_read_b128 v[34:37], v241 offset:13504
	s_waitcnt lgkmcnt(7)
; template <int DIR>
; __device__ __forceinline__ void dn_solve(const P& p, int task, int m0, int h, int t2, const bf16_t* kn_s, const bf16_t* v_s, const float* gc, const float* be, float* L) {
;     ...
; #pragma unroll
;     for (int cp = 1; cp < 64; ++cp) {
;         float a0 = 0.f, a1 = 0.f, a2 = 0.f, a3 = 0.f;
; #pragma unroll
;         for (int s4 = 0; s4 < cp; s4 += 4) { const f32x4 l4 = *(const f32x4*)(L + cp * 64 + s4); a0 += l4[0] * x[s4]; a1 += l4[1] * x[s4 + 1]; a2 += l4[2] * x[s4 + 2]; a3 += l4[3] * x[s4 + 3]; }
;         x[cp] -= (a0 + a1) + (a2 + a3);
;     }
	v_pk_fma_f32 v[208:209], v[38:39], v[92:93], v[208:209] op_sel:[0,0,0] op_sel_hi:[0,1,1] neg_lo:[1,0,0] neg_hi:[1,0,0]
	v_pk_fma_f32 v[234:235], v[38:39], v[94:95], v[234:235] op_sel:[1,0,0] op_sel_hi:[1,1,1] neg_lo:[1,0,0] neg_hi:[1,0,0]
	v_pk_fma_f32 v[236:237], v[40:41], v[96:97], v[236:237] op_sel:[0,0,0] op_sel_hi:[0,1,1] neg_lo:[1,0,0] neg_hi:[1,0,0]
	v_pk_fma_f32 v[238:239], v[40:41], v[98:99], v[238:239] op_sel:[1,0,0] op_sel_hi:[1,1,1] neg_lo:[1,0,0] neg_hi:[1,0,0]
	ds_read_b128 v[38:41], v241 offset:13568
	s_waitcnt lgkmcnt(7)
	v_pk_fma_f32 v[208:209], v[42:43], v[100:101], v[208:209] op_sel:[0,0,0] op_sel_hi:[0,1,1] neg_lo:[1,0,0] neg_hi:[1,0,0]
	v_pk_fma_f32 v[234:235], v[42:43], v[102:103], v[234:235] op_sel:[1,0,0] op_sel_hi:[1,1,1] neg_lo:[1,0,0] neg_hi:[1,0,0]
	v_pk_fma_f32 v[236:237], v[44:45], v[104:105], v[236:237] op_sel:[0,0,0] op_sel_hi:[0,1,1] neg_lo:[1,0,0] neg_hi:[1,0,0]
	v_pk_fma_f32 v[238:239], v[44:45], v[106:107], v[238:239] op_sel:[1,0,0] op_sel_hi:[1,1,1] neg_lo:[1,0,0] neg_hi:[1,0,0]
	ds_read_b128 v[42:45], v241 offset:13584
	s_waitcnt lgkmcnt(7)
	v_pk_fma_f32 v[208:209], v[46:47], v[108:109], v[208:209] op_sel:[0,0,0] op_sel_hi:[0,1,1] neg_lo:[1,0,0] neg_hi:[1,0,0]
	v_pk_fma_f32 v[234:235], v[46:47], v[110:111], v[234:235] op_sel:[1,0,0] op_sel_hi:[1,1,1] neg_lo:[1,0,0] neg_hi:[1,0,0]
	v_pk_fma_f32 v[236:237], v[48:49], v[112:113], v[236:237] op_sel:[0,0,0] op_sel_hi:[0,1,1] neg_lo:[1,0,0] neg_hi:[1,0,0]
	v_pk_fma_f32 v[238:239], v[48:49], v[114:115], v[238:239] op_sel:[1,0,0] op_sel_hi:[1,1,1] neg_lo:[1,0,0] neg_hi:[1,0,0]
	ds_read_b128 v[46:49], v241 offset:13600
	s_waitcnt lgkmcnt(7)
	v_pk_fma_f32 v[208:209], v[50:51], v[116:117], v[208:209] op_sel:[0,0,0] op_sel_hi:[0,1,1] neg_lo:[1,0,0] neg_hi:[1,0,0]
	v_pk_fma_f32 v[234:235], v[50:51], v[118:119], v[234:235] op_sel:[1,0,0] op_sel_hi:[1,1,1] neg_lo:[1,0,0] neg_hi:[1,0,0]
	v_pk_fma_f32 v[236:237], v[52:53], v[152:153], v[236:237] op_sel:[0,0,0] op_sel_hi:[0,1,1] neg_lo:[1,0,0] neg_hi:[1,0,0]
	v_pk_fma_f32 v[238:239], v[52:53], v[154:155], v[238:239] op_sel:[1,0,0] op_sel_hi:[1,1,1] neg_lo:[1,0,0] neg_hi:[1,0,0]
	ds_read_b128 v[50:53], v241 offset:13616
	s_waitcnt lgkmcnt(7)
	v_pk_fma_f32 v[208:209], v[2:3], v[156:157], v[208:209] op_sel:[0,0,0] op_sel_hi:[0,1,1] neg_lo:[1,0,0] neg_hi:[1,0,0]
	v_pk_fma_f32 v[234:235], v[2:3], v[158:159], v[234:235] op_sel:[1,0,0] op_sel_hi:[1,1,1] neg_lo:[1,0,0] neg_hi:[1,0,0]
	v_pk_fma_f32 v[236:237], v[4:5], v[160:161], v[236:237] op_sel:[0,0,0] op_sel_hi:[0,1,1] neg_lo:[1,0,0] neg_hi:[1,0,0]
	v_pk_fma_f32 v[238:239], v[4:5], v[162:163], v[238:239] op_sel:[1,0,0] op_sel_hi:[1,1,1] neg_lo:[1,0,0] neg_hi:[1,0,0]
	ds_read_b128 v[2:5], v241 offset:13632
	s_waitcnt lgkmcnt(7)
	v_pk_fma_f32 v[208:209], v[26:27], v[164:165], v[208:209] op_sel:[0,0,0] op_sel_hi:[0,1,1] neg_lo:[1,0,0] neg_hi:[1,0,0]
	v_pk_fma_f32 v[234:235], v[26:27], v[166:167], v[234:235] op_sel:[1,0,0] op_sel_hi:[1,1,1] neg_lo:[1,0,0] neg_hi:[1,0,0]
	v_pk_fma_f32 v[236:237], v[28:29], v[168:169], v[236:237] op_sel:[0,0,0] op_sel_hi:[0,1,1] neg_lo:[1,0,0] neg_hi:[1,0,0]
	v_pk_fma_f32 v[238:239], v[28:29], v[170:171], v[238:239] op_sel:[1,0,0] op_sel_hi:[1,1,1] neg_lo:[1,0,0] neg_hi:[1,0,0]
	ds_read_b128 v[26:29], v241 offset:13648
	s_waitcnt lgkmcnt(7)
	v_pk_fma_f32 v[208:209], v[30:31], v[172:173], v[208:209] op_sel:[0,0,0] op_sel_hi:[0,1,1] neg_lo:[1,0,0] neg_hi:[1,0,0]
	v_pk_fma_f32 v[234:235], v[30:31], v[174:175], v[234:235] op_sel:[1,0,0] op_sel_hi:[1,1,1] neg_lo:[1,0,0] neg_hi:[1,0,0]
	v_pk_fma_f32 v[236:237], v[32:33], v[176:177], v[236:237] op_sel:[0,0,0] op_sel_hi:[0,1,1] neg_lo:[1,0,0] neg_hi:[1,0,0]
	v_pk_fma_f32 v[238:239], v[32:33], v[178:179], v[238:239] op_sel:[1,0,0] op_sel_hi:[1,1,1] neg_lo:[1,0,0] neg_hi:[1,0,0]
	ds_read_b128 v[30:33], v241 offset:13664
	s_waitcnt lgkmcnt(7)
	v_pk_fma_f32 v[208:209], v[34:35], v[180:181], v[208:209] op_sel:[0,0,0] op_sel_hi:[0,1,1] neg_lo:[1,0,0] neg_hi:[1,0,0]
	v_pk_fma_f32 v[234:235], v[34:35], v[182:183], v[234:235] op_sel:[1,0,0] op_sel_hi:[1,1,1] neg_lo:[1,0,0] neg_hi:[1,0,0]
	v_pk_fma_f32 v[236:237], v[36:37], v[202:203], v[236:237] op_sel:[0,0,0] op_sel_hi:[0,1,1] neg_lo:[1,0,0] neg_hi:[1,0,0]
	v_pk_fma_f32 v[238:239], v[36:37], v[204:205], v[238:239] op_sel:[1,0,0] op_sel_hi:[1,1,1] neg_lo:[1,0,0] neg_hi:[1,0,0]
	v_pk_add_f32 v[234:235], v[208:209], v[234:235]
	v_pk_add_f32 v[234:235], v[234:235], v[236:237]
	v_pk_add_f32 v[208:209], v[234:235], v[238:239]
	ds_read_b128 v[34:37], v241 offset:13680
	s_waitcnt lgkmcnt(7)
	v_pk_fma_f32 v[210:211], v[38:39], v[6:7], v[210:211] op_sel:[0,0,0] op_sel_hi:[0,1,1] neg_lo:[1,0,0] neg_hi:[1,0,0]
	v_pk_mul_f32 v[234:235], v[38:39], v[54:55] op_sel:[1,0] op_sel_hi:[1,1] neg_lo:[1,0] neg_hi:[1,0]
	v_pk_mul_f32 v[236:237], v[40:41], v[56:57] op_sel:[0,0] op_sel_hi:[0,1] neg_lo:[1,0] neg_hi:[1,0]
	v_pk_mul_f32 v[238:239], v[40:41], v[58:59] op_sel:[1,0] op_sel_hi:[1,1] neg_lo:[1,0] neg_hi:[1,0]
	ds_read_b128 v[38:41], v241 offset:13696
	s_waitcnt lgkmcnt(7)
	v_pk_fma_f32 v[210:211], v[42:43], v[60:61], v[210:211] op_sel:[0,0,0] op_sel_hi:[0,1,1] neg_lo:[1,0,0] neg_hi:[1,0,0]
	v_pk_fma_f32 v[234:235], v[42:43], v[62:63], v[234:235] op_sel:[1,0,0] op_sel_hi:[1,1,1] neg_lo:[1,0,0] neg_hi:[1,0,0]
	v_pk_fma_f32 v[236:237], v[44:45], v[64:65], v[236:237] op_sel:[0,0,0] op_sel_hi:[0,1,1] neg_lo:[1,0,0] neg_hi:[1,0,0]
	v_pk_fma_f32 v[238:239], v[44:45], v[66:67], v[238:239] op_sel:[1,0,0] op_sel_hi:[1,1,1] neg_lo:[1,0,0] neg_hi:[1,0,0]
	ds_read_b128 v[42:45], v241 offset:13712
	s_waitcnt lgkmcnt(7)
; template <int DIR>
; __device__ __forceinline__ void dn_solve(const P& p, int task, int m0, int h, int t2, const bf16_t* kn_s, const bf16_t* v_s, const float* gc, const float* be, float* L) {
;     ...
; #pragma unroll
;     for (int cp = 1; cp < 64; ++cp) {
;         float a0 = 0.f, a1 = 0.f, a2 = 0.f, a3 = 0.f;
; #pragma unroll
;         for (int s4 = 0; s4 < cp; s4 += 4) { const f32x4 l4 = *(const f32x4*)(L + cp * 64 + s4); a0 += l4[0] * x[s4]; a1 += l4[1] * x[s4 + 1]; a2 += l4[2] * x[s4 + 2]; a3 += l4[3] * x[s4 + 3]; }
;         x[cp] -= (a0 + a1) + (a2 + a3);
;     }
	v_pk_fma_f32 v[210:211], v[46:47], v[68:69], v[210:211] op_sel:[0,0,0] op_sel_hi:[0,1,1] neg_lo:[1,0,0] neg_hi:[1,0,0]
	v_pk_fma_f32 v[234:235], v[46:47], v[70:71], v[234:235] op_sel:[1,0,0] op_sel_hi:[1,1,1] neg_lo:[1,0,0] neg_hi:[1,0,0]
	v_pk_fma_f32 v[236:237], v[48:49], v[72:73], v[236:237] op_sel:[0,0,0] op_sel_hi:[0,1,1] neg_lo:[1,0,0] neg_hi:[1,0,0]
	v_pk_fma_f32 v[238:239], v[48:49], v[74:75], v[238:239] op_sel:[1,0,0] op_sel_hi:[1,1,1] neg_lo:[1,0,0] neg_hi:[1,0,0]
	ds_read_b128 v[46:49], v241 offset:13728
	s_waitcnt lgkmcnt(7)
	v_pk_fma_f32 v[210:211], v[50:51], v[76:77], v[210:211] op_sel:[0,0,0] op_sel_hi:[0,1,1] neg_lo:[1,0,0] neg_hi:[1,0,0]
	v_pk_fma_f32 v[234:235], v[50:51], v[78:79], v[234:235] op_sel:[1,0,0] op_sel_hi:[1,1,1] neg_lo:[1,0,0] neg_hi:[1,0,0]
	v_pk_fma_f32 v[236:237], v[52:53], v[80:81], v[236:237] op_sel:[0,0,0] op_sel_hi:[0,1,1] neg_lo:[1,0,0] neg_hi:[1,0,0]
	v_pk_fma_f32 v[238:239], v[52:53], v[82:83], v[238:239] op_sel:[1,0,0] op_sel_hi:[1,1,1] neg_lo:[1,0,0] neg_hi:[1,0,0]
	ds_read_b128 v[50:53], v241 offset:13744
	s_waitcnt lgkmcnt(7)
	v_pk_fma_f32 v[210:211], v[2:3], v[84:85], v[210:211] op_sel:[0,0,0] op_sel_hi:[0,1,1] neg_lo:[1,0,0] neg_hi:[1,0,0]
	v_pk_fma_f32 v[234:235], v[2:3], v[86:87], v[234:235] op_sel:[1,0,0] op_sel_hi:[1,1,1] neg_lo:[1,0,0] neg_hi:[1,0,0]
	v_pk_fma_f32 v[236:237], v[4:5], v[88:89], v[236:237] op_sel:[0,0,0] op_sel_hi:[0,1,1] neg_lo:[1,0,0] neg_hi:[1,0,0]
	v_pk_fma_f32 v[238:239], v[4:5], v[90:91], v[238:239] op_sel:[1,0,0] op_sel_hi:[1,1,1] neg_lo:[1,0,0] neg_hi:[1,0,0]
	ds_read_b128 v[2:5], v241 offset:13760
	s_waitcnt lgkmcnt(7)
	v_pk_fma_f32 v[210:211], v[26:27], v[92:93], v[210:211] op_sel:[0,0,0] op_sel_hi:[0,1,1] neg_lo:[1,0,0] neg_hi:[1,0,0]
	v_pk_fma_f32 v[234:235], v[26:27], v[94:95], v[234:235] op_sel:[1,0,0] op_sel_hi:[1,1,1] neg_lo:[1,0,0] neg_hi:[1,0,0]
	v_pk_fma_f32 v[236:237], v[28:29], v[96:97], v[236:237] op_sel:[0,0,0] op_sel_hi:[0,1,1] neg_lo:[1,0,0] neg_hi:[1,0,0]
	v_pk_fma_f32 v[238:239], v[28:29], v[98:99], v[238:239] op_sel:[1,0,0] op_sel_hi:[1,1,1] neg_lo:[1,0,0] neg_hi:[1,0,0]
	ds_read_b128 v[26:29], v241 offset:13776
	s_waitcnt lgkmcnt(7)
	v_pk_fma_f32 v[210:211], v[30:31], v[100:101], v[210:211] op_sel:[0,0,0] op_sel_hi:[0,1,1] neg_lo:[1,0,0] neg_hi:[1,0,0]
	v_pk_fma_f32 v[234:235], v[30:31], v[102:103], v[234:235] op_sel:[1,0,0] op_sel_hi:[1,1,1] neg_lo:[1,0,0] neg_hi:[1,0,0]
	v_pk_fma_f32 v[236:237], v[32:33], v[104:105], v[236:237] op_sel:[0,0,0] op_sel_hi:[0,1,1] neg_lo:[1,0,0] neg_hi:[1,0,0]
	v_pk_fma_f32 v[238:239], v[32:33], v[106:107], v[238:239] op_sel:[1,0,0] op_sel_hi:[1,1,1] neg_lo:[1,0,0] neg_hi:[1,0,0]
	ds_read_b128 v[30:33], v241 offset:13824
	s_waitcnt lgkmcnt(7)
	v_pk_fma_f32 v[210:211], v[34:35], v[108:109], v[210:211] op_sel:[0,0,0] op_sel_hi:[0,1,1] neg_lo:[1,0,0] neg_hi:[1,0,0]
	v_pk_fma_f32 v[234:235], v[34:35], v[110:111], v[234:235] op_sel:[1,0,0] op_sel_hi:[1,1,1] neg_lo:[1,0,0] neg_hi:[1,0,0]
	v_pk_fma_f32 v[236:237], v[36:37], v[112:113], v[236:237] op_sel:[0,0,0] op_sel_hi:[0,1,1] neg_lo:[1,0,0] neg_hi:[1,0,0]
	v_pk_fma_f32 v[238:239], v[36:37], v[114:115], v[238:239] op_sel:[1,0,0] op_sel_hi:[1,1,1] neg_lo:[1,0,0] neg_hi:[1,0,0]
	ds_read_b128 v[34:37], v241 offset:13840
	s_waitcnt lgkmcnt(7)
	v_pk_fma_f32 v[210:211], v[38:39], v[116:117], v[210:211] op_sel:[0,0,0] op_sel_hi:[0,1,1] neg_lo:[1,0,0] neg_hi:[1,0,0]
	v_pk_fma_f32 v[234:235], v[38:39], v[118:119], v[234:235] op_sel:[1,0,0] op_sel_hi:[1,1,1] neg_lo:[1,0,0] neg_hi:[1,0,0]
	v_pk_fma_f32 v[236:237], v[40:41], v[152:153], v[236:237] op_sel:[0,0,0] op_sel_hi:[0,1,1] neg_lo:[1,0,0] neg_hi:[1,0,0]
	v_pk_fma_f32 v[238:239], v[40:41], v[154:155], v[238:239] op_sel:[1,0,0] op_sel_hi:[1,1,1] neg_lo:[1,0,0] neg_hi:[1,0,0]
	ds_read_b128 v[38:41], v241 offset:13856
	s_waitcnt lgkmcnt(7)
	v_pk_fma_f32 v[210:211], v[42:43], v[156:157], v[210:211] op_sel:[0,0,0] op_sel_hi:[0,1,1] neg_lo:[1,0,0] neg_hi:[1,0,0]
	v_pk_fma_f32 v[234:235], v[42:43], v[158:159], v[234:235] op_sel:[1,0,0] op_sel_hi:[1,1,1] neg_lo:[1,0,0] neg_hi:[1,0,0]
	v_pk_fma_f32 v[236:237], v[44:45], v[160:161], v[236:237] op_sel:[0,0,0] op_sel_hi:[0,1,1] neg_lo:[1,0,0] neg_hi:[1,0,0]
	v_pk_fma_f32 v[238:239], v[44:45], v[162:163], v[238:239] op_sel:[1,0,0] op_sel_hi:[1,1,1] neg_lo:[1,0,0] neg_hi:[1,0,0]
	ds_read_b128 v[42:45], v241 offset:13872
	s_waitcnt lgkmcnt(7)
	v_pk_fma_f32 v[210:211], v[46:47], v[164:165], v[210:211] op_sel:[0,0,0] op_sel_hi:[0,1,1] neg_lo:[1,0,0] neg_hi:[1,0,0]
	v_pk_fma_f32 v[234:235], v[46:47], v[166:167], v[234:235] op_sel:[1,0,0] op_sel_hi:[1,1,1] neg_lo:[1,0,0] neg_hi:[1,0,0]
	v_pk_fma_f32 v[236:237], v[48:49], v[168:169], v[236:237] op_sel:[0,0,0] op_sel_hi:[0,1,1] neg_lo:[1,0,0] neg_hi:[1,0,0]
	v_pk_fma_f32 v[238:239], v[48:49], v[170:171], v[238:239] op_sel:[1,0,0] op_sel_hi:[1,1,1] neg_lo:[1,0,0] neg_hi:[1,0,0]
	ds_read_b128 v[46:49], v241 offset:13888
	s_waitcnt lgkmcnt(7)
	v_pk_fma_f32 v[210:211], v[50:51], v[172:173], v[210:211] op_sel:[0,0,0] op_sel_hi:[0,1,1] neg_lo:[1,0,0] neg_hi:[1,0,0]
	v_pk_fma_f32 v[234:235], v[50:51], v[174:175], v[234:235] op_sel:[1,0,0] op_sel_hi:[1,1,1] neg_lo:[1,0,0] neg_hi:[1,0,0]
	v_pk_fma_f32 v[236:237], v[52:53], v[176:177], v[236:237] op_sel:[0,0,0] op_sel_hi:[0,1,1] neg_lo:[1,0,0] neg_hi:[1,0,0]
	v_pk_fma_f32 v[238:239], v[52:53], v[178:179], v[238:239] op_sel:[1,0,0] op_sel_hi:[1,1,1] neg_lo:[1,0,0] neg_hi:[1,0,0]
	ds_read_b128 v[50:53], v241 offset:13904
	s_waitcnt lgkmcnt(7)
; template <int DIR>
; __device__ __forceinline__ void dn_solve(const P& p, int task, int m0, int h, int t2, const bf16_t* kn_s, const bf16_t* v_s, const float* gc, const float* be, float* L) {
;     ...
; #pragma unroll
;     for (int cp = 1; cp < 64; ++cp) {
;         float a0 = 0.f, a1 = 0.f, a2 = 0.f, a3 = 0.f;
; #pragma unroll
;         for (int s4 = 0; s4 < cp; s4 += 4) { const f32x4 l4 = *(const f32x4*)(L + cp * 64 + s4); a0 += l4[0] * x[s4]; a1 += l4[1] * x[s4 + 1]; a2 += l4[2] * x[s4 + 2]; a3 += l4[3] * x[s4 + 3]; }
;         x[cp] -= (a0 + a1) + (a2 + a3);
;     }
	v_pk_fma_f32 v[210:211], v[2:3], v[180:181], v[210:211] op_sel:[0,0,0] op_sel_hi:[0,1,1] neg_lo:[1,0,0] neg_hi:[1,0,0]
	v_pk_fma_f32 v[234:235], v[2:3], v[182:183], v[234:235] op_sel:[1,0,0] op_sel_hi:[1,1,1] neg_lo:[1,0,0] neg_hi:[1,0,0]
	v_pk_fma_f32 v[236:237], v[4:5], v[202:203], v[236:237] op_sel:[0,0,0] op_sel_hi:[0,1,1] neg_lo:[1,0,0] neg_hi:[1,0,0]
	v_pk_fma_f32 v[238:239], v[4:5], v[204:205], v[238:239] op_sel:[1,0,0] op_sel_hi:[1,1,1] neg_lo:[1,0,0] neg_hi:[1,0,0]
	ds_read_b128 v[2:5], v241 offset:13920
	s_waitcnt lgkmcnt(7)
	v_pk_fma_f32 v[210:211], v[26:27], v[208:209], v[210:211] op_sel:[0,0,0] op_sel_hi:[0,1,1] neg_lo:[1,0,0] neg_hi:[1,0,0]
	v_pk_add_f32 v[234:235], v[234:235], v[236:237]
	v_pk_add_f32 v[234:235], v[234:235], v[238:239]
	v_pk_add_f32 v[210:211], v[234:235], v[210:211]
	ds_read_b128 v[26:29], v241 offset:13936
	s_waitcnt lgkmcnt(7)
	v_pk_fma_f32 v[212:213], v[30:31], v[6:7], v[212:213] op_sel:[0,0,0] op_sel_hi:[0,1,1] neg_lo:[1,0,0] neg_hi:[1,0,0]
	v_pk_mul_f32 v[234:235], v[30:31], v[54:55] op_sel:[1,0] op_sel_hi:[1,1] neg_lo:[1,0] neg_hi:[1,0]
	v_pk_mul_f32 v[236:237], v[32:33], v[56:57] op_sel:[0,0] op_sel_hi:[0,1] neg_lo:[1,0] neg_hi:[1,0]
	v_pk_mul_f32 v[238:239], v[32:33], v[58:59] op_sel:[1,0] op_sel_hi:[1,1] neg_lo:[1,0] neg_hi:[1,0]
	ds_read_b128 v[30:33], v241 offset:13952
	s_waitcnt lgkmcnt(7)
	v_pk_fma_f32 v[212:213], v[34:35], v[60:61], v[212:213] op_sel:[0,0,0] op_sel_hi:[0,1,1] neg_lo:[1,0,0] neg_hi:[1,0,0]
	v_pk_fma_f32 v[234:235], v[34:35], v[62:63], v[234:235] op_sel:[1,0,0] op_sel_hi:[1,1,1] neg_lo:[1,0,0] neg_hi:[1,0,0]
	v_pk_fma_f32 v[236:237], v[36:37], v[64:65], v[236:237] op_sel:[0,0,0] op_sel_hi:[0,1,1] neg_lo:[1,0,0] neg_hi:[1,0,0]
	v_pk_fma_f32 v[238:239], v[36:37], v[66:67], v[238:239] op_sel:[1,0,0] op_sel_hi:[1,1,1] neg_lo:[1,0,0] neg_hi:[1,0,0]
	ds_read_b128 v[34:37], v241 offset:13968
	s_waitcnt lgkmcnt(7)
	v_pk_fma_f32 v[212:213], v[38:39], v[68:69], v[212:213] op_sel:[0,0,0] op_sel_hi:[0,1,1] neg_lo:[1,0,0] neg_hi:[1,0,0]
	v_pk_fma_f32 v[234:235], v[38:39], v[70:71], v[234:235] op_sel:[1,0,0] op_sel_hi:[1,1,1] neg_lo:[1,0,0] neg_hi:[1,0,0]
	v_pk_fma_f32 v[236:237], v[40:41], v[72:73], v[236:237] op_sel:[0,0,0] op_sel_hi:[0,1,1] neg_lo:[1,0,0] neg_hi:[1,0,0]
	v_pk_fma_f32 v[238:239], v[40:41], v[74:75], v[238:239] op_sel:[1,0,0] op_sel_hi:[1,1,1] neg_lo:[1,0,0] neg_hi:[1,0,0]
	ds_read_b128 v[38:41], v241 offset:13984
	s_waitcnt lgkmcnt(7)
	v_pk_fma_f32 v[212:213], v[42:43], v[76:77], v[212:213] op_sel:[0,0,0] op_sel_hi:[0,1,1] neg_lo:[1,0,0] neg_hi:[1,0,0]
	v_pk_fma_f32 v[234:235], v[42:43], v[78:79], v[234:235] op_sel:[1,0,0] op_sel_hi:[1,1,1] neg_lo:[1,0,0] neg_hi:[1,0,0]
	v_pk_fma_f32 v[236:237], v[44:45], v[80:81], v[236:237] op_sel:[0,0,0] op_sel_hi:[0,1,1] neg_lo:[1,0,0] neg_hi:[1,0,0]
	v_pk_fma_f32 v[238:239], v[44:45], v[82:83], v[238:239] op_sel:[1,0,0] op_sel_hi:[1,1,1] neg_lo:[1,0,0] neg_hi:[1,0,0]
	ds_read_b128 v[42:45], v241 offset:14000
	s_waitcnt lgkmcnt(7)
	v_pk_fma_f32 v[212:213], v[46:47], v[84:85], v[212:213] op_sel:[0,0,0] op_sel_hi:[0,1,1] neg_lo:[1,0,0] neg_hi:[1,0,0]
	v_pk_fma_f32 v[234:235], v[46:47], v[86:87], v[234:235] op_sel:[1,0,0] op_sel_hi:[1,1,1] neg_lo:[1,0,0] neg_hi:[1,0,0]
	v_pk_fma_f32 v[236:237], v[48:49], v[88:89], v[236:237] op_sel:[0,0,0] op_sel_hi:[0,1,1] neg_lo:[1,0,0] neg_hi:[1,0,0]
	v_pk_fma_f32 v[238:239], v[48:49], v[90:91], v[238:239] op_sel:[1,0,0] op_sel_hi:[1,1,1] neg_lo:[1,0,0] neg_hi:[1,0,0]
	ds_read_b128 v[46:49], v241 offset:14016
	s_waitcnt lgkmcnt(7)
	v_pk_fma_f32 v[212:213], v[50:51], v[92:93], v[212:213] op_sel:[0,0,0] op_sel_hi:[0,1,1] neg_lo:[1,0,0] neg_hi:[1,0,0]
	v_pk_fma_f32 v[234:235], v[50:51], v[94:95], v[234:235] op_sel:[1,0,0] op_sel_hi:[1,1,1] neg_lo:[1,0,0] neg_hi:[1,0,0]
	v_pk_fma_f32 v[236:237], v[52:53], v[96:97], v[236:237] op_sel:[0,0,0] op_sel_hi:[0,1,1] neg_lo:[1,0,0] neg_hi:[1,0,0]
	v_pk_fma_f32 v[238:239], v[52:53], v[98:99], v[238:239] op_sel:[1,0,0] op_sel_hi:[1,1,1] neg_lo:[1,0,0] neg_hi:[1,0,0]
	ds_read_b128 v[50:53], v241 offset:14032
	s_waitcnt lgkmcnt(7)
	v_pk_fma_f32 v[212:213], v[2:3], v[100:101], v[212:213] op_sel:[0,0,0] op_sel_hi:[0,1,1] neg_lo:[1,0,0] neg_hi:[1,0,0]
	v_pk_fma_f32 v[234:235], v[2:3], v[102:103], v[234:235] op_sel:[1,0,0] op_sel_hi:[1,1,1] neg_lo:[1,0,0] neg_hi:[1,0,0]
	v_pk_fma_f32 v[236:237], v[4:5], v[104:105], v[236:237] op_sel:[0,0,0] op_sel_hi:[0,1,1] neg_lo:[1,0,0] neg_hi:[1,0,0]
	v_pk_fma_f32 v[238:239], v[4:5], v[106:107], v[238:239] op_sel:[1,0,0] op_sel_hi:[1,1,1] neg_lo:[1,0,0] neg_hi:[1,0,0]
	ds_read_b128 v[2:5], v241 offset:14080
	s_waitcnt lgkmcnt(7)
	v_pk_fma_f32 v[212:213], v[26:27], v[108:109], v[212:213] op_sel:[0,0,0] op_sel_hi:[0,1,1] neg_lo:[1,0,0] neg_hi:[1,0,0]
	v_pk_fma_f32 v[234:235], v[26:27], v[110:111], v[234:235] op_sel:[1,0,0] op_sel_hi:[1,1,1] neg_lo:[1,0,0] neg_hi:[1,0,0]
	v_pk_fma_f32 v[236:237], v[28:29], v[112:113], v[236:237] op_sel:[0,0,0] op_sel_hi:[0,1,1] neg_lo:[1,0,0] neg_hi:[1,0,0]
	v_pk_fma_f32 v[238:239], v[28:29], v[114:115], v[238:239] op_sel:[1,0,0] op_sel_hi:[1,1,1] neg_lo:[1,0,0] neg_hi:[1,0,0]
	ds_read_b128 v[26:29], v241 offset:14096
	s_waitcnt lgkmcnt(7)
	v_pk_fma_f32 v[212:213], v[30:31], v[116:117], v[212:213] op_sel:[0,0,0] op_sel_hi:[0,1,1] neg_lo:[1,0,0] neg_hi:[1,0,0]
	v_pk_fma_f32 v[234:235], v[30:31], v[118:119], v[234:235] op_sel:[1,0,0] op_sel_hi:[1,1,1] neg_lo:[1,0,0] neg_hi:[1,0,0]
	v_pk_fma_f32 v[236:237], v[32:33], v[152:153], v[236:237] op_sel:[0,0,0] op_sel_hi:[0,1,1] neg_lo:[1,0,0] neg_hi:[1,0,0]
	v_pk_fma_f32 v[238:239], v[32:33], v[154:155], v[238:239] op_sel:[1,0,0] op_sel_hi:[1,1,1] neg_lo:[1,0,0] neg_hi:[1,0,0]
	ds_read_b128 v[30:33], v241 offset:14112
	s_waitcnt lgkmcnt(7)
; template <int DIR>
; __device__ __forceinline__ void dn_solve(const P& p, int task, int m0, int h, int t2, const bf16_t* kn_s, const bf16_t* v_s, const float* gc, const float* be, float* L) {
;     ...
; #pragma unroll
;     for (int cp = 1; cp < 64; ++cp) {
;         float a0 = 0.f, a1 = 0.f, a2 = 0.f, a3 = 0.f;
; #pragma unroll
;         for (int s4 = 0; s4 < cp; s4 += 4) { const f32x4 l4 = *(const f32x4*)(L + cp * 64 + s4); a0 += l4[0] * x[s4]; a1 += l4[1] * x[s4 + 1]; a2 += l4[2] * x[s4 + 2]; a3 += l4[3] * x[s4 + 3]; }
;         x[cp] -= (a0 + a1) + (a2 + a3);
;     }
	v_pk_fma_f32 v[212:213], v[34:35], v[156:157], v[212:213] op_sel:[0,0,0] op_sel_hi:[0,1,1] neg_lo:[1,0,0] neg_hi:[1,0,0]
	v_pk_fma_f32 v[234:235], v[34:35], v[158:159], v[234:235] op_sel:[1,0,0] op_sel_hi:[1,1,1] neg_lo:[1,0,0] neg_hi:[1,0,0]
	v_pk_fma_f32 v[236:237], v[36:37], v[160:161], v[236:237] op_sel:[0,0,0] op_sel_hi:[0,1,1] neg_lo:[1,0,0] neg_hi:[1,0,0]
	v_pk_fma_f32 v[238:239], v[36:37], v[162:163], v[238:239] op_sel:[1,0,0] op_sel_hi:[1,1,1] neg_lo:[1,0,0] neg_hi:[1,0,0]
	ds_read_b128 v[34:37], v241 offset:14128
	s_waitcnt lgkmcnt(7)
	v_pk_fma_f32 v[212:213], v[38:39], v[164:165], v[212:213] op_sel:[0,0,0] op_sel_hi:[0,1,1] neg_lo:[1,0,0] neg_hi:[1,0,0]
	v_pk_fma_f32 v[234:235], v[38:39], v[166:167], v[234:235] op_sel:[1,0,0] op_sel_hi:[1,1,1] neg_lo:[1,0,0] neg_hi:[1,0,0]
	v_pk_fma_f32 v[236:237], v[40:41], v[168:169], v[236:237] op_sel:[0,0,0] op_sel_hi:[0,1,1] neg_lo:[1,0,0] neg_hi:[1,0,0]
	v_pk_fma_f32 v[238:239], v[40:41], v[170:171], v[238:239] op_sel:[1,0,0] op_sel_hi:[1,1,1] neg_lo:[1,0,0] neg_hi:[1,0,0]
	ds_read_b128 v[38:41], v241 offset:14144
	s_waitcnt lgkmcnt(7)
	v_pk_fma_f32 v[212:213], v[42:43], v[172:173], v[212:213] op_sel:[0,0,0] op_sel_hi:[0,1,1] neg_lo:[1,0,0] neg_hi:[1,0,0]
	v_pk_fma_f32 v[234:235], v[42:43], v[174:175], v[234:235] op_sel:[1,0,0] op_sel_hi:[1,1,1] neg_lo:[1,0,0] neg_hi:[1,0,0]
	v_pk_fma_f32 v[236:237], v[44:45], v[176:177], v[236:237] op_sel:[0,0,0] op_sel_hi:[0,1,1] neg_lo:[1,0,0] neg_hi:[1,0,0]
	v_pk_fma_f32 v[238:239], v[44:45], v[178:179], v[238:239] op_sel:[1,0,0] op_sel_hi:[1,1,1] neg_lo:[1,0,0] neg_hi:[1,0,0]
	ds_read_b128 v[42:45], v241 offset:14160
	s_waitcnt lgkmcnt(7)
	v_pk_fma_f32 v[212:213], v[46:47], v[180:181], v[212:213] op_sel:[0,0,0] op_sel_hi:[0,1,1] neg_lo:[1,0,0] neg_hi:[1,0,0]
	v_pk_fma_f32 v[234:235], v[46:47], v[182:183], v[234:235] op_sel:[1,0,0] op_sel_hi:[1,1,1] neg_lo:[1,0,0] neg_hi:[1,0,0]
	v_pk_fma_f32 v[236:237], v[48:49], v[202:203], v[236:237] op_sel:[0,0,0] op_sel_hi:[0,1,1] neg_lo:[1,0,0] neg_hi:[1,0,0]
	v_pk_fma_f32 v[238:239], v[48:49], v[204:205], v[238:239] op_sel:[1,0,0] op_sel_hi:[1,1,1] neg_lo:[1,0,0] neg_hi:[1,0,0]
	ds_read_b128 v[46:49], v241 offset:14176
	s_waitcnt lgkmcnt(7)
	v_pk_fma_f32 v[212:213], v[50:51], v[208:209], v[212:213] op_sel:[0,0,0] op_sel_hi:[0,1,1] neg_lo:[1,0,0] neg_hi:[1,0,0]
	v_pk_fma_f32 v[234:235], v[50:51], v[210:211], v[234:235] op_sel:[1,0,0] op_sel_hi:[1,1,1] neg_lo:[1,0,0] neg_hi:[1,0,0]
	v_pk_add_f32 v[236:237], v[212:213], v[236:237]
	v_pk_add_f32 v[236:237], v[236:237], v[238:239]
	v_pk_add_f32 v[212:213], v[236:237], v[234:235]
	ds_read_b128 v[50:53], v241 offset:14192
	s_waitcnt lgkmcnt(7)
	v_pk_fma_f32 v[214:215], v[2:3], v[6:7], v[214:215] op_sel:[0,0,0] op_sel_hi:[0,1,1] neg_lo:[1,0,0] neg_hi:[1,0,0]
	v_pk_mul_f32 v[234:235], v[2:3], v[54:55] op_sel:[1,0] op_sel_hi:[1,1] neg_lo:[1,0] neg_hi:[1,0]
	v_pk_mul_f32 v[236:237], v[4:5], v[56:57] op_sel:[0,0] op_sel_hi:[0,1] neg_lo:[1,0] neg_hi:[1,0]
	v_pk_mul_f32 v[238:239], v[4:5], v[58:59] op_sel:[1,0] op_sel_hi:[1,1] neg_lo:[1,0] neg_hi:[1,0]
	ds_read_b128 v[2:5], v241 offset:14208
	s_waitcnt lgkmcnt(7)
	v_pk_fma_f32 v[214:215], v[26:27], v[60:61], v[214:215] op_sel:[0,0,0] op_sel_hi:[0,1,1] neg_lo:[1,0,0] neg_hi:[1,0,0]
	v_pk_fma_f32 v[234:235], v[26:27], v[62:63], v[234:235] op_sel:[1,0,0] op_sel_hi:[1,1,1] neg_lo:[1,0,0] neg_hi:[1,0,0]
	v_pk_fma_f32 v[236:237], v[28:29], v[64:65], v[236:237] op_sel:[0,0,0] op_sel_hi:[0,1,1] neg_lo:[1,0,0] neg_hi:[1,0,0]
	v_pk_fma_f32 v[238:239], v[28:29], v[66:67], v[238:239] op_sel:[1,0,0] op_sel_hi:[1,1,1] neg_lo:[1,0,0] neg_hi:[1,0,0]
	ds_read_b128 v[26:29], v241 offset:14224
	s_waitcnt lgkmcnt(7)
	v_pk_fma_f32 v[214:215], v[30:31], v[68:69], v[214:215] op_sel:[0,0,0] op_sel_hi:[0,1,1] neg_lo:[1,0,0] neg_hi:[1,0,0]
	v_pk_fma_f32 v[234:235], v[30:31], v[70:71], v[234:235] op_sel:[1,0,0] op_sel_hi:[1,1,1] neg_lo:[1,0,0] neg_hi:[1,0,0]
	v_pk_fma_f32 v[236:237], v[32:33], v[72:73], v[236:237] op_sel:[0,0,0] op_sel_hi:[0,1,1] neg_lo:[1,0,0] neg_hi:[1,0,0]
	v_pk_fma_f32 v[238:239], v[32:33], v[74:75], v[238:239] op_sel:[1,0,0] op_sel_hi:[1,1,1] neg_lo:[1,0,0] neg_hi:[1,0,0]
	ds_read_b128 v[30:33], v241 offset:14240
	s_waitcnt lgkmcnt(7)
	v_pk_fma_f32 v[214:215], v[34:35], v[76:77], v[214:215] op_sel:[0,0,0] op_sel_hi:[0,1,1] neg_lo:[1,0,0] neg_hi:[1,0,0]
	v_pk_fma_f32 v[234:235], v[34:35], v[78:79], v[234:235] op_sel:[1,0,0] op_sel_hi:[1,1,1] neg_lo:[1,0,0] neg_hi:[1,0,0]
	v_pk_fma_f32 v[236:237], v[36:37], v[80:81], v[236:237] op_sel:[0,0,0] op_sel_hi:[0,1,1] neg_lo:[1,0,0] neg_hi:[1,0,0]
	v_pk_fma_f32 v[238:239], v[36:37], v[82:83], v[238:239] op_sel:[1,0,0] op_sel_hi:[1,1,1] neg_lo:[1,0,0] neg_hi:[1,0,0]
	ds_read_b128 v[34:37], v241 offset:14256
	s_waitcnt lgkmcnt(7)
	v_pk_fma_f32 v[214:215], v[38:39], v[84:85], v[214:215] op_sel:[0,0,0] op_sel_hi:[0,1,1] neg_lo:[1,0,0] neg_hi:[1,0,0]
	v_pk_fma_f32 v[234:235], v[38:39], v[86:87], v[234:235] op_sel:[1,0,0] op_sel_hi:[1,1,1] neg_lo:[1,0,0] neg_hi:[1,0,0]
	v_pk_fma_f32 v[236:237], v[40:41], v[88:89], v[236:237] op_sel:[0,0,0] op_sel_hi:[0,1,1] neg_lo:[1,0,0] neg_hi:[1,0,0]
	v_pk_fma_f32 v[238:239], v[40:41], v[90:91], v[238:239] op_sel:[1,0,0] op_sel_hi:[1,1,1] neg_lo:[1,0,0] neg_hi:[1,0,0]
	ds_read_b128 v[38:41], v241 offset:14272
	s_waitcnt lgkmcnt(7)
	v_pk_fma_f32 v[214:215], v[42:43], v[92:93], v[214:215] op_sel:[0,0,0] op_sel_hi:[0,1,1] neg_lo:[1,0,0] neg_hi:[1,0,0]
	v_pk_fma_f32 v[234:235], v[42:43], v[94:95], v[234:235] op_sel:[1,0,0] op_sel_hi:[1,1,1] neg_lo:[1,0,0] neg_hi:[1,0,0]
	v_pk_fma_f32 v[236:237], v[44:45], v[96:97], v[236:237] op_sel:[0,0,0] op_sel_hi:[0,1,1] neg_lo:[1,0,0] neg_hi:[1,0,0]
	v_pk_fma_f32 v[238:239], v[44:45], v[98:99], v[238:239] op_sel:[1,0,0] op_sel_hi:[1,1,1] neg_lo:[1,0,0] neg_hi:[1,0,0]
	ds_read_b128 v[42:45], v241 offset:14288
	s_waitcnt lgkmcnt(7)
; template <int DIR>
; __device__ __forceinline__ void dn_solve(const P& p, int task, int m0, int h, int t2, const bf16_t* kn_s, const bf16_t* v_s, const float* gc, const float* be, float* L) {
;     ...
; #pragma unroll
;     for (int cp = 1; cp < 64; ++cp) {
;         float a0 = 0.f, a1 = 0.f, a2 = 0.f, a3 = 0.f;
; #pragma unroll
;         for (int s4 = 0; s4 < cp; s4 += 4) { const f32x4 l4 = *(const f32x4*)(L + cp * 64 + s4); a0 += l4[0] * x[s4]; a1 += l4[1] * x[s4 + 1]; a2 += l4[2] * x[s4 + 2]; a3 += l4[3] * x[s4 + 3]; }
;         x[cp] -= (a0 + a1) + (a2 + a3);
;     }
	v_pk_fma_f32 v[214:215], v[46:47], v[100:101], v[214:215] op_sel:[0,0,0] op_sel_hi:[0,1,1] neg_lo:[1,0,0] neg_hi:[1,0,0]
	v_pk_fma_f32 v[234:235], v[46:47], v[102:103], v[234:235] op_sel:[1,0,0] op_sel_hi:[1,1,1] neg_lo:[1,0,0] neg_hi:[1,0,0]
	v_pk_fma_f32 v[236:237], v[48:49], v[104:105], v[236:237] op_sel:[0,0,0] op_sel_hi:[0,1,1] neg_lo:[1,0,0] neg_hi:[1,0,0]
	v_pk_fma_f32 v[238:239], v[48:49], v[106:107], v[238:239] op_sel:[1,0,0] op_sel_hi:[1,1,1] neg_lo:[1,0,0] neg_hi:[1,0,0]
	ds_read_b128 v[46:49], v241 offset:14336
	s_waitcnt lgkmcnt(7)
	v_pk_fma_f32 v[214:215], v[50:51], v[108:109], v[214:215] op_sel:[0,0,0] op_sel_hi:[0,1,1] neg_lo:[1,0,0] neg_hi:[1,0,0]
	v_pk_fma_f32 v[234:235], v[50:51], v[110:111], v[234:235] op_sel:[1,0,0] op_sel_hi:[1,1,1] neg_lo:[1,0,0] neg_hi:[1,0,0]
	v_pk_fma_f32 v[236:237], v[52:53], v[112:113], v[236:237] op_sel:[0,0,0] op_sel_hi:[0,1,1] neg_lo:[1,0,0] neg_hi:[1,0,0]
	v_pk_fma_f32 v[238:239], v[52:53], v[114:115], v[238:239] op_sel:[1,0,0] op_sel_hi:[1,1,1] neg_lo:[1,0,0] neg_hi:[1,0,0]
	ds_read_b128 v[50:53], v241 offset:14352
	s_waitcnt lgkmcnt(7)
	v_pk_fma_f32 v[214:215], v[2:3], v[116:117], v[214:215] op_sel:[0,0,0] op_sel_hi:[0,1,1] neg_lo:[1,0,0] neg_hi:[1,0,0]
	v_pk_fma_f32 v[234:235], v[2:3], v[118:119], v[234:235] op_sel:[1,0,0] op_sel_hi:[1,1,1] neg_lo:[1,0,0] neg_hi:[1,0,0]
	v_pk_fma_f32 v[236:237], v[4:5], v[152:153], v[236:237] op_sel:[0,0,0] op_sel_hi:[0,1,1] neg_lo:[1,0,0] neg_hi:[1,0,0]
	v_pk_fma_f32 v[238:239], v[4:5], v[154:155], v[238:239] op_sel:[1,0,0] op_sel_hi:[1,1,1] neg_lo:[1,0,0] neg_hi:[1,0,0]
	ds_read_b128 v[2:5], v241 offset:14368
	s_waitcnt lgkmcnt(7)
	v_pk_fma_f32 v[214:215], v[26:27], v[156:157], v[214:215] op_sel:[0,0,0] op_sel_hi:[0,1,1] neg_lo:[1,0,0] neg_hi:[1,0,0]
	v_pk_fma_f32 v[234:235], v[26:27], v[158:159], v[234:235] op_sel:[1,0,0] op_sel_hi:[1,1,1] neg_lo:[1,0,0] neg_hi:[1,0,0]
	v_pk_fma_f32 v[236:237], v[28:29], v[160:161], v[236:237] op_sel:[0,0,0] op_sel_hi:[0,1,1] neg_lo:[1,0,0] neg_hi:[1,0,0]
	v_pk_fma_f32 v[238:239], v[28:29], v[162:163], v[238:239] op_sel:[1,0,0] op_sel_hi:[1,1,1] neg_lo:[1,0,0] neg_hi:[1,0,0]
	ds_read_b128 v[26:29], v241 offset:14384
	s_waitcnt lgkmcnt(7)
	v_pk_fma_f32 v[214:215], v[30:31], v[164:165], v[214:215] op_sel:[0,0,0] op_sel_hi:[0,1,1] neg_lo:[1,0,0] neg_hi:[1,0,0]
	v_pk_fma_f32 v[234:235], v[30:31], v[166:167], v[234:235] op_sel:[1,0,0] op_sel_hi:[1,1,1] neg_lo:[1,0,0] neg_hi:[1,0,0]
	v_pk_fma_f32 v[236:237], v[32:33], v[168:169], v[236:237] op_sel:[0,0,0] op_sel_hi:[0,1,1] neg_lo:[1,0,0] neg_hi:[1,0,0]
	v_pk_fma_f32 v[238:239], v[32:33], v[170:171], v[238:239] op_sel:[1,0,0] op_sel_hi:[1,1,1] neg_lo:[1,0,0] neg_hi:[1,0,0]
	ds_read_b128 v[30:33], v241 offset:14400
	s_waitcnt lgkmcnt(7)
	v_pk_fma_f32 v[214:215], v[34:35], v[172:173], v[214:215] op_sel:[0,0,0] op_sel_hi:[0,1,1] neg_lo:[1,0,0] neg_hi:[1,0,0]
	v_pk_fma_f32 v[234:235], v[34:35], v[174:175], v[234:235] op_sel:[1,0,0] op_sel_hi:[1,1,1] neg_lo:[1,0,0] neg_hi:[1,0,0]
	v_pk_fma_f32 v[236:237], v[36:37], v[176:177], v[236:237] op_sel:[0,0,0] op_sel_hi:[0,1,1] neg_lo:[1,0,0] neg_hi:[1,0,0]
	v_pk_fma_f32 v[238:239], v[36:37], v[178:179], v[238:239] op_sel:[1,0,0] op_sel_hi:[1,1,1] neg_lo:[1,0,0] neg_hi:[1,0,0]
	ds_read_b128 v[34:37], v241 offset:14416
	s_waitcnt lgkmcnt(7)
	v_pk_fma_f32 v[214:215], v[38:39], v[180:181], v[214:215] op_sel:[0,0,0] op_sel_hi:[0,1,1] neg_lo:[1,0,0] neg_hi:[1,0,0]
	v_pk_fma_f32 v[234:235], v[38:39], v[182:183], v[234:235] op_sel:[1,0,0] op_sel_hi:[1,1,1] neg_lo:[1,0,0] neg_hi:[1,0,0]
	v_pk_fma_f32 v[236:237], v[40:41], v[202:203], v[236:237] op_sel:[0,0,0] op_sel_hi:[0,1,1] neg_lo:[1,0,0] neg_hi:[1,0,0]
	v_pk_fma_f32 v[238:239], v[40:41], v[204:205], v[238:239] op_sel:[1,0,0] op_sel_hi:[1,1,1] neg_lo:[1,0,0] neg_hi:[1,0,0]
	ds_read_b128 v[38:41], v241 offset:14432
	s_waitcnt lgkmcnt(7)
	v_pk_fma_f32 v[214:215], v[42:43], v[208:209], v[214:215] op_sel:[0,0,0] op_sel_hi:[0,1,1] neg_lo:[1,0,0] neg_hi:[1,0,0]
	v_pk_fma_f32 v[234:235], v[42:43], v[210:211], v[234:235] op_sel:[1,0,0] op_sel_hi:[1,1,1] neg_lo:[1,0,0] neg_hi:[1,0,0]
	v_pk_fma_f32 v[236:237], v[44:45], v[212:213], v[236:237] op_sel:[0,0,0] op_sel_hi:[0,1,1] neg_lo:[1,0,0] neg_hi:[1,0,0]
	v_pk_add_f32 v[234:235], v[214:215], v[234:235]
	v_pk_add_f32 v[234:235], v[234:235], v[238:239]
	v_pk_add_f32 v[214:215], v[234:235], v[236:237]
	ds_read_b128 v[42:45], v241 offset:14448
	s_waitcnt lgkmcnt(7)
	v_pk_fma_f32 v[216:217], v[46:47], v[6:7], v[216:217] op_sel:[0,0,0] op_sel_hi:[0,1,1] neg_lo:[1,0,0] neg_hi:[1,0,0]
	v_pk_mul_f32 v[234:235], v[46:47], v[54:55] op_sel:[1,0] op_sel_hi:[1,1] neg_lo:[1,0] neg_hi:[1,0]
	v_pk_mul_f32 v[236:237], v[48:49], v[56:57] op_sel:[0,0] op_sel_hi:[0,1] neg_lo:[1,0] neg_hi:[1,0]
	v_pk_mul_f32 v[238:239], v[48:49], v[58:59] op_sel:[1,0] op_sel_hi:[1,1] neg_lo:[1,0] neg_hi:[1,0]
	ds_read_b128 v[46:49], v241 offset:14464
	s_waitcnt lgkmcnt(7)
	v_pk_fma_f32 v[216:217], v[50:51], v[60:61], v[216:217] op_sel:[0,0,0] op_sel_hi:[0,1,1] neg_lo:[1,0,0] neg_hi:[1,0,0]
	v_pk_fma_f32 v[234:235], v[50:51], v[62:63], v[234:235] op_sel:[1,0,0] op_sel_hi:[1,1,1] neg_lo:[1,0,0] neg_hi:[1,0,0]
	v_pk_fma_f32 v[236:237], v[52:53], v[64:65], v[236:237] op_sel:[0,0,0] op_sel_hi:[0,1,1] neg_lo:[1,0,0] neg_hi:[1,0,0]
	v_pk_fma_f32 v[238:239], v[52:53], v[66:67], v[238:239] op_sel:[1,0,0] op_sel_hi:[1,1,1] neg_lo:[1,0,0] neg_hi:[1,0,0]
	ds_read_b128 v[50:53], v241 offset:14480
	s_waitcnt lgkmcnt(7)
; template <int DIR>
; __device__ __forceinline__ void dn_solve(const P& p, int task, int m0, int h, int t2, const bf16_t* kn_s, const bf16_t* v_s, const float* gc, const float* be, float* L) {
;     ...
; #pragma unroll
;     for (int cp = 1; cp < 64; ++cp) {
;         float a0 = 0.f, a1 = 0.f, a2 = 0.f, a3 = 0.f;
; #pragma unroll
;         for (int s4 = 0; s4 < cp; s4 += 4) { const f32x4 l4 = *(const f32x4*)(L + cp * 64 + s4); a0 += l4[0] * x[s4]; a1 += l4[1] * x[s4 + 1]; a2 += l4[2] * x[s4 + 2]; a3 += l4[3] * x[s4 + 3]; }
;         x[cp] -= (a0 + a1) + (a2 + a3);
;     }
	v_pk_fma_f32 v[216:217], v[2:3], v[68:69], v[216:217] op_sel:[0,0,0] op_sel_hi:[0,1,1] neg_lo:[1,0,0] neg_hi:[1,0,0]
	v_pk_fma_f32 v[234:235], v[2:3], v[70:71], v[234:235] op_sel:[1,0,0] op_sel_hi:[1,1,1] neg_lo:[1,0,0] neg_hi:[1,0,0]
	v_pk_fma_f32 v[236:237], v[4:5], v[72:73], v[236:237] op_sel:[0,0,0] op_sel_hi:[0,1,1] neg_lo:[1,0,0] neg_hi:[1,0,0]
	v_pk_fma_f32 v[238:239], v[4:5], v[74:75], v[238:239] op_sel:[1,0,0] op_sel_hi:[1,1,1] neg_lo:[1,0,0] neg_hi:[1,0,0]
	ds_read_b128 v[2:5], v241 offset:14496
	s_waitcnt lgkmcnt(7)
	v_pk_fma_f32 v[216:217], v[26:27], v[76:77], v[216:217] op_sel:[0,0,0] op_sel_hi:[0,1,1] neg_lo:[1,0,0] neg_hi:[1,0,0]
	v_pk_fma_f32 v[234:235], v[26:27], v[78:79], v[234:235] op_sel:[1,0,0] op_sel_hi:[1,1,1] neg_lo:[1,0,0] neg_hi:[1,0,0]
	v_pk_fma_f32 v[236:237], v[28:29], v[80:81], v[236:237] op_sel:[0,0,0] op_sel_hi:[0,1,1] neg_lo:[1,0,0] neg_hi:[1,0,0]
	v_pk_fma_f32 v[238:239], v[28:29], v[82:83], v[238:239] op_sel:[1,0,0] op_sel_hi:[1,1,1] neg_lo:[1,0,0] neg_hi:[1,0,0]
	ds_read_b128 v[26:29], v241 offset:14512
	s_waitcnt lgkmcnt(7)
	v_pk_fma_f32 v[216:217], v[30:31], v[84:85], v[216:217] op_sel:[0,0,0] op_sel_hi:[0,1,1] neg_lo:[1,0,0] neg_hi:[1,0,0]
	v_pk_fma_f32 v[234:235], v[30:31], v[86:87], v[234:235] op_sel:[1,0,0] op_sel_hi:[1,1,1] neg_lo:[1,0,0] neg_hi:[1,0,0]
	v_pk_fma_f32 v[236:237], v[32:33], v[88:89], v[236:237] op_sel:[0,0,0] op_sel_hi:[0,1,1] neg_lo:[1,0,0] neg_hi:[1,0,0]
	v_pk_fma_f32 v[238:239], v[32:33], v[90:91], v[238:239] op_sel:[1,0,0] op_sel_hi:[1,1,1] neg_lo:[1,0,0] neg_hi:[1,0,0]
	ds_read_b128 v[30:33], v241 offset:14528
	s_waitcnt lgkmcnt(7)
	v_pk_fma_f32 v[216:217], v[34:35], v[92:93], v[216:217] op_sel:[0,0,0] op_sel_hi:[0,1,1] neg_lo:[1,0,0] neg_hi:[1,0,0]
	v_pk_fma_f32 v[234:235], v[34:35], v[94:95], v[234:235] op_sel:[1,0,0] op_sel_hi:[1,1,1] neg_lo:[1,0,0] neg_hi:[1,0,0]
	v_pk_fma_f32 v[236:237], v[36:37], v[96:97], v[236:237] op_sel:[0,0,0] op_sel_hi:[0,1,1] neg_lo:[1,0,0] neg_hi:[1,0,0]
	v_pk_fma_f32 v[238:239], v[36:37], v[98:99], v[238:239] op_sel:[1,0,0] op_sel_hi:[1,1,1] neg_lo:[1,0,0] neg_hi:[1,0,0]
	ds_read_b128 v[34:37], v241 offset:14544
	s_waitcnt lgkmcnt(7)
	v_pk_fma_f32 v[216:217], v[38:39], v[100:101], v[216:217] op_sel:[0,0,0] op_sel_hi:[0,1,1] neg_lo:[1,0,0] neg_hi:[1,0,0]
	v_pk_fma_f32 v[234:235], v[38:39], v[102:103], v[234:235] op_sel:[1,0,0] op_sel_hi:[1,1,1] neg_lo:[1,0,0] neg_hi:[1,0,0]
	v_pk_fma_f32 v[236:237], v[40:41], v[104:105], v[236:237] op_sel:[0,0,0] op_sel_hi:[0,1,1] neg_lo:[1,0,0] neg_hi:[1,0,0]
	v_pk_fma_f32 v[238:239], v[40:41], v[106:107], v[238:239] op_sel:[1,0,0] op_sel_hi:[1,1,1] neg_lo:[1,0,0] neg_hi:[1,0,0]
	ds_read_b128 v[38:41], v241 offset:14592
	s_waitcnt lgkmcnt(7)
	v_pk_fma_f32 v[216:217], v[42:43], v[108:109], v[216:217] op_sel:[0,0,0] op_sel_hi:[0,1,1] neg_lo:[1,0,0] neg_hi:[1,0,0]
	v_pk_fma_f32 v[234:235], v[42:43], v[110:111], v[234:235] op_sel:[1,0,0] op_sel_hi:[1,1,1] neg_lo:[1,0,0] neg_hi:[1,0,0]
	v_pk_fma_f32 v[236:237], v[44:45], v[112:113], v[236:237] op_sel:[0,0,0] op_sel_hi:[0,1,1] neg_lo:[1,0,0] neg_hi:[1,0,0]
	v_pk_fma_f32 v[238:239], v[44:45], v[114:115], v[238:239] op_sel:[1,0,0] op_sel_hi:[1,1,1] neg_lo:[1,0,0] neg_hi:[1,0,0]
	ds_read_b128 v[42:45], v241 offset:14608
	s_waitcnt lgkmcnt(7)
	v_pk_fma_f32 v[216:217], v[46:47], v[116:117], v[216:217] op_sel:[0,0,0] op_sel_hi:[0,1,1] neg_lo:[1,0,0] neg_hi:[1,0,0]
	v_pk_fma_f32 v[234:235], v[46:47], v[118:119], v[234:235] op_sel:[1,0,0] op_sel_hi:[1,1,1] neg_lo:[1,0,0] neg_hi:[1,0,0]
	v_pk_fma_f32 v[236:237], v[48:49], v[152:153], v[236:237] op_sel:[0,0,0] op_sel_hi:[0,1,1] neg_lo:[1,0,0] neg_hi:[1,0,0]
	v_pk_fma_f32 v[238:239], v[48:49], v[154:155], v[238:239] op_sel:[1,0,0] op_sel_hi:[1,1,1] neg_lo:[1,0,0] neg_hi:[1,0,0]
	ds_read_b128 v[46:49], v241 offset:14624
	s_waitcnt lgkmcnt(7)
	v_pk_fma_f32 v[216:217], v[50:51], v[156:157], v[216:217] op_sel:[0,0,0] op_sel_hi:[0,1,1] neg_lo:[1,0,0] neg_hi:[1,0,0]
	v_pk_fma_f32 v[234:235], v[50:51], v[158:159], v[234:235] op_sel:[1,0,0] op_sel_hi:[1,1,1] neg_lo:[1,0,0] neg_hi:[1,0,0]
	v_pk_fma_f32 v[236:237], v[52:53], v[160:161], v[236:237] op_sel:[0,0,0] op_sel_hi:[0,1,1] neg_lo:[1,0,0] neg_hi:[1,0,0]
	v_pk_fma_f32 v[238:239], v[52:53], v[162:163], v[238:239] op_sel:[1,0,0] op_sel_hi:[1,1,1] neg_lo:[1,0,0] neg_hi:[1,0,0]
	ds_read_b128 v[50:53], v241 offset:14640
	s_waitcnt lgkmcnt(7)
	v_pk_fma_f32 v[216:217], v[2:3], v[164:165], v[216:217] op_sel:[0,0,0] op_sel_hi:[0,1,1] neg_lo:[1,0,0] neg_hi:[1,0,0]
	v_pk_fma_f32 v[234:235], v[2:3], v[166:167], v[234:235] op_sel:[1,0,0] op_sel_hi:[1,1,1] neg_lo:[1,0,0] neg_hi:[1,0,0]
	v_pk_fma_f32 v[236:237], v[4:5], v[168:169], v[236:237] op_sel:[0,0,0] op_sel_hi:[0,1,1] neg_lo:[1,0,0] neg_hi:[1,0,0]
	v_pk_fma_f32 v[238:239], v[4:5], v[170:171], v[238:239] op_sel:[1,0,0] op_sel_hi:[1,1,1] neg_lo:[1,0,0] neg_hi:[1,0,0]
	ds_read_b128 v[2:5], v241 offset:14656
	s_waitcnt lgkmcnt(7)
	v_pk_fma_f32 v[216:217], v[26:27], v[172:173], v[216:217] op_sel:[0,0,0] op_sel_hi:[0,1,1] neg_lo:[1,0,0] neg_hi:[1,0,0]
	v_pk_fma_f32 v[234:235], v[26:27], v[174:175], v[234:235] op_sel:[1,0,0] op_sel_hi:[1,1,1] neg_lo:[1,0,0] neg_hi:[1,0,0]
	v_pk_fma_f32 v[236:237], v[28:29], v[176:177], v[236:237] op_sel:[0,0,0] op_sel_hi:[0,1,1] neg_lo:[1,0,0] neg_hi:[1,0,0]
	v_pk_fma_f32 v[238:239], v[28:29], v[178:179], v[238:239] op_sel:[1,0,0] op_sel_hi:[1,1,1] neg_lo:[1,0,0] neg_hi:[1,0,0]
	ds_read_b128 v[26:29], v241 offset:14672
	s_waitcnt lgkmcnt(7)
; template <int DIR>
; __device__ __forceinline__ void dn_solve(const P& p, int task, int m0, int h, int t2, const bf16_t* kn_s, const bf16_t* v_s, const float* gc, const float* be, float* L) {
;     ...
; #pragma unroll
;     for (int cp = 1; cp < 64; ++cp) {
;         float a0 = 0.f, a1 = 0.f, a2 = 0.f, a3 = 0.f;
; #pragma unroll
;         for (int s4 = 0; s4 < cp; s4 += 4) { const f32x4 l4 = *(const f32x4*)(L + cp * 64 + s4); a0 += l4[0] * x[s4]; a1 += l4[1] * x[s4 + 1]; a2 += l4[2] * x[s4 + 2]; a3 += l4[3] * x[s4 + 3]; }
;         x[cp] -= (a0 + a1) + (a2 + a3);
;     }
	v_pk_fma_f32 v[216:217], v[30:31], v[180:181], v[216:217] op_sel:[0,0,0] op_sel_hi:[0,1,1] neg_lo:[1,0,0] neg_hi:[1,0,0]
	v_pk_fma_f32 v[234:235], v[30:31], v[182:183], v[234:235] op_sel:[1,0,0] op_sel_hi:[1,1,1] neg_lo:[1,0,0] neg_hi:[1,0,0]
	v_pk_fma_f32 v[236:237], v[32:33], v[202:203], v[236:237] op_sel:[0,0,0] op_sel_hi:[0,1,1] neg_lo:[1,0,0] neg_hi:[1,0,0]
	v_pk_fma_f32 v[238:239], v[32:33], v[204:205], v[238:239] op_sel:[1,0,0] op_sel_hi:[1,1,1] neg_lo:[1,0,0] neg_hi:[1,0,0]
	ds_read_b128 v[30:33], v241 offset:14688
	s_waitcnt lgkmcnt(7)
	v_pk_fma_f32 v[216:217], v[34:35], v[208:209], v[216:217] op_sel:[0,0,0] op_sel_hi:[0,1,1] neg_lo:[1,0,0] neg_hi:[1,0,0]
	v_pk_fma_f32 v[234:235], v[34:35], v[210:211], v[234:235] op_sel:[1,0,0] op_sel_hi:[1,1,1] neg_lo:[1,0,0] neg_hi:[1,0,0]
	v_pk_fma_f32 v[236:237], v[36:37], v[212:213], v[236:237] op_sel:[0,0,0] op_sel_hi:[0,1,1] neg_lo:[1,0,0] neg_hi:[1,0,0]
	v_pk_fma_f32 v[238:239], v[36:37], v[214:215], v[238:239] op_sel:[1,0,0] op_sel_hi:[1,1,1] neg_lo:[1,0,0] neg_hi:[1,0,0]
	v_pk_add_f32 v[234:235], v[216:217], v[234:235]
	v_pk_add_f32 v[234:235], v[234:235], v[236:237]
	v_pk_add_f32 v[216:217], v[234:235], v[238:239]
	ds_read_b128 v[34:37], v241 offset:14704
	s_waitcnt lgkmcnt(7)
	v_pk_fma_f32 v[218:219], v[38:39], v[6:7], v[218:219] op_sel:[0,0,0] op_sel_hi:[0,1,1] neg_lo:[1,0,0] neg_hi:[1,0,0]
	v_pk_mul_f32 v[234:235], v[38:39], v[54:55] op_sel:[1,0] op_sel_hi:[1,1] neg_lo:[1,0] neg_hi:[1,0]
	v_pk_mul_f32 v[236:237], v[40:41], v[56:57] op_sel:[0,0] op_sel_hi:[0,1] neg_lo:[1,0] neg_hi:[1,0]
	v_pk_mul_f32 v[238:239], v[40:41], v[58:59] op_sel:[1,0] op_sel_hi:[1,1] neg_lo:[1,0] neg_hi:[1,0]
	ds_read_b128 v[38:41], v241 offset:14720
	s_waitcnt lgkmcnt(7)
	v_pk_fma_f32 v[218:219], v[42:43], v[60:61], v[218:219] op_sel:[0,0,0] op_sel_hi:[0,1,1] neg_lo:[1,0,0] neg_hi:[1,0,0]
	v_pk_fma_f32 v[234:235], v[42:43], v[62:63], v[234:235] op_sel:[1,0,0] op_sel_hi:[1,1,1] neg_lo:[1,0,0] neg_hi:[1,0,0]
	v_pk_fma_f32 v[236:237], v[44:45], v[64:65], v[236:237] op_sel:[0,0,0] op_sel_hi:[0,1,1] neg_lo:[1,0,0] neg_hi:[1,0,0]
	v_pk_fma_f32 v[238:239], v[44:45], v[66:67], v[238:239] op_sel:[1,0,0] op_sel_hi:[1,1,1] neg_lo:[1,0,0] neg_hi:[1,0,0]
	ds_read_b128 v[42:45], v241 offset:14736
	s_waitcnt lgkmcnt(7)
	v_pk_fma_f32 v[218:219], v[46:47], v[68:69], v[218:219] op_sel:[0,0,0] op_sel_hi:[0,1,1] neg_lo:[1,0,0] neg_hi:[1,0,0]
	v_pk_fma_f32 v[234:235], v[46:47], v[70:71], v[234:235] op_sel:[1,0,0] op_sel_hi:[1,1,1] neg_lo:[1,0,0] neg_hi:[1,0,0]
	v_pk_fma_f32 v[236:237], v[48:49], v[72:73], v[236:237] op_sel:[0,0,0] op_sel_hi:[0,1,1] neg_lo:[1,0,0] neg_hi:[1,0,0]
	v_pk_fma_f32 v[238:239], v[48:49], v[74:75], v[238:239] op_sel:[1,0,0] op_sel_hi:[1,1,1] neg_lo:[1,0,0] neg_hi:[1,0,0]
	ds_read_b128 v[46:49], v241 offset:14752
	s_waitcnt lgkmcnt(7)
	v_pk_fma_f32 v[218:219], v[50:51], v[76:77], v[218:219] op_sel:[0,0,0] op_sel_hi:[0,1,1] neg_lo:[1,0,0] neg_hi:[1,0,0]
	v_pk_fma_f32 v[234:235], v[50:51], v[78:79], v[234:235] op_sel:[1,0,0] op_sel_hi:[1,1,1] neg_lo:[1,0,0] neg_hi:[1,0,0]
	v_pk_fma_f32 v[236:237], v[52:53], v[80:81], v[236:237] op_sel:[0,0,0] op_sel_hi:[0,1,1] neg_lo:[1,0,0] neg_hi:[1,0,0]
	v_pk_fma_f32 v[238:239], v[52:53], v[82:83], v[238:239] op_sel:[1,0,0] op_sel_hi:[1,1,1] neg_lo:[1,0,0] neg_hi:[1,0,0]
	ds_read_b128 v[50:53], v241 offset:14768
	s_waitcnt lgkmcnt(7)
	v_pk_fma_f32 v[218:219], v[2:3], v[84:85], v[218:219] op_sel:[0,0,0] op_sel_hi:[0,1,1] neg_lo:[1,0,0] neg_hi:[1,0,0]
	v_pk_fma_f32 v[234:235], v[2:3], v[86:87], v[234:235] op_sel:[1,0,0] op_sel_hi:[1,1,1] neg_lo:[1,0,0] neg_hi:[1,0,0]
	v_pk_fma_f32 v[236:237], v[4:5], v[88:89], v[236:237] op_sel:[0,0,0] op_sel_hi:[0,1,1] neg_lo:[1,0,0] neg_hi:[1,0,0]
	v_pk_fma_f32 v[238:239], v[4:5], v[90:91], v[238:239] op_sel:[1,0,0] op_sel_hi:[1,1,1] neg_lo:[1,0,0] neg_hi:[1,0,0]
	ds_read_b128 v[2:5], v241 offset:14784
	s_waitcnt lgkmcnt(7)
	v_pk_fma_f32 v[218:219], v[26:27], v[92:93], v[218:219] op_sel:[0,0,0] op_sel_hi:[0,1,1] neg_lo:[1,0,0] neg_hi:[1,0,0]
	v_pk_fma_f32 v[234:235], v[26:27], v[94:95], v[234:235] op_sel:[1,0,0] op_sel_hi:[1,1,1] neg_lo:[1,0,0] neg_hi:[1,0,0]
	v_pk_fma_f32 v[236:237], v[28:29], v[96:97], v[236:237] op_sel:[0,0,0] op_sel_hi:[0,1,1] neg_lo:[1,0,0] neg_hi:[1,0,0]
	v_pk_fma_f32 v[238:239], v[28:29], v[98:99], v[238:239] op_sel:[1,0,0] op_sel_hi:[1,1,1] neg_lo:[1,0,0] neg_hi:[1,0,0]
	ds_read_b128 v[26:29], v241 offset:14800
	s_waitcnt lgkmcnt(7)
	v_pk_fma_f32 v[218:219], v[30:31], v[100:101], v[218:219] op_sel:[0,0,0] op_sel_hi:[0,1,1] neg_lo:[1,0,0] neg_hi:[1,0,0]
	v_pk_fma_f32 v[234:235], v[30:31], v[102:103], v[234:235] op_sel:[1,0,0] op_sel_hi:[1,1,1] neg_lo:[1,0,0] neg_hi:[1,0,0]
	v_pk_fma_f32 v[236:237], v[32:33], v[104:105], v[236:237] op_sel:[0,0,0] op_sel_hi:[0,1,1] neg_lo:[1,0,0] neg_hi:[1,0,0]
	v_pk_fma_f32 v[238:239], v[32:33], v[106:107], v[238:239] op_sel:[1,0,0] op_sel_hi:[1,1,1] neg_lo:[1,0,0] neg_hi:[1,0,0]
	ds_read_b128 v[30:33], v241 offset:14816
	s_waitcnt lgkmcnt(7)
	v_pk_fma_f32 v[218:219], v[34:35], v[108:109], v[218:219] op_sel:[0,0,0] op_sel_hi:[0,1,1] neg_lo:[1,0,0] neg_hi:[1,0,0]
	v_pk_fma_f32 v[234:235], v[34:35], v[110:111], v[234:235] op_sel:[1,0,0] op_sel_hi:[1,1,1] neg_lo:[1,0,0] neg_hi:[1,0,0]
	v_pk_fma_f32 v[236:237], v[36:37], v[112:113], v[236:237] op_sel:[0,0,0] op_sel_hi:[0,1,1] neg_lo:[1,0,0] neg_hi:[1,0,0]
	v_pk_fma_f32 v[238:239], v[36:37], v[114:115], v[238:239] op_sel:[1,0,0] op_sel_hi:[1,1,1] neg_lo:[1,0,0] neg_hi:[1,0,0]
	ds_read_b128 v[34:37], v241 offset:14848
	s_waitcnt lgkmcnt(7)
; template <int DIR>
; __device__ __forceinline__ void dn_solve(const P& p, int task, int m0, int h, int t2, const bf16_t* kn_s, const bf16_t* v_s, const float* gc, const float* be, float* L) {
;     ...
; #pragma unroll
;     for (int cp = 1; cp < 64; ++cp) {
;         float a0 = 0.f, a1 = 0.f, a2 = 0.f, a3 = 0.f;
; #pragma unroll
;         for (int s4 = 0; s4 < cp; s4 += 4) { const f32x4 l4 = *(const f32x4*)(L + cp * 64 + s4); a0 += l4[0] * x[s4]; a1 += l4[1] * x[s4 + 1]; a2 += l4[2] * x[s4 + 2]; a3 += l4[3] * x[s4 + 3]; }
;         x[cp] -= (a0 + a1) + (a2 + a3);
;     }
	v_pk_fma_f32 v[218:219], v[38:39], v[116:117], v[218:219] op_sel:[0,0,0] op_sel_hi:[0,1,1] neg_lo:[1,0,0] neg_hi:[1,0,0]
	v_pk_fma_f32 v[234:235], v[38:39], v[118:119], v[234:235] op_sel:[1,0,0] op_sel_hi:[1,1,1] neg_lo:[1,0,0] neg_hi:[1,0,0]
	v_pk_fma_f32 v[236:237], v[40:41], v[152:153], v[236:237] op_sel:[0,0,0] op_sel_hi:[0,1,1] neg_lo:[1,0,0] neg_hi:[1,0,0]
	v_pk_fma_f32 v[238:239], v[40:41], v[154:155], v[238:239] op_sel:[1,0,0] op_sel_hi:[1,1,1] neg_lo:[1,0,0] neg_hi:[1,0,0]
	ds_read_b128 v[38:41], v241 offset:14864
	s_waitcnt lgkmcnt(7)
	v_pk_fma_f32 v[218:219], v[42:43], v[156:157], v[218:219] op_sel:[0,0,0] op_sel_hi:[0,1,1] neg_lo:[1,0,0] neg_hi:[1,0,0]
	v_pk_fma_f32 v[234:235], v[42:43], v[158:159], v[234:235] op_sel:[1,0,0] op_sel_hi:[1,1,1] neg_lo:[1,0,0] neg_hi:[1,0,0]
	v_pk_fma_f32 v[236:237], v[44:45], v[160:161], v[236:237] op_sel:[0,0,0] op_sel_hi:[0,1,1] neg_lo:[1,0,0] neg_hi:[1,0,0]
	v_pk_fma_f32 v[238:239], v[44:45], v[162:163], v[238:239] op_sel:[1,0,0] op_sel_hi:[1,1,1] neg_lo:[1,0,0] neg_hi:[1,0,0]
	ds_read_b128 v[42:45], v241 offset:14880
	s_waitcnt lgkmcnt(7)
	v_pk_fma_f32 v[218:219], v[46:47], v[164:165], v[218:219] op_sel:[0,0,0] op_sel_hi:[0,1,1] neg_lo:[1,0,0] neg_hi:[1,0,0]
	v_pk_fma_f32 v[234:235], v[46:47], v[166:167], v[234:235] op_sel:[1,0,0] op_sel_hi:[1,1,1] neg_lo:[1,0,0] neg_hi:[1,0,0]
	v_pk_fma_f32 v[236:237], v[48:49], v[168:169], v[236:237] op_sel:[0,0,0] op_sel_hi:[0,1,1] neg_lo:[1,0,0] neg_hi:[1,0,0]
	v_pk_fma_f32 v[238:239], v[48:49], v[170:171], v[238:239] op_sel:[1,0,0] op_sel_hi:[1,1,1] neg_lo:[1,0,0] neg_hi:[1,0,0]
	ds_read_b128 v[46:49], v241 offset:14896
	s_waitcnt lgkmcnt(7)
	v_pk_fma_f32 v[218:219], v[50:51], v[172:173], v[218:219] op_sel:[0,0,0] op_sel_hi:[0,1,1] neg_lo:[1,0,0] neg_hi:[1,0,0]
	v_pk_fma_f32 v[234:235], v[50:51], v[174:175], v[234:235] op_sel:[1,0,0] op_sel_hi:[1,1,1] neg_lo:[1,0,0] neg_hi:[1,0,0]
	v_pk_fma_f32 v[236:237], v[52:53], v[176:177], v[236:237] op_sel:[0,0,0] op_sel_hi:[0,1,1] neg_lo:[1,0,0] neg_hi:[1,0,0]
	v_pk_fma_f32 v[238:239], v[52:53], v[178:179], v[238:239] op_sel:[1,0,0] op_sel_hi:[1,1,1] neg_lo:[1,0,0] neg_hi:[1,0,0]
	ds_read_b128 v[50:53], v241 offset:14912
	s_waitcnt lgkmcnt(7)
	v_pk_fma_f32 v[218:219], v[2:3], v[180:181], v[218:219] op_sel:[0,0,0] op_sel_hi:[0,1,1] neg_lo:[1,0,0] neg_hi:[1,0,0]
	v_pk_fma_f32 v[234:235], v[2:3], v[182:183], v[234:235] op_sel:[1,0,0] op_sel_hi:[1,1,1] neg_lo:[1,0,0] neg_hi:[1,0,0]
	v_pk_fma_f32 v[236:237], v[4:5], v[202:203], v[236:237] op_sel:[0,0,0] op_sel_hi:[0,1,1] neg_lo:[1,0,0] neg_hi:[1,0,0]
	v_pk_fma_f32 v[238:239], v[4:5], v[204:205], v[238:239] op_sel:[1,0,0] op_sel_hi:[1,1,1] neg_lo:[1,0,0] neg_hi:[1,0,0]
	ds_read_b128 v[2:5], v241 offset:14928
	s_waitcnt lgkmcnt(7)
	v_pk_fma_f32 v[218:219], v[26:27], v[208:209], v[218:219] op_sel:[0,0,0] op_sel_hi:[0,1,1] neg_lo:[1,0,0] neg_hi:[1,0,0]
	v_pk_fma_f32 v[234:235], v[26:27], v[210:211], v[234:235] op_sel:[1,0,0] op_sel_hi:[1,1,1] neg_lo:[1,0,0] neg_hi:[1,0,0]
	v_pk_fma_f32 v[236:237], v[28:29], v[212:213], v[236:237] op_sel:[0,0,0] op_sel_hi:[0,1,1] neg_lo:[1,0,0] neg_hi:[1,0,0]
	v_pk_fma_f32 v[238:239], v[28:29], v[214:215], v[238:239] op_sel:[1,0,0] op_sel_hi:[1,1,1] neg_lo:[1,0,0] neg_hi:[1,0,0]
	ds_read_b128 v[26:29], v241 offset:14944
	s_waitcnt lgkmcnt(7)
	v_pk_fma_f32 v[218:219], v[30:31], v[216:217], v[218:219] op_sel:[0,0,0] op_sel_hi:[0,1,1] neg_lo:[1,0,0] neg_hi:[1,0,0]
	v_pk_add_f32 v[234:235], v[234:235], v[236:237]
	v_pk_add_f32 v[234:235], v[234:235], v[238:239]
	v_pk_add_f32 v[218:219], v[234:235], v[218:219]
	ds_read_b128 v[30:33], v241 offset:14960
	s_waitcnt lgkmcnt(7)
	v_pk_fma_f32 v[220:221], v[34:35], v[6:7], v[220:221] op_sel:[0,0,0] op_sel_hi:[0,1,1] neg_lo:[1,0,0] neg_hi:[1,0,0]
	v_pk_mul_f32 v[234:235], v[34:35], v[54:55] op_sel:[1,0] op_sel_hi:[1,1] neg_lo:[1,0] neg_hi:[1,0]
	v_pk_mul_f32 v[236:237], v[36:37], v[56:57] op_sel:[0,0] op_sel_hi:[0,1] neg_lo:[1,0] neg_hi:[1,0]
	v_pk_mul_f32 v[238:239], v[36:37], v[58:59] op_sel:[1,0] op_sel_hi:[1,1] neg_lo:[1,0] neg_hi:[1,0]
	ds_read_b128 v[34:37], v241 offset:14976
	s_waitcnt lgkmcnt(7)
	v_pk_fma_f32 v[220:221], v[38:39], v[60:61], v[220:221] op_sel:[0,0,0] op_sel_hi:[0,1,1] neg_lo:[1,0,0] neg_hi:[1,0,0]
	v_pk_fma_f32 v[234:235], v[38:39], v[62:63], v[234:235] op_sel:[1,0,0] op_sel_hi:[1,1,1] neg_lo:[1,0,0] neg_hi:[1,0,0]
	v_pk_fma_f32 v[236:237], v[40:41], v[64:65], v[236:237] op_sel:[0,0,0] op_sel_hi:[0,1,1] neg_lo:[1,0,0] neg_hi:[1,0,0]
	v_pk_fma_f32 v[238:239], v[40:41], v[66:67], v[238:239] op_sel:[1,0,0] op_sel_hi:[1,1,1] neg_lo:[1,0,0] neg_hi:[1,0,0]
	ds_read_b128 v[38:41], v241 offset:14992
	s_waitcnt lgkmcnt(7)
	v_pk_fma_f32 v[220:221], v[42:43], v[68:69], v[220:221] op_sel:[0,0,0] op_sel_hi:[0,1,1] neg_lo:[1,0,0] neg_hi:[1,0,0]
	v_pk_fma_f32 v[234:235], v[42:43], v[70:71], v[234:235] op_sel:[1,0,0] op_sel_hi:[1,1,1] neg_lo:[1,0,0] neg_hi:[1,0,0]
	v_pk_fma_f32 v[236:237], v[44:45], v[72:73], v[236:237] op_sel:[0,0,0] op_sel_hi:[0,1,1] neg_lo:[1,0,0] neg_hi:[1,0,0]
	v_pk_fma_f32 v[238:239], v[44:45], v[74:75], v[238:239] op_sel:[1,0,0] op_sel_hi:[1,1,1] neg_lo:[1,0,0] neg_hi:[1,0,0]
	ds_read_b128 v[42:45], v241 offset:15008
	s_waitcnt lgkmcnt(7)
	v_pk_fma_f32 v[220:221], v[46:47], v[76:77], v[220:221] op_sel:[0,0,0] op_sel_hi:[0,1,1] neg_lo:[1,0,0] neg_hi:[1,0,0]
	v_pk_fma_f32 v[234:235], v[46:47], v[78:79], v[234:235] op_sel:[1,0,0] op_sel_hi:[1,1,1] neg_lo:[1,0,0] neg_hi:[1,0,0]
	v_pk_fma_f32 v[236:237], v[48:49], v[80:81], v[236:237] op_sel:[0,0,0] op_sel_hi:[0,1,1] neg_lo:[1,0,0] neg_hi:[1,0,0]
	v_pk_fma_f32 v[238:239], v[48:49], v[82:83], v[238:239] op_sel:[1,0,0] op_sel_hi:[1,1,1] neg_lo:[1,0,0] neg_hi:[1,0,0]
	ds_read_b128 v[46:49], v241 offset:15024
	s_waitcnt lgkmcnt(7)
; template <int DIR>
; __device__ __forceinline__ void dn_solve(const P& p, int task, int m0, int h, int t2, const bf16_t* kn_s, const bf16_t* v_s, const float* gc, const float* be, float* L) {
;     ...
; #pragma unroll
;     for (int cp = 1; cp < 64; ++cp) {
;         float a0 = 0.f, a1 = 0.f, a2 = 0.f, a3 = 0.f;
; #pragma unroll
;         for (int s4 = 0; s4 < cp; s4 += 4) { const f32x4 l4 = *(const f32x4*)(L + cp * 64 + s4); a0 += l4[0] * x[s4]; a1 += l4[1] * x[s4 + 1]; a2 += l4[2] * x[s4 + 2]; a3 += l4[3] * x[s4 + 3]; }
;         x[cp] -= (a0 + a1) + (a2 + a3);
;     }
	v_pk_fma_f32 v[220:221], v[50:51], v[84:85], v[220:221] op_sel:[0,0,0] op_sel_hi:[0,1,1] neg_lo:[1,0,0] neg_hi:[1,0,0]
	v_pk_fma_f32 v[234:235], v[50:51], v[86:87], v[234:235] op_sel:[1,0,0] op_sel_hi:[1,1,1] neg_lo:[1,0,0] neg_hi:[1,0,0]
	v_pk_fma_f32 v[236:237], v[52:53], v[88:89], v[236:237] op_sel:[0,0,0] op_sel_hi:[0,1,1] neg_lo:[1,0,0] neg_hi:[1,0,0]
	v_pk_fma_f32 v[238:239], v[52:53], v[90:91], v[238:239] op_sel:[1,0,0] op_sel_hi:[1,1,1] neg_lo:[1,0,0] neg_hi:[1,0,0]
	ds_read_b128 v[50:53], v241 offset:15040
	s_waitcnt lgkmcnt(7)
	v_pk_fma_f32 v[220:221], v[2:3], v[92:93], v[220:221] op_sel:[0,0,0] op_sel_hi:[0,1,1] neg_lo:[1,0,0] neg_hi:[1,0,0]
	v_pk_fma_f32 v[234:235], v[2:3], v[94:95], v[234:235] op_sel:[1,0,0] op_sel_hi:[1,1,1] neg_lo:[1,0,0] neg_hi:[1,0,0]
	v_pk_fma_f32 v[236:237], v[4:5], v[96:97], v[236:237] op_sel:[0,0,0] op_sel_hi:[0,1,1] neg_lo:[1,0,0] neg_hi:[1,0,0]
	v_pk_fma_f32 v[238:239], v[4:5], v[98:99], v[238:239] op_sel:[1,0,0] op_sel_hi:[1,1,1] neg_lo:[1,0,0] neg_hi:[1,0,0]
	ds_read_b128 v[2:5], v241 offset:15056
	s_waitcnt lgkmcnt(7)
	v_pk_fma_f32 v[220:221], v[26:27], v[100:101], v[220:221] op_sel:[0,0,0] op_sel_hi:[0,1,1] neg_lo:[1,0,0] neg_hi:[1,0,0]
	v_pk_fma_f32 v[234:235], v[26:27], v[102:103], v[234:235] op_sel:[1,0,0] op_sel_hi:[1,1,1] neg_lo:[1,0,0] neg_hi:[1,0,0]
	v_pk_fma_f32 v[236:237], v[28:29], v[104:105], v[236:237] op_sel:[0,0,0] op_sel_hi:[0,1,1] neg_lo:[1,0,0] neg_hi:[1,0,0]
	v_pk_fma_f32 v[238:239], v[28:29], v[106:107], v[238:239] op_sel:[1,0,0] op_sel_hi:[1,1,1] neg_lo:[1,0,0] neg_hi:[1,0,0]
	ds_read_b128 v[26:29], v241 offset:15072
	s_waitcnt lgkmcnt(7)
	v_pk_fma_f32 v[220:221], v[30:31], v[108:109], v[220:221] op_sel:[0,0,0] op_sel_hi:[0,1,1] neg_lo:[1,0,0] neg_hi:[1,0,0]
	v_pk_fma_f32 v[234:235], v[30:31], v[110:111], v[234:235] op_sel:[1,0,0] op_sel_hi:[1,1,1] neg_lo:[1,0,0] neg_hi:[1,0,0]
	v_pk_fma_f32 v[236:237], v[32:33], v[112:113], v[236:237] op_sel:[0,0,0] op_sel_hi:[0,1,1] neg_lo:[1,0,0] neg_hi:[1,0,0]
	v_pk_fma_f32 v[238:239], v[32:33], v[114:115], v[238:239] op_sel:[1,0,0] op_sel_hi:[1,1,1] neg_lo:[1,0,0] neg_hi:[1,0,0]
	ds_read_b128 v[30:33], v241 offset:15104
	s_waitcnt lgkmcnt(7)
	v_pk_fma_f32 v[220:221], v[34:35], v[116:117], v[220:221] op_sel:[0,0,0] op_sel_hi:[0,1,1] neg_lo:[1,0,0] neg_hi:[1,0,0]
	v_pk_fma_f32 v[234:235], v[34:35], v[118:119], v[234:235] op_sel:[1,0,0] op_sel_hi:[1,1,1] neg_lo:[1,0,0] neg_hi:[1,0,0]
	v_pk_fma_f32 v[236:237], v[36:37], v[152:153], v[236:237] op_sel:[0,0,0] op_sel_hi:[0,1,1] neg_lo:[1,0,0] neg_hi:[1,0,0]
	v_pk_fma_f32 v[238:239], v[36:37], v[154:155], v[238:239] op_sel:[1,0,0] op_sel_hi:[1,1,1] neg_lo:[1,0,0] neg_hi:[1,0,0]
	ds_read_b128 v[34:37], v241 offset:15120
	s_waitcnt lgkmcnt(7)
	v_pk_fma_f32 v[220:221], v[38:39], v[156:157], v[220:221] op_sel:[0,0,0] op_sel_hi:[0,1,1] neg_lo:[1,0,0] neg_hi:[1,0,0]
	v_pk_fma_f32 v[234:235], v[38:39], v[158:159], v[234:235] op_sel:[1,0,0] op_sel_hi:[1,1,1] neg_lo:[1,0,0] neg_hi:[1,0,0]
	v_pk_fma_f32 v[236:237], v[40:41], v[160:161], v[236:237] op_sel:[0,0,0] op_sel_hi:[0,1,1] neg_lo:[1,0,0] neg_hi:[1,0,0]
	v_pk_fma_f32 v[238:239], v[40:41], v[162:163], v[238:239] op_sel:[1,0,0] op_sel_hi:[1,1,1] neg_lo:[1,0,0] neg_hi:[1,0,0]
	ds_read_b128 v[38:41], v241 offset:15136
	s_waitcnt lgkmcnt(7)
	v_pk_fma_f32 v[220:221], v[42:43], v[164:165], v[220:221] op_sel:[0,0,0] op_sel_hi:[0,1,1] neg_lo:[1,0,0] neg_hi:[1,0,0]
	v_pk_fma_f32 v[234:235], v[42:43], v[166:167], v[234:235] op_sel:[1,0,0] op_sel_hi:[1,1,1] neg_lo:[1,0,0] neg_hi:[1,0,0]
	v_pk_fma_f32 v[236:237], v[44:45], v[168:169], v[236:237] op_sel:[0,0,0] op_sel_hi:[0,1,1] neg_lo:[1,0,0] neg_hi:[1,0,0]
	v_pk_fma_f32 v[238:239], v[44:45], v[170:171], v[238:239] op_sel:[1,0,0] op_sel_hi:[1,1,1] neg_lo:[1,0,0] neg_hi:[1,0,0]
	ds_read_b128 v[42:45], v241 offset:15152
	s_waitcnt lgkmcnt(7)
	v_pk_fma_f32 v[220:221], v[46:47], v[172:173], v[220:221] op_sel:[0,0,0] op_sel_hi:[0,1,1] neg_lo:[1,0,0] neg_hi:[1,0,0]
	v_pk_fma_f32 v[234:235], v[46:47], v[174:175], v[234:235] op_sel:[1,0,0] op_sel_hi:[1,1,1] neg_lo:[1,0,0] neg_hi:[1,0,0]
	v_pk_fma_f32 v[236:237], v[48:49], v[176:177], v[236:237] op_sel:[0,0,0] op_sel_hi:[0,1,1] neg_lo:[1,0,0] neg_hi:[1,0,0]
	v_pk_fma_f32 v[238:239], v[48:49], v[178:179], v[238:239] op_sel:[1,0,0] op_sel_hi:[1,1,1] neg_lo:[1,0,0] neg_hi:[1,0,0]
	ds_read_b128 v[46:49], v241 offset:15168
	s_waitcnt lgkmcnt(7)
	v_pk_fma_f32 v[220:221], v[50:51], v[180:181], v[220:221] op_sel:[0,0,0] op_sel_hi:[0,1,1] neg_lo:[1,0,0] neg_hi:[1,0,0]
	v_pk_fma_f32 v[234:235], v[50:51], v[182:183], v[234:235] op_sel:[1,0,0] op_sel_hi:[1,1,1] neg_lo:[1,0,0] neg_hi:[1,0,0]
	v_pk_fma_f32 v[236:237], v[52:53], v[202:203], v[236:237] op_sel:[0,0,0] op_sel_hi:[0,1,1] neg_lo:[1,0,0] neg_hi:[1,0,0]
	v_pk_fma_f32 v[238:239], v[52:53], v[204:205], v[238:239] op_sel:[1,0,0] op_sel_hi:[1,1,1] neg_lo:[1,0,0] neg_hi:[1,0,0]
	ds_read_b128 v[50:53], v241 offset:15184
	s_waitcnt lgkmcnt(7)
	v_pk_fma_f32 v[220:221], v[2:3], v[208:209], v[220:221] op_sel:[0,0,0] op_sel_hi:[0,1,1] neg_lo:[1,0,0] neg_hi:[1,0,0]
	v_pk_fma_f32 v[234:235], v[2:3], v[210:211], v[234:235] op_sel:[1,0,0] op_sel_hi:[1,1,1] neg_lo:[1,0,0] neg_hi:[1,0,0]
	v_pk_fma_f32 v[236:237], v[4:5], v[212:213], v[236:237] op_sel:[0,0,0] op_sel_hi:[0,1,1] neg_lo:[1,0,0] neg_hi:[1,0,0]
	v_pk_fma_f32 v[238:239], v[4:5], v[214:215], v[238:239] op_sel:[1,0,0] op_sel_hi:[1,1,1] neg_lo:[1,0,0] neg_hi:[1,0,0]
	ds_read_b128 v[2:5], v241 offset:15200
	s_waitcnt lgkmcnt(7)
; template <int DIR>
; __device__ __forceinline__ void dn_solve(const P& p, int task, int m0, int h, int t2, const bf16_t* kn_s, const bf16_t* v_s, const float* gc, const float* be, float* L) {
;     ...
; #pragma unroll
;     for (int cp = 1; cp < 64; ++cp) {
;         float a0 = 0.f, a1 = 0.f, a2 = 0.f, a3 = 0.f;
; #pragma unroll
;         for (int s4 = 0; s4 < cp; s4 += 4) { const f32x4 l4 = *(const f32x4*)(L + cp * 64 + s4); a0 += l4[0] * x[s4]; a1 += l4[1] * x[s4 + 1]; a2 += l4[2] * x[s4 + 2]; a3 += l4[3] * x[s4 + 3]; }
;         x[cp] -= (a0 + a1) + (a2 + a3);
;     }
	v_pk_fma_f32 v[220:221], v[26:27], v[216:217], v[220:221] op_sel:[0,0,0] op_sel_hi:[0,1,1] neg_lo:[1,0,0] neg_hi:[1,0,0]
	v_pk_fma_f32 v[234:235], v[26:27], v[218:219], v[234:235] op_sel:[1,0,0] op_sel_hi:[1,1,1] neg_lo:[1,0,0] neg_hi:[1,0,0]
	v_pk_add_f32 v[236:237], v[220:221], v[236:237]
	v_pk_add_f32 v[236:237], v[236:237], v[238:239]
	v_pk_add_f32 v[220:221], v[236:237], v[234:235]
	ds_read_b128 v[26:29], v241 offset:15216
	s_waitcnt lgkmcnt(7)
	v_pk_fma_f32 v[222:223], v[30:31], v[6:7], v[222:223] op_sel:[0,0,0] op_sel_hi:[0,1,1] neg_lo:[1,0,0] neg_hi:[1,0,0]
	v_pk_mul_f32 v[234:235], v[30:31], v[54:55] op_sel:[1,0] op_sel_hi:[1,1] neg_lo:[1,0] neg_hi:[1,0]
	v_pk_mul_f32 v[236:237], v[32:33], v[56:57] op_sel:[0,0] op_sel_hi:[0,1] neg_lo:[1,0] neg_hi:[1,0]
	v_pk_mul_f32 v[238:239], v[32:33], v[58:59] op_sel:[1,0] op_sel_hi:[1,1] neg_lo:[1,0] neg_hi:[1,0]
	ds_read_b128 v[30:33], v241 offset:15232
	s_waitcnt lgkmcnt(7)
	v_pk_fma_f32 v[222:223], v[34:35], v[60:61], v[222:223] op_sel:[0,0,0] op_sel_hi:[0,1,1] neg_lo:[1,0,0] neg_hi:[1,0,0]
	v_pk_fma_f32 v[234:235], v[34:35], v[62:63], v[234:235] op_sel:[1,0,0] op_sel_hi:[1,1,1] neg_lo:[1,0,0] neg_hi:[1,0,0]
	v_pk_fma_f32 v[236:237], v[36:37], v[64:65], v[236:237] op_sel:[0,0,0] op_sel_hi:[0,1,1] neg_lo:[1,0,0] neg_hi:[1,0,0]
	v_pk_fma_f32 v[238:239], v[36:37], v[66:67], v[238:239] op_sel:[1,0,0] op_sel_hi:[1,1,1] neg_lo:[1,0,0] neg_hi:[1,0,0]
	ds_read_b128 v[34:37], v241 offset:15248
	s_waitcnt lgkmcnt(7)
	v_pk_fma_f32 v[222:223], v[38:39], v[68:69], v[222:223] op_sel:[0,0,0] op_sel_hi:[0,1,1] neg_lo:[1,0,0] neg_hi:[1,0,0]
	v_pk_fma_f32 v[234:235], v[38:39], v[70:71], v[234:235] op_sel:[1,0,0] op_sel_hi:[1,1,1] neg_lo:[1,0,0] neg_hi:[1,0,0]
	v_pk_fma_f32 v[236:237], v[40:41], v[72:73], v[236:237] op_sel:[0,0,0] op_sel_hi:[0,1,1] neg_lo:[1,0,0] neg_hi:[1,0,0]
	v_pk_fma_f32 v[238:239], v[40:41], v[74:75], v[238:239] op_sel:[1,0,0] op_sel_hi:[1,1,1] neg_lo:[1,0,0] neg_hi:[1,0,0]
	ds_read_b128 v[38:41], v241 offset:15264
	s_waitcnt lgkmcnt(7)
	v_pk_fma_f32 v[222:223], v[42:43], v[76:77], v[222:223] op_sel:[0,0,0] op_sel_hi:[0,1,1] neg_lo:[1,0,0] neg_hi:[1,0,0]
	v_pk_fma_f32 v[234:235], v[42:43], v[78:79], v[234:235] op_sel:[1,0,0] op_sel_hi:[1,1,1] neg_lo:[1,0,0] neg_hi:[1,0,0]
	v_pk_fma_f32 v[236:237], v[44:45], v[80:81], v[236:237] op_sel:[0,0,0] op_sel_hi:[0,1,1] neg_lo:[1,0,0] neg_hi:[1,0,0]
	v_pk_fma_f32 v[238:239], v[44:45], v[82:83], v[238:239] op_sel:[1,0,0] op_sel_hi:[1,1,1] neg_lo:[1,0,0] neg_hi:[1,0,0]
	ds_read_b128 v[42:45], v241 offset:15280
	s_waitcnt lgkmcnt(7)
	v_pk_fma_f32 v[222:223], v[46:47], v[84:85], v[222:223] op_sel:[0,0,0] op_sel_hi:[0,1,1] neg_lo:[1,0,0] neg_hi:[1,0,0]
	v_pk_fma_f32 v[234:235], v[46:47], v[86:87], v[234:235] op_sel:[1,0,0] op_sel_hi:[1,1,1] neg_lo:[1,0,0] neg_hi:[1,0,0]
	v_pk_fma_f32 v[236:237], v[48:49], v[88:89], v[236:237] op_sel:[0,0,0] op_sel_hi:[0,1,1] neg_lo:[1,0,0] neg_hi:[1,0,0]
	v_pk_fma_f32 v[238:239], v[48:49], v[90:91], v[238:239] op_sel:[1,0,0] op_sel_hi:[1,1,1] neg_lo:[1,0,0] neg_hi:[1,0,0]
	ds_read_b128 v[46:49], v241 offset:15296
	s_waitcnt lgkmcnt(7)
	v_pk_fma_f32 v[222:223], v[50:51], v[92:93], v[222:223] op_sel:[0,0,0] op_sel_hi:[0,1,1] neg_lo:[1,0,0] neg_hi:[1,0,0]
	v_pk_fma_f32 v[234:235], v[50:51], v[94:95], v[234:235] op_sel:[1,0,0] op_sel_hi:[1,1,1] neg_lo:[1,0,0] neg_hi:[1,0,0]
	v_pk_fma_f32 v[236:237], v[52:53], v[96:97], v[236:237] op_sel:[0,0,0] op_sel_hi:[0,1,1] neg_lo:[1,0,0] neg_hi:[1,0,0]
	v_pk_fma_f32 v[238:239], v[52:53], v[98:99], v[238:239] op_sel:[1,0,0] op_sel_hi:[1,1,1] neg_lo:[1,0,0] neg_hi:[1,0,0]
	ds_read_b128 v[50:53], v241 offset:15312
	s_waitcnt lgkmcnt(7)
	v_pk_fma_f32 v[222:223], v[2:3], v[100:101], v[222:223] op_sel:[0,0,0] op_sel_hi:[0,1,1] neg_lo:[1,0,0] neg_hi:[1,0,0]
	v_pk_fma_f32 v[234:235], v[2:3], v[102:103], v[234:235] op_sel:[1,0,0] op_sel_hi:[1,1,1] neg_lo:[1,0,0] neg_hi:[1,0,0]
	v_pk_fma_f32 v[236:237], v[4:5], v[104:105], v[236:237] op_sel:[0,0,0] op_sel_hi:[0,1,1] neg_lo:[1,0,0] neg_hi:[1,0,0]
	v_pk_fma_f32 v[238:239], v[4:5], v[106:107], v[238:239] op_sel:[1,0,0] op_sel_hi:[1,1,1] neg_lo:[1,0,0] neg_hi:[1,0,0]
	ds_read_b128 v[2:5], v241 offset:15328
	s_waitcnt lgkmcnt(7)
	v_pk_fma_f32 v[222:223], v[26:27], v[108:109], v[222:223] op_sel:[0,0,0] op_sel_hi:[0,1,1] neg_lo:[1,0,0] neg_hi:[1,0,0]
	v_pk_fma_f32 v[234:235], v[26:27], v[110:111], v[234:235] op_sel:[1,0,0] op_sel_hi:[1,1,1] neg_lo:[1,0,0] neg_hi:[1,0,0]
	v_pk_fma_f32 v[236:237], v[28:29], v[112:113], v[236:237] op_sel:[0,0,0] op_sel_hi:[0,1,1] neg_lo:[1,0,0] neg_hi:[1,0,0]
	v_pk_fma_f32 v[238:239], v[28:29], v[114:115], v[238:239] op_sel:[1,0,0] op_sel_hi:[1,1,1] neg_lo:[1,0,0] neg_hi:[1,0,0]
	ds_read_b128 v[26:29], v241 offset:15360
	s_waitcnt lgkmcnt(7)
	v_pk_fma_f32 v[222:223], v[30:31], v[116:117], v[222:223] op_sel:[0,0,0] op_sel_hi:[0,1,1] neg_lo:[1,0,0] neg_hi:[1,0,0]
	v_pk_fma_f32 v[234:235], v[30:31], v[118:119], v[234:235] op_sel:[1,0,0] op_sel_hi:[1,1,1] neg_lo:[1,0,0] neg_hi:[1,0,0]
	v_pk_fma_f32 v[236:237], v[32:33], v[152:153], v[236:237] op_sel:[0,0,0] op_sel_hi:[0,1,1] neg_lo:[1,0,0] neg_hi:[1,0,0]
	v_pk_fma_f32 v[238:239], v[32:33], v[154:155], v[238:239] op_sel:[1,0,0] op_sel_hi:[1,1,1] neg_lo:[1,0,0] neg_hi:[1,0,0]
	ds_read_b128 v[30:33], v241 offset:15376
	s_waitcnt lgkmcnt(7)
	v_pk_fma_f32 v[222:223], v[34:35], v[156:157], v[222:223] op_sel:[0,0,0] op_sel_hi:[0,1,1] neg_lo:[1,0,0] neg_hi:[1,0,0]
	v_pk_fma_f32 v[234:235], v[34:35], v[158:159], v[234:235] op_sel:[1,0,0] op_sel_hi:[1,1,1] neg_lo:[1,0,0] neg_hi:[1,0,0]
	v_pk_fma_f32 v[236:237], v[36:37], v[160:161], v[236:237] op_sel:[0,0,0] op_sel_hi:[0,1,1] neg_lo:[1,0,0] neg_hi:[1,0,0]
	v_pk_fma_f32 v[238:239], v[36:37], v[162:163], v[238:239] op_sel:[1,0,0] op_sel_hi:[1,1,1] neg_lo:[1,0,0] neg_hi:[1,0,0]
	ds_read_b128 v[34:37], v241 offset:15392
	s_waitcnt lgkmcnt(7)
; template <int DIR>
; __device__ __forceinline__ void dn_solve(const P& p, int task, int m0, int h, int t2, const bf16_t* kn_s, const bf16_t* v_s, const float* gc, const float* be, float* L) {
;     ...
; #pragma unroll
;     for (int cp = 1; cp < 64; ++cp) {
;         float a0 = 0.f, a1 = 0.f, a2 = 0.f, a3 = 0.f;
; #pragma unroll
;         for (int s4 = 0; s4 < cp; s4 += 4) { const f32x4 l4 = *(const f32x4*)(L + cp * 64 + s4); a0 += l4[0] * x[s4]; a1 += l4[1] * x[s4 + 1]; a2 += l4[2] * x[s4 + 2]; a3 += l4[3] * x[s4 + 3]; }
;         x[cp] -= (a0 + a1) + (a2 + a3);
;     }
	v_pk_fma_f32 v[222:223], v[38:39], v[164:165], v[222:223] op_sel:[0,0,0] op_sel_hi:[0,1,1] neg_lo:[1,0,0] neg_hi:[1,0,0]
	v_pk_fma_f32 v[234:235], v[38:39], v[166:167], v[234:235] op_sel:[1,0,0] op_sel_hi:[1,1,1] neg_lo:[1,0,0] neg_hi:[1,0,0]
	v_pk_fma_f32 v[236:237], v[40:41], v[168:169], v[236:237] op_sel:[0,0,0] op_sel_hi:[0,1,1] neg_lo:[1,0,0] neg_hi:[1,0,0]
	v_pk_fma_f32 v[238:239], v[40:41], v[170:171], v[238:239] op_sel:[1,0,0] op_sel_hi:[1,1,1] neg_lo:[1,0,0] neg_hi:[1,0,0]
	ds_read_b128 v[38:41], v241 offset:15408
	s_waitcnt lgkmcnt(7)
	v_pk_fma_f32 v[222:223], v[42:43], v[172:173], v[222:223] op_sel:[0,0,0] op_sel_hi:[0,1,1] neg_lo:[1,0,0] neg_hi:[1,0,0]
	v_pk_fma_f32 v[234:235], v[42:43], v[174:175], v[234:235] op_sel:[1,0,0] op_sel_hi:[1,1,1] neg_lo:[1,0,0] neg_hi:[1,0,0]
	v_pk_fma_f32 v[236:237], v[44:45], v[176:177], v[236:237] op_sel:[0,0,0] op_sel_hi:[0,1,1] neg_lo:[1,0,0] neg_hi:[1,0,0]
	v_pk_fma_f32 v[238:239], v[44:45], v[178:179], v[238:239] op_sel:[1,0,0] op_sel_hi:[1,1,1] neg_lo:[1,0,0] neg_hi:[1,0,0]
	ds_read_b128 v[42:45], v241 offset:15424
	s_waitcnt lgkmcnt(7)
	v_pk_fma_f32 v[222:223], v[46:47], v[180:181], v[222:223] op_sel:[0,0,0] op_sel_hi:[0,1,1] neg_lo:[1,0,0] neg_hi:[1,0,0]
	v_pk_fma_f32 v[234:235], v[46:47], v[182:183], v[234:235] op_sel:[1,0,0] op_sel_hi:[1,1,1] neg_lo:[1,0,0] neg_hi:[1,0,0]
	v_pk_fma_f32 v[236:237], v[48:49], v[202:203], v[236:237] op_sel:[0,0,0] op_sel_hi:[0,1,1] neg_lo:[1,0,0] neg_hi:[1,0,0]
	v_pk_fma_f32 v[238:239], v[48:49], v[204:205], v[238:239] op_sel:[1,0,0] op_sel_hi:[1,1,1] neg_lo:[1,0,0] neg_hi:[1,0,0]
	ds_read_b128 v[46:49], v241 offset:15440
	s_waitcnt lgkmcnt(7)
	v_pk_fma_f32 v[222:223], v[50:51], v[208:209], v[222:223] op_sel:[0,0,0] op_sel_hi:[0,1,1] neg_lo:[1,0,0] neg_hi:[1,0,0]
	v_pk_fma_f32 v[234:235], v[50:51], v[210:211], v[234:235] op_sel:[1,0,0] op_sel_hi:[1,1,1] neg_lo:[1,0,0] neg_hi:[1,0,0]
	v_pk_fma_f32 v[236:237], v[52:53], v[212:213], v[236:237] op_sel:[0,0,0] op_sel_hi:[0,1,1] neg_lo:[1,0,0] neg_hi:[1,0,0]
	v_pk_fma_f32 v[238:239], v[52:53], v[214:215], v[238:239] op_sel:[1,0,0] op_sel_hi:[1,1,1] neg_lo:[1,0,0] neg_hi:[1,0,0]
	ds_read_b128 v[50:53], v241 offset:15456
	s_waitcnt lgkmcnt(7)
	v_pk_fma_f32 v[222:223], v[2:3], v[216:217], v[222:223] op_sel:[0,0,0] op_sel_hi:[0,1,1] neg_lo:[1,0,0] neg_hi:[1,0,0]
	v_pk_fma_f32 v[234:235], v[2:3], v[218:219], v[234:235] op_sel:[1,0,0] op_sel_hi:[1,1,1] neg_lo:[1,0,0] neg_hi:[1,0,0]
	v_pk_fma_f32 v[236:237], v[4:5], v[220:221], v[236:237] op_sel:[0,0,0] op_sel_hi:[0,1,1] neg_lo:[1,0,0] neg_hi:[1,0,0]
	v_pk_add_f32 v[234:235], v[222:223], v[234:235]
	v_pk_add_f32 v[234:235], v[234:235], v[238:239]
	v_pk_add_f32 v[222:223], v[234:235], v[236:237]
	ds_read_b128 v[2:5], v241 offset:15472
	s_waitcnt lgkmcnt(7)
	v_pk_fma_f32 v[224:225], v[26:27], v[6:7], v[224:225] op_sel:[0,0,0] op_sel_hi:[0,1,1] neg_lo:[1,0,0] neg_hi:[1,0,0]
	v_pk_mul_f32 v[234:235], v[26:27], v[54:55] op_sel:[1,0] op_sel_hi:[1,1] neg_lo:[1,0] neg_hi:[1,0]
	v_pk_mul_f32 v[236:237], v[28:29], v[56:57] op_sel:[0,0] op_sel_hi:[0,1] neg_lo:[1,0] neg_hi:[1,0]
	v_pk_mul_f32 v[238:239], v[28:29], v[58:59] op_sel:[1,0] op_sel_hi:[1,1] neg_lo:[1,0] neg_hi:[1,0]
	ds_read_b128 v[26:29], v241 offset:15488
	s_waitcnt lgkmcnt(7)
	v_pk_fma_f32 v[224:225], v[30:31], v[60:61], v[224:225] op_sel:[0,0,0] op_sel_hi:[0,1,1] neg_lo:[1,0,0] neg_hi:[1,0,0]
	v_pk_fma_f32 v[234:235], v[30:31], v[62:63], v[234:235] op_sel:[1,0,0] op_sel_hi:[1,1,1] neg_lo:[1,0,0] neg_hi:[1,0,0]
	v_pk_fma_f32 v[236:237], v[32:33], v[64:65], v[236:237] op_sel:[0,0,0] op_sel_hi:[0,1,1] neg_lo:[1,0,0] neg_hi:[1,0,0]
	v_pk_fma_f32 v[238:239], v[32:33], v[66:67], v[238:239] op_sel:[1,0,0] op_sel_hi:[1,1,1] neg_lo:[1,0,0] neg_hi:[1,0,0]
	ds_read_b128 v[30:33], v241 offset:15504
	s_waitcnt lgkmcnt(7)
	v_pk_fma_f32 v[224:225], v[34:35], v[68:69], v[224:225] op_sel:[0,0,0] op_sel_hi:[0,1,1] neg_lo:[1,0,0] neg_hi:[1,0,0]
	v_pk_fma_f32 v[234:235], v[34:35], v[70:71], v[234:235] op_sel:[1,0,0] op_sel_hi:[1,1,1] neg_lo:[1,0,0] neg_hi:[1,0,0]
	v_pk_fma_f32 v[236:237], v[36:37], v[72:73], v[236:237] op_sel:[0,0,0] op_sel_hi:[0,1,1] neg_lo:[1,0,0] neg_hi:[1,0,0]
	v_pk_fma_f32 v[238:239], v[36:37], v[74:75], v[238:239] op_sel:[1,0,0] op_sel_hi:[1,1,1] neg_lo:[1,0,0] neg_hi:[1,0,0]
	ds_read_b128 v[34:37], v241 offset:15520
	s_waitcnt lgkmcnt(7)
	v_pk_fma_f32 v[224:225], v[38:39], v[76:77], v[224:225] op_sel:[0,0,0] op_sel_hi:[0,1,1] neg_lo:[1,0,0] neg_hi:[1,0,0]
	v_pk_fma_f32 v[234:235], v[38:39], v[78:79], v[234:235] op_sel:[1,0,0] op_sel_hi:[1,1,1] neg_lo:[1,0,0] neg_hi:[1,0,0]
	v_pk_fma_f32 v[236:237], v[40:41], v[80:81], v[236:237] op_sel:[0,0,0] op_sel_hi:[0,1,1] neg_lo:[1,0,0] neg_hi:[1,0,0]
	v_pk_fma_f32 v[238:239], v[40:41], v[82:83], v[238:239] op_sel:[1,0,0] op_sel_hi:[1,1,1] neg_lo:[1,0,0] neg_hi:[1,0,0]
	ds_read_b128 v[38:41], v241 offset:15536
	s_waitcnt lgkmcnt(7)
	v_pk_fma_f32 v[224:225], v[42:43], v[84:85], v[224:225] op_sel:[0,0,0] op_sel_hi:[0,1,1] neg_lo:[1,0,0] neg_hi:[1,0,0]
	v_pk_fma_f32 v[234:235], v[42:43], v[86:87], v[234:235] op_sel:[1,0,0] op_sel_hi:[1,1,1] neg_lo:[1,0,0] neg_hi:[1,0,0]
	v_pk_fma_f32 v[236:237], v[44:45], v[88:89], v[236:237] op_sel:[0,0,0] op_sel_hi:[0,1,1] neg_lo:[1,0,0] neg_hi:[1,0,0]
	v_pk_fma_f32 v[238:239], v[44:45], v[90:91], v[238:239] op_sel:[1,0,0] op_sel_hi:[1,1,1] neg_lo:[1,0,0] neg_hi:[1,0,0]
	ds_read_b128 v[42:45], v241 offset:15552
	s_waitcnt lgkmcnt(7)
; template <int DIR>
; __device__ __forceinline__ void dn_solve(const P& p, int task, int m0, int h, int t2, const bf16_t* kn_s, const bf16_t* v_s, const float* gc, const float* be, float* L) {
;     ...
; #pragma unroll
;     for (int cp = 1; cp < 64; ++cp) {
;         float a0 = 0.f, a1 = 0.f, a2 = 0.f, a3 = 0.f;
; #pragma unroll
;         for (int s4 = 0; s4 < cp; s4 += 4) { const f32x4 l4 = *(const f32x4*)(L + cp * 64 + s4); a0 += l4[0] * x[s4]; a1 += l4[1] * x[s4 + 1]; a2 += l4[2] * x[s4 + 2]; a3 += l4[3] * x[s4 + 3]; }
;         x[cp] -= (a0 + a1) + (a2 + a3);
;     }
	v_pk_fma_f32 v[224:225], v[46:47], v[92:93], v[224:225] op_sel:[0,0,0] op_sel_hi:[0,1,1] neg_lo:[1,0,0] neg_hi:[1,0,0]
	v_pk_fma_f32 v[234:235], v[46:47], v[94:95], v[234:235] op_sel:[1,0,0] op_sel_hi:[1,1,1] neg_lo:[1,0,0] neg_hi:[1,0,0]
	v_pk_fma_f32 v[236:237], v[48:49], v[96:97], v[236:237] op_sel:[0,0,0] op_sel_hi:[0,1,1] neg_lo:[1,0,0] neg_hi:[1,0,0]
	v_pk_fma_f32 v[238:239], v[48:49], v[98:99], v[238:239] op_sel:[1,0,0] op_sel_hi:[1,1,1] neg_lo:[1,0,0] neg_hi:[1,0,0]
	ds_read_b128 v[46:49], v241 offset:15568
	s_waitcnt lgkmcnt(7)
	v_pk_fma_f32 v[224:225], v[50:51], v[100:101], v[224:225] op_sel:[0,0,0] op_sel_hi:[0,1,1] neg_lo:[1,0,0] neg_hi:[1,0,0]
	v_pk_fma_f32 v[234:235], v[50:51], v[102:103], v[234:235] op_sel:[1,0,0] op_sel_hi:[1,1,1] neg_lo:[1,0,0] neg_hi:[1,0,0]
	v_pk_fma_f32 v[236:237], v[52:53], v[104:105], v[236:237] op_sel:[0,0,0] op_sel_hi:[0,1,1] neg_lo:[1,0,0] neg_hi:[1,0,0]
	v_pk_fma_f32 v[238:239], v[52:53], v[106:107], v[238:239] op_sel:[1,0,0] op_sel_hi:[1,1,1] neg_lo:[1,0,0] neg_hi:[1,0,0]
	ds_read_b128 v[50:53], v241 offset:15584
	s_waitcnt lgkmcnt(7)
	v_pk_fma_f32 v[224:225], v[2:3], v[108:109], v[224:225] op_sel:[0,0,0] op_sel_hi:[0,1,1] neg_lo:[1,0,0] neg_hi:[1,0,0]
	v_pk_fma_f32 v[234:235], v[2:3], v[110:111], v[234:235] op_sel:[1,0,0] op_sel_hi:[1,1,1] neg_lo:[1,0,0] neg_hi:[1,0,0]
	v_pk_fma_f32 v[236:237], v[4:5], v[112:113], v[236:237] op_sel:[0,0,0] op_sel_hi:[0,1,1] neg_lo:[1,0,0] neg_hi:[1,0,0]
	v_pk_fma_f32 v[238:239], v[4:5], v[114:115], v[238:239] op_sel:[1,0,0] op_sel_hi:[1,1,1] neg_lo:[1,0,0] neg_hi:[1,0,0]
	ds_read_b128 v[2:5], v241 offset:15616
	s_waitcnt lgkmcnt(7)
	v_pk_fma_f32 v[224:225], v[26:27], v[116:117], v[224:225] op_sel:[0,0,0] op_sel_hi:[0,1,1] neg_lo:[1,0,0] neg_hi:[1,0,0]
	v_pk_fma_f32 v[234:235], v[26:27], v[118:119], v[234:235] op_sel:[1,0,0] op_sel_hi:[1,1,1] neg_lo:[1,0,0] neg_hi:[1,0,0]
	v_pk_fma_f32 v[236:237], v[28:29], v[152:153], v[236:237] op_sel:[0,0,0] op_sel_hi:[0,1,1] neg_lo:[1,0,0] neg_hi:[1,0,0]
	v_pk_fma_f32 v[238:239], v[28:29], v[154:155], v[238:239] op_sel:[1,0,0] op_sel_hi:[1,1,1] neg_lo:[1,0,0] neg_hi:[1,0,0]
	ds_read_b128 v[26:29], v241 offset:15632
	s_waitcnt lgkmcnt(7)
	v_pk_fma_f32 v[224:225], v[30:31], v[156:157], v[224:225] op_sel:[0,0,0] op_sel_hi:[0,1,1] neg_lo:[1,0,0] neg_hi:[1,0,0]
	v_pk_fma_f32 v[234:235], v[30:31], v[158:159], v[234:235] op_sel:[1,0,0] op_sel_hi:[1,1,1] neg_lo:[1,0,0] neg_hi:[1,0,0]
	v_pk_fma_f32 v[236:237], v[32:33], v[160:161], v[236:237] op_sel:[0,0,0] op_sel_hi:[0,1,1] neg_lo:[1,0,0] neg_hi:[1,0,0]
	v_pk_fma_f32 v[238:239], v[32:33], v[162:163], v[238:239] op_sel:[1,0,0] op_sel_hi:[1,1,1] neg_lo:[1,0,0] neg_hi:[1,0,0]
	ds_read_b128 v[30:33], v241 offset:15648
	s_waitcnt lgkmcnt(7)
	v_pk_fma_f32 v[224:225], v[34:35], v[164:165], v[224:225] op_sel:[0,0,0] op_sel_hi:[0,1,1] neg_lo:[1,0,0] neg_hi:[1,0,0]
	v_pk_fma_f32 v[234:235], v[34:35], v[166:167], v[234:235] op_sel:[1,0,0] op_sel_hi:[1,1,1] neg_lo:[1,0,0] neg_hi:[1,0,0]
	v_pk_fma_f32 v[236:237], v[36:37], v[168:169], v[236:237] op_sel:[0,0,0] op_sel_hi:[0,1,1] neg_lo:[1,0,0] neg_hi:[1,0,0]
	v_pk_fma_f32 v[238:239], v[36:37], v[170:171], v[238:239] op_sel:[1,0,0] op_sel_hi:[1,1,1] neg_lo:[1,0,0] neg_hi:[1,0,0]
	ds_read_b128 v[34:37], v241 offset:15664
	s_waitcnt lgkmcnt(7)
	v_pk_fma_f32 v[224:225], v[38:39], v[172:173], v[224:225] op_sel:[0,0,0] op_sel_hi:[0,1,1] neg_lo:[1,0,0] neg_hi:[1,0,0]
	v_pk_fma_f32 v[234:235], v[38:39], v[174:175], v[234:235] op_sel:[1,0,0] op_sel_hi:[1,1,1] neg_lo:[1,0,0] neg_hi:[1,0,0]
	v_pk_fma_f32 v[236:237], v[40:41], v[176:177], v[236:237] op_sel:[0,0,0] op_sel_hi:[0,1,1] neg_lo:[1,0,0] neg_hi:[1,0,0]
	v_pk_fma_f32 v[238:239], v[40:41], v[178:179], v[238:239] op_sel:[1,0,0] op_sel_hi:[1,1,1] neg_lo:[1,0,0] neg_hi:[1,0,0]
	ds_read_b128 v[38:41], v241 offset:15680
	s_waitcnt lgkmcnt(7)
	v_pk_fma_f32 v[224:225], v[42:43], v[180:181], v[224:225] op_sel:[0,0,0] op_sel_hi:[0,1,1] neg_lo:[1,0,0] neg_hi:[1,0,0]
	v_pk_fma_f32 v[234:235], v[42:43], v[182:183], v[234:235] op_sel:[1,0,0] op_sel_hi:[1,1,1] neg_lo:[1,0,0] neg_hi:[1,0,0]
	v_pk_fma_f32 v[236:237], v[44:45], v[202:203], v[236:237] op_sel:[0,0,0] op_sel_hi:[0,1,1] neg_lo:[1,0,0] neg_hi:[1,0,0]
	v_pk_fma_f32 v[238:239], v[44:45], v[204:205], v[238:239] op_sel:[1,0,0] op_sel_hi:[1,1,1] neg_lo:[1,0,0] neg_hi:[1,0,0]
	ds_read_b128 v[42:45], v241 offset:15696
	s_waitcnt lgkmcnt(7)
	v_pk_fma_f32 v[224:225], v[46:47], v[208:209], v[224:225] op_sel:[0,0,0] op_sel_hi:[0,1,1] neg_lo:[1,0,0] neg_hi:[1,0,0]
	v_pk_fma_f32 v[234:235], v[46:47], v[210:211], v[234:235] op_sel:[1,0,0] op_sel_hi:[1,1,1] neg_lo:[1,0,0] neg_hi:[1,0,0]
	v_pk_fma_f32 v[236:237], v[48:49], v[212:213], v[236:237] op_sel:[0,0,0] op_sel_hi:[0,1,1] neg_lo:[1,0,0] neg_hi:[1,0,0]
	v_pk_fma_f32 v[238:239], v[48:49], v[214:215], v[238:239] op_sel:[1,0,0] op_sel_hi:[1,1,1] neg_lo:[1,0,0] neg_hi:[1,0,0]
	ds_read_b128 v[46:49], v241 offset:15712
	s_waitcnt lgkmcnt(7)
	v_pk_fma_f32 v[224:225], v[50:51], v[216:217], v[224:225] op_sel:[0,0,0] op_sel_hi:[0,1,1] neg_lo:[1,0,0] neg_hi:[1,0,0]
	v_pk_fma_f32 v[234:235], v[50:51], v[218:219], v[234:235] op_sel:[1,0,0] op_sel_hi:[1,1,1] neg_lo:[1,0,0] neg_hi:[1,0,0]
	v_pk_fma_f32 v[236:237], v[52:53], v[220:221], v[236:237] op_sel:[0,0,0] op_sel_hi:[0,1,1] neg_lo:[1,0,0] neg_hi:[1,0,0]
	v_pk_fma_f32 v[238:239], v[52:53], v[222:223], v[238:239] op_sel:[1,0,0] op_sel_hi:[1,1,1] neg_lo:[1,0,0] neg_hi:[1,0,0]
	v_pk_add_f32 v[234:235], v[224:225], v[234:235]
	v_pk_add_f32 v[234:235], v[234:235], v[236:237]
	v_pk_add_f32 v[224:225], v[234:235], v[238:239]
	ds_read_b128 v[50:53], v241 offset:15728
	s_waitcnt lgkmcnt(7)
; template <int DIR>
; __device__ __forceinline__ void dn_solve(const P& p, int task, int m0, int h, int t2, const bf16_t* kn_s, const bf16_t* v_s, const float* gc, const float* be, float* L) {
;     ...
; #pragma unroll
;     for (int cp = 1; cp < 64; ++cp) {
;         float a0 = 0.f, a1 = 0.f, a2 = 0.f, a3 = 0.f;
; #pragma unroll
;         for (int s4 = 0; s4 < cp; s4 += 4) { const f32x4 l4 = *(const f32x4*)(L + cp * 64 + s4); a0 += l4[0] * x[s4]; a1 += l4[1] * x[s4 + 1]; a2 += l4[2] * x[s4 + 2]; a3 += l4[3] * x[s4 + 3]; }
;         x[cp] -= (a0 + a1) + (a2 + a3);
;     }
	v_pk_fma_f32 v[226:227], v[2:3], v[6:7], v[226:227] op_sel:[0,0,0] op_sel_hi:[0,1,1] neg_lo:[1,0,0] neg_hi:[1,0,0]
	v_pk_mul_f32 v[234:235], v[2:3], v[54:55] op_sel:[1,0] op_sel_hi:[1,1] neg_lo:[1,0] neg_hi:[1,0]
	v_pk_mul_f32 v[236:237], v[4:5], v[56:57] op_sel:[0,0] op_sel_hi:[0,1] neg_lo:[1,0] neg_hi:[1,0]
	v_pk_mul_f32 v[238:239], v[4:5], v[58:59] op_sel:[1,0] op_sel_hi:[1,1] neg_lo:[1,0] neg_hi:[1,0]
	ds_read_b128 v[2:5], v241 offset:15744
	s_waitcnt lgkmcnt(7)
	v_pk_fma_f32 v[226:227], v[26:27], v[60:61], v[226:227] op_sel:[0,0,0] op_sel_hi:[0,1,1] neg_lo:[1,0,0] neg_hi:[1,0,0]
	v_pk_fma_f32 v[234:235], v[26:27], v[62:63], v[234:235] op_sel:[1,0,0] op_sel_hi:[1,1,1] neg_lo:[1,0,0] neg_hi:[1,0,0]
	v_pk_fma_f32 v[236:237], v[28:29], v[64:65], v[236:237] op_sel:[0,0,0] op_sel_hi:[0,1,1] neg_lo:[1,0,0] neg_hi:[1,0,0]
	v_pk_fma_f32 v[238:239], v[28:29], v[66:67], v[238:239] op_sel:[1,0,0] op_sel_hi:[1,1,1] neg_lo:[1,0,0] neg_hi:[1,0,0]
	ds_read_b128 v[26:29], v241 offset:15760
	s_waitcnt lgkmcnt(7)
	v_pk_fma_f32 v[226:227], v[30:31], v[68:69], v[226:227] op_sel:[0,0,0] op_sel_hi:[0,1,1] neg_lo:[1,0,0] neg_hi:[1,0,0]
	v_pk_fma_f32 v[234:235], v[30:31], v[70:71], v[234:235] op_sel:[1,0,0] op_sel_hi:[1,1,1] neg_lo:[1,0,0] neg_hi:[1,0,0]
	v_pk_fma_f32 v[236:237], v[32:33], v[72:73], v[236:237] op_sel:[0,0,0] op_sel_hi:[0,1,1] neg_lo:[1,0,0] neg_hi:[1,0,0]
	v_pk_fma_f32 v[238:239], v[32:33], v[74:75], v[238:239] op_sel:[1,0,0] op_sel_hi:[1,1,1] neg_lo:[1,0,0] neg_hi:[1,0,0]
	ds_read_b128 v[30:33], v241 offset:15776
	s_waitcnt lgkmcnt(7)
	v_pk_fma_f32 v[226:227], v[34:35], v[76:77], v[226:227] op_sel:[0,0,0] op_sel_hi:[0,1,1] neg_lo:[1,0,0] neg_hi:[1,0,0]
	v_pk_fma_f32 v[234:235], v[34:35], v[78:79], v[234:235] op_sel:[1,0,0] op_sel_hi:[1,1,1] neg_lo:[1,0,0] neg_hi:[1,0,0]
	v_pk_fma_f32 v[236:237], v[36:37], v[80:81], v[236:237] op_sel:[0,0,0] op_sel_hi:[0,1,1] neg_lo:[1,0,0] neg_hi:[1,0,0]
	v_pk_fma_f32 v[238:239], v[36:37], v[82:83], v[238:239] op_sel:[1,0,0] op_sel_hi:[1,1,1] neg_lo:[1,0,0] neg_hi:[1,0,0]
	ds_read_b128 v[34:37], v241 offset:15792
	s_waitcnt lgkmcnt(7)
	v_pk_fma_f32 v[226:227], v[38:39], v[84:85], v[226:227] op_sel:[0,0,0] op_sel_hi:[0,1,1] neg_lo:[1,0,0] neg_hi:[1,0,0]
	v_pk_fma_f32 v[234:235], v[38:39], v[86:87], v[234:235] op_sel:[1,0,0] op_sel_hi:[1,1,1] neg_lo:[1,0,0] neg_hi:[1,0,0]
	v_pk_fma_f32 v[236:237], v[40:41], v[88:89], v[236:237] op_sel:[0,0,0] op_sel_hi:[0,1,1] neg_lo:[1,0,0] neg_hi:[1,0,0]
	v_pk_fma_f32 v[238:239], v[40:41], v[90:91], v[238:239] op_sel:[1,0,0] op_sel_hi:[1,1,1] neg_lo:[1,0,0] neg_hi:[1,0,0]
	ds_read_b128 v[38:41], v241 offset:15808
	s_waitcnt lgkmcnt(7)
	v_pk_fma_f32 v[226:227], v[42:43], v[92:93], v[226:227] op_sel:[0,0,0] op_sel_hi:[0,1,1] neg_lo:[1,0,0] neg_hi:[1,0,0]
	v_pk_fma_f32 v[234:235], v[42:43], v[94:95], v[234:235] op_sel:[1,0,0] op_sel_hi:[1,1,1] neg_lo:[1,0,0] neg_hi:[1,0,0]
	v_pk_fma_f32 v[236:237], v[44:45], v[96:97], v[236:237] op_sel:[0,0,0] op_sel_hi:[0,1,1] neg_lo:[1,0,0] neg_hi:[1,0,0]
	v_pk_fma_f32 v[238:239], v[44:45], v[98:99], v[238:239] op_sel:[1,0,0] op_sel_hi:[1,1,1] neg_lo:[1,0,0] neg_hi:[1,0,0]
	ds_read_b128 v[42:45], v241 offset:15824
	s_waitcnt lgkmcnt(7)
	v_pk_fma_f32 v[226:227], v[46:47], v[100:101], v[226:227] op_sel:[0,0,0] op_sel_hi:[0,1,1] neg_lo:[1,0,0] neg_hi:[1,0,0]
	v_pk_fma_f32 v[234:235], v[46:47], v[102:103], v[234:235] op_sel:[1,0,0] op_sel_hi:[1,1,1] neg_lo:[1,0,0] neg_hi:[1,0,0]
	v_pk_fma_f32 v[236:237], v[48:49], v[104:105], v[236:237] op_sel:[0,0,0] op_sel_hi:[0,1,1] neg_lo:[1,0,0] neg_hi:[1,0,0]
	v_pk_fma_f32 v[238:239], v[48:49], v[106:107], v[238:239] op_sel:[1,0,0] op_sel_hi:[1,1,1] neg_lo:[1,0,0] neg_hi:[1,0,0]
	ds_read_b128 v[46:49], v241 offset:15840
	s_waitcnt lgkmcnt(7)
	v_pk_fma_f32 v[226:227], v[50:51], v[108:109], v[226:227] op_sel:[0,0,0] op_sel_hi:[0,1,1] neg_lo:[1,0,0] neg_hi:[1,0,0]
	v_pk_fma_f32 v[234:235], v[50:51], v[110:111], v[234:235] op_sel:[1,0,0] op_sel_hi:[1,1,1] neg_lo:[1,0,0] neg_hi:[1,0,0]
	v_pk_fma_f32 v[236:237], v[52:53], v[112:113], v[236:237] op_sel:[0,0,0] op_sel_hi:[0,1,1] neg_lo:[1,0,0] neg_hi:[1,0,0]
	v_pk_fma_f32 v[238:239], v[52:53], v[114:115], v[238:239] op_sel:[1,0,0] op_sel_hi:[1,1,1] neg_lo:[1,0,0] neg_hi:[1,0,0]
	ds_read_b128 v[50:53], v241 offset:15856
	s_waitcnt lgkmcnt(7)
	v_pk_fma_f32 v[226:227], v[2:3], v[116:117], v[226:227] op_sel:[0,0,0] op_sel_hi:[0,1,1] neg_lo:[1,0,0] neg_hi:[1,0,0]
	v_pk_fma_f32 v[234:235], v[2:3], v[118:119], v[234:235] op_sel:[1,0,0] op_sel_hi:[1,1,1] neg_lo:[1,0,0] neg_hi:[1,0,0]
	v_pk_fma_f32 v[236:237], v[4:5], v[152:153], v[236:237] op_sel:[0,0,0] op_sel_hi:[0,1,1] neg_lo:[1,0,0] neg_hi:[1,0,0]
	v_pk_fma_f32 v[238:239], v[4:5], v[154:155], v[238:239] op_sel:[1,0,0] op_sel_hi:[1,1,1] neg_lo:[1,0,0] neg_hi:[1,0,0]
	ds_read_b128 v[2:5], v241 offset:15872
	s_waitcnt lgkmcnt(7)
	v_pk_fma_f32 v[226:227], v[26:27], v[156:157], v[226:227] op_sel:[0,0,0] op_sel_hi:[0,1,1] neg_lo:[1,0,0] neg_hi:[1,0,0]
	v_pk_fma_f32 v[234:235], v[26:27], v[158:159], v[234:235] op_sel:[1,0,0] op_sel_hi:[1,1,1] neg_lo:[1,0,0] neg_hi:[1,0,0]
	v_pk_fma_f32 v[236:237], v[28:29], v[160:161], v[236:237] op_sel:[0,0,0] op_sel_hi:[0,1,1] neg_lo:[1,0,0] neg_hi:[1,0,0]
	v_pk_fma_f32 v[238:239], v[28:29], v[162:163], v[238:239] op_sel:[1,0,0] op_sel_hi:[1,1,1] neg_lo:[1,0,0] neg_hi:[1,0,0]
	ds_read_b128 v[26:29], v241 offset:15888
	s_waitcnt lgkmcnt(7)
; template <int DIR>
; __device__ __forceinline__ void dn_solve(const P& p, int task, int m0, int h, int t2, const bf16_t* kn_s, const bf16_t* v_s, const float* gc, const float* be, float* L) {
;     ...
; #pragma unroll
;     for (int cp = 1; cp < 64; ++cp) {
;         float a0 = 0.f, a1 = 0.f, a2 = 0.f, a3 = 0.f;
; #pragma unroll
;         for (int s4 = 0; s4 < cp; s4 += 4) { const f32x4 l4 = *(const f32x4*)(L + cp * 64 + s4); a0 += l4[0] * x[s4]; a1 += l4[1] * x[s4 + 1]; a2 += l4[2] * x[s4 + 2]; a3 += l4[3] * x[s4 + 3]; }
;         x[cp] -= (a0 + a1) + (a2 + a3);
;     }
	v_pk_fma_f32 v[226:227], v[30:31], v[164:165], v[226:227] op_sel:[0,0,0] op_sel_hi:[0,1,1] neg_lo:[1,0,0] neg_hi:[1,0,0]
	v_pk_fma_f32 v[234:235], v[30:31], v[166:167], v[234:235] op_sel:[1,0,0] op_sel_hi:[1,1,1] neg_lo:[1,0,0] neg_hi:[1,0,0]
	v_pk_fma_f32 v[236:237], v[32:33], v[168:169], v[236:237] op_sel:[0,0,0] op_sel_hi:[0,1,1] neg_lo:[1,0,0] neg_hi:[1,0,0]
	v_pk_fma_f32 v[238:239], v[32:33], v[170:171], v[238:239] op_sel:[1,0,0] op_sel_hi:[1,1,1] neg_lo:[1,0,0] neg_hi:[1,0,0]
	ds_read_b128 v[30:33], v241 offset:15904
	s_waitcnt lgkmcnt(7)
	v_pk_fma_f32 v[226:227], v[34:35], v[172:173], v[226:227] op_sel:[0,0,0] op_sel_hi:[0,1,1] neg_lo:[1,0,0] neg_hi:[1,0,0]
	v_pk_fma_f32 v[234:235], v[34:35], v[174:175], v[234:235] op_sel:[1,0,0] op_sel_hi:[1,1,1] neg_lo:[1,0,0] neg_hi:[1,0,0]
	v_pk_fma_f32 v[236:237], v[36:37], v[176:177], v[236:237] op_sel:[0,0,0] op_sel_hi:[0,1,1] neg_lo:[1,0,0] neg_hi:[1,0,0]
	v_pk_fma_f32 v[238:239], v[36:37], v[178:179], v[238:239] op_sel:[1,0,0] op_sel_hi:[1,1,1] neg_lo:[1,0,0] neg_hi:[1,0,0]
	ds_read_b128 v[34:37], v241 offset:15920
	s_waitcnt lgkmcnt(7)
	v_pk_fma_f32 v[226:227], v[38:39], v[180:181], v[226:227] op_sel:[0,0,0] op_sel_hi:[0,1,1] neg_lo:[1,0,0] neg_hi:[1,0,0]
	v_pk_fma_f32 v[234:235], v[38:39], v[182:183], v[234:235] op_sel:[1,0,0] op_sel_hi:[1,1,1] neg_lo:[1,0,0] neg_hi:[1,0,0]
	v_pk_fma_f32 v[236:237], v[40:41], v[202:203], v[236:237] op_sel:[0,0,0] op_sel_hi:[0,1,1] neg_lo:[1,0,0] neg_hi:[1,0,0]
	v_pk_fma_f32 v[238:239], v[40:41], v[204:205], v[238:239] op_sel:[1,0,0] op_sel_hi:[1,1,1] neg_lo:[1,0,0] neg_hi:[1,0,0]
	ds_read_b128 v[38:41], v241 offset:15936
	s_waitcnt lgkmcnt(7)
	v_pk_fma_f32 v[226:227], v[42:43], v[208:209], v[226:227] op_sel:[0,0,0] op_sel_hi:[0,1,1] neg_lo:[1,0,0] neg_hi:[1,0,0]
	v_pk_fma_f32 v[234:235], v[42:43], v[210:211], v[234:235] op_sel:[1,0,0] op_sel_hi:[1,1,1] neg_lo:[1,0,0] neg_hi:[1,0,0]
	v_pk_fma_f32 v[236:237], v[44:45], v[212:213], v[236:237] op_sel:[0,0,0] op_sel_hi:[0,1,1] neg_lo:[1,0,0] neg_hi:[1,0,0]
	v_pk_fma_f32 v[238:239], v[44:45], v[214:215], v[238:239] op_sel:[1,0,0] op_sel_hi:[1,1,1] neg_lo:[1,0,0] neg_hi:[1,0,0]
	ds_read_b128 v[42:45], v241 offset:15952
	s_waitcnt lgkmcnt(7)
	v_pk_fma_f32 v[226:227], v[46:47], v[216:217], v[226:227] op_sel:[0,0,0] op_sel_hi:[0,1,1] neg_lo:[1,0,0] neg_hi:[1,0,0]
	v_pk_fma_f32 v[234:235], v[46:47], v[218:219], v[234:235] op_sel:[1,0,0] op_sel_hi:[1,1,1] neg_lo:[1,0,0] neg_hi:[1,0,0]
	v_pk_fma_f32 v[236:237], v[48:49], v[220:221], v[236:237] op_sel:[0,0,0] op_sel_hi:[0,1,1] neg_lo:[1,0,0] neg_hi:[1,0,0]
	v_pk_fma_f32 v[238:239], v[48:49], v[222:223], v[238:239] op_sel:[1,0,0] op_sel_hi:[1,1,1] neg_lo:[1,0,0] neg_hi:[1,0,0]
	ds_read_b128 v[46:49], v241 offset:15968
	s_waitcnt lgkmcnt(7)
	v_pk_fma_f32 v[226:227], v[50:51], v[224:225], v[226:227] op_sel:[0,0,0] op_sel_hi:[0,1,1] neg_lo:[1,0,0] neg_hi:[1,0,0]
	v_pk_add_f32 v[234:235], v[234:235], v[236:237]
	v_pk_add_f32 v[234:235], v[234:235], v[238:239]
	v_pk_add_f32 v[226:227], v[234:235], v[226:227]
	ds_read_b128 v[50:53], v241 offset:15984
	s_waitcnt lgkmcnt(7)
	v_pk_fma_f32 v[230:231], v[2:3], v[6:7], v[230:231] op_sel:[0,0,0] op_sel_hi:[0,1,1] neg_lo:[1,0,0] neg_hi:[1,0,0]
	v_pk_mul_f32 v[234:235], v[2:3], v[54:55] op_sel:[1,0] op_sel_hi:[1,1] neg_lo:[1,0] neg_hi:[1,0]
	v_pk_mul_f32 v[236:237], v[4:5], v[56:57] op_sel:[0,0] op_sel_hi:[0,1] neg_lo:[1,0] neg_hi:[1,0]
	v_pk_mul_f32 v[238:239], v[4:5], v[58:59] op_sel:[1,0] op_sel_hi:[1,1] neg_lo:[1,0] neg_hi:[1,0]
	ds_read_b128 v[2:5], v241 offset:16000
	s_waitcnt lgkmcnt(7)
	v_pk_fma_f32 v[230:231], v[26:27], v[60:61], v[230:231] op_sel:[0,0,0] op_sel_hi:[0,1,1] neg_lo:[1,0,0] neg_hi:[1,0,0]
	v_pk_fma_f32 v[234:235], v[26:27], v[62:63], v[234:235] op_sel:[1,0,0] op_sel_hi:[1,1,1] neg_lo:[1,0,0] neg_hi:[1,0,0]
	v_pk_fma_f32 v[236:237], v[28:29], v[64:65], v[236:237] op_sel:[0,0,0] op_sel_hi:[0,1,1] neg_lo:[1,0,0] neg_hi:[1,0,0]
	v_pk_fma_f32 v[238:239], v[28:29], v[66:67], v[238:239] op_sel:[1,0,0] op_sel_hi:[1,1,1] neg_lo:[1,0,0] neg_hi:[1,0,0]
	ds_read_b128 v[26:29], v241 offset:16016
	s_waitcnt lgkmcnt(7)
	v_pk_fma_f32 v[230:231], v[30:31], v[68:69], v[230:231] op_sel:[0,0,0] op_sel_hi:[0,1,1] neg_lo:[1,0,0] neg_hi:[1,0,0]
	v_pk_fma_f32 v[234:235], v[30:31], v[70:71], v[234:235] op_sel:[1,0,0] op_sel_hi:[1,1,1] neg_lo:[1,0,0] neg_hi:[1,0,0]
	v_pk_fma_f32 v[236:237], v[32:33], v[72:73], v[236:237] op_sel:[0,0,0] op_sel_hi:[0,1,1] neg_lo:[1,0,0] neg_hi:[1,0,0]
	v_pk_fma_f32 v[238:239], v[32:33], v[74:75], v[238:239] op_sel:[1,0,0] op_sel_hi:[1,1,1] neg_lo:[1,0,0] neg_hi:[1,0,0]
	ds_read_b128 v[30:33], v241 offset:16032
	s_waitcnt lgkmcnt(7)
	v_pk_fma_f32 v[230:231], v[34:35], v[76:77], v[230:231] op_sel:[0,0,0] op_sel_hi:[0,1,1] neg_lo:[1,0,0] neg_hi:[1,0,0]
	v_pk_fma_f32 v[234:235], v[34:35], v[78:79], v[234:235] op_sel:[1,0,0] op_sel_hi:[1,1,1] neg_lo:[1,0,0] neg_hi:[1,0,0]
	v_pk_fma_f32 v[236:237], v[36:37], v[80:81], v[236:237] op_sel:[0,0,0] op_sel_hi:[0,1,1] neg_lo:[1,0,0] neg_hi:[1,0,0]
	v_pk_fma_f32 v[238:239], v[36:37], v[82:83], v[238:239] op_sel:[1,0,0] op_sel_hi:[1,1,1] neg_lo:[1,0,0] neg_hi:[1,0,0]
	ds_read_b128 v[34:37], v241 offset:16048
	s_waitcnt lgkmcnt(7)
	v_pk_fma_f32 v[230:231], v[38:39], v[84:85], v[230:231] op_sel:[0,0,0] op_sel_hi:[0,1,1] neg_lo:[1,0,0] neg_hi:[1,0,0]
	v_pk_fma_f32 v[234:235], v[38:39], v[86:87], v[234:235] op_sel:[1,0,0] op_sel_hi:[1,1,1] neg_lo:[1,0,0] neg_hi:[1,0,0]
	v_pk_fma_f32 v[236:237], v[40:41], v[88:89], v[236:237] op_sel:[0,0,0] op_sel_hi:[0,1,1] neg_lo:[1,0,0] neg_hi:[1,0,0]
	v_pk_fma_f32 v[238:239], v[40:41], v[90:91], v[238:239] op_sel:[1,0,0] op_sel_hi:[1,1,1] neg_lo:[1,0,0] neg_hi:[1,0,0]
	ds_read_b128 v[38:41], v241 offset:16064
	s_waitcnt lgkmcnt(7)
; template <int DIR>
; __device__ __forceinline__ void dn_solve(const P& p, int task, int m0, int h, int t2, const bf16_t* kn_s, const bf16_t* v_s, const float* gc, const float* be, float* L) {
;     ...
; #pragma unroll
;     for (int cp = 1; cp < 64; ++cp) {
;         float a0 = 0.f, a1 = 0.f, a2 = 0.f, a3 = 0.f;
; #pragma unroll
;         for (int s4 = 0; s4 < cp; s4 += 4) { const f32x4 l4 = *(const f32x4*)(L + cp * 64 + s4); a0 += l4[0] * x[s4]; a1 += l4[1] * x[s4 + 1]; a2 += l4[2] * x[s4 + 2]; a3 += l4[3] * x[s4 + 3]; }
;         x[cp] -= (a0 + a1) + (a2 + a3);
;     }
	v_pk_fma_f32 v[230:231], v[42:43], v[92:93], v[230:231] op_sel:[0,0,0] op_sel_hi:[0,1,1] neg_lo:[1,0,0] neg_hi:[1,0,0]
	v_pk_fma_f32 v[234:235], v[42:43], v[94:95], v[234:235] op_sel:[1,0,0] op_sel_hi:[1,1,1] neg_lo:[1,0,0] neg_hi:[1,0,0]
	v_pk_fma_f32 v[236:237], v[44:45], v[96:97], v[236:237] op_sel:[0,0,0] op_sel_hi:[0,1,1] neg_lo:[1,0,0] neg_hi:[1,0,0]
	v_pk_fma_f32 v[238:239], v[44:45], v[98:99], v[238:239] op_sel:[1,0,0] op_sel_hi:[1,1,1] neg_lo:[1,0,0] neg_hi:[1,0,0]
	ds_read_b128 v[42:45], v241 offset:16080
	s_waitcnt lgkmcnt(7)
	v_pk_fma_f32 v[230:231], v[46:47], v[100:101], v[230:231] op_sel:[0,0,0] op_sel_hi:[0,1,1] neg_lo:[1,0,0] neg_hi:[1,0,0]
	v_pk_fma_f32 v[234:235], v[46:47], v[102:103], v[234:235] op_sel:[1,0,0] op_sel_hi:[1,1,1] neg_lo:[1,0,0] neg_hi:[1,0,0]
	v_pk_fma_f32 v[236:237], v[48:49], v[104:105], v[236:237] op_sel:[0,0,0] op_sel_hi:[0,1,1] neg_lo:[1,0,0] neg_hi:[1,0,0]
	v_pk_fma_f32 v[238:239], v[48:49], v[106:107], v[238:239] op_sel:[1,0,0] op_sel_hi:[1,1,1] neg_lo:[1,0,0] neg_hi:[1,0,0]
	ds_read_b128 v[46:49], v241 offset:16096
	s_waitcnt lgkmcnt(7)
	v_pk_fma_f32 v[230:231], v[50:51], v[108:109], v[230:231] op_sel:[0,0,0] op_sel_hi:[0,1,1] neg_lo:[1,0,0] neg_hi:[1,0,0]
	v_pk_fma_f32 v[234:235], v[50:51], v[110:111], v[234:235] op_sel:[1,0,0] op_sel_hi:[1,1,1] neg_lo:[1,0,0] neg_hi:[1,0,0]
	v_pk_fma_f32 v[236:237], v[52:53], v[112:113], v[236:237] op_sel:[0,0,0] op_sel_hi:[0,1,1] neg_lo:[1,0,0] neg_hi:[1,0,0]
	v_pk_fma_f32 v[238:239], v[52:53], v[114:115], v[238:239] op_sel:[1,0,0] op_sel_hi:[1,1,1] neg_lo:[1,0,0] neg_hi:[1,0,0]
	ds_read_b128 v[50:53], v241 offset:16112
	s_waitcnt lgkmcnt(7)
	v_pk_fma_f32 v[230:231], v[2:3], v[116:117], v[230:231] op_sel:[0,0,0] op_sel_hi:[0,1,1] neg_lo:[1,0,0] neg_hi:[1,0,0]
	v_pk_fma_f32 v[234:235], v[2:3], v[118:119], v[234:235] op_sel:[1,0,0] op_sel_hi:[1,1,1] neg_lo:[1,0,0] neg_hi:[1,0,0]
	v_pk_fma_f32 v[236:237], v[4:5], v[152:153], v[236:237] op_sel:[0,0,0] op_sel_hi:[0,1,1] neg_lo:[1,0,0] neg_hi:[1,0,0]
	v_pk_fma_f32 v[238:239], v[4:5], v[154:155], v[238:239] op_sel:[1,0,0] op_sel_hi:[1,1,1] neg_lo:[1,0,0] neg_hi:[1,0,0]
	ds_read_b128 v[2:5], v241 offset:16128
	s_waitcnt lgkmcnt(7)
	v_pk_fma_f32 v[230:231], v[26:27], v[156:157], v[230:231] op_sel:[0,0,0] op_sel_hi:[0,1,1] neg_lo:[1,0,0] neg_hi:[1,0,0]
	v_pk_fma_f32 v[234:235], v[26:27], v[158:159], v[234:235] op_sel:[1,0,0] op_sel_hi:[1,1,1] neg_lo:[1,0,0] neg_hi:[1,0,0]
	v_pk_fma_f32 v[236:237], v[28:29], v[160:161], v[236:237] op_sel:[0,0,0] op_sel_hi:[0,1,1] neg_lo:[1,0,0] neg_hi:[1,0,0]
	v_pk_fma_f32 v[238:239], v[28:29], v[162:163], v[238:239] op_sel:[1,0,0] op_sel_hi:[1,1,1] neg_lo:[1,0,0] neg_hi:[1,0,0]
	ds_read_b128 v[26:29], v241 offset:16144
	s_waitcnt lgkmcnt(7)
	v_pk_fma_f32 v[230:231], v[30:31], v[164:165], v[230:231] op_sel:[0,0,0] op_sel_hi:[0,1,1] neg_lo:[1,0,0] neg_hi:[1,0,0]
	v_pk_fma_f32 v[234:235], v[30:31], v[166:167], v[234:235] op_sel:[1,0,0] op_sel_hi:[1,1,1] neg_lo:[1,0,0] neg_hi:[1,0,0]
	v_pk_fma_f32 v[236:237], v[32:33], v[168:169], v[236:237] op_sel:[0,0,0] op_sel_hi:[0,1,1] neg_lo:[1,0,0] neg_hi:[1,0,0]
	v_pk_fma_f32 v[238:239], v[32:33], v[170:171], v[238:239] op_sel:[1,0,0] op_sel_hi:[1,1,1] neg_lo:[1,0,0] neg_hi:[1,0,0]
	ds_read_b128 v[30:33], v241 offset:16160
	s_waitcnt lgkmcnt(7)
	v_pk_fma_f32 v[230:231], v[34:35], v[172:173], v[230:231] op_sel:[0,0,0] op_sel_hi:[0,1,1] neg_lo:[1,0,0] neg_hi:[1,0,0]
	v_pk_fma_f32 v[234:235], v[34:35], v[174:175], v[234:235] op_sel:[1,0,0] op_sel_hi:[1,1,1] neg_lo:[1,0,0] neg_hi:[1,0,0]
	v_pk_fma_f32 v[236:237], v[36:37], v[176:177], v[236:237] op_sel:[0,0,0] op_sel_hi:[0,1,1] neg_lo:[1,0,0] neg_hi:[1,0,0]
	v_pk_fma_f32 v[238:239], v[36:37], v[178:179], v[238:239] op_sel:[1,0,0] op_sel_hi:[1,1,1] neg_lo:[1,0,0] neg_hi:[1,0,0]
	ds_read_b128 v[34:37], v241 offset:16176
	s_waitcnt lgkmcnt(7)
	v_pk_fma_f32 v[230:231], v[38:39], v[180:181], v[230:231] op_sel:[0,0,0] op_sel_hi:[0,1,1] neg_lo:[1,0,0] neg_hi:[1,0,0]
	v_pk_fma_f32 v[234:235], v[38:39], v[182:183], v[234:235] op_sel:[1,0,0] op_sel_hi:[1,1,1] neg_lo:[1,0,0] neg_hi:[1,0,0]
	v_pk_fma_f32 v[236:237], v[40:41], v[202:203], v[236:237] op_sel:[0,0,0] op_sel_hi:[0,1,1] neg_lo:[1,0,0] neg_hi:[1,0,0]
	v_pk_fma_f32 v[238:239], v[40:41], v[204:205], v[238:239] op_sel:[1,0,0] op_sel_hi:[1,1,1] neg_lo:[1,0,0] neg_hi:[1,0,0]
	ds_read_b128 v[38:41], v241 offset:16192
	s_waitcnt lgkmcnt(7)
	v_pk_fma_f32 v[230:231], v[42:43], v[208:209], v[230:231] op_sel:[0,0,0] op_sel_hi:[0,1,1] neg_lo:[1,0,0] neg_hi:[1,0,0]
	v_pk_fma_f32 v[234:235], v[42:43], v[210:211], v[234:235] op_sel:[1,0,0] op_sel_hi:[1,1,1] neg_lo:[1,0,0] neg_hi:[1,0,0]
	v_pk_fma_f32 v[236:237], v[44:45], v[212:213], v[236:237] op_sel:[0,0,0] op_sel_hi:[0,1,1] neg_lo:[1,0,0] neg_hi:[1,0,0]
	v_pk_fma_f32 v[238:239], v[44:45], v[214:215], v[238:239] op_sel:[1,0,0] op_sel_hi:[1,1,1] neg_lo:[1,0,0] neg_hi:[1,0,0]
	ds_read_b128 v[42:45], v241 offset:16208
	s_waitcnt lgkmcnt(7)
	v_pk_fma_f32 v[230:231], v[46:47], v[216:217], v[230:231] op_sel:[0,0,0] op_sel_hi:[0,1,1] neg_lo:[1,0,0] neg_hi:[1,0,0]
	v_pk_fma_f32 v[234:235], v[46:47], v[218:219], v[234:235] op_sel:[1,0,0] op_sel_hi:[1,1,1] neg_lo:[1,0,0] neg_hi:[1,0,0]
	v_pk_fma_f32 v[236:237], v[48:49], v[220:221], v[236:237] op_sel:[0,0,0] op_sel_hi:[0,1,1] neg_lo:[1,0,0] neg_hi:[1,0,0]
	v_pk_fma_f32 v[238:239], v[48:49], v[222:223], v[238:239] op_sel:[1,0,0] op_sel_hi:[1,1,1] neg_lo:[1,0,0] neg_hi:[1,0,0]
	ds_read_b128 v[46:49], v241 offset:16224
	s_waitcnt lgkmcnt(7)
; template <int DIR>
; __device__ __forceinline__ void dn_solve(const P& p, int task, int m0, int h, int t2, const bf16_t* kn_s, const bf16_t* v_s, const float* gc, const float* be, float* L) {
;     ...
; #pragma unroll
;     for (int cp = 1; cp < 64; ++cp) {
;         float a0 = 0.f, a1 = 0.f, a2 = 0.f, a3 = 0.f;
; #pragma unroll
;         for (int s4 = 0; s4 < cp; s4 += 4) { const f32x4 l4 = *(const f32x4*)(L + cp * 64 + s4); a0 += l4[0] * x[s4]; a1 += l4[1] * x[s4 + 1]; a2 += l4[2] * x[s4 + 2]; a3 += l4[3] * x[s4 + 3]; }
;         x[cp] -= (a0 + a1) + (a2 + a3);
;     }
	v_pk_fma_f32 v[230:231], v[50:51], v[224:225], v[230:231] op_sel:[0,0,0] op_sel_hi:[0,1,1] neg_lo:[1,0,0] neg_hi:[1,0,0]
	v_pk_fma_f32 v[234:235], v[50:51], v[226:227], v[234:235] op_sel:[1,0,0] op_sel_hi:[1,1,1] neg_lo:[1,0,0] neg_hi:[1,0,0]
	v_pk_add_f32 v[236:237], v[230:231], v[236:237]
	v_pk_add_f32 v[236:237], v[236:237], v[238:239]
	v_pk_add_f32 v[230:231], v[236:237], v[234:235]
	ds_read_b128 v[50:53], v241 offset:16240
	s_waitcnt lgkmcnt(7)
	v_pk_fma_f32 v[232:233], v[2:3], v[6:7], v[232:233] op_sel:[0,0,0] op_sel_hi:[0,1,1] neg_lo:[1,0,0] neg_hi:[1,0,0]
	v_pk_mul_f32 v[234:235], v[2:3], v[54:55] op_sel:[1,0] op_sel_hi:[1,1] neg_lo:[1,0] neg_hi:[1,0]
	v_pk_mul_f32 v[236:237], v[4:5], v[56:57] op_sel:[0,0] op_sel_hi:[0,1] neg_lo:[1,0] neg_hi:[1,0]
	v_pk_mul_f32 v[238:239], v[4:5], v[58:59] op_sel:[1,0] op_sel_hi:[1,1] neg_lo:[1,0] neg_hi:[1,0]
	ds_read_b128 v[2:5], v241 offset:16256
	s_waitcnt lgkmcnt(7)
	v_pk_fma_f32 v[232:233], v[26:27], v[60:61], v[232:233] op_sel:[0,0,0] op_sel_hi:[0,1,1] neg_lo:[1,0,0] neg_hi:[1,0,0]
	v_pk_fma_f32 v[234:235], v[26:27], v[62:63], v[234:235] op_sel:[1,0,0] op_sel_hi:[1,1,1] neg_lo:[1,0,0] neg_hi:[1,0,0]
	v_pk_fma_f32 v[236:237], v[28:29], v[64:65], v[236:237] op_sel:[0,0,0] op_sel_hi:[0,1,1] neg_lo:[1,0,0] neg_hi:[1,0,0]
	v_pk_fma_f32 v[238:239], v[28:29], v[66:67], v[238:239] op_sel:[1,0,0] op_sel_hi:[1,1,1] neg_lo:[1,0,0] neg_hi:[1,0,0]
	ds_read_b128 v[26:29], v241 offset:16272
	s_waitcnt lgkmcnt(7)
	v_pk_fma_f32 v[232:233], v[30:31], v[68:69], v[232:233] op_sel:[0,0,0] op_sel_hi:[0,1,1] neg_lo:[1,0,0] neg_hi:[1,0,0]
	v_pk_fma_f32 v[234:235], v[30:31], v[70:71], v[234:235] op_sel:[1,0,0] op_sel_hi:[1,1,1] neg_lo:[1,0,0] neg_hi:[1,0,0]
	v_pk_fma_f32 v[236:237], v[32:33], v[72:73], v[236:237] op_sel:[0,0,0] op_sel_hi:[0,1,1] neg_lo:[1,0,0] neg_hi:[1,0,0]
	v_pk_fma_f32 v[238:239], v[32:33], v[74:75], v[238:239] op_sel:[1,0,0] op_sel_hi:[1,1,1] neg_lo:[1,0,0] neg_hi:[1,0,0]
	ds_read_b128 v[30:33], v241 offset:16288
	s_waitcnt lgkmcnt(7)
	v_pk_fma_f32 v[232:233], v[34:35], v[76:77], v[232:233] op_sel:[0,0,0] op_sel_hi:[0,1,1] neg_lo:[1,0,0] neg_hi:[1,0,0]
	v_pk_fma_f32 v[234:235], v[34:35], v[78:79], v[234:235] op_sel:[1,0,0] op_sel_hi:[1,1,1] neg_lo:[1,0,0] neg_hi:[1,0,0]
	v_pk_fma_f32 v[236:237], v[36:37], v[80:81], v[236:237] op_sel:[0,0,0] op_sel_hi:[0,1,1] neg_lo:[1,0,0] neg_hi:[1,0,0]
	v_pk_fma_f32 v[238:239], v[36:37], v[82:83], v[238:239] op_sel:[1,0,0] op_sel_hi:[1,1,1] neg_lo:[1,0,0] neg_hi:[1,0,0]
	ds_read_b128 v[34:37], v241 offset:16304
	s_waitcnt lgkmcnt(7)
	v_pk_fma_f32 v[232:233], v[38:39], v[84:85], v[232:233] op_sel:[0,0,0] op_sel_hi:[0,1,1] neg_lo:[1,0,0] neg_hi:[1,0,0]
	v_pk_fma_f32 v[234:235], v[38:39], v[86:87], v[234:235] op_sel:[1,0,0] op_sel_hi:[1,1,1] neg_lo:[1,0,0] neg_hi:[1,0,0]
	v_pk_fma_f32 v[236:237], v[40:41], v[88:89], v[236:237] op_sel:[0,0,0] op_sel_hi:[0,1,1] neg_lo:[1,0,0] neg_hi:[1,0,0]
	v_pk_fma_f32 v[238:239], v[40:41], v[90:91], v[238:239] op_sel:[1,0,0] op_sel_hi:[1,1,1] neg_lo:[1,0,0] neg_hi:[1,0,0]
	ds_read_b128 v[38:41], v241 offset:16320
	s_waitcnt lgkmcnt(7)
	v_pk_fma_f32 v[232:233], v[42:43], v[92:93], v[232:233] op_sel:[0,0,0] op_sel_hi:[0,1,1] neg_lo:[1,0,0] neg_hi:[1,0,0]
	v_pk_fma_f32 v[234:235], v[42:43], v[94:95], v[234:235] op_sel:[1,0,0] op_sel_hi:[1,1,1] neg_lo:[1,0,0] neg_hi:[1,0,0]
	v_pk_fma_f32 v[236:237], v[44:45], v[96:97], v[236:237] op_sel:[0,0,0] op_sel_hi:[0,1,1] neg_lo:[1,0,0] neg_hi:[1,0,0]
	v_pk_fma_f32 v[238:239], v[44:45], v[98:99], v[238:239] op_sel:[1,0,0] op_sel_hi:[1,1,1] neg_lo:[1,0,0] neg_hi:[1,0,0]
	ds_read_b128 v[42:45], v241 offset:16336
	s_waitcnt lgkmcnt(7)
	v_pk_fma_f32 v[232:233], v[46:47], v[100:101], v[232:233] op_sel:[0,0,0] op_sel_hi:[0,1,1] neg_lo:[1,0,0] neg_hi:[1,0,0]
	v_pk_fma_f32 v[234:235], v[46:47], v[102:103], v[234:235] op_sel:[1,0,0] op_sel_hi:[1,1,1] neg_lo:[1,0,0] neg_hi:[1,0,0]
	v_pk_fma_f32 v[236:237], v[48:49], v[104:105], v[236:237] op_sel:[0,0,0] op_sel_hi:[0,1,1] neg_lo:[1,0,0] neg_hi:[1,0,0]
	v_pk_fma_f32 v[238:239], v[48:49], v[106:107], v[238:239] op_sel:[1,0,0] op_sel_hi:[1,1,1] neg_lo:[1,0,0] neg_hi:[1,0,0]
	ds_read_b128 v[46:49], v241 offset:16352
	s_waitcnt lgkmcnt(7)
	v_pk_fma_f32 v[232:233], v[50:51], v[108:109], v[232:233] op_sel:[0,0,0] op_sel_hi:[0,1,1] neg_lo:[1,0,0] neg_hi:[1,0,0]
	v_pk_fma_f32 v[234:235], v[50:51], v[110:111], v[234:235] op_sel:[1,0,0] op_sel_hi:[1,1,1] neg_lo:[1,0,0] neg_hi:[1,0,0]
	v_pk_fma_f32 v[236:237], v[52:53], v[112:113], v[236:237] op_sel:[0,0,0] op_sel_hi:[0,1,1] neg_lo:[1,0,0] neg_hi:[1,0,0]
	v_pk_fma_f32 v[238:239], v[52:53], v[114:115], v[238:239] op_sel:[1,0,0] op_sel_hi:[1,1,1] neg_lo:[1,0,0] neg_hi:[1,0,0]
	ds_read_b128 v[50:53], v241 offset:16368
	s_waitcnt lgkmcnt(7)
	v_pk_fma_f32 v[232:233], v[2:3], v[116:117], v[232:233] op_sel:[0,0,0] op_sel_hi:[0,1,1] neg_lo:[1,0,0] neg_hi:[1,0,0]
	v_pk_fma_f32 v[234:235], v[2:3], v[118:119], v[234:235] op_sel:[1,0,0] op_sel_hi:[1,1,1] neg_lo:[1,0,0] neg_hi:[1,0,0]
	v_pk_fma_f32 v[236:237], v[4:5], v[152:153], v[236:237] op_sel:[0,0,0] op_sel_hi:[0,1,1] neg_lo:[1,0,0] neg_hi:[1,0,0]
	v_pk_fma_f32 v[238:239], v[4:5], v[154:155], v[238:239] op_sel:[1,0,0] op_sel_hi:[1,1,1] neg_lo:[1,0,0] neg_hi:[1,0,0]
	s_waitcnt lgkmcnt(6)
	v_pk_fma_f32 v[232:233], v[26:27], v[156:157], v[232:233] op_sel:[0,0,0] op_sel_hi:[0,1,1] neg_lo:[1,0,0] neg_hi:[1,0,0]
	v_pk_fma_f32 v[234:235], v[26:27], v[158:159], v[234:235] op_sel:[1,0,0] op_sel_hi:[1,1,1] neg_lo:[1,0,0] neg_hi:[1,0,0]
	v_pk_fma_f32 v[236:237], v[28:29], v[160:161], v[236:237] op_sel:[0,0,0] op_sel_hi:[0,1,1] neg_lo:[1,0,0] neg_hi:[1,0,0]
	v_pk_fma_f32 v[238:239], v[28:29], v[162:163], v[238:239] op_sel:[1,0,0] op_sel_hi:[1,1,1] neg_lo:[1,0,0] neg_hi:[1,0,0]
	s_waitcnt lgkmcnt(5)
; __device__ __forceinline__ unsigned f2bf(float f) { unsigned u = __builtin_bit_cast(unsigned, f); return (u + 0x7fffu + ((u >> 16) & 1u)) >> 16; }
; __device__ __forceinline__ unsigned pk2(float lo, float hi) { unsigned r; asm("v_cvt_pk_bf16_f32 %0, %1, %2" : "=v"(r) : "v"(lo), "v"(hi)); return r; }
; template <int DIR>
; __device__ __forceinline__ void dn_solve(const P& p, int task, int m0, int h, int t2, const bf16_t* kn_s, const bf16_t* v_s, const float* gc, const float* be, float* L) {
;     ...
; #pragma unroll
;     for (int cp = 1; cp < 64; ++cp) {
;         float a0 = 0.f, a1 = 0.f, a2 = 0.f, a3 = 0.f;
; #pragma unroll
;         for (int s4 = 0; s4 < cp; s4 += 4) { const f32x4 l4 = *(const f32x4*)(L + cp * 64 + s4); a0 += l4[0] * x[s4]; a1 += l4[1] * x[s4 + 1]; a2 += l4[2] * x[s4 + 2]; a3 += l4[3] * x[s4 + 3]; }
;         x[cp] -= (a0 + a1) + (a2 + a3);
;     }
;     const size_t dt = (size_t)task * 2 + DIR;
;     if (t2 < 128) {
;         bf16_t* dst = (bf16_t*)(p.ws + WS_UT) + dt * 8192 + t2 * 64;
; #pragma unroll
;         for (int t8 = 0; t8 < 64; t8 += 8) {
;             u32x4 o;
;             o.x = pk2(x[DIR ? 63 - t8 : t8], x[DIR ? 62 - t8 : t8 + 1]); o.y = pk2(x[DIR ? 61 - t8 : t8 + 2], x[DIR ? 60 - t8 : t8 + 3]);
;             o.z = pk2(x[DIR ? 59 - t8 : t8 + 4], x[DIR ? 58 - t8 : t8 + 5]); o.w = pk2(x[DIR ? 57 - t8 : t8 + 6], x[DIR ? 56 - t8 : t8 + 7]);
;             *(u32x4*)(dst + t8) = o;
;         }
;     }
;     __syncthreads();
;     bf16_t* wt = (bf16_t*)L;
;     if (t2 >= 128) {
;         const int k = t2 - 128;
; #pragma unroll
;         for (int cp = 0; cp < 64; ++cp) { const int tok = DIR ? 63 - cp : cp; wt[tok * 128 + k] = (bf16_t)f2bf(-x[cp]); }
	v_pk_fma_f32 v[232:233], v[30:31], v[164:165], v[232:233] op_sel:[0,0,0] op_sel_hi:[0,1,1] neg_lo:[1,0,0] neg_hi:[1,0,0]
	v_pk_fma_f32 v[234:235], v[30:31], v[166:167], v[234:235] op_sel:[1,0,0] op_sel_hi:[1,1,1] neg_lo:[1,0,0] neg_hi:[1,0,0]
	v_pk_fma_f32 v[236:237], v[32:33], v[168:169], v[236:237] op_sel:[0,0,0] op_sel_hi:[0,1,1] neg_lo:[1,0,0] neg_hi:[1,0,0]
	v_pk_fma_f32 v[238:239], v[32:33], v[170:171], v[238:239] op_sel:[1,0,0] op_sel_hi:[1,1,1] neg_lo:[1,0,0] neg_hi:[1,0,0]
	s_waitcnt lgkmcnt(4)
	v_pk_fma_f32 v[232:233], v[34:35], v[172:173], v[232:233] op_sel:[0,0,0] op_sel_hi:[0,1,1] neg_lo:[1,0,0] neg_hi:[1,0,0]
	v_pk_fma_f32 v[234:235], v[34:35], v[174:175], v[234:235] op_sel:[1,0,0] op_sel_hi:[1,1,1] neg_lo:[1,0,0] neg_hi:[1,0,0]
	v_pk_fma_f32 v[236:237], v[36:37], v[176:177], v[236:237] op_sel:[0,0,0] op_sel_hi:[0,1,1] neg_lo:[1,0,0] neg_hi:[1,0,0]
	v_pk_fma_f32 v[238:239], v[36:37], v[178:179], v[238:239] op_sel:[1,0,0] op_sel_hi:[1,1,1] neg_lo:[1,0,0] neg_hi:[1,0,0]
	s_waitcnt lgkmcnt(3)
	v_pk_fma_f32 v[232:233], v[38:39], v[180:181], v[232:233] op_sel:[0,0,0] op_sel_hi:[0,1,1] neg_lo:[1,0,0] neg_hi:[1,0,0]
	v_pk_fma_f32 v[234:235], v[38:39], v[182:183], v[234:235] op_sel:[1,0,0] op_sel_hi:[1,1,1] neg_lo:[1,0,0] neg_hi:[1,0,0]
	v_pk_fma_f32 v[236:237], v[40:41], v[202:203], v[236:237] op_sel:[0,0,0] op_sel_hi:[0,1,1] neg_lo:[1,0,0] neg_hi:[1,0,0]
	v_pk_fma_f32 v[238:239], v[40:41], v[204:205], v[238:239] op_sel:[1,0,0] op_sel_hi:[1,1,1] neg_lo:[1,0,0] neg_hi:[1,0,0]
	s_waitcnt lgkmcnt(2)
	v_pk_fma_f32 v[232:233], v[42:43], v[208:209], v[232:233] op_sel:[0,0,0] op_sel_hi:[0,1,1] neg_lo:[1,0,0] neg_hi:[1,0,0]
	v_pk_fma_f32 v[234:235], v[42:43], v[210:211], v[234:235] op_sel:[1,0,0] op_sel_hi:[1,1,1] neg_lo:[1,0,0] neg_hi:[1,0,0]
	v_pk_fma_f32 v[236:237], v[44:45], v[212:213], v[236:237] op_sel:[0,0,0] op_sel_hi:[0,1,1] neg_lo:[1,0,0] neg_hi:[1,0,0]
	v_pk_fma_f32 v[238:239], v[44:45], v[214:215], v[238:239] op_sel:[1,0,0] op_sel_hi:[1,1,1] neg_lo:[1,0,0] neg_hi:[1,0,0]
	s_waitcnt lgkmcnt(1)
	v_pk_fma_f32 v[232:233], v[46:47], v[216:217], v[232:233] op_sel:[0,0,0] op_sel_hi:[0,1,1] neg_lo:[1,0,0] neg_hi:[1,0,0]
	v_pk_fma_f32 v[234:235], v[46:47], v[218:219], v[234:235] op_sel:[1,0,0] op_sel_hi:[1,1,1] neg_lo:[1,0,0] neg_hi:[1,0,0]
	v_pk_fma_f32 v[236:237], v[48:49], v[220:221], v[236:237] op_sel:[0,0,0] op_sel_hi:[0,1,1] neg_lo:[1,0,0] neg_hi:[1,0,0]
	v_pk_fma_f32 v[238:239], v[48:49], v[222:223], v[238:239] op_sel:[1,0,0] op_sel_hi:[1,1,1] neg_lo:[1,0,0] neg_hi:[1,0,0]
	s_waitcnt lgkmcnt(0)
	v_pk_fma_f32 v[232:233], v[50:51], v[224:225], v[232:233] op_sel:[0,0,0] op_sel_hi:[0,1,1] neg_lo:[1,0,0] neg_hi:[1,0,0]
	v_pk_fma_f32 v[234:235], v[50:51], v[226:227], v[234:235] op_sel:[1,0,0] op_sel_hi:[1,1,1] neg_lo:[1,0,0] neg_hi:[1,0,0]
	v_pk_fma_f32 v[236:237], v[52:53], v[230:231], v[236:237] op_sel:[0,0,0] op_sel_hi:[0,1,1] neg_lo:[1,0,0] neg_hi:[1,0,0]
	v_pk_add_f32 v[234:235], v[232:233], v[234:235]
	v_pk_add_f32 v[234:235], v[234:235], v[238:239]
	v_pk_add_f32 v[232:233], v[234:235], v[236:237]
	s_lshl_b32 s80, s2, 15
	s_lshl_b32 s81, s73, 14
	s_add_u32 s80, s80, s81
	s_add_u32 s82, s44, 0xa300000
	s_addc_u32 s83, s45, 0
	s_add_u32 s82, s82, s80
	s_addc_u32 s83, s83, 0
	v_lshlrev_b32_e32 v245, 7, v207
	s_cmp_eq_u32 s73, 0
	s_cbranch_scc0 .Lpz_out1
	v_cvt_pk_bf16_f32 v2, v6, v54
	v_cvt_pk_bf16_f32 v3, v56, v58
	v_cvt_pk_bf16_f32 v4, v60, v62
	v_cvt_pk_bf16_f32 v5, v64, v66
	global_store_dwordx4 v245, v[2:5], s[82:83] offset:0
	v_cvt_pk_bf16_f32 v26, v68, v70
	v_cvt_pk_bf16_f32 v27, v72, v74
	v_cvt_pk_bf16_f32 v28, v76, v78
	v_cvt_pk_bf16_f32 v29, v80, v82
	global_store_dwordx4 v245, v[26:29], s[82:83] offset:16
	v_cvt_pk_bf16_f32 v30, v84, v86
	v_cvt_pk_bf16_f32 v31, v88, v90
	v_cvt_pk_bf16_f32 v32, v92, v94
	v_cvt_pk_bf16_f32 v33, v96, v98
	global_store_dwordx4 v245, v[30:33], s[82:83] offset:32
	v_cvt_pk_bf16_f32 v34, v100, v102
	v_cvt_pk_bf16_f32 v35, v104, v106
	v_cvt_pk_bf16_f32 v36, v108, v110
	v_cvt_pk_bf16_f32 v37, v112, v114
	global_store_dwordx4 v245, v[34:37], s[82:83] offset:48
	v_cvt_pk_bf16_f32 v38, v116, v118
	v_cvt_pk_bf16_f32 v39, v152, v154
	v_cvt_pk_bf16_f32 v40, v156, v158
	v_cvt_pk_bf16_f32 v41, v160, v162
	global_store_dwordx4 v245, v[38:41], s[82:83] offset:64
	v_cvt_pk_bf16_f32 v42, v164, v166
	v_cvt_pk_bf16_f32 v43, v168, v170
	v_cvt_pk_bf16_f32 v44, v172, v174
	v_cvt_pk_bf16_f32 v45, v176, v178
	global_store_dwordx4 v245, v[42:45], s[82:83] offset:80
	v_cvt_pk_bf16_f32 v46, v180, v182
	v_cvt_pk_bf16_f32 v47, v202, v204
	v_cvt_pk_bf16_f32 v48, v208, v210
	v_cvt_pk_bf16_f32 v49, v212, v214
	global_store_dwordx4 v245, v[46:49], s[82:83] offset:96
	v_cvt_pk_bf16_f32 v50, v216, v218
	v_cvt_pk_bf16_f32 v51, v220, v222
	v_cvt_pk_bf16_f32 v52, v224, v226
	v_cvt_pk_bf16_f32 v53, v230, v232
	global_store_dwordx4 v245, v[50:53], s[82:83] offset:112
	v_cvt_pk_bf16_f32 v246, -v7, -v55
	ds_write_b16 v242, v246 offset:0
	ds_write_b16_d16_hi v242, v246 offset:256
	v_cvt_pk_bf16_f32 v247, -v57, -v59
	ds_write_b16 v242, v247 offset:512
	ds_write_b16_d16_hi v242, v247 offset:768
	v_cvt_pk_bf16_f32 v246, -v61, -v63
	ds_write_b16 v242, v246 offset:1024
	ds_write_b16_d16_hi v242, v246 offset:1280
	v_cvt_pk_bf16_f32 v247, -v65, -v67
	ds_write_b16 v242, v247 offset:1536
	ds_write_b16_d16_hi v242, v247 offset:1792
	v_cvt_pk_bf16_f32 v246, -v69, -v71
	ds_write_b16 v242, v246 offset:2048
	ds_write_b16_d16_hi v242, v246 offset:2304
	v_cvt_pk_bf16_f32 v247, -v73, -v75
	ds_write_b16 v242, v247 offset:2560
	ds_write_b16_d16_hi v242, v247 offset:2816
	v_cvt_pk_bf16_f32 v246, -v77, -v79
	ds_write_b16 v242, v246 offset:3072
; __device__ __forceinline__ unsigned f2bf(float f) { unsigned u = __builtin_bit_cast(unsigned, f); return (u + 0x7fffu + ((u >> 16) & 1u)) >> 16; }
; __device__ __forceinline__ unsigned pk2(float lo, float hi) { unsigned r; asm("v_cvt_pk_bf16_f32 %0, %1, %2" : "=v"(r) : "v"(lo), "v"(hi)); return r; }
; template <int DIR>
; __device__ __forceinline__ void dn_solve(const P& p, int task, int m0, int h, int t2, const bf16_t* kn_s, const bf16_t* v_s, const float* gc, const float* be, float* L) {
;     ...
;     if (t2 < 128) {
;         bf16_t* dst = (bf16_t*)(p.ws + WS_UT) + dt * 8192 + t2 * 64;
; #pragma unroll
;         for (int t8 = 0; t8 < 64; t8 += 8) {
;             u32x4 o;
;             o.x = pk2(x[DIR ? 63 - t8 : t8], x[DIR ? 62 - t8 : t8 + 1]); o.y = pk2(x[DIR ? 61 - t8 : t8 + 2], x[DIR ? 60 - t8 : t8 + 3]);
;             o.z = pk2(x[DIR ? 59 - t8 : t8 + 4], x[DIR ? 58 - t8 : t8 + 5]); o.w = pk2(x[DIR ? 57 - t8 : t8 + 6], x[DIR ? 56 - t8 : t8 + 7]);
;             *(u32x4*)(dst + t8) = o;
;         }
;     }
;     __syncthreads();
;     bf16_t* wt = (bf16_t*)L;
;     if (t2 >= 128) {
;         const int k = t2 - 128;
; #pragma unroll
;         for (int cp = 0; cp < 64; ++cp) { const int tok = DIR ? 63 - cp : cp; wt[tok * 128 + k] = (bf16_t)f2bf(-x[cp]); }
	ds_write_b16_d16_hi v242, v246 offset:3328
	v_cvt_pk_bf16_f32 v247, -v81, -v83
	ds_write_b16 v242, v247 offset:3584
	ds_write_b16_d16_hi v242, v247 offset:3840
	v_cvt_pk_bf16_f32 v246, -v85, -v87
	ds_write_b16 v242, v246 offset:4096
	ds_write_b16_d16_hi v242, v246 offset:4352
	v_cvt_pk_bf16_f32 v247, -v89, -v91
	ds_write_b16 v242, v247 offset:4608
	ds_write_b16_d16_hi v242, v247 offset:4864
	v_cvt_pk_bf16_f32 v246, -v93, -v95
	ds_write_b16 v242, v246 offset:5120
	ds_write_b16_d16_hi v242, v246 offset:5376
	v_cvt_pk_bf16_f32 v247, -v97, -v99
	ds_write_b16 v242, v247 offset:5632
	ds_write_b16_d16_hi v242, v247 offset:5888
	v_cvt_pk_bf16_f32 v246, -v101, -v103
	ds_write_b16 v242, v246 offset:6144
	ds_write_b16_d16_hi v242, v246 offset:6400
	v_cvt_pk_bf16_f32 v247, -v105, -v107
	ds_write_b16 v242, v247 offset:6656
	ds_write_b16_d16_hi v242, v247 offset:6912
	v_cvt_pk_bf16_f32 v246, -v109, -v111
	ds_write_b16 v242, v246 offset:7168
	ds_write_b16_d16_hi v242, v246 offset:7424
	v_cvt_pk_bf16_f32 v247, -v113, -v115
	ds_write_b16 v242, v247 offset:7680
	ds_write_b16_d16_hi v242, v247 offset:7936
	v_cvt_pk_bf16_f32 v246, -v117, -v119
	ds_write_b16 v242, v246 offset:8192
	ds_write_b16_d16_hi v242, v246 offset:8448
	v_cvt_pk_bf16_f32 v247, -v153, -v155
	ds_write_b16 v242, v247 offset:8704
	ds_write_b16_d16_hi v242, v247 offset:8960
	v_cvt_pk_bf16_f32 v246, -v157, -v159
	ds_write_b16 v242, v246 offset:9216
	ds_write_b16_d16_hi v242, v246 offset:9472
	v_cvt_pk_bf16_f32 v247, -v161, -v163
	ds_write_b16 v242, v247 offset:9728
	ds_write_b16_d16_hi v242, v247 offset:9984
	v_cvt_pk_bf16_f32 v246, -v165, -v167
	ds_write_b16 v242, v246 offset:10240
	ds_write_b16_d16_hi v242, v246 offset:10496
	v_cvt_pk_bf16_f32 v247, -v169, -v171
	ds_write_b16 v242, v247 offset:10752
	ds_write_b16_d16_hi v242, v247 offset:11008
	v_cvt_pk_bf16_f32 v246, -v173, -v175
	ds_write_b16 v242, v246 offset:11264
	ds_write_b16_d16_hi v242, v246 offset:11520
	v_cvt_pk_bf16_f32 v247, -v177, -v179
	ds_write_b16 v242, v247 offset:11776
	ds_write_b16_d16_hi v242, v247 offset:12032
	v_cvt_pk_bf16_f32 v246, -v181, -v183
	ds_write_b16 v242, v246 offset:12288
	ds_write_b16_d16_hi v242, v246 offset:12544
	v_cvt_pk_bf16_f32 v247, -v203, -v205
	ds_write_b16 v242, v247 offset:12800
	ds_write_b16_d16_hi v242, v247 offset:13056
	v_cvt_pk_bf16_f32 v246, -v209, -v211
	ds_write_b16 v242, v246 offset:13312
	ds_write_b16_d16_hi v242, v246 offset:13568
	v_cvt_pk_bf16_f32 v247, -v213, -v215
	ds_write_b16 v242, v247 offset:13824
	ds_write_b16_d16_hi v242, v247 offset:14080
	v_cvt_pk_bf16_f32 v246, -v217, -v219
	ds_write_b16 v242, v246 offset:14336
	ds_write_b16_d16_hi v242, v246 offset:14592
	v_cvt_pk_bf16_f32 v247, -v221, -v223
	ds_write_b16 v242, v247 offset:14848
	ds_write_b16_d16_hi v242, v247 offset:15104
	v_cvt_pk_bf16_f32 v246, -v225, -v227
	ds_write_b16 v242, v246 offset:15360
	ds_write_b16_d16_hi v242, v246 offset:15616
	v_cvt_pk_bf16_f32 v247, -v231, -v233
	ds_write_b16 v242, v247 offset:15872
	ds_write_b16_d16_hi v242, v247 offset:16128
	s_branch .Lpz_restore
.Lpz_out1:
	v_cvt_pk_bf16_f32 v2, v232, v230
	v_cvt_pk_bf16_f32 v3, v226, v224
	v_cvt_pk_bf16_f32 v4, v222, v220
	v_cvt_pk_bf16_f32 v5, v218, v216
	global_store_dwordx4 v245, v[2:5], s[82:83] offset:0
	v_cvt_pk_bf16_f32 v26, v214, v212
	v_cvt_pk_bf16_f32 v27, v210, v208
	v_cvt_pk_bf16_f32 v28, v204, v202
	v_cvt_pk_bf16_f32 v29, v182, v180
	global_store_dwordx4 v245, v[26:29], s[82:83] offset:16
	v_cvt_pk_bf16_f32 v30, v178, v176
	v_cvt_pk_bf16_f32 v31, v174, v172
	v_cvt_pk_bf16_f32 v32, v170, v168
	v_cvt_pk_bf16_f32 v33, v166, v164
	global_store_dwordx4 v245, v[30:33], s[82:83] offset:32
	v_cvt_pk_bf16_f32 v34, v162, v160
	v_cvt_pk_bf16_f32 v35, v158, v156
	v_cvt_pk_bf16_f32 v36, v154, v152
	v_cvt_pk_bf16_f32 v37, v118, v116
	global_store_dwordx4 v245, v[34:37], s[82:83] offset:48
	v_cvt_pk_bf16_f32 v38, v114, v112
	v_cvt_pk_bf16_f32 v39, v110, v108
	v_cvt_pk_bf16_f32 v40, v106, v104
	v_cvt_pk_bf16_f32 v41, v102, v100
	global_store_dwordx4 v245, v[38:41], s[82:83] offset:64
	v_cvt_pk_bf16_f32 v42, v98, v96
	v_cvt_pk_bf16_f32 v43, v94, v92
	v_cvt_pk_bf16_f32 v44, v90, v88
	v_cvt_pk_bf16_f32 v45, v86, v84
	global_store_dwordx4 v245, v[42:45], s[82:83] offset:80
	v_cvt_pk_bf16_f32 v46, v82, v80
	v_cvt_pk_bf16_f32 v47, v78, v76
	v_cvt_pk_bf16_f32 v48, v74, v72
	v_cvt_pk_bf16_f32 v49, v70, v68
	global_store_dwordx4 v245, v[46:49], s[82:83] offset:96
	v_cvt_pk_bf16_f32 v50, v66, v64
	v_cvt_pk_bf16_f32 v51, v62, v60
	v_cvt_pk_bf16_f32 v52, v58, v56
	v_cvt_pk_bf16_f32 v53, v54, v6
	global_store_dwordx4 v245, v[50:53], s[82:83] offset:112
	v_cvt_pk_bf16_f32 v246, -v233, -v231
	ds_write_b16 v242, v246 offset:0
	ds_write_b16_d16_hi v242, v246 offset:256
	v_cvt_pk_bf16_f32 v247, -v227, -v225
	ds_write_b16 v242, v247 offset:512
	ds_write_b16_d16_hi v242, v247 offset:768
	v_cvt_pk_bf16_f32 v246, -v223, -v221
	ds_write_b16 v242, v246 offset:1024
	ds_write_b16_d16_hi v242, v246 offset:1280
	v_cvt_pk_bf16_f32 v247, -v219, -v217
	ds_write_b16 v242, v247 offset:1536
	ds_write_b16_d16_hi v242, v247 offset:1792
	v_cvt_pk_bf16_f32 v246, -v215, -v213
	ds_write_b16 v242, v246 offset:2048
	ds_write_b16_d16_hi v242, v246 offset:2304
	v_cvt_pk_bf16_f32 v247, -v211, -v209
	ds_write_b16 v242, v247 offset:2560
	ds_write_b16_d16_hi v242, v247 offset:2816
	v_cvt_pk_bf16_f32 v246, -v205, -v203
	ds_write_b16 v242, v246 offset:3072
	ds_write_b16_d16_hi v242, v246 offset:3328
; __device__ __forceinline__ unsigned f2bf(float f) { unsigned u = __builtin_bit_cast(unsigned, f); return (u + 0x7fffu + ((u >> 16) & 1u)) >> 16; }
; #define REP(k) for (int rep_ = 0; rep_ < (((REPMASK) >> (k)) & 1) + 1; ++rep_)
; template <int DIR>
; __device__ __forceinline__ void dn_solve(const P& p, int task, int m0, int h, int t2, const bf16_t* kn_s, const bf16_t* v_s, const float* gc, const float* be, float* L) {
;     ...
;     if (t2 >= 128) {
;         const int k = t2 - 128;
; #pragma unroll
;         for (int cp = 0; cp < 64; ++cp) { const int tok = DIR ? 63 - cp : cp; wt[tok * 128 + k] = (bf16_t)f2bf(-x[cp]); }
;     }
;     __syncthreads();
;     {
;         u32x4* dst = (u32x4*)((bf16_t*)(p.ws + WS_NEGW) + dt * 8192);
; #pragma unroll
;         for (int i = 0; i < 4; ++i) dst[t2 + 256 * i] = *(const u32x4*)(wt + (t2 + 256 * i) * 8);
;     }
; __global__ void __launch_bounds__(NTHREADS) mega_fwd(P p) {
;     ...
;                 if (RUN(7)) REP(7) for (int t = blockIdx.x; t < 1152; t += G) dn_prep_task(q, t, lds, tidl);
	v_cvt_pk_bf16_f32 v247, -v183, -v181
	ds_write_b16 v242, v247 offset:3584
	ds_write_b16_d16_hi v242, v247 offset:3840
	v_cvt_pk_bf16_f32 v246, -v179, -v177
	ds_write_b16 v242, v246 offset:4096
	ds_write_b16_d16_hi v242, v246 offset:4352
	v_cvt_pk_bf16_f32 v247, -v175, -v173
	ds_write_b16 v242, v247 offset:4608
	ds_write_b16_d16_hi v242, v247 offset:4864
	v_cvt_pk_bf16_f32 v246, -v171, -v169
	ds_write_b16 v242, v246 offset:5120
	ds_write_b16_d16_hi v242, v246 offset:5376
	v_cvt_pk_bf16_f32 v247, -v167, -v165
	ds_write_b16 v242, v247 offset:5632
	ds_write_b16_d16_hi v242, v247 offset:5888
	v_cvt_pk_bf16_f32 v246, -v163, -v161
	ds_write_b16 v242, v246 offset:6144
	ds_write_b16_d16_hi v242, v246 offset:6400
	v_cvt_pk_bf16_f32 v247, -v159, -v157
	ds_write_b16 v242, v247 offset:6656
	ds_write_b16_d16_hi v242, v247 offset:6912
	v_cvt_pk_bf16_f32 v246, -v155, -v153
	ds_write_b16 v242, v246 offset:7168
	ds_write_b16_d16_hi v242, v246 offset:7424
	v_cvt_pk_bf16_f32 v247, -v119, -v117
	ds_write_b16 v242, v247 offset:7680
	ds_write_b16_d16_hi v242, v247 offset:7936
	v_cvt_pk_bf16_f32 v246, -v115, -v113
	ds_write_b16 v242, v246 offset:8192
	ds_write_b16_d16_hi v242, v246 offset:8448
	v_cvt_pk_bf16_f32 v247, -v111, -v109
	ds_write_b16 v242, v247 offset:8704
	ds_write_b16_d16_hi v242, v247 offset:8960
	v_cvt_pk_bf16_f32 v246, -v107, -v105
	ds_write_b16 v242, v246 offset:9216
	ds_write_b16_d16_hi v242, v246 offset:9472
	v_cvt_pk_bf16_f32 v247, -v103, -v101
	ds_write_b16 v242, v247 offset:9728
	ds_write_b16_d16_hi v242, v247 offset:9984
	v_cvt_pk_bf16_f32 v246, -v99, -v97
	ds_write_b16 v242, v246 offset:10240
	ds_write_b16_d16_hi v242, v246 offset:10496
	v_cvt_pk_bf16_f32 v247, -v95, -v93
	ds_write_b16 v242, v247 offset:10752
	ds_write_b16_d16_hi v242, v247 offset:11008
	v_cvt_pk_bf16_f32 v246, -v91, -v89
	ds_write_b16 v242, v246 offset:11264
	ds_write_b16_d16_hi v242, v246 offset:11520
	v_cvt_pk_bf16_f32 v247, -v87, -v85
	ds_write_b16 v242, v247 offset:11776
	ds_write_b16_d16_hi v242, v247 offset:12032
	v_cvt_pk_bf16_f32 v246, -v83, -v81
	ds_write_b16 v242, v246 offset:12288
	ds_write_b16_d16_hi v242, v246 offset:12544
	v_cvt_pk_bf16_f32 v247, -v79, -v77
	ds_write_b16 v242, v247 offset:12800
	ds_write_b16_d16_hi v242, v247 offset:13056
	v_cvt_pk_bf16_f32 v246, -v75, -v73
	ds_write_b16 v242, v246 offset:13312
	ds_write_b16_d16_hi v242, v246 offset:13568
	v_cvt_pk_bf16_f32 v247, -v71, -v69
	ds_write_b16 v242, v247 offset:13824
	ds_write_b16_d16_hi v242, v247 offset:14080
	v_cvt_pk_bf16_f32 v246, -v67, -v65
	ds_write_b16 v242, v246 offset:14336
	ds_write_b16_d16_hi v242, v246 offset:14592
	v_cvt_pk_bf16_f32 v247, -v63, -v61
	ds_write_b16 v242, v247 offset:14848
	ds_write_b16_d16_hi v242, v247 offset:15104
	v_cvt_pk_bf16_f32 v246, -v59, -v57
	ds_write_b16 v242, v246 offset:15360
	ds_write_b16_d16_hi v242, v246 offset:15616
	v_cvt_pk_bf16_f32 v247, -v55, -v7
	ds_write_b16 v242, v247 offset:15872
	ds_write_b16_d16_hi v242, v247 offset:16128
.Lpz_restore:
	ds_read_b32 v88, v244 offset:0
	ds_read_b32 v89, v244 offset:256
	ds_read_b32 v90, v244 offset:512
	ds_read_b32 v91, v244 offset:768
	ds_read_b32 v92, v244 offset:1024
	ds_read_b32 v93, v244 offset:1280
	ds_read_b32 v94, v244 offset:1536
	ds_read_b32 v95, v244 offset:1792
	ds_read_b32 v96, v244 offset:2048
	ds_read_b32 v97, v244 offset:2304
	ds_read_b32 v98, v244 offset:2560
	ds_read_b32 v99, v244 offset:2816
	ds_read_b32 v100, v244 offset:3072
	ds_read_b32 v101, v244 offset:3328
	ds_read_b32 v102, v244 offset:3584
	ds_read_b32 v103, v244 offset:3840
	ds_read_b32 v104, v244 offset:4096
	ds_read_b32 v105, v244 offset:4352
	ds_read_b32 v106, v244 offset:4608
	ds_read_b32 v107, v244 offset:4864
	ds_read_b32 v108, v244 offset:5120
	ds_read_b32 v109, v244 offset:5376
	ds_read_b32 v110, v244 offset:5632
	ds_read_b32 v111, v244 offset:5888
	ds_read_b32 v112, v244 offset:6144
	ds_read_b32 v113, v244 offset:6400
	ds_read_b32 v114, v244 offset:6656
	ds_read_b32 v115, v244 offset:6912
	ds_read_b32 v116, v244 offset:7168
	ds_read_b32 v117, v244 offset:7424
	ds_read_b32 v118, v244 offset:7680
	ds_read_b32 v119, v244 offset:7936
.Lpz_join:
	s_waitcnt lgkmcnt(0)
	s_barrier
	v_lshlrev_b32_e32 v6, 4, v144
	ds_read_b128 v[2:5], v6 offset:34816
	ds_read_b128 v[26:29], v6 offset:43008
	ds_read_b128 v[30:33], v6 offset:51200
	ds_read_b128 v[34:37], v6 offset:59392
	s_lshl_b32 s80, s2, 15
	s_add_u32 s82, s44, 0x7f00000
	s_addc_u32 s83, s45, 0
	s_add_u32 s82, s82, s80
	s_addc_u32 s83, s83, 0
	v_add_u32_e32 v7, 0x2000, v6
	v_add_u32_e32 v38, 0x4000, v6
	v_add_u32_e32 v39, 0x6000, v6
	s_waitcnt lgkmcnt(3)
	global_store_dwordx4 v6, v[2:5], s[82:83]
	s_waitcnt lgkmcnt(2)
	global_store_dwordx4 v7, v[26:29], s[82:83]
	s_waitcnt lgkmcnt(1)
	global_store_dwordx4 v38, v[30:33], s[82:83]
	s_waitcnt lgkmcnt(0)
	global_store_dwordx4 v39, v[34:37], s[82:83]
	s_add_i32 s2, s2, s38
	v_readlane_b32 s72, v254, 30
	v_readlane_b32 s73, v254, 31
	v_readlane_b32 s74, v254, 34
	v_readlane_b32 s75, v254, 35
	v_readlane_b32 s80, v254, 36
	v_readlane_b32 s81, v254, 37
	s_add_u32 s76, s76, s72
	s_addc_u32 s77, s77, s73
	s_nop 1
	v_lshl_add_u64 v[12:13], v[12:13], 0, s[72:73]
	v_lshl_add_u64 v[16:17], v[16:17], 0, s[72:73]
	v_lshl_add_u64 v[14:15], v[14:15], 0, s[74:75]
	v_lshl_add_u64 v[18:19], v[18:19], 0, s[80:81]
	v_lshl_add_u64 v[20:21], v[20:21], 0, s[80:81]
	v_lshl_add_u64 v[22:23], v[22:23], 0, s[74:75]
	s_cmpk_gt_i32 s2, 0x47f
	s_barrier
	s_cbranch_scc1 .LBB0_665
	s_branch .LBB0_573
